# asymmetric half-workgroup K-loops (leading half load-MFMA-barrier, trailing half load-barrier-MFMA): 2 barriers per K-tile instead of 4, no epilogue alignment barriers
# baseline (speedup 1.0000x reference)
.LBB0_135:
	s_lshl_b32 s10, s71, 5
	s_and_b32 s37, s10, 0x60
	s_mov_b64 s[10:11], 0x80
	s_add_i32 m0, s47, 0x18000
	v_lshl_add_u64 v[6:7], v[6:7], 0, s[10:11]
	s_lshl_b32 s36, s1, 13
	s_lshr_b32 s38, s37, 3
	s_nop 0
	global_load_lds_dwordx4 v[6:7], off
	v_lshl_add_u64 v[4:5], v[4:5], 0, s[10:11]
	s_add_i32 m0, s47, 0x1a000
	s_add_i32 s69, s47, 0x8000
	s_add_i32 s70, s47, 0xa000
	global_load_lds_dwordx4 v[4:5], off
	v_lshl_add_u64 v[0:1], v[0:1], 0, s[10:11]
	s_mov_b32 m0, s69
	s_add_u32 s26, s50, 0x40080
	global_load_lds_dwordx4 v[0:1], off
	v_lshl_add_u64 v[0:1], v[2:3], 0, s[10:11]
	s_mov_b32 m0, s70
	s_addc_u32 s27, s51, 0
	global_load_lds_dwordx4 v[0:1], off
	s_add_i32 m0, s47, 0x1c000
	v_lshl_add_u64 v[0:1], s[26:27], 0, v[132:133]
	global_load_lds_dwordx4 v[0:1], off
	v_lshl_add_u64 v[0:1], s[26:27], 0, v[128:129]
	s_add_i32 m0, s47, 0x1e000
	v_lshrrev_b32_e32 v2, 6, v10
	global_load_lds_dwordx4 v[0:1], off
	v_and_b32_e32 v0, 15, v10
	v_lshlrev_b32_e32 v5, 2, v10
	v_lshl_or_b32 v144, s1, 6, v0
	v_and_b32_e32 v3, 48, v10
	v_lshlrev_b32_e32 v4, 10, v2
	v_lshlrev_b32_e32 v0, 6, v0
	v_and_b32_e32 v5, 32, v5
	v_or_b32_e32 v2, s38, v2
	v_bitop3_b32 v6, v0, v5, v3 bitop3:0x36
	v_or_b32_e32 v0, v0, v3
	v_lshlrev_b32_e32 v2, 10, v2
	v_lshrrev_b32_e32 v1, 1, v10
	v_bitop3_b32 v145, v0, v2, v5 bitop3:0xde
	v_lshlrev_b32_e32 v0, 14, v12
	v_and_b32_e32 v1, 56, v1
	v_and_b32_e32 v0, 0xffff8000, v0
	v_add_u32_e32 v146, s37, v1
	v_lshl_add_u32 v0, v13, 11, v0
	v_and_b32_e32 v1, 1, v12
	v_lshl_or_b32 v0, v1, 6, v0
	v_lshl_add_u32 v136, v14, 1, v0
	v_lshlrev_b32_e32 v0, 14, v8
	v_and_b32_e32 v0, 0xffff8000, v0
	s_waitcnt vmcnt(6)
	s_cmpk_lt_u32 s3, 0x100
	v_lshl_add_u32 v0, v9, 11, v0
	v_and_b32_e32 v1, 1, v8
	v_or3_b32 v4, v4, s36, v6
	s_cselect_b64 s[26:27], -1, 0
	v_lshl_or_b32 v0, v1, 6, v0
	s_add_i32 s73, 0, 0x10000
	s_add_i32 s74, 0, 0x14000
	s_sext_i32_i16 s76, s0
	s_ashr_i32 s71, s34, 31
	s_mov_b32 s72, s34
	v_mov_b32_e32 v137, v133
	v_lshl_add_u32 v138, v11, 1, v0
	v_mov_b32_e32 v139, v133
	v_mov_b64_e32 v[140:141], 0x1b80
	v_mov_b64_e32 v[142:143], 0x1b7f
	v_add_u32_e32 v147, s73, v145
	v_add_u32_e32 v148, s74, v145
	v_add_u32_e32 v149, 0, v4
	s_movk_i32 s75, 0x1600
	s_barrier
	s_branch .LBB0_138

.LBB0_140:
	s_ashr_i32 s37, s36, 31
	s_lshl_b64 s[42:43], s[36:37], 19
	s_add_u32 s42, s62, s42
	s_addc_u32 s43, s63, s43
	s_and_b64 s[44:45], s[0:1], exec
	s_cselect_b32 s37, s43, s49
	s_cselect_b32 s77, s42, s48
	s_ashr_i32 s39, s38, 31
	s_lshl_b64 s[44:45], s[38:39], 19
	s_add_u32 s44, s54, s44
	s_addc_u32 s45, s55, s45
	s_and_b64 s[52:53], s[0:1], exec
	s_cselect_b32 s39, s45, s51
	s_cselect_b32 s78, s44, s50
	s_add_u32 s48, s48, 0x40080
	s_addc_u32 s49, s49, 0
	s_add_u32 s79, s50, 0x100
	s_addc_u32 s80, s51, 0
	s_mov_b32 s81, -2
	s_and_b64 vcc, exec, s[26:27]
	s_cbranch_vccz .Lh1p_1
	ds_read_b128 v[150:153], v147
	ds_read_b128 v[154:157], v147 offset:1024
	ds_read_b128 v[158:161], v147 offset:2048
	ds_read_b128 v[162:165], v147 offset:3072
	ds_read_b128 v[166:169], v148
	ds_read_b128 v[170:173], v148 offset:1024
	ds_read_b128 v[174:177], v148 offset:2048
	ds_read_b128 v[178:181], v148 offset:3072
	s_add_u32 s50, s48, 0xfffc0080
	s_addc_u32 s51, s49, -1
	s_cmp_eq_u32 s81, 12
	s_cselect_b32 s53, s37, s51
	s_cselect_b32 s52, s77, s50
	s_cselect_b32 s51, s39, s80
	s_cselect_b32 s50, s78, s79
	v_lshl_add_u64 v[214:215], s[48:49], 0, v[136:137]
	s_add_i32 m0, s47, 0xc000
	ds_read_b128 v[182:185], v149
	ds_read_b128 v[186:189], v149 offset:1024
	ds_read_b128 v[190:193], v149 offset:2048
	ds_read_b128 v[194:197], v149 offset:3072
	ds_read_b128 v[198:201], v149 offset:4096
	ds_read_b128 v[202:205], v149 offset:5120
	ds_read_b128 v[206:209], v149 offset:6144
	ds_read_b128 v[210:213], v149 offset:7168
	global_load_lds_dwordx4 v[214:215], off
	v_lshl_add_u64 v[214:215], s[48:49], 0, v[138:139]
	s_add_i32 m0, s47, 0xe000
	s_nop 0
	global_load_lds_dwordx4 v[214:215], off
	s_waitcnt vmcnt(8)
	s_waitcnt lgkmcnt(0)
	s_setprio 1
	v_mfma_f32_16x16x32_bf16 v[124:127], v[150:153], v[182:185], 0
	v_mfma_f32_16x16x32_bf16 v[116:119], v[158:161], v[182:185], 0
	v_mfma_f32_16x16x32_bf16 v[108:111], v[150:153], v[190:193], 0
	v_mfma_f32_16x16x32_bf16 v[100:103], v[158:161], v[190:193], 0
	v_mfma_f32_16x16x32_bf16 v[92:95], v[150:153], v[198:201], 0
	v_mfma_f32_16x16x32_bf16 v[84:87], v[158:161], v[198:201], 0
	v_mfma_f32_16x16x32_bf16 v[76:79], v[150:153], v[206:209], 0
	v_mfma_f32_16x16x32_bf16 v[68:71], v[158:161], v[206:209], 0
	v_mfma_f32_16x16x32_bf16 v[124:127], v[154:157], v[186:189], v[124:127]
	v_mfma_f32_16x16x32_bf16 v[116:119], v[162:165], v[186:189], v[116:119]
	v_mfma_f32_16x16x32_bf16 v[108:111], v[154:157], v[194:197], v[108:111]
	v_mfma_f32_16x16x32_bf16 v[100:103], v[162:165], v[194:197], v[100:103]
	v_mfma_f32_16x16x32_bf16 v[92:95], v[154:157], v[202:205], v[92:95]
	v_mfma_f32_16x16x32_bf16 v[84:87], v[162:165], v[202:205], v[84:87]
	v_mfma_f32_16x16x32_bf16 v[76:79], v[154:157], v[210:213], v[76:79]
	v_mfma_f32_16x16x32_bf16 v[68:71], v[162:165], v[210:213], v[68:71]
	v_mfma_f32_16x16x32_bf16 v[120:123], v[166:169], v[182:185], 0
	v_mfma_f32_16x16x32_bf16 v[112:115], v[174:177], v[182:185], 0
	v_mfma_f32_16x16x32_bf16 v[104:107], v[166:169], v[190:193], 0
	v_mfma_f32_16x16x32_bf16 v[96:99], v[174:177], v[190:193], 0
	v_mfma_f32_16x16x32_bf16 v[88:91], v[166:169], v[198:201], 0
	v_mfma_f32_16x16x32_bf16 v[80:83], v[174:177], v[198:201], 0
	v_mfma_f32_16x16x32_bf16 v[72:75], v[166:169], v[206:209], 0
	v_mfma_f32_16x16x32_bf16 v[64:67], v[174:177], v[206:209], 0
	v_mfma_f32_16x16x32_bf16 v[120:123], v[170:173], v[186:189], v[120:123]
	v_mfma_f32_16x16x32_bf16 v[112:115], v[178:181], v[186:189], v[112:115]
	v_mfma_f32_16x16x32_bf16 v[104:107], v[170:173], v[194:197], v[104:107]
	v_mfma_f32_16x16x32_bf16 v[96:99], v[178:181], v[194:197], v[96:99]
	v_mfma_f32_16x16x32_bf16 v[88:91], v[170:173], v[202:205], v[88:91]
	v_mfma_f32_16x16x32_bf16 v[80:83], v[178:181], v[202:205], v[80:83]
	v_mfma_f32_16x16x32_bf16 v[72:75], v[170:173], v[210:213], v[72:75]
	v_mfma_f32_16x16x32_bf16 v[64:67], v[178:181], v[210:213], v[64:67]
	s_setprio 0
	s_barrier
	s_add_i32 s82, s73, s56
	v_lshl_add_u64 v[214:215], s[50:51], 0, v[132:133]
	s_mov_b32 m0, s82
	ds_read_b128 v[182:185], v149 offset:16384
	ds_read_b128 v[186:189], v149 offset:17408
	ds_read_b128 v[190:193], v149 offset:18432
	ds_read_b128 v[194:197], v149 offset:19456
	ds_read_b128 v[198:201], v149 offset:20480
	ds_read_b128 v[202:205], v149 offset:21504
	ds_read_b128 v[206:209], v149 offset:22528
	ds_read_b128 v[210:213], v149 offset:23552
	global_load_lds_dwordx4 v[214:215], off
	s_add_i32 m0, s82, 0x2000
	s_add_u32 s88, s50, 0x40000
	v_lshl_add_u64 v[216:217], s[50:51], 0, v[128:129]
	s_addc_u32 s89, s51, 0
	s_add_i32 s82, s74, s56
	global_load_lds_dwordx4 v[216:217], off
	v_lshl_add_u64 v[218:219], s[88:89], 0, v[132:133]
	s_mov_b32 m0, s82
	v_lshl_add_u64 v[220:221], s[52:53], 0, v[130:131]
	global_load_lds_dwordx4 v[218:219], off
	v_lshl_add_u64 v[218:219], s[88:89], 0, v[128:129]
	s_add_i32 m0, s82, 0x2000
	s_nop 0
	global_load_lds_dwordx4 v[218:219], off
	v_lshl_add_u64 v[218:219], s[52:53], 0, v[134:135]
	s_mov_b32 m0, s47
	s_nop 0
	global_load_lds_dwordx4 v[218:219], off
	s_mov_b32 m0, s59
	s_nop 0
	global_load_lds_dwordx4 v[220:221], off
	s_waitcnt vmcnt(8)
	s_waitcnt lgkmcnt(0)
	s_setprio 1
	v_mfma_f32_16x16x32_bf16 v[60:63], v[150:153], v[182:185], 0
	v_mfma_f32_16x16x32_bf16 v[52:55], v[158:161], v[182:185], 0
	v_mfma_f32_16x16x32_bf16 v[44:47], v[150:153], v[190:193], 0
	v_mfma_f32_16x16x32_bf16 v[36:39], v[158:161], v[190:193], 0
	v_mfma_f32_16x16x32_bf16 v[28:31], v[150:153], v[198:201], 0
	v_mfma_f32_16x16x32_bf16 v[20:23], v[158:161], v[198:201], 0
	v_mfma_f32_16x16x32_bf16 v[12:15], v[150:153], v[206:209], 0
	v_mfma_f32_16x16x32_bf16 v[4:7], v[158:161], v[206:209], 0
	v_mfma_f32_16x16x32_bf16 v[60:63], v[154:157], v[186:189], v[60:63]
	v_mfma_f32_16x16x32_bf16 v[52:55], v[162:165], v[186:189], v[52:55]
	v_mfma_f32_16x16x32_bf16 v[44:47], v[154:157], v[194:197], v[44:47]
	v_mfma_f32_16x16x32_bf16 v[36:39], v[162:165], v[194:197], v[36:39]
	v_mfma_f32_16x16x32_bf16 v[28:31], v[154:157], v[202:205], v[28:31]
	v_mfma_f32_16x16x32_bf16 v[20:23], v[162:165], v[202:205], v[20:23]
	v_mfma_f32_16x16x32_bf16 v[12:15], v[154:157], v[210:213], v[12:15]
	v_mfma_f32_16x16x32_bf16 v[4:7], v[162:165], v[210:213], v[4:7]
	v_mfma_f32_16x16x32_bf16 v[56:59], v[166:169], v[182:185], 0
	v_mfma_f32_16x16x32_bf16 v[48:51], v[174:177], v[182:185], 0
	v_mfma_f32_16x16x32_bf16 v[40:43], v[166:169], v[190:193], 0
	v_mfma_f32_16x16x32_bf16 v[32:35], v[174:177], v[190:193], 0
	v_mfma_f32_16x16x32_bf16 v[24:27], v[166:169], v[198:201], 0
	v_mfma_f32_16x16x32_bf16 v[16:19], v[174:177], v[198:201], 0
	v_mfma_f32_16x16x32_bf16 v[8:11], v[166:169], v[206:209], 0
	v_mfma_f32_16x16x32_bf16 v[0:3], v[174:177], v[206:209], 0
	v_mfma_f32_16x16x32_bf16 v[56:59], v[170:173], v[186:189], v[56:59]
	v_mfma_f32_16x16x32_bf16 v[48:51], v[178:181], v[186:189], v[48:51]
	v_mfma_f32_16x16x32_bf16 v[40:43], v[170:173], v[194:197], v[40:43]
	v_mfma_f32_16x16x32_bf16 v[32:35], v[178:181], v[194:197], v[32:35]
	v_mfma_f32_16x16x32_bf16 v[24:27], v[170:173], v[202:205], v[24:27]
	v_mfma_f32_16x16x32_bf16 v[16:19], v[178:181], v[202:205], v[16:19]
	v_mfma_f32_16x16x32_bf16 v[8:11], v[170:173], v[210:213], v[8:11]
	v_mfma_f32_16x16x32_bf16 v[0:3], v[178:181], v[210:213], v[0:3]
	s_setprio 0
	s_barrier
	s_add_i32 s82, 0, 0x18000
	s_add_i32 s85, 0, 0x1c000
	v_add_u32_e32 v162, s82, v145
	v_add_u32_e32 v178, s85, v145
	ds_read_b128 v[150:153], v162
	ds_read_b128 v[154:157], v162 offset:1024
	ds_read_b128 v[158:161], v162 offset:2048
	ds_read_b128 v[162:165], v162 offset:3072
	ds_read_b128 v[166:169], v178
	ds_read_b128 v[170:173], v178 offset:1024
	ds_read_b128 v[174:177], v178 offset:2048
	ds_read_b128 v[178:181], v178 offset:3072
	s_add_u32 s52, s52, 0x40000
	s_addc_u32 s53, s53, 0
	s_mov_b32 m0, s66
	v_lshl_add_u64 v[222:223], s[52:53], 0, v[134:135]
	ds_read_b128 v[182:185], v149 offset:32768
	ds_read_b128 v[186:189], v149 offset:33792
	ds_read_b128 v[190:193], v149 offset:34816
	ds_read_b128 v[194:197], v149 offset:35840
	ds_read_b128 v[198:201], v149 offset:36864
	ds_read_b128 v[202:205], v149 offset:37888
	ds_read_b128 v[206:209], v149 offset:38912
	ds_read_b128 v[210:213], v149 offset:39936
	global_load_lds_dwordx4 v[222:223], off
	v_lshl_add_u64 v[222:223], s[52:53], 0, v[130:131]
	s_mov_b32 m0, s67
	s_nop 0
	global_load_lds_dwordx4 v[222:223], off
	s_waitcnt vmcnt(8)
	s_waitcnt lgkmcnt(0)
	s_setprio 1
	v_mfma_f32_16x16x32_bf16 v[124:127], v[150:153], v[182:185], v[124:127]
	v_mfma_f32_16x16x32_bf16 v[116:119], v[158:161], v[182:185], v[116:119]
	v_mfma_f32_16x16x32_bf16 v[108:111], v[150:153], v[190:193], v[108:111]
	v_mfma_f32_16x16x32_bf16 v[100:103], v[158:161], v[190:193], v[100:103]
	v_mfma_f32_16x16x32_bf16 v[92:95], v[150:153], v[198:201], v[92:95]
	v_mfma_f32_16x16x32_bf16 v[84:87], v[158:161], v[198:201], v[84:87]
	v_mfma_f32_16x16x32_bf16 v[76:79], v[150:153], v[206:209], v[76:79]
	v_mfma_f32_16x16x32_bf16 v[68:71], v[158:161], v[206:209], v[68:71]
	v_mfma_f32_16x16x32_bf16 v[124:127], v[154:157], v[186:189], v[124:127]
	v_mfma_f32_16x16x32_bf16 v[116:119], v[162:165], v[186:189], v[116:119]
	v_mfma_f32_16x16x32_bf16 v[108:111], v[154:157], v[194:197], v[108:111]
	v_mfma_f32_16x16x32_bf16 v[100:103], v[162:165], v[194:197], v[100:103]
	v_mfma_f32_16x16x32_bf16 v[92:95], v[154:157], v[202:205], v[92:95]
	v_mfma_f32_16x16x32_bf16 v[84:87], v[162:165], v[202:205], v[84:87]
	v_mfma_f32_16x16x32_bf16 v[76:79], v[154:157], v[210:213], v[76:79]
	v_mfma_f32_16x16x32_bf16 v[68:71], v[162:165], v[210:213], v[68:71]
	v_mfma_f32_16x16x32_bf16 v[120:123], v[166:169], v[182:185], v[120:123]
	v_mfma_f32_16x16x32_bf16 v[112:115], v[174:177], v[182:185], v[112:115]
	v_mfma_f32_16x16x32_bf16 v[104:107], v[166:169], v[190:193], v[104:107]
	v_mfma_f32_16x16x32_bf16 v[96:99], v[174:177], v[190:193], v[96:99]
	v_mfma_f32_16x16x32_bf16 v[88:91], v[166:169], v[198:201], v[88:91]
	v_mfma_f32_16x16x32_bf16 v[80:83], v[174:177], v[198:201], v[80:83]
	v_mfma_f32_16x16x32_bf16 v[72:75], v[166:169], v[206:209], v[72:75]
	v_mfma_f32_16x16x32_bf16 v[64:67], v[174:177], v[206:209], v[64:67]
	v_mfma_f32_16x16x32_bf16 v[120:123], v[170:173], v[186:189], v[120:123]
	v_mfma_f32_16x16x32_bf16 v[112:115], v[178:181], v[186:189], v[112:115]
	v_mfma_f32_16x16x32_bf16 v[104:107], v[170:173], v[194:197], v[104:107]
	v_mfma_f32_16x16x32_bf16 v[96:99], v[178:181], v[194:197], v[96:99]
	v_mfma_f32_16x16x32_bf16 v[88:91], v[170:173], v[202:205], v[88:91]
	v_mfma_f32_16x16x32_bf16 v[80:83], v[178:181], v[202:205], v[80:83]
	v_mfma_f32_16x16x32_bf16 v[72:75], v[170:173], v[210:213], v[72:75]
	v_mfma_f32_16x16x32_bf16 v[64:67], v[178:181], v[210:213], v[64:67]
	s_setprio 0
	s_barrier
	s_add_i32 s52, s82, s56
	v_lshl_add_u64 v[214:215], v[214:215], 0, s[10:11]
	s_mov_b32 m0, s52
	ds_read_b128 v[182:185], v149 offset:49152
	ds_read_b128 v[186:189], v149 offset:50176
	ds_read_b128 v[190:193], v149 offset:51200
	ds_read_b128 v[194:197], v149 offset:52224
	ds_read_b128 v[198:201], v149 offset:53248
	ds_read_b128 v[202:205], v149 offset:54272
	ds_read_b128 v[206:209], v149 offset:55296
	ds_read_b128 v[210:213], v149 offset:56320
	global_load_lds_dwordx4 v[214:215], off
	s_add_i32 m0, s52, 0x2000
	s_add_u32 s50, s50, 0x40080
	v_lshl_add_u64 v[214:215], v[216:217], 0, s[10:11]
	s_addc_u32 s51, s51, 0
	s_add_i32 s52, s85, s56
	global_load_lds_dwordx4 v[214:215], off
	v_lshl_add_u64 v[214:215], s[50:51], 0, v[132:133]
	s_mov_b32 m0, s52
	s_nop 0
	global_load_lds_dwordx4 v[214:215], off
	v_lshl_add_u64 v[214:215], s[50:51], 0, v[128:129]
	s_add_i32 m0, s52, 0x2000
	s_nop 0
	global_load_lds_dwordx4 v[214:215], off
	v_lshl_add_u64 v[214:215], v[218:219], 0, s[10:11]
	s_mov_b32 m0, s69
	s_nop 0
	global_load_lds_dwordx4 v[214:215], off
	v_lshl_add_u64 v[214:215], v[220:221], 0, s[10:11]
	s_mov_b32 m0, s70
	s_nop 0
	global_load_lds_dwordx4 v[214:215], off
	s_waitcnt vmcnt(8)
	s_waitcnt lgkmcnt(0)
	s_setprio 1
	v_mfma_f32_16x16x32_bf16 v[60:63], v[150:153], v[182:185], v[60:63]
	v_mfma_f32_16x16x32_bf16 v[52:55], v[158:161], v[182:185], v[52:55]
	v_mfma_f32_16x16x32_bf16 v[44:47], v[150:153], v[190:193], v[44:47]
	v_mfma_f32_16x16x32_bf16 v[36:39], v[158:161], v[190:193], v[36:39]
	v_mfma_f32_16x16x32_bf16 v[28:31], v[150:153], v[198:201], v[28:31]
	v_mfma_f32_16x16x32_bf16 v[20:23], v[158:161], v[198:201], v[20:23]
	v_mfma_f32_16x16x32_bf16 v[12:15], v[150:153], v[206:209], v[12:15]
	v_mfma_f32_16x16x32_bf16 v[4:7], v[158:161], v[206:209], v[4:7]
	v_mfma_f32_16x16x32_bf16 v[60:63], v[154:157], v[186:189], v[60:63]
	v_mfma_f32_16x16x32_bf16 v[52:55], v[162:165], v[186:189], v[52:55]
	v_mfma_f32_16x16x32_bf16 v[44:47], v[154:157], v[194:197], v[44:47]
	v_mfma_f32_16x16x32_bf16 v[36:39], v[162:165], v[194:197], v[36:39]
	v_mfma_f32_16x16x32_bf16 v[28:31], v[154:157], v[202:205], v[28:31]
	v_mfma_f32_16x16x32_bf16 v[20:23], v[162:165], v[202:205], v[20:23]
	v_mfma_f32_16x16x32_bf16 v[12:15], v[154:157], v[210:213], v[12:15]
	v_mfma_f32_16x16x32_bf16 v[4:7], v[162:165], v[210:213], v[4:7]
	v_mfma_f32_16x16x32_bf16 v[56:59], v[166:169], v[182:185], v[56:59]
	v_mfma_f32_16x16x32_bf16 v[48:51], v[174:177], v[182:185], v[48:51]
	v_mfma_f32_16x16x32_bf16 v[40:43], v[166:169], v[190:193], v[40:43]
	v_mfma_f32_16x16x32_bf16 v[32:35], v[174:177], v[190:193], v[32:35]
	v_mfma_f32_16x16x32_bf16 v[24:27], v[166:169], v[198:201], v[24:27]
	v_mfma_f32_16x16x32_bf16 v[16:19], v[174:177], v[198:201], v[16:19]
	v_mfma_f32_16x16x32_bf16 v[8:11], v[166:169], v[206:209], v[8:11]
	v_mfma_f32_16x16x32_bf16 v[0:3], v[174:177], v[206:209], v[0:3]
	v_mfma_f32_16x16x32_bf16 v[56:59], v[170:173], v[186:189], v[56:59]
	v_mfma_f32_16x16x32_bf16 v[48:51], v[178:181], v[186:189], v[48:51]
	v_mfma_f32_16x16x32_bf16 v[40:43], v[170:173], v[194:197], v[40:43]
	v_mfma_f32_16x16x32_bf16 v[32:35], v[178:181], v[194:197], v[32:35]
	v_mfma_f32_16x16x32_bf16 v[24:27], v[170:173], v[202:205], v[24:27]
	v_mfma_f32_16x16x32_bf16 v[16:19], v[178:181], v[202:205], v[16:19]
	v_mfma_f32_16x16x32_bf16 v[8:11], v[170:173], v[210:213], v[8:11]
	v_mfma_f32_16x16x32_bf16 v[0:3], v[178:181], v[210:213], v[0:3]
	s_setprio 0
	s_barrier
	s_add_i32 s81, s81, 2
	s_add_u32 s48, s48, 0x100
	s_addc_u32 s49, s49, 0
	s_add_u32 s79, s79, 0x100
	s_addc_u32 s80, s80, 0
	s_cmp_gt_u32 s81, 13
.Lh0_1:
	ds_read_b128 v[150:153], v147
	ds_read_b128 v[154:157], v147 offset:1024
	ds_read_b128 v[158:161], v147 offset:2048
	ds_read_b128 v[162:165], v147 offset:3072
	ds_read_b128 v[166:169], v148
	ds_read_b128 v[170:173], v148 offset:1024
	ds_read_b128 v[174:177], v148 offset:2048
	ds_read_b128 v[178:181], v148 offset:3072
	s_add_u32 s50, s48, 0xfffc0080
	s_addc_u32 s51, s49, -1
	s_cmp_eq_u32 s81, 12
	s_cselect_b32 s53, s37, s51
	s_cselect_b32 s52, s77, s50
	s_cselect_b32 s51, s39, s80
	s_cselect_b32 s50, s78, s79
	v_lshl_add_u64 v[214:215], s[48:49], 0, v[136:137]
	s_add_i32 m0, s47, 0xc000
	ds_read_b128 v[182:185], v149
	ds_read_b128 v[186:189], v149 offset:1024
	ds_read_b128 v[190:193], v149 offset:2048
	ds_read_b128 v[194:197], v149 offset:3072
	ds_read_b128 v[198:201], v149 offset:4096
	ds_read_b128 v[202:205], v149 offset:5120
	ds_read_b128 v[206:209], v149 offset:6144
	ds_read_b128 v[210:213], v149 offset:7168
	global_load_lds_dwordx4 v[214:215], off
	v_lshl_add_u64 v[214:215], s[48:49], 0, v[138:139]
	s_add_i32 m0, s47, 0xe000
	s_nop 0
	global_load_lds_dwordx4 v[214:215], off
	s_waitcnt vmcnt(8)
	s_waitcnt lgkmcnt(0)
	s_setprio 1
	v_mfma_f32_16x16x32_bf16 v[124:127], v[150:153], v[182:185], v[124:127]
	v_mfma_f32_16x16x32_bf16 v[116:119], v[158:161], v[182:185], v[116:119]
	v_mfma_f32_16x16x32_bf16 v[108:111], v[150:153], v[190:193], v[108:111]
	v_mfma_f32_16x16x32_bf16 v[100:103], v[158:161], v[190:193], v[100:103]
	v_mfma_f32_16x16x32_bf16 v[92:95], v[150:153], v[198:201], v[92:95]
	v_mfma_f32_16x16x32_bf16 v[84:87], v[158:161], v[198:201], v[84:87]
	v_mfma_f32_16x16x32_bf16 v[76:79], v[150:153], v[206:209], v[76:79]
	v_mfma_f32_16x16x32_bf16 v[68:71], v[158:161], v[206:209], v[68:71]
	v_mfma_f32_16x16x32_bf16 v[124:127], v[154:157], v[186:189], v[124:127]
	v_mfma_f32_16x16x32_bf16 v[116:119], v[162:165], v[186:189], v[116:119]
	v_mfma_f32_16x16x32_bf16 v[108:111], v[154:157], v[194:197], v[108:111]
	v_mfma_f32_16x16x32_bf16 v[100:103], v[162:165], v[194:197], v[100:103]
	v_mfma_f32_16x16x32_bf16 v[92:95], v[154:157], v[202:205], v[92:95]
	v_mfma_f32_16x16x32_bf16 v[84:87], v[162:165], v[202:205], v[84:87]
	v_mfma_f32_16x16x32_bf16 v[76:79], v[154:157], v[210:213], v[76:79]
	v_mfma_f32_16x16x32_bf16 v[68:71], v[162:165], v[210:213], v[68:71]
	v_mfma_f32_16x16x32_bf16 v[120:123], v[166:169], v[182:185], v[120:123]
	v_mfma_f32_16x16x32_bf16 v[112:115], v[174:177], v[182:185], v[112:115]
	v_mfma_f32_16x16x32_bf16 v[104:107], v[166:169], v[190:193], v[104:107]
	v_mfma_f32_16x16x32_bf16 v[96:99], v[174:177], v[190:193], v[96:99]
	v_mfma_f32_16x16x32_bf16 v[88:91], v[166:169], v[198:201], v[88:91]
	v_mfma_f32_16x16x32_bf16 v[80:83], v[174:177], v[198:201], v[80:83]
	v_mfma_f32_16x16x32_bf16 v[72:75], v[166:169], v[206:209], v[72:75]
	v_mfma_f32_16x16x32_bf16 v[64:67], v[174:177], v[206:209], v[64:67]
	v_mfma_f32_16x16x32_bf16 v[120:123], v[170:173], v[186:189], v[120:123]
	v_mfma_f32_16x16x32_bf16 v[112:115], v[178:181], v[186:189], v[112:115]
	v_mfma_f32_16x16x32_bf16 v[104:107], v[170:173], v[194:197], v[104:107]
	v_mfma_f32_16x16x32_bf16 v[96:99], v[178:181], v[194:197], v[96:99]
	v_mfma_f32_16x16x32_bf16 v[88:91], v[170:173], v[202:205], v[88:91]
	v_mfma_f32_16x16x32_bf16 v[80:83], v[178:181], v[202:205], v[80:83]
	v_mfma_f32_16x16x32_bf16 v[72:75], v[170:173], v[210:213], v[72:75]
	v_mfma_f32_16x16x32_bf16 v[64:67], v[178:181], v[210:213], v[64:67]
	s_setprio 0
	s_barrier
	s_add_i32 s82, s73, s56
	v_lshl_add_u64 v[214:215], s[50:51], 0, v[132:133]
	s_mov_b32 m0, s82
	ds_read_b128 v[182:185], v149 offset:16384
	ds_read_b128 v[186:189], v149 offset:17408
	ds_read_b128 v[190:193], v149 offset:18432
	ds_read_b128 v[194:197], v149 offset:19456
	ds_read_b128 v[198:201], v149 offset:20480
	ds_read_b128 v[202:205], v149 offset:21504
	ds_read_b128 v[206:209], v149 offset:22528
	ds_read_b128 v[210:213], v149 offset:23552
	global_load_lds_dwordx4 v[214:215], off
	s_add_i32 m0, s82, 0x2000
	s_add_u32 s88, s50, 0x40000
	v_lshl_add_u64 v[216:217], s[50:51], 0, v[128:129]
	s_addc_u32 s89, s51, 0
	s_add_i32 s82, s74, s56
	global_load_lds_dwordx4 v[216:217], off
	v_lshl_add_u64 v[218:219], s[88:89], 0, v[132:133]
	s_mov_b32 m0, s82
	v_lshl_add_u64 v[220:221], s[52:53], 0, v[130:131]
	global_load_lds_dwordx4 v[218:219], off
	v_lshl_add_u64 v[218:219], s[88:89], 0, v[128:129]
	s_add_i32 m0, s82, 0x2000
	s_nop 0
	global_load_lds_dwordx4 v[218:219], off
	v_lshl_add_u64 v[218:219], s[52:53], 0, v[134:135]
	s_mov_b32 m0, s47
	s_nop 0
	global_load_lds_dwordx4 v[218:219], off
	s_mov_b32 m0, s59
	s_nop 0
	global_load_lds_dwordx4 v[220:221], off
	s_waitcnt vmcnt(8)
	s_waitcnt lgkmcnt(0)
	s_setprio 1
	v_mfma_f32_16x16x32_bf16 v[60:63], v[150:153], v[182:185], v[60:63]
	v_mfma_f32_16x16x32_bf16 v[52:55], v[158:161], v[182:185], v[52:55]
	v_mfma_f32_16x16x32_bf16 v[44:47], v[150:153], v[190:193], v[44:47]
	v_mfma_f32_16x16x32_bf16 v[36:39], v[158:161], v[190:193], v[36:39]
	v_mfma_f32_16x16x32_bf16 v[28:31], v[150:153], v[198:201], v[28:31]
	v_mfma_f32_16x16x32_bf16 v[20:23], v[158:161], v[198:201], v[20:23]
	v_mfma_f32_16x16x32_bf16 v[12:15], v[150:153], v[206:209], v[12:15]
	v_mfma_f32_16x16x32_bf16 v[4:7], v[158:161], v[206:209], v[4:7]
	v_mfma_f32_16x16x32_bf16 v[60:63], v[154:157], v[186:189], v[60:63]
	v_mfma_f32_16x16x32_bf16 v[52:55], v[162:165], v[186:189], v[52:55]
	v_mfma_f32_16x16x32_bf16 v[44:47], v[154:157], v[194:197], v[44:47]
	v_mfma_f32_16x16x32_bf16 v[36:39], v[162:165], v[194:197], v[36:39]
	v_mfma_f32_16x16x32_bf16 v[28:31], v[154:157], v[202:205], v[28:31]
	v_mfma_f32_16x16x32_bf16 v[20:23], v[162:165], v[202:205], v[20:23]
	v_mfma_f32_16x16x32_bf16 v[12:15], v[154:157], v[210:213], v[12:15]
	v_mfma_f32_16x16x32_bf16 v[4:7], v[162:165], v[210:213], v[4:7]
	v_mfma_f32_16x16x32_bf16 v[56:59], v[166:169], v[182:185], v[56:59]
	v_mfma_f32_16x16x32_bf16 v[48:51], v[174:177], v[182:185], v[48:51]
	v_mfma_f32_16x16x32_bf16 v[40:43], v[166:169], v[190:193], v[40:43]
	v_mfma_f32_16x16x32_bf16 v[32:35], v[174:177], v[190:193], v[32:35]
	v_mfma_f32_16x16x32_bf16 v[24:27], v[166:169], v[198:201], v[24:27]
	v_mfma_f32_16x16x32_bf16 v[16:19], v[174:177], v[198:201], v[16:19]
	v_mfma_f32_16x16x32_bf16 v[8:11], v[166:169], v[206:209], v[8:11]
	v_mfma_f32_16x16x32_bf16 v[0:3], v[174:177], v[206:209], v[0:3]
	v_mfma_f32_16x16x32_bf16 v[56:59], v[170:173], v[186:189], v[56:59]
	v_mfma_f32_16x16x32_bf16 v[48:51], v[178:181], v[186:189], v[48:51]
	v_mfma_f32_16x16x32_bf16 v[40:43], v[170:173], v[194:197], v[40:43]
	v_mfma_f32_16x16x32_bf16 v[32:35], v[178:181], v[194:197], v[32:35]
	v_mfma_f32_16x16x32_bf16 v[24:27], v[170:173], v[202:205], v[24:27]
	v_mfma_f32_16x16x32_bf16 v[16:19], v[178:181], v[202:205], v[16:19]
	v_mfma_f32_16x16x32_bf16 v[8:11], v[170:173], v[210:213], v[8:11]
	v_mfma_f32_16x16x32_bf16 v[0:3], v[178:181], v[210:213], v[0:3]
	s_setprio 0
	s_barrier
	s_add_i32 s82, 0, 0x18000
	s_add_i32 s85, 0, 0x1c000
	v_add_u32_e32 v162, s82, v145
	v_add_u32_e32 v178, s85, v145
	ds_read_b128 v[150:153], v162
	ds_read_b128 v[154:157], v162 offset:1024
	ds_read_b128 v[158:161], v162 offset:2048
	ds_read_b128 v[162:165], v162 offset:3072
	ds_read_b128 v[166:169], v178
	ds_read_b128 v[170:173], v178 offset:1024
	ds_read_b128 v[174:177], v178 offset:2048
	ds_read_b128 v[178:181], v178 offset:3072
	s_add_u32 s52, s52, 0x40000
	s_addc_u32 s53, s53, 0
	s_mov_b32 m0, s66
	v_lshl_add_u64 v[222:223], s[52:53], 0, v[134:135]
	ds_read_b128 v[182:185], v149 offset:32768
	ds_read_b128 v[186:189], v149 offset:33792
	ds_read_b128 v[190:193], v149 offset:34816
	ds_read_b128 v[194:197], v149 offset:35840
	ds_read_b128 v[198:201], v149 offset:36864
	ds_read_b128 v[202:205], v149 offset:37888
	ds_read_b128 v[206:209], v149 offset:38912
	ds_read_b128 v[210:213], v149 offset:39936
	global_load_lds_dwordx4 v[222:223], off
	v_lshl_add_u64 v[222:223], s[52:53], 0, v[130:131]
	s_mov_b32 m0, s67
	s_nop 0
	global_load_lds_dwordx4 v[222:223], off
	s_waitcnt vmcnt(8)
	s_waitcnt lgkmcnt(0)
	s_setprio 1
	v_mfma_f32_16x16x32_bf16 v[124:127], v[150:153], v[182:185], v[124:127]
	v_mfma_f32_16x16x32_bf16 v[116:119], v[158:161], v[182:185], v[116:119]
	v_mfma_f32_16x16x32_bf16 v[108:111], v[150:153], v[190:193], v[108:111]
	v_mfma_f32_16x16x32_bf16 v[100:103], v[158:161], v[190:193], v[100:103]
	v_mfma_f32_16x16x32_bf16 v[92:95], v[150:153], v[198:201], v[92:95]
	v_mfma_f32_16x16x32_bf16 v[84:87], v[158:161], v[198:201], v[84:87]
	v_mfma_f32_16x16x32_bf16 v[76:79], v[150:153], v[206:209], v[76:79]
	v_mfma_f32_16x16x32_bf16 v[68:71], v[158:161], v[206:209], v[68:71]
	v_mfma_f32_16x16x32_bf16 v[124:127], v[154:157], v[186:189], v[124:127]
	v_mfma_f32_16x16x32_bf16 v[116:119], v[162:165], v[186:189], v[116:119]
	v_mfma_f32_16x16x32_bf16 v[108:111], v[154:157], v[194:197], v[108:111]
	v_mfma_f32_16x16x32_bf16 v[100:103], v[162:165], v[194:197], v[100:103]
	v_mfma_f32_16x16x32_bf16 v[92:95], v[154:157], v[202:205], v[92:95]
	v_mfma_f32_16x16x32_bf16 v[84:87], v[162:165], v[202:205], v[84:87]
	v_mfma_f32_16x16x32_bf16 v[76:79], v[154:157], v[210:213], v[76:79]
	v_mfma_f32_16x16x32_bf16 v[68:71], v[162:165], v[210:213], v[68:71]
	v_mfma_f32_16x16x32_bf16 v[120:123], v[166:169], v[182:185], v[120:123]
	v_mfma_f32_16x16x32_bf16 v[112:115], v[174:177], v[182:185], v[112:115]
	v_mfma_f32_16x16x32_bf16 v[104:107], v[166:169], v[190:193], v[104:107]
	v_mfma_f32_16x16x32_bf16 v[96:99], v[174:177], v[190:193], v[96:99]
	v_mfma_f32_16x16x32_bf16 v[88:91], v[166:169], v[198:201], v[88:91]
	v_mfma_f32_16x16x32_bf16 v[80:83], v[174:177], v[198:201], v[80:83]
	v_mfma_f32_16x16x32_bf16 v[72:75], v[166:169], v[206:209], v[72:75]
	v_mfma_f32_16x16x32_bf16 v[64:67], v[174:177], v[206:209], v[64:67]
	v_mfma_f32_16x16x32_bf16 v[120:123], v[170:173], v[186:189], v[120:123]
	v_mfma_f32_16x16x32_bf16 v[112:115], v[178:181], v[186:189], v[112:115]
	v_mfma_f32_16x16x32_bf16 v[104:107], v[170:173], v[194:197], v[104:107]
	v_mfma_f32_16x16x32_bf16 v[96:99], v[178:181], v[194:197], v[96:99]
	v_mfma_f32_16x16x32_bf16 v[88:91], v[170:173], v[202:205], v[88:91]
	v_mfma_f32_16x16x32_bf16 v[80:83], v[178:181], v[202:205], v[80:83]
	v_mfma_f32_16x16x32_bf16 v[72:75], v[170:173], v[210:213], v[72:75]
	v_mfma_f32_16x16x32_bf16 v[64:67], v[178:181], v[210:213], v[64:67]
	s_setprio 0
	s_barrier
	s_add_i32 s52, s82, s56
	v_lshl_add_u64 v[214:215], v[214:215], 0, s[10:11]
	s_mov_b32 m0, s52
	ds_read_b128 v[182:185], v149 offset:49152
	ds_read_b128 v[186:189], v149 offset:50176
	ds_read_b128 v[190:193], v149 offset:51200
	ds_read_b128 v[194:197], v149 offset:52224
	ds_read_b128 v[198:201], v149 offset:53248
	ds_read_b128 v[202:205], v149 offset:54272
	ds_read_b128 v[206:209], v149 offset:55296
	ds_read_b128 v[210:213], v149 offset:56320
	global_load_lds_dwordx4 v[214:215], off
	s_add_i32 m0, s52, 0x2000
	s_add_u32 s50, s50, 0x40080
	v_lshl_add_u64 v[214:215], v[216:217], 0, s[10:11]
	s_addc_u32 s51, s51, 0
	s_add_i32 s52, s85, s56
	global_load_lds_dwordx4 v[214:215], off
	v_lshl_add_u64 v[214:215], s[50:51], 0, v[132:133]
	s_mov_b32 m0, s52
	s_nop 0
	global_load_lds_dwordx4 v[214:215], off
	v_lshl_add_u64 v[214:215], s[50:51], 0, v[128:129]
	s_add_i32 m0, s52, 0x2000
	s_nop 0
	global_load_lds_dwordx4 v[214:215], off
	v_lshl_add_u64 v[214:215], v[218:219], 0, s[10:11]
	s_mov_b32 m0, s69
	s_nop 0
	global_load_lds_dwordx4 v[214:215], off
	v_lshl_add_u64 v[214:215], v[220:221], 0, s[10:11]
	s_mov_b32 m0, s70
	s_nop 0
	global_load_lds_dwordx4 v[214:215], off
	s_waitcnt vmcnt(8)
	s_waitcnt lgkmcnt(0)
	s_setprio 1
	v_mfma_f32_16x16x32_bf16 v[60:63], v[150:153], v[182:185], v[60:63]
	v_mfma_f32_16x16x32_bf16 v[52:55], v[158:161], v[182:185], v[52:55]
	v_mfma_f32_16x16x32_bf16 v[44:47], v[150:153], v[190:193], v[44:47]
	v_mfma_f32_16x16x32_bf16 v[36:39], v[158:161], v[190:193], v[36:39]
	v_mfma_f32_16x16x32_bf16 v[28:31], v[150:153], v[198:201], v[28:31]
	v_mfma_f32_16x16x32_bf16 v[20:23], v[158:161], v[198:201], v[20:23]
	v_mfma_f32_16x16x32_bf16 v[12:15], v[150:153], v[206:209], v[12:15]
	v_mfma_f32_16x16x32_bf16 v[4:7], v[158:161], v[206:209], v[4:7]
	v_mfma_f32_16x16x32_bf16 v[60:63], v[154:157], v[186:189], v[60:63]
	v_mfma_f32_16x16x32_bf16 v[52:55], v[162:165], v[186:189], v[52:55]
	v_mfma_f32_16x16x32_bf16 v[44:47], v[154:157], v[194:197], v[44:47]
	v_mfma_f32_16x16x32_bf16 v[36:39], v[162:165], v[194:197], v[36:39]
	v_mfma_f32_16x16x32_bf16 v[28:31], v[154:157], v[202:205], v[28:31]
	v_mfma_f32_16x16x32_bf16 v[20:23], v[162:165], v[202:205], v[20:23]
	v_mfma_f32_16x16x32_bf16 v[12:15], v[154:157], v[210:213], v[12:15]
	v_mfma_f32_16x16x32_bf16 v[4:7], v[162:165], v[210:213], v[4:7]
	v_mfma_f32_16x16x32_bf16 v[56:59], v[166:169], v[182:185], v[56:59]
	v_mfma_f32_16x16x32_bf16 v[48:51], v[174:177], v[182:185], v[48:51]
	v_mfma_f32_16x16x32_bf16 v[40:43], v[166:169], v[190:193], v[40:43]
	v_mfma_f32_16x16x32_bf16 v[32:35], v[174:177], v[190:193], v[32:35]
	v_mfma_f32_16x16x32_bf16 v[24:27], v[166:169], v[198:201], v[24:27]
	v_mfma_f32_16x16x32_bf16 v[16:19], v[174:177], v[198:201], v[16:19]
	v_mfma_f32_16x16x32_bf16 v[8:11], v[166:169], v[206:209], v[8:11]
	v_mfma_f32_16x16x32_bf16 v[0:3], v[174:177], v[206:209], v[0:3]
	v_mfma_f32_16x16x32_bf16 v[56:59], v[170:173], v[186:189], v[56:59]
	v_mfma_f32_16x16x32_bf16 v[48:51], v[178:181], v[186:189], v[48:51]
	v_mfma_f32_16x16x32_bf16 v[40:43], v[170:173], v[194:197], v[40:43]
	v_mfma_f32_16x16x32_bf16 v[32:35], v[178:181], v[194:197], v[32:35]
	v_mfma_f32_16x16x32_bf16 v[24:27], v[170:173], v[202:205], v[24:27]
	v_mfma_f32_16x16x32_bf16 v[16:19], v[178:181], v[202:205], v[16:19]
	v_mfma_f32_16x16x32_bf16 v[8:11], v[170:173], v[210:213], v[8:11]
	v_mfma_f32_16x16x32_bf16 v[0:3], v[178:181], v[210:213], v[0:3]
	s_setprio 0
	s_barrier
	s_add_i32 s81, s81, 2
	s_add_u32 s48, s48, 0x100
	s_addc_u32 s49, s49, 0
	s_add_u32 s79, s79, 0x100
	s_addc_u32 s80, s80, 0
	s_cmp_gt_u32 s81, 13
	s_cbranch_scc0 .Lh0_1
	s_branch .Ljoin_1
.Lh1p_1:
	ds_read_b128 v[150:153], v147
	ds_read_b128 v[154:157], v147 offset:1024
	ds_read_b128 v[158:161], v147 offset:2048
	ds_read_b128 v[162:165], v147 offset:3072
	ds_read_b128 v[166:169], v148
	ds_read_b128 v[170:173], v148 offset:1024
	ds_read_b128 v[174:177], v148 offset:2048
	ds_read_b128 v[178:181], v148 offset:3072
	s_add_u32 s50, s48, 0xfffc0080
	s_addc_u32 s51, s49, -1
	s_cmp_eq_u32 s81, 12
	s_cselect_b32 s53, s37, s51
	s_cselect_b32 s52, s77, s50
	s_cselect_b32 s51, s39, s80
	s_cselect_b32 s50, s78, s79
	v_lshl_add_u64 v[214:215], s[48:49], 0, v[136:137]
	s_add_i32 m0, s47, 0xc000
	ds_read_b128 v[182:185], v149
	ds_read_b128 v[186:189], v149 offset:1024
	ds_read_b128 v[190:193], v149 offset:2048
	ds_read_b128 v[194:197], v149 offset:3072
	ds_read_b128 v[198:201], v149 offset:4096
	ds_read_b128 v[202:205], v149 offset:5120
	ds_read_b128 v[206:209], v149 offset:6144
	ds_read_b128 v[210:213], v149 offset:7168
	global_load_lds_dwordx4 v[214:215], off
	v_lshl_add_u64 v[214:215], s[48:49], 0, v[138:139]
	s_add_i32 m0, s47, 0xe000
	s_nop 0
	global_load_lds_dwordx4 v[214:215], off
	s_waitcnt vmcnt(8)
	s_waitcnt lgkmcnt(0)
	s_barrier
	s_setprio 2
	v_mfma_f32_16x16x32_bf16 v[124:127], v[150:153], v[182:185], 0
	v_mfma_f32_16x16x32_bf16 v[116:119], v[158:161], v[182:185], 0
	v_mfma_f32_16x16x32_bf16 v[108:111], v[150:153], v[190:193], 0
	v_mfma_f32_16x16x32_bf16 v[100:103], v[158:161], v[190:193], 0
	v_mfma_f32_16x16x32_bf16 v[92:95], v[150:153], v[198:201], 0
	v_mfma_f32_16x16x32_bf16 v[84:87], v[158:161], v[198:201], 0
	v_mfma_f32_16x16x32_bf16 v[76:79], v[150:153], v[206:209], 0
	v_mfma_f32_16x16x32_bf16 v[68:71], v[158:161], v[206:209], 0
	v_mfma_f32_16x16x32_bf16 v[124:127], v[154:157], v[186:189], v[124:127]
	v_mfma_f32_16x16x32_bf16 v[116:119], v[162:165], v[186:189], v[116:119]
	v_mfma_f32_16x16x32_bf16 v[108:111], v[154:157], v[194:197], v[108:111]
	v_mfma_f32_16x16x32_bf16 v[100:103], v[162:165], v[194:197], v[100:103]
	v_mfma_f32_16x16x32_bf16 v[92:95], v[154:157], v[202:205], v[92:95]
	v_mfma_f32_16x16x32_bf16 v[84:87], v[162:165], v[202:205], v[84:87]
	v_mfma_f32_16x16x32_bf16 v[76:79], v[154:157], v[210:213], v[76:79]
	v_mfma_f32_16x16x32_bf16 v[68:71], v[162:165], v[210:213], v[68:71]
	v_mfma_f32_16x16x32_bf16 v[120:123], v[166:169], v[182:185], 0
	v_mfma_f32_16x16x32_bf16 v[112:115], v[174:177], v[182:185], 0
	v_mfma_f32_16x16x32_bf16 v[104:107], v[166:169], v[190:193], 0
	v_mfma_f32_16x16x32_bf16 v[96:99], v[174:177], v[190:193], 0
	v_mfma_f32_16x16x32_bf16 v[88:91], v[166:169], v[198:201], 0
	v_mfma_f32_16x16x32_bf16 v[80:83], v[174:177], v[198:201], 0
	v_mfma_f32_16x16x32_bf16 v[72:75], v[166:169], v[206:209], 0
	v_mfma_f32_16x16x32_bf16 v[64:67], v[174:177], v[206:209], 0
	v_mfma_f32_16x16x32_bf16 v[120:123], v[170:173], v[186:189], v[120:123]
	v_mfma_f32_16x16x32_bf16 v[112:115], v[178:181], v[186:189], v[112:115]
	v_mfma_f32_16x16x32_bf16 v[104:107], v[170:173], v[194:197], v[104:107]
	v_mfma_f32_16x16x32_bf16 v[96:99], v[178:181], v[194:197], v[96:99]
	v_mfma_f32_16x16x32_bf16 v[88:91], v[170:173], v[202:205], v[88:91]
	v_mfma_f32_16x16x32_bf16 v[80:83], v[178:181], v[202:205], v[80:83]
	v_mfma_f32_16x16x32_bf16 v[72:75], v[170:173], v[210:213], v[72:75]
	v_mfma_f32_16x16x32_bf16 v[64:67], v[178:181], v[210:213], v[64:67]
	s_setprio 0
	s_add_i32 s82, s73, s56
	v_lshl_add_u64 v[214:215], s[50:51], 0, v[132:133]
	s_mov_b32 m0, s82
	ds_read_b128 v[182:185], v149 offset:16384
	ds_read_b128 v[186:189], v149 offset:17408
	ds_read_b128 v[190:193], v149 offset:18432
	ds_read_b128 v[194:197], v149 offset:19456
	ds_read_b128 v[198:201], v149 offset:20480
	ds_read_b128 v[202:205], v149 offset:21504
	ds_read_b128 v[206:209], v149 offset:22528
	ds_read_b128 v[210:213], v149 offset:23552
	global_load_lds_dwordx4 v[214:215], off
	s_add_i32 m0, s82, 0x2000
	s_add_u32 s88, s50, 0x40000
	v_lshl_add_u64 v[216:217], s[50:51], 0, v[128:129]
	s_addc_u32 s89, s51, 0
	s_add_i32 s82, s74, s56
	global_load_lds_dwordx4 v[216:217], off
	v_lshl_add_u64 v[218:219], s[88:89], 0, v[132:133]
	s_mov_b32 m0, s82
	v_lshl_add_u64 v[220:221], s[52:53], 0, v[130:131]
	global_load_lds_dwordx4 v[218:219], off
	v_lshl_add_u64 v[218:219], s[88:89], 0, v[128:129]
	s_add_i32 m0, s82, 0x2000
	s_nop 0
	global_load_lds_dwordx4 v[218:219], off
	v_lshl_add_u64 v[218:219], s[52:53], 0, v[134:135]
	s_mov_b32 m0, s47
	s_nop 0
	global_load_lds_dwordx4 v[218:219], off
	s_mov_b32 m0, s59
	s_nop 0
	global_load_lds_dwordx4 v[220:221], off
	s_waitcnt vmcnt(8)
	s_waitcnt lgkmcnt(0)
	s_barrier
	s_setprio 2
	v_mfma_f32_16x16x32_bf16 v[60:63], v[150:153], v[182:185], 0
	v_mfma_f32_16x16x32_bf16 v[52:55], v[158:161], v[182:185], 0
	v_mfma_f32_16x16x32_bf16 v[44:47], v[150:153], v[190:193], 0
	v_mfma_f32_16x16x32_bf16 v[36:39], v[158:161], v[190:193], 0
	v_mfma_f32_16x16x32_bf16 v[28:31], v[150:153], v[198:201], 0
	v_mfma_f32_16x16x32_bf16 v[20:23], v[158:161], v[198:201], 0
	v_mfma_f32_16x16x32_bf16 v[12:15], v[150:153], v[206:209], 0
	v_mfma_f32_16x16x32_bf16 v[4:7], v[158:161], v[206:209], 0
	v_mfma_f32_16x16x32_bf16 v[60:63], v[154:157], v[186:189], v[60:63]
	v_mfma_f32_16x16x32_bf16 v[52:55], v[162:165], v[186:189], v[52:55]
	v_mfma_f32_16x16x32_bf16 v[44:47], v[154:157], v[194:197], v[44:47]
	v_mfma_f32_16x16x32_bf16 v[36:39], v[162:165], v[194:197], v[36:39]
	v_mfma_f32_16x16x32_bf16 v[28:31], v[154:157], v[202:205], v[28:31]
	v_mfma_f32_16x16x32_bf16 v[20:23], v[162:165], v[202:205], v[20:23]
	v_mfma_f32_16x16x32_bf16 v[12:15], v[154:157], v[210:213], v[12:15]
	v_mfma_f32_16x16x32_bf16 v[4:7], v[162:165], v[210:213], v[4:7]
	v_mfma_f32_16x16x32_bf16 v[56:59], v[166:169], v[182:185], 0
	v_mfma_f32_16x16x32_bf16 v[48:51], v[174:177], v[182:185], 0
	v_mfma_f32_16x16x32_bf16 v[40:43], v[166:169], v[190:193], 0
	v_mfma_f32_16x16x32_bf16 v[32:35], v[174:177], v[190:193], 0
	v_mfma_f32_16x16x32_bf16 v[24:27], v[166:169], v[198:201], 0
	v_mfma_f32_16x16x32_bf16 v[16:19], v[174:177], v[198:201], 0
	v_mfma_f32_16x16x32_bf16 v[8:11], v[166:169], v[206:209], 0
	v_mfma_f32_16x16x32_bf16 v[0:3], v[174:177], v[206:209], 0
	v_mfma_f32_16x16x32_bf16 v[56:59], v[170:173], v[186:189], v[56:59]
	v_mfma_f32_16x16x32_bf16 v[48:51], v[178:181], v[186:189], v[48:51]
	v_mfma_f32_16x16x32_bf16 v[40:43], v[170:173], v[194:197], v[40:43]
	v_mfma_f32_16x16x32_bf16 v[32:35], v[178:181], v[194:197], v[32:35]
	v_mfma_f32_16x16x32_bf16 v[24:27], v[170:173], v[202:205], v[24:27]
	v_mfma_f32_16x16x32_bf16 v[16:19], v[178:181], v[202:205], v[16:19]
	v_mfma_f32_16x16x32_bf16 v[8:11], v[170:173], v[210:213], v[8:11]
	v_mfma_f32_16x16x32_bf16 v[0:3], v[178:181], v[210:213], v[0:3]
	s_setprio 0
	s_add_i32 s82, 0, 0x18000
	s_add_i32 s85, 0, 0x1c000
	v_add_u32_e32 v162, s82, v145
	v_add_u32_e32 v178, s85, v145
	ds_read_b128 v[150:153], v162
	ds_read_b128 v[154:157], v162 offset:1024
	ds_read_b128 v[158:161], v162 offset:2048
	ds_read_b128 v[162:165], v162 offset:3072
	ds_read_b128 v[166:169], v178
	ds_read_b128 v[170:173], v178 offset:1024
	ds_read_b128 v[174:177], v178 offset:2048
	ds_read_b128 v[178:181], v178 offset:3072
	s_add_u32 s52, s52, 0x40000
	s_addc_u32 s53, s53, 0
	s_mov_b32 m0, s66
	v_lshl_add_u64 v[222:223], s[52:53], 0, v[134:135]
	ds_read_b128 v[182:185], v149 offset:32768
	ds_read_b128 v[186:189], v149 offset:33792
	ds_read_b128 v[190:193], v149 offset:34816
	ds_read_b128 v[194:197], v149 offset:35840
	ds_read_b128 v[198:201], v149 offset:36864
	ds_read_b128 v[202:205], v149 offset:37888
	ds_read_b128 v[206:209], v149 offset:38912
	ds_read_b128 v[210:213], v149 offset:39936
	global_load_lds_dwordx4 v[222:223], off
	v_lshl_add_u64 v[222:223], s[52:53], 0, v[130:131]
	s_mov_b32 m0, s67
	s_nop 0
	global_load_lds_dwordx4 v[222:223], off
	s_waitcnt vmcnt(8)
	s_waitcnt lgkmcnt(0)
	s_barrier
	s_setprio 2
	v_mfma_f32_16x16x32_bf16 v[124:127], v[150:153], v[182:185], v[124:127]
	v_mfma_f32_16x16x32_bf16 v[116:119], v[158:161], v[182:185], v[116:119]
	v_mfma_f32_16x16x32_bf16 v[108:111], v[150:153], v[190:193], v[108:111]
	v_mfma_f32_16x16x32_bf16 v[100:103], v[158:161], v[190:193], v[100:103]
	v_mfma_f32_16x16x32_bf16 v[92:95], v[150:153], v[198:201], v[92:95]
	v_mfma_f32_16x16x32_bf16 v[84:87], v[158:161], v[198:201], v[84:87]
	v_mfma_f32_16x16x32_bf16 v[76:79], v[150:153], v[206:209], v[76:79]
	v_mfma_f32_16x16x32_bf16 v[68:71], v[158:161], v[206:209], v[68:71]
	v_mfma_f32_16x16x32_bf16 v[124:127], v[154:157], v[186:189], v[124:127]
	v_mfma_f32_16x16x32_bf16 v[116:119], v[162:165], v[186:189], v[116:119]
	v_mfma_f32_16x16x32_bf16 v[108:111], v[154:157], v[194:197], v[108:111]
	v_mfma_f32_16x16x32_bf16 v[100:103], v[162:165], v[194:197], v[100:103]
	v_mfma_f32_16x16x32_bf16 v[92:95], v[154:157], v[202:205], v[92:95]
	v_mfma_f32_16x16x32_bf16 v[84:87], v[162:165], v[202:205], v[84:87]
	v_mfma_f32_16x16x32_bf16 v[76:79], v[154:157], v[210:213], v[76:79]
	v_mfma_f32_16x16x32_bf16 v[68:71], v[162:165], v[210:213], v[68:71]
	v_mfma_f32_16x16x32_bf16 v[120:123], v[166:169], v[182:185], v[120:123]
	v_mfma_f32_16x16x32_bf16 v[112:115], v[174:177], v[182:185], v[112:115]
	v_mfma_f32_16x16x32_bf16 v[104:107], v[166:169], v[190:193], v[104:107]
	v_mfma_f32_16x16x32_bf16 v[96:99], v[174:177], v[190:193], v[96:99]
	v_mfma_f32_16x16x32_bf16 v[88:91], v[166:169], v[198:201], v[88:91]
	v_mfma_f32_16x16x32_bf16 v[80:83], v[174:177], v[198:201], v[80:83]
	v_mfma_f32_16x16x32_bf16 v[72:75], v[166:169], v[206:209], v[72:75]
	v_mfma_f32_16x16x32_bf16 v[64:67], v[174:177], v[206:209], v[64:67]
	v_mfma_f32_16x16x32_bf16 v[120:123], v[170:173], v[186:189], v[120:123]
	v_mfma_f32_16x16x32_bf16 v[112:115], v[178:181], v[186:189], v[112:115]
	v_mfma_f32_16x16x32_bf16 v[104:107], v[170:173], v[194:197], v[104:107]
	v_mfma_f32_16x16x32_bf16 v[96:99], v[178:181], v[194:197], v[96:99]
	v_mfma_f32_16x16x32_bf16 v[88:91], v[170:173], v[202:205], v[88:91]
	v_mfma_f32_16x16x32_bf16 v[80:83], v[178:181], v[202:205], v[80:83]
	v_mfma_f32_16x16x32_bf16 v[72:75], v[170:173], v[210:213], v[72:75]
	v_mfma_f32_16x16x32_bf16 v[64:67], v[178:181], v[210:213], v[64:67]
	s_setprio 0
	s_add_i32 s52, s82, s56
	v_lshl_add_u64 v[214:215], v[214:215], 0, s[10:11]
	s_mov_b32 m0, s52
	ds_read_b128 v[182:185], v149 offset:49152
	ds_read_b128 v[186:189], v149 offset:50176
	ds_read_b128 v[190:193], v149 offset:51200
	ds_read_b128 v[194:197], v149 offset:52224
	ds_read_b128 v[198:201], v149 offset:53248
	ds_read_b128 v[202:205], v149 offset:54272
	ds_read_b128 v[206:209], v149 offset:55296
	ds_read_b128 v[210:213], v149 offset:56320
	global_load_lds_dwordx4 v[214:215], off
	s_add_i32 m0, s52, 0x2000
	s_add_u32 s50, s50, 0x40080
	v_lshl_add_u64 v[214:215], v[216:217], 0, s[10:11]
	s_addc_u32 s51, s51, 0
	s_add_i32 s52, s85, s56
	global_load_lds_dwordx4 v[214:215], off
	v_lshl_add_u64 v[214:215], s[50:51], 0, v[132:133]
	s_mov_b32 m0, s52
	s_nop 0
	global_load_lds_dwordx4 v[214:215], off
	v_lshl_add_u64 v[214:215], s[50:51], 0, v[128:129]
	s_add_i32 m0, s52, 0x2000
	s_nop 0
	global_load_lds_dwordx4 v[214:215], off
	v_lshl_add_u64 v[214:215], v[218:219], 0, s[10:11]
	s_mov_b32 m0, s69
	s_nop 0
	global_load_lds_dwordx4 v[214:215], off
	v_lshl_add_u64 v[214:215], v[220:221], 0, s[10:11]
	s_mov_b32 m0, s70
	s_nop 0
	global_load_lds_dwordx4 v[214:215], off
	s_waitcnt vmcnt(8)
	s_waitcnt lgkmcnt(0)
	s_barrier
	s_setprio 2
	v_mfma_f32_16x16x32_bf16 v[60:63], v[150:153], v[182:185], v[60:63]
	v_mfma_f32_16x16x32_bf16 v[52:55], v[158:161], v[182:185], v[52:55]
	v_mfma_f32_16x16x32_bf16 v[44:47], v[150:153], v[190:193], v[44:47]
	v_mfma_f32_16x16x32_bf16 v[36:39], v[158:161], v[190:193], v[36:39]
	v_mfma_f32_16x16x32_bf16 v[28:31], v[150:153], v[198:201], v[28:31]
	v_mfma_f32_16x16x32_bf16 v[20:23], v[158:161], v[198:201], v[20:23]
	v_mfma_f32_16x16x32_bf16 v[12:15], v[150:153], v[206:209], v[12:15]
	v_mfma_f32_16x16x32_bf16 v[4:7], v[158:161], v[206:209], v[4:7]
	v_mfma_f32_16x16x32_bf16 v[60:63], v[154:157], v[186:189], v[60:63]
	v_mfma_f32_16x16x32_bf16 v[52:55], v[162:165], v[186:189], v[52:55]
	v_mfma_f32_16x16x32_bf16 v[44:47], v[154:157], v[194:197], v[44:47]
	v_mfma_f32_16x16x32_bf16 v[36:39], v[162:165], v[194:197], v[36:39]
	v_mfma_f32_16x16x32_bf16 v[28:31], v[154:157], v[202:205], v[28:31]
	v_mfma_f32_16x16x32_bf16 v[20:23], v[162:165], v[202:205], v[20:23]
	v_mfma_f32_16x16x32_bf16 v[12:15], v[154:157], v[210:213], v[12:15]
	v_mfma_f32_16x16x32_bf16 v[4:7], v[162:165], v[210:213], v[4:7]
	v_mfma_f32_16x16x32_bf16 v[56:59], v[166:169], v[182:185], v[56:59]
	v_mfma_f32_16x16x32_bf16 v[48:51], v[174:177], v[182:185], v[48:51]
	v_mfma_f32_16x16x32_bf16 v[40:43], v[166:169], v[190:193], v[40:43]
	v_mfma_f32_16x16x32_bf16 v[32:35], v[174:177], v[190:193], v[32:35]
	v_mfma_f32_16x16x32_bf16 v[24:27], v[166:169], v[198:201], v[24:27]
	v_mfma_f32_16x16x32_bf16 v[16:19], v[174:177], v[198:201], v[16:19]
	v_mfma_f32_16x16x32_bf16 v[8:11], v[166:169], v[206:209], v[8:11]
	v_mfma_f32_16x16x32_bf16 v[0:3], v[174:177], v[206:209], v[0:3]
	v_mfma_f32_16x16x32_bf16 v[56:59], v[170:173], v[186:189], v[56:59]
	v_mfma_f32_16x16x32_bf16 v[48:51], v[178:181], v[186:189], v[48:51]
	v_mfma_f32_16x16x32_bf16 v[40:43], v[170:173], v[194:197], v[40:43]
	v_mfma_f32_16x16x32_bf16 v[32:35], v[178:181], v[194:197], v[32:35]
	v_mfma_f32_16x16x32_bf16 v[24:27], v[170:173], v[202:205], v[24:27]
	v_mfma_f32_16x16x32_bf16 v[16:19], v[178:181], v[202:205], v[16:19]
	v_mfma_f32_16x16x32_bf16 v[8:11], v[170:173], v[210:213], v[8:11]
	v_mfma_f32_16x16x32_bf16 v[0:3], v[178:181], v[210:213], v[0:3]
	s_setprio 0
	s_add_i32 s81, s81, 2
	s_add_u32 s48, s48, 0x100
	s_addc_u32 s49, s49, 0
	s_add_u32 s79, s79, 0x100
	s_addc_u32 s80, s80, 0
	s_cmp_gt_u32 s81, 13
.Lh1_1:
	ds_read_b128 v[150:153], v147
	ds_read_b128 v[154:157], v147 offset:1024
	ds_read_b128 v[158:161], v147 offset:2048
	ds_read_b128 v[162:165], v147 offset:3072
	ds_read_b128 v[166:169], v148
	ds_read_b128 v[170:173], v148 offset:1024
	ds_read_b128 v[174:177], v148 offset:2048
	ds_read_b128 v[178:181], v148 offset:3072
	s_add_u32 s50, s48, 0xfffc0080
	s_addc_u32 s51, s49, -1
	s_cmp_eq_u32 s81, 12
	s_cselect_b32 s53, s37, s51
	s_cselect_b32 s52, s77, s50
	s_cselect_b32 s51, s39, s80
	s_cselect_b32 s50, s78, s79
	v_lshl_add_u64 v[214:215], s[48:49], 0, v[136:137]
	s_add_i32 m0, s47, 0xc000
	ds_read_b128 v[182:185], v149
	ds_read_b128 v[186:189], v149 offset:1024
	ds_read_b128 v[190:193], v149 offset:2048
	ds_read_b128 v[194:197], v149 offset:3072
	ds_read_b128 v[198:201], v149 offset:4096
	ds_read_b128 v[202:205], v149 offset:5120
	ds_read_b128 v[206:209], v149 offset:6144
	ds_read_b128 v[210:213], v149 offset:7168
	global_load_lds_dwordx4 v[214:215], off
	v_lshl_add_u64 v[214:215], s[48:49], 0, v[138:139]
	s_add_i32 m0, s47, 0xe000
	s_nop 0
	global_load_lds_dwordx4 v[214:215], off
	s_waitcnt vmcnt(8)
	s_waitcnt lgkmcnt(0)
	s_barrier
	s_setprio 2
	v_mfma_f32_16x16x32_bf16 v[124:127], v[150:153], v[182:185], v[124:127]
	v_mfma_f32_16x16x32_bf16 v[116:119], v[158:161], v[182:185], v[116:119]
	v_mfma_f32_16x16x32_bf16 v[108:111], v[150:153], v[190:193], v[108:111]
	v_mfma_f32_16x16x32_bf16 v[100:103], v[158:161], v[190:193], v[100:103]
	v_mfma_f32_16x16x32_bf16 v[92:95], v[150:153], v[198:201], v[92:95]
	v_mfma_f32_16x16x32_bf16 v[84:87], v[158:161], v[198:201], v[84:87]
	v_mfma_f32_16x16x32_bf16 v[76:79], v[150:153], v[206:209], v[76:79]
	v_mfma_f32_16x16x32_bf16 v[68:71], v[158:161], v[206:209], v[68:71]
	v_mfma_f32_16x16x32_bf16 v[124:127], v[154:157], v[186:189], v[124:127]
	v_mfma_f32_16x16x32_bf16 v[116:119], v[162:165], v[186:189], v[116:119]
	v_mfma_f32_16x16x32_bf16 v[108:111], v[154:157], v[194:197], v[108:111]
	v_mfma_f32_16x16x32_bf16 v[100:103], v[162:165], v[194:197], v[100:103]
	v_mfma_f32_16x16x32_bf16 v[92:95], v[154:157], v[202:205], v[92:95]
	v_mfma_f32_16x16x32_bf16 v[84:87], v[162:165], v[202:205], v[84:87]
	v_mfma_f32_16x16x32_bf16 v[76:79], v[154:157], v[210:213], v[76:79]
	v_mfma_f32_16x16x32_bf16 v[68:71], v[162:165], v[210:213], v[68:71]
	v_mfma_f32_16x16x32_bf16 v[120:123], v[166:169], v[182:185], v[120:123]
	v_mfma_f32_16x16x32_bf16 v[112:115], v[174:177], v[182:185], v[112:115]
	v_mfma_f32_16x16x32_bf16 v[104:107], v[166:169], v[190:193], v[104:107]
	v_mfma_f32_16x16x32_bf16 v[96:99], v[174:177], v[190:193], v[96:99]
	v_mfma_f32_16x16x32_bf16 v[88:91], v[166:169], v[198:201], v[88:91]
	v_mfma_f32_16x16x32_bf16 v[80:83], v[174:177], v[198:201], v[80:83]
	v_mfma_f32_16x16x32_bf16 v[72:75], v[166:169], v[206:209], v[72:75]
	v_mfma_f32_16x16x32_bf16 v[64:67], v[174:177], v[206:209], v[64:67]
	v_mfma_f32_16x16x32_bf16 v[120:123], v[170:173], v[186:189], v[120:123]
	v_mfma_f32_16x16x32_bf16 v[112:115], v[178:181], v[186:189], v[112:115]
	v_mfma_f32_16x16x32_bf16 v[104:107], v[170:173], v[194:197], v[104:107]
	v_mfma_f32_16x16x32_bf16 v[96:99], v[178:181], v[194:197], v[96:99]
	v_mfma_f32_16x16x32_bf16 v[88:91], v[170:173], v[202:205], v[88:91]
	v_mfma_f32_16x16x32_bf16 v[80:83], v[178:181], v[202:205], v[80:83]
	v_mfma_f32_16x16x32_bf16 v[72:75], v[170:173], v[210:213], v[72:75]
	v_mfma_f32_16x16x32_bf16 v[64:67], v[178:181], v[210:213], v[64:67]
	s_setprio 0
	s_add_i32 s82, s73, s56
	v_lshl_add_u64 v[214:215], s[50:51], 0, v[132:133]
	s_mov_b32 m0, s82
	ds_read_b128 v[182:185], v149 offset:16384
	ds_read_b128 v[186:189], v149 offset:17408
	ds_read_b128 v[190:193], v149 offset:18432
	ds_read_b128 v[194:197], v149 offset:19456
	ds_read_b128 v[198:201], v149 offset:20480
	ds_read_b128 v[202:205], v149 offset:21504
	ds_read_b128 v[206:209], v149 offset:22528
	ds_read_b128 v[210:213], v149 offset:23552
	global_load_lds_dwordx4 v[214:215], off
	s_add_i32 m0, s82, 0x2000
	s_add_u32 s88, s50, 0x40000
	v_lshl_add_u64 v[216:217], s[50:51], 0, v[128:129]
	s_addc_u32 s89, s51, 0
	s_add_i32 s82, s74, s56
	global_load_lds_dwordx4 v[216:217], off
	v_lshl_add_u64 v[218:219], s[88:89], 0, v[132:133]
	s_mov_b32 m0, s82
	v_lshl_add_u64 v[220:221], s[52:53], 0, v[130:131]
	global_load_lds_dwordx4 v[218:219], off
	v_lshl_add_u64 v[218:219], s[88:89], 0, v[128:129]
	s_add_i32 m0, s82, 0x2000
	s_nop 0
	global_load_lds_dwordx4 v[218:219], off
	v_lshl_add_u64 v[218:219], s[52:53], 0, v[134:135]
	s_mov_b32 m0, s47
	s_nop 0
	global_load_lds_dwordx4 v[218:219], off
	s_mov_b32 m0, s59
	s_nop 0
	global_load_lds_dwordx4 v[220:221], off
	s_waitcnt vmcnt(8)
	s_waitcnt lgkmcnt(0)
	s_barrier
	s_setprio 2
	v_mfma_f32_16x16x32_bf16 v[60:63], v[150:153], v[182:185], v[60:63]
	v_mfma_f32_16x16x32_bf16 v[52:55], v[158:161], v[182:185], v[52:55]
	v_mfma_f32_16x16x32_bf16 v[44:47], v[150:153], v[190:193], v[44:47]
	v_mfma_f32_16x16x32_bf16 v[36:39], v[158:161], v[190:193], v[36:39]
	v_mfma_f32_16x16x32_bf16 v[28:31], v[150:153], v[198:201], v[28:31]
	v_mfma_f32_16x16x32_bf16 v[20:23], v[158:161], v[198:201], v[20:23]
	v_mfma_f32_16x16x32_bf16 v[12:15], v[150:153], v[206:209], v[12:15]
	v_mfma_f32_16x16x32_bf16 v[4:7], v[158:161], v[206:209], v[4:7]
	v_mfma_f32_16x16x32_bf16 v[60:63], v[154:157], v[186:189], v[60:63]
	v_mfma_f32_16x16x32_bf16 v[52:55], v[162:165], v[186:189], v[52:55]
	v_mfma_f32_16x16x32_bf16 v[44:47], v[154:157], v[194:197], v[44:47]
	v_mfma_f32_16x16x32_bf16 v[36:39], v[162:165], v[194:197], v[36:39]
	v_mfma_f32_16x16x32_bf16 v[28:31], v[154:157], v[202:205], v[28:31]
	v_mfma_f32_16x16x32_bf16 v[20:23], v[162:165], v[202:205], v[20:23]
	v_mfma_f32_16x16x32_bf16 v[12:15], v[154:157], v[210:213], v[12:15]
	v_mfma_f32_16x16x32_bf16 v[4:7], v[162:165], v[210:213], v[4:7]
	v_mfma_f32_16x16x32_bf16 v[56:59], v[166:169], v[182:185], v[56:59]
	v_mfma_f32_16x16x32_bf16 v[48:51], v[174:177], v[182:185], v[48:51]
	v_mfma_f32_16x16x32_bf16 v[40:43], v[166:169], v[190:193], v[40:43]
	v_mfma_f32_16x16x32_bf16 v[32:35], v[174:177], v[190:193], v[32:35]
	v_mfma_f32_16x16x32_bf16 v[24:27], v[166:169], v[198:201], v[24:27]
	v_mfma_f32_16x16x32_bf16 v[16:19], v[174:177], v[198:201], v[16:19]
	v_mfma_f32_16x16x32_bf16 v[8:11], v[166:169], v[206:209], v[8:11]
	v_mfma_f32_16x16x32_bf16 v[0:3], v[174:177], v[206:209], v[0:3]
	v_mfma_f32_16x16x32_bf16 v[56:59], v[170:173], v[186:189], v[56:59]
	v_mfma_f32_16x16x32_bf16 v[48:51], v[178:181], v[186:189], v[48:51]
	v_mfma_f32_16x16x32_bf16 v[40:43], v[170:173], v[194:197], v[40:43]
	v_mfma_f32_16x16x32_bf16 v[32:35], v[178:181], v[194:197], v[32:35]
	v_mfma_f32_16x16x32_bf16 v[24:27], v[170:173], v[202:205], v[24:27]
	v_mfma_f32_16x16x32_bf16 v[16:19], v[178:181], v[202:205], v[16:19]
	v_mfma_f32_16x16x32_bf16 v[8:11], v[170:173], v[210:213], v[8:11]
	v_mfma_f32_16x16x32_bf16 v[0:3], v[178:181], v[210:213], v[0:3]
	s_setprio 0
	s_add_i32 s82, 0, 0x18000
	s_add_i32 s85, 0, 0x1c000
	v_add_u32_e32 v162, s82, v145
	v_add_u32_e32 v178, s85, v145
	ds_read_b128 v[150:153], v162
	ds_read_b128 v[154:157], v162 offset:1024
	ds_read_b128 v[158:161], v162 offset:2048
	ds_read_b128 v[162:165], v162 offset:3072
	ds_read_b128 v[166:169], v178
	ds_read_b128 v[170:173], v178 offset:1024
	ds_read_b128 v[174:177], v178 offset:2048
	ds_read_b128 v[178:181], v178 offset:3072
	s_add_u32 s52, s52, 0x40000
	s_addc_u32 s53, s53, 0
	s_mov_b32 m0, s66
	v_lshl_add_u64 v[222:223], s[52:53], 0, v[134:135]
	ds_read_b128 v[182:185], v149 offset:32768
	ds_read_b128 v[186:189], v149 offset:33792
	ds_read_b128 v[190:193], v149 offset:34816
	ds_read_b128 v[194:197], v149 offset:35840
	ds_read_b128 v[198:201], v149 offset:36864
	ds_read_b128 v[202:205], v149 offset:37888
	ds_read_b128 v[206:209], v149 offset:38912
	ds_read_b128 v[210:213], v149 offset:39936
	global_load_lds_dwordx4 v[222:223], off
	v_lshl_add_u64 v[222:223], s[52:53], 0, v[130:131]
	s_mov_b32 m0, s67
	s_nop 0
	global_load_lds_dwordx4 v[222:223], off
	s_waitcnt vmcnt(8)
	s_waitcnt lgkmcnt(0)
	s_barrier
	s_setprio 2
	v_mfma_f32_16x16x32_bf16 v[124:127], v[150:153], v[182:185], v[124:127]
	v_mfma_f32_16x16x32_bf16 v[116:119], v[158:161], v[182:185], v[116:119]
	v_mfma_f32_16x16x32_bf16 v[108:111], v[150:153], v[190:193], v[108:111]
	v_mfma_f32_16x16x32_bf16 v[100:103], v[158:161], v[190:193], v[100:103]
	v_mfma_f32_16x16x32_bf16 v[92:95], v[150:153], v[198:201], v[92:95]
	v_mfma_f32_16x16x32_bf16 v[84:87], v[158:161], v[198:201], v[84:87]
	v_mfma_f32_16x16x32_bf16 v[76:79], v[150:153], v[206:209], v[76:79]
	v_mfma_f32_16x16x32_bf16 v[68:71], v[158:161], v[206:209], v[68:71]
	v_mfma_f32_16x16x32_bf16 v[124:127], v[154:157], v[186:189], v[124:127]
	v_mfma_f32_16x16x32_bf16 v[116:119], v[162:165], v[186:189], v[116:119]
	v_mfma_f32_16x16x32_bf16 v[108:111], v[154:157], v[194:197], v[108:111]
	v_mfma_f32_16x16x32_bf16 v[100:103], v[162:165], v[194:197], v[100:103]
	v_mfma_f32_16x16x32_bf16 v[92:95], v[154:157], v[202:205], v[92:95]
	v_mfma_f32_16x16x32_bf16 v[84:87], v[162:165], v[202:205], v[84:87]
	v_mfma_f32_16x16x32_bf16 v[76:79], v[154:157], v[210:213], v[76:79]
	v_mfma_f32_16x16x32_bf16 v[68:71], v[162:165], v[210:213], v[68:71]
	v_mfma_f32_16x16x32_bf16 v[120:123], v[166:169], v[182:185], v[120:123]
	v_mfma_f32_16x16x32_bf16 v[112:115], v[174:177], v[182:185], v[112:115]
	v_mfma_f32_16x16x32_bf16 v[104:107], v[166:169], v[190:193], v[104:107]
	v_mfma_f32_16x16x32_bf16 v[96:99], v[174:177], v[190:193], v[96:99]
	v_mfma_f32_16x16x32_bf16 v[88:91], v[166:169], v[198:201], v[88:91]
	v_mfma_f32_16x16x32_bf16 v[80:83], v[174:177], v[198:201], v[80:83]
	v_mfma_f32_16x16x32_bf16 v[72:75], v[166:169], v[206:209], v[72:75]
	v_mfma_f32_16x16x32_bf16 v[64:67], v[174:177], v[206:209], v[64:67]
	v_mfma_f32_16x16x32_bf16 v[120:123], v[170:173], v[186:189], v[120:123]
	v_mfma_f32_16x16x32_bf16 v[112:115], v[178:181], v[186:189], v[112:115]
	v_mfma_f32_16x16x32_bf16 v[104:107], v[170:173], v[194:197], v[104:107]
	v_mfma_f32_16x16x32_bf16 v[96:99], v[178:181], v[194:197], v[96:99]
	v_mfma_f32_16x16x32_bf16 v[88:91], v[170:173], v[202:205], v[88:91]
	v_mfma_f32_16x16x32_bf16 v[80:83], v[178:181], v[202:205], v[80:83]
	v_mfma_f32_16x16x32_bf16 v[72:75], v[170:173], v[210:213], v[72:75]
	v_mfma_f32_16x16x32_bf16 v[64:67], v[178:181], v[210:213], v[64:67]
	s_setprio 0
	s_add_i32 s52, s82, s56
	v_lshl_add_u64 v[214:215], v[214:215], 0, s[10:11]
	s_mov_b32 m0, s52
	ds_read_b128 v[182:185], v149 offset:49152
	ds_read_b128 v[186:189], v149 offset:50176
	ds_read_b128 v[190:193], v149 offset:51200
	ds_read_b128 v[194:197], v149 offset:52224
	ds_read_b128 v[198:201], v149 offset:53248
	ds_read_b128 v[202:205], v149 offset:54272
	ds_read_b128 v[206:209], v149 offset:55296
	ds_read_b128 v[210:213], v149 offset:56320
	global_load_lds_dwordx4 v[214:215], off
	s_add_i32 m0, s52, 0x2000
	s_add_u32 s50, s50, 0x40080
	v_lshl_add_u64 v[214:215], v[216:217], 0, s[10:11]
	s_addc_u32 s51, s51, 0
	s_add_i32 s52, s85, s56
	global_load_lds_dwordx4 v[214:215], off
	v_lshl_add_u64 v[214:215], s[50:51], 0, v[132:133]
	s_mov_b32 m0, s52
	s_nop 0
	global_load_lds_dwordx4 v[214:215], off
	v_lshl_add_u64 v[214:215], s[50:51], 0, v[128:129]
	s_add_i32 m0, s52, 0x2000
	s_nop 0
	global_load_lds_dwordx4 v[214:215], off
	v_lshl_add_u64 v[214:215], v[218:219], 0, s[10:11]
	s_mov_b32 m0, s69
	s_nop 0
	global_load_lds_dwordx4 v[214:215], off
	v_lshl_add_u64 v[214:215], v[220:221], 0, s[10:11]
	s_mov_b32 m0, s70
	s_nop 0
	global_load_lds_dwordx4 v[214:215], off
	s_waitcnt vmcnt(8)
	s_waitcnt lgkmcnt(0)
	s_barrier
	s_setprio 2
	v_mfma_f32_16x16x32_bf16 v[60:63], v[150:153], v[182:185], v[60:63]
	v_mfma_f32_16x16x32_bf16 v[52:55], v[158:161], v[182:185], v[52:55]
	v_mfma_f32_16x16x32_bf16 v[44:47], v[150:153], v[190:193], v[44:47]
	v_mfma_f32_16x16x32_bf16 v[36:39], v[158:161], v[190:193], v[36:39]
	v_mfma_f32_16x16x32_bf16 v[28:31], v[150:153], v[198:201], v[28:31]
	v_mfma_f32_16x16x32_bf16 v[20:23], v[158:161], v[198:201], v[20:23]
	v_mfma_f32_16x16x32_bf16 v[12:15], v[150:153], v[206:209], v[12:15]
	v_mfma_f32_16x16x32_bf16 v[4:7], v[158:161], v[206:209], v[4:7]
	v_mfma_f32_16x16x32_bf16 v[60:63], v[154:157], v[186:189], v[60:63]
	v_mfma_f32_16x16x32_bf16 v[52:55], v[162:165], v[186:189], v[52:55]
	v_mfma_f32_16x16x32_bf16 v[44:47], v[154:157], v[194:197], v[44:47]
	v_mfma_f32_16x16x32_bf16 v[36:39], v[162:165], v[194:197], v[36:39]
	v_mfma_f32_16x16x32_bf16 v[28:31], v[154:157], v[202:205], v[28:31]
	v_mfma_f32_16x16x32_bf16 v[20:23], v[162:165], v[202:205], v[20:23]
	v_mfma_f32_16x16x32_bf16 v[12:15], v[154:157], v[210:213], v[12:15]
	v_mfma_f32_16x16x32_bf16 v[4:7], v[162:165], v[210:213], v[4:7]
	v_mfma_f32_16x16x32_bf16 v[56:59], v[166:169], v[182:185], v[56:59]
	v_mfma_f32_16x16x32_bf16 v[48:51], v[174:177], v[182:185], v[48:51]
	v_mfma_f32_16x16x32_bf16 v[40:43], v[166:169], v[190:193], v[40:43]
	v_mfma_f32_16x16x32_bf16 v[32:35], v[174:177], v[190:193], v[32:35]
	v_mfma_f32_16x16x32_bf16 v[24:27], v[166:169], v[198:201], v[24:27]
	v_mfma_f32_16x16x32_bf16 v[16:19], v[174:177], v[198:201], v[16:19]
	v_mfma_f32_16x16x32_bf16 v[8:11], v[166:169], v[206:209], v[8:11]
	v_mfma_f32_16x16x32_bf16 v[0:3], v[174:177], v[206:209], v[0:3]
	v_mfma_f32_16x16x32_bf16 v[56:59], v[170:173], v[186:189], v[56:59]
	v_mfma_f32_16x16x32_bf16 v[48:51], v[178:181], v[186:189], v[48:51]
	v_mfma_f32_16x16x32_bf16 v[40:43], v[170:173], v[194:197], v[40:43]
	v_mfma_f32_16x16x32_bf16 v[32:35], v[178:181], v[194:197], v[32:35]
	v_mfma_f32_16x16x32_bf16 v[24:27], v[170:173], v[202:205], v[24:27]
	v_mfma_f32_16x16x32_bf16 v[16:19], v[178:181], v[202:205], v[16:19]
	v_mfma_f32_16x16x32_bf16 v[8:11], v[170:173], v[210:213], v[8:11]
	v_mfma_f32_16x16x32_bf16 v[0:3], v[178:181], v[210:213], v[0:3]
	s_setprio 0
	s_add_i32 s81, s81, 2
	s_add_u32 s48, s48, 0x100
	s_addc_u32 s49, s49, 0
	s_add_u32 s79, s79, 0x100
	s_addc_u32 s80, s80, 0
	s_cmp_gt_u32 s81, 13
	s_cbranch_scc0 .Lh1_1
.Ljoin_1:
	s_and_b64 vcc, exec, s[26:27]
	s_cbranch_vccz .LBB0_144
.LBB0_144:
	v_exp_f32_e64 v156, -v126
	v_exp_f32_e64 v157, -v127
	v_exp_f32_e64 v152, -v124
	v_exp_f32_e64 v153, -v125
	v_pk_mul_f32 v[120:121], v[124:125], v[120:121]
	v_pk_add_f32 v[124:125], v[156:157], 1.0 op_sel_hi:[1,0]
	v_pk_mul_f32 v[122:123], v[126:127], v[122:123]
	v_rcp_f32_e32 v124, v124
	v_rcp_f32_e32 v125, v125
	v_pk_add_f32 v[152:153], v[152:153], 1.0 op_sel_hi:[1,0]
	v_exp_f32_e64 v126, -v116
	v_rcp_f32_e32 v152, v152
	v_rcp_f32_e32 v153, v153
	v_exp_f32_e64 v127, -v117
	v_pk_mul_f32 v[122:123], v[124:125], v[122:123]
	v_exp_f32_e64 v124, -v118
	v_exp_f32_e64 v125, -v119
	v_pk_mul_f32 v[120:121], v[152:153], v[120:121]
	v_pk_mul_f32 v[114:115], v[118:119], v[114:115]
	v_cvt_pk_bf16_f32 v120, v120, v121
	v_cvt_pk_bf16_f32 v121, v122, v123
	v_pk_add_f32 v[122:123], v[126:127], 1.0 op_sel_hi:[1,0]
	v_pk_add_f32 v[118:119], v[124:125], 1.0 op_sel_hi:[1,0]
	v_rcp_f32_e32 v122, v122
	v_rcp_f32_e32 v123, v123
	v_rcp_f32_e32 v118, v118
	v_rcp_f32_e32 v119, v119
	v_pk_mul_f32 v[112:113], v[116:117], v[112:113]
	v_lshl_add_u32 v154, s76, 7, v146
	v_pk_mul_f32 v[112:113], v[122:123], v[112:113]
	v_lshl_add_u32 v150, s46, 8, v144
	v_cvt_pk_bf16_f32 v122, v112, v113
	v_pk_mul_f32 v[112:113], v[118:119], v[114:115]
	v_exp_f32_e64 v118, -v108
	v_exp_f32_e64 v119, -v109
	v_ashrrev_i32_e32 v155, 31, v154
	v_cvt_pk_bf16_f32 v123, v112, v113
	v_mov_b64_e32 v[112:113], s[24:25]
	v_mad_i64_i32 v[116:117], s[48:49], v150, s75, v[112:113]
	v_lshlrev_b64 v[114:115], 1, v[154:155]
	v_lshl_add_u64 v[116:117], v[116:117], 0, v[114:115]
	global_store_dwordx4 v[116:117], v[120:123], off
	v_pk_add_f32 v[116:117], v[118:119], 1.0 op_sel_hi:[1,0]
	v_exp_f32_e64 v118, -v110
	v_exp_f32_e64 v119, -v111
	v_pk_mul_f32 v[104:105], v[108:109], v[104:105]
	v_rcp_f32_e32 v116, v116
	v_rcp_f32_e32 v117, v117
	v_pk_add_f32 v[108:109], v[118:119], 1.0 op_sel_hi:[1,0]
	v_pk_mul_f32 v[106:107], v[110:111], v[106:107]
	v_rcp_f32_e32 v108, v108
	v_rcp_f32_e32 v109, v109
	v_exp_f32_e64 v110, -v100
	v_exp_f32_e64 v111, -v101
	v_pk_mul_f32 v[104:105], v[116:117], v[104:105]
	v_pk_mul_f32 v[106:107], v[108:109], v[106:107]
	v_exp_f32_e64 v108, -v102
	v_exp_f32_e64 v109, -v103
	v_cvt_pk_bf16_f32 v104, v104, v105
	v_cvt_pk_bf16_f32 v105, v106, v107
	v_pk_add_f32 v[106:107], v[110:111], 1.0 op_sel_hi:[1,0]
	v_pk_mul_f32 v[98:99], v[102:103], v[98:99]
	v_rcp_f32_e32 v106, v106
	v_rcp_f32_e32 v107, v107
	v_pk_add_f32 v[102:103], v[108:109], 1.0 op_sel_hi:[1,0]
	v_pk_mul_f32 v[96:97], v[100:101], v[96:97]
	v_rcp_f32_e32 v102, v102
	v_rcp_f32_e32 v103, v103
	v_pk_mul_f32 v[96:97], v[106:107], v[96:97]
	v_or_b32_e32 v120, 16, v150
	v_cvt_pk_bf16_f32 v106, v96, v97
	v_pk_mul_f32 v[96:97], v[102:103], v[98:99]
	v_exp_f32_e64 v98, -v92
	v_exp_f32_e64 v99, -v93
	v_cvt_pk_bf16_f32 v107, v96, v97
	v_mad_i64_i32 v[96:97], s[48:49], v120, s75, v[112:113]
	v_lshl_add_u64 v[96:97], v[96:97], 0, v[114:115]
	global_store_dwordx4 v[96:97], v[104:107], off
	v_pk_add_f32 v[96:97], v[98:99], 1.0 op_sel_hi:[1,0]
	v_exp_f32_e64 v98, -v94
	v_exp_f32_e64 v99, -v95
	v_pk_mul_f32 v[88:89], v[92:93], v[88:89]
	v_rcp_f32_e32 v96, v96
	v_rcp_f32_e32 v97, v97
	v_pk_add_f32 v[92:93], v[98:99], 1.0 op_sel_hi:[1,0]
	v_pk_mul_f32 v[90:91], v[94:95], v[90:91]
	v_rcp_f32_e32 v92, v92
	v_rcp_f32_e32 v93, v93
	v_exp_f32_e64 v94, -v84
	v_exp_f32_e64 v95, -v85
	v_pk_mul_f32 v[88:89], v[96:97], v[88:89]
	v_pk_mul_f32 v[90:91], v[92:93], v[90:91]
	v_exp_f32_e64 v92, -v86
	v_exp_f32_e64 v93, -v87
	v_cvt_pk_bf16_f32 v88, v88, v89
	v_cvt_pk_bf16_f32 v89, v90, v91
	v_pk_add_f32 v[90:91], v[94:95], 1.0 op_sel_hi:[1,0]
	v_pk_mul_f32 v[82:83], v[86:87], v[82:83]
	v_rcp_f32_e32 v90, v90
	v_rcp_f32_e32 v91, v91
	v_pk_add_f32 v[86:87], v[92:93], 1.0 op_sel_hi:[1,0]
	v_pk_mul_f32 v[80:81], v[84:85], v[80:81]
	v_rcp_f32_e32 v86, v86
	v_rcp_f32_e32 v87, v87
	v_pk_mul_f32 v[80:81], v[90:91], v[80:81]
	v_or_b32_e32 v100, 32, v150
	v_cvt_pk_bf16_f32 v90, v80, v81
	v_pk_mul_f32 v[80:81], v[86:87], v[82:83]
	v_exp_f32_e64 v82, -v76
	v_exp_f32_e64 v83, -v77
	v_cvt_pk_bf16_f32 v91, v80, v81
	v_mad_i64_i32 v[80:81], s[48:49], v100, s75, v[112:113]
	v_lshl_add_u64 v[80:81], v[80:81], 0, v[114:115]
	global_store_dwordx4 v[80:81], v[88:91], off
	v_pk_add_f32 v[80:81], v[82:83], 1.0 op_sel_hi:[1,0]
	v_exp_f32_e64 v82, -v78
	v_exp_f32_e64 v83, -v79
	v_pk_mul_f32 v[72:73], v[76:77], v[72:73]
	v_rcp_f32_e32 v80, v80
	v_rcp_f32_e32 v81, v81
	v_pk_add_f32 v[76:77], v[82:83], 1.0 op_sel_hi:[1,0]
	v_pk_mul_f32 v[74:75], v[78:79], v[74:75]
	v_rcp_f32_e32 v76, v76
	v_rcp_f32_e32 v77, v77
	v_exp_f32_e64 v78, -v68
	v_exp_f32_e64 v79, -v69
	v_pk_mul_f32 v[72:73], v[80:81], v[72:73]
	v_pk_mul_f32 v[74:75], v[76:77], v[74:75]
	v_exp_f32_e64 v76, -v70
	v_exp_f32_e64 v77, -v71
	v_cvt_pk_bf16_f32 v72, v72, v73
	v_cvt_pk_bf16_f32 v73, v74, v75
	v_pk_add_f32 v[74:75], v[78:79], 1.0 op_sel_hi:[1,0]
	v_pk_mul_f32 v[66:67], v[70:71], v[66:67]
	v_rcp_f32_e32 v74, v74
	v_rcp_f32_e32 v75, v75
	v_pk_add_f32 v[70:71], v[76:77], 1.0 op_sel_hi:[1,0]
	v_pk_mul_f32 v[64:65], v[68:69], v[64:65]
	v_rcp_f32_e32 v70, v70
	v_rcp_f32_e32 v71, v71
	v_pk_mul_f32 v[64:65], v[74:75], v[64:65]
	v_or_b32_e32 v84, 48, v150
	v_cvt_pk_bf16_f32 v74, v64, v65
	v_pk_mul_f32 v[64:65], v[70:71], v[66:67]
	v_exp_f32_e64 v66, -v60
	v_exp_f32_e64 v67, -v61
	v_cvt_pk_bf16_f32 v75, v64, v65
	v_mad_i64_i32 v[64:65], s[48:49], v84, s75, v[112:113]
	v_lshl_add_u64 v[64:65], v[64:65], 0, v[114:115]
	global_store_dwordx4 v[64:65], v[72:75], off
	v_pk_add_f32 v[64:65], v[66:67], 1.0 op_sel_hi:[1,0]
	v_exp_f32_e64 v66, -v62
	v_exp_f32_e64 v67, -v63
	v_pk_mul_f32 v[56:57], v[60:61], v[56:57]
	v_rcp_f32_e32 v64, v64
	v_rcp_f32_e32 v65, v65
	v_pk_add_f32 v[60:61], v[66:67], 1.0 op_sel_hi:[1,0]
	v_pk_mul_f32 v[58:59], v[62:63], v[58:59]
	v_rcp_f32_e32 v60, v60
	v_rcp_f32_e32 v61, v61
	v_exp_f32_e64 v62, -v52
	v_exp_f32_e64 v63, -v53
	v_pk_mul_f32 v[56:57], v[64:65], v[56:57]
	v_pk_mul_f32 v[58:59], v[60:61], v[58:59]
	v_exp_f32_e64 v60, -v54
	v_exp_f32_e64 v61, -v55
	v_cvt_pk_bf16_f32 v56, v56, v57
	v_cvt_pk_bf16_f32 v57, v58, v59
	v_pk_add_f32 v[58:59], v[62:63], 1.0 op_sel_hi:[1,0]
	v_pk_mul_f32 v[50:51], v[54:55], v[50:51]
	v_rcp_f32_e32 v58, v58
	v_rcp_f32_e32 v59, v59
	v_pk_add_f32 v[54:55], v[60:61], 1.0 op_sel_hi:[1,0]
	v_pk_mul_f32 v[48:49], v[52:53], v[48:49]
	v_rcp_f32_e32 v54, v54
	v_rcp_f32_e32 v55, v55
	v_pk_mul_f32 v[48:49], v[58:59], v[48:49]
	v_add_u32_e32 v68, 0x80, v150
	v_cvt_pk_bf16_f32 v58, v48, v49
	v_pk_mul_f32 v[48:49], v[54:55], v[50:51]
	v_exp_f32_e64 v50, -v44
	v_exp_f32_e64 v51, -v45
	v_cvt_pk_bf16_f32 v59, v48, v49
	v_mad_i64_i32 v[48:49], s[48:49], v68, s75, v[112:113]
	v_lshl_add_u64 v[48:49], v[48:49], 0, v[114:115]
	global_store_dwordx4 v[48:49], v[56:59], off
	v_pk_add_f32 v[48:49], v[50:51], 1.0 op_sel_hi:[1,0]
	v_exp_f32_e64 v50, -v46
	v_exp_f32_e64 v51, -v47
	v_pk_mul_f32 v[40:41], v[44:45], v[40:41]
	v_rcp_f32_e32 v48, v48
	v_rcp_f32_e32 v49, v49
	v_pk_add_f32 v[44:45], v[50:51], 1.0 op_sel_hi:[1,0]
	v_pk_mul_f32 v[42:43], v[46:47], v[42:43]
	v_rcp_f32_e32 v44, v44
	v_rcp_f32_e32 v45, v45
	v_exp_f32_e64 v46, -v36
	v_exp_f32_e64 v47, -v37
	v_pk_mul_f32 v[40:41], v[48:49], v[40:41]
	v_pk_mul_f32 v[42:43], v[44:45], v[42:43]
	v_exp_f32_e64 v44, -v38
	v_exp_f32_e64 v45, -v39
	v_cvt_pk_bf16_f32 v40, v40, v41
	v_cvt_pk_bf16_f32 v41, v42, v43
	v_pk_add_f32 v[42:43], v[46:47], 1.0 op_sel_hi:[1,0]
	v_pk_mul_f32 v[34:35], v[38:39], v[34:35]
	v_rcp_f32_e32 v42, v42
	v_rcp_f32_e32 v43, v43
	v_pk_add_f32 v[38:39], v[44:45], 1.0 op_sel_hi:[1,0]
	v_pk_mul_f32 v[32:33], v[36:37], v[32:33]
	v_rcp_f32_e32 v38, v38
	v_rcp_f32_e32 v39, v39
	v_pk_mul_f32 v[32:33], v[42:43], v[32:33]
	v_add_u32_e32 v52, 0x90, v150
	v_cvt_pk_bf16_f32 v42, v32, v33
	v_pk_mul_f32 v[32:33], v[38:39], v[34:35]
	v_exp_f32_e64 v34, -v28
	v_exp_f32_e64 v35, -v29
	v_cvt_pk_bf16_f32 v43, v32, v33
	v_mad_i64_i32 v[32:33], s[48:49], v52, s75, v[112:113]
	v_lshl_add_u64 v[32:33], v[32:33], 0, v[114:115]
	global_store_dwordx4 v[32:33], v[40:43], off
	v_pk_add_f32 v[32:33], v[34:35], 1.0 op_sel_hi:[1,0]
	v_exp_f32_e64 v34, -v30
	v_exp_f32_e64 v35, -v31
	v_pk_mul_f32 v[24:25], v[28:29], v[24:25]
	v_rcp_f32_e32 v32, v32
	v_rcp_f32_e32 v33, v33
	v_pk_add_f32 v[28:29], v[34:35], 1.0 op_sel_hi:[1,0]
	v_pk_mul_f32 v[26:27], v[30:31], v[26:27]
	v_rcp_f32_e32 v28, v28
	v_rcp_f32_e32 v29, v29
	v_exp_f32_e64 v30, -v20
	v_exp_f32_e64 v31, -v21
	v_pk_mul_f32 v[24:25], v[32:33], v[24:25]
	v_pk_mul_f32 v[26:27], v[28:29], v[26:27]
	v_exp_f32_e64 v28, -v22
	v_exp_f32_e64 v29, -v23
	v_cvt_pk_bf16_f32 v24, v24, v25
	v_cvt_pk_bf16_f32 v25, v26, v27
	v_pk_add_f32 v[26:27], v[30:31], 1.0 op_sel_hi:[1,0]
	v_pk_mul_f32 v[18:19], v[22:23], v[18:19]
	v_rcp_f32_e32 v26, v26
	v_rcp_f32_e32 v27, v27
	v_pk_add_f32 v[22:23], v[28:29], 1.0 op_sel_hi:[1,0]
	v_pk_mul_f32 v[16:17], v[20:21], v[16:17]
	v_rcp_f32_e32 v22, v22
	v_rcp_f32_e32 v23, v23
	v_pk_mul_f32 v[16:17], v[26:27], v[16:17]
	v_add_u32_e32 v36, 0xa0, v150
	v_cvt_pk_bf16_f32 v26, v16, v17
	v_pk_mul_f32 v[16:17], v[22:23], v[18:19]
	v_exp_f32_e64 v18, -v12
	v_exp_f32_e64 v19, -v13
	v_cvt_pk_bf16_f32 v27, v16, v17
	v_mad_i64_i32 v[16:17], s[48:49], v36, s75, v[112:113]
	v_lshl_add_u64 v[16:17], v[16:17], 0, v[114:115]
	global_store_dwordx4 v[16:17], v[24:27], off
	v_pk_add_f32 v[16:17], v[18:19], 1.0 op_sel_hi:[1,0]
	v_exp_f32_e64 v18, -v14
	v_exp_f32_e64 v19, -v15
	v_pk_mul_f32 v[8:9], v[12:13], v[8:9]
	v_rcp_f32_e32 v16, v16
	v_rcp_f32_e32 v17, v17
	v_pk_add_f32 v[12:13], v[18:19], 1.0 op_sel_hi:[1,0]
	v_pk_mul_f32 v[10:11], v[14:15], v[10:11]
	v_rcp_f32_e32 v12, v12
	v_rcp_f32_e32 v13, v13
	v_exp_f32_e64 v14, -v4
	v_exp_f32_e64 v15, -v5
	v_pk_mul_f32 v[8:9], v[16:17], v[8:9]
	v_pk_mul_f32 v[10:11], v[12:13], v[10:11]
	v_exp_f32_e64 v12, -v6
	v_exp_f32_e64 v13, -v7
	v_cvt_pk_bf16_f32 v8, v8, v9
	v_cvt_pk_bf16_f32 v9, v10, v11
	v_pk_add_f32 v[10:11], v[14:15], 1.0 op_sel_hi:[1,0]
	v_pk_mul_f32 v[2:3], v[6:7], v[2:3]
	v_rcp_f32_e32 v10, v10
	v_rcp_f32_e32 v11, v11
	v_pk_add_f32 v[6:7], v[12:13], 1.0 op_sel_hi:[1,0]
	v_pk_mul_f32 v[0:1], v[4:5], v[0:1]
	v_rcp_f32_e32 v6, v6
	v_rcp_f32_e32 v7, v7
	v_pk_mul_f32 v[0:1], v[10:11], v[0:1]
	v_add_u32_e32 v20, 0xb0, v150
	v_cvt_pk_bf16_f32 v10, v0, v1
	v_pk_mul_f32 v[0:1], v[6:7], v[2:3]
	s_andn2_b64 vcc, exec, s[0:1]
	v_cvt_pk_bf16_f32 v11, v0, v1
	v_mad_i64_i32 v[0:1], s[48:49], v20, s75, v[112:113]
	v_lshl_add_u64 v[0:1], v[0:1], 0, v[114:115]
	s_mov_b64 s[0:1], -1
	global_store_dwordx4 v[0:1], v[8:11], off
	s_cbranch_vccnz .LBB0_137
	s_andn2_b64 vcc, exec, s[8:9]
	s_cbranch_vccnz .LBB0_136
	s_branch .LBB0_136

.LBB0_212:
	s_add_u32 s44, s30, 0x3800000
	s_mov_b64 s[46:47], 0x80
	s_addc_u32 s45, s31, 0
	s_bfe_u32 s72, s3, 0x20006
	s_add_i32 m0, s67, 0x18000
	v_lshl_add_u64 v[6:7], v[6:7], 0, s[46:47]
	s_lshl_b32 s73, s4, 6
	s_lshl_b32 s7, s4, 13
	s_lshl_b32 s8, s72, 12
	s_nop 0
	global_load_lds_dwordx4 v[6:7], off
	v_lshl_add_u64 v[2:3], v[2:3], 0, s[46:47]
	s_add_i32 m0, s67, 0x1a000
	s_add_i32 s74, s67, 0x8000
	s_add_i32 s75, s67, 0xa000
	global_load_lds_dwordx4 v[2:3], off
	v_lshl_add_u64 v[0:1], v[0:1], 0, s[46:47]
	s_mov_b32 m0, s74
	s_add_u32 s4, s52, 0xb0080
	global_load_lds_dwordx4 v[0:1], off
	v_lshl_add_u64 v[0:1], v[4:5], 0, s[46:47]
	s_mov_b32 m0, s75
	s_addc_u32 s5, s53, 0
	global_load_lds_dwordx4 v[0:1], off
	s_add_i32 m0, s67, 0x1c000
	v_lshl_add_u64 v[0:1], s[4:5], 0, v[186:187]
	global_load_lds_dwordx4 v[0:1], off
	v_lshl_add_u64 v[0:1], s[4:5], 0, v[190:191]
	s_add_i32 m0, s67, 0x1e000
	v_and_b32_e32 v229, 15, v9
	global_load_lds_dwordx4 v[0:1], off
	v_lshlrev_b32_e32 v2, 2, v9
	v_and_b32_e32 v1, 48, v9
	v_lshlrev_b32_e32 v4, 6, v229
	v_and_b32_e32 v2, 32, v2
	v_and_b32_e32 v3, 0x400, v16
	v_bitop3_b32 v1, v4, v2, v1 bitop3:0x36
	v_or3_b32 v5, v3, s7, v1
	v_or3_b32 v230, v3, s8, v1
	v_lshlrev_b32_e32 v1, 10, v9
	v_and_b32_e32 v3, 64, v9
	v_and_b32_e32 v4, 0x1c00, v1
	v_xor_b32_e32 v1, 16, v9
	v_add_u32_e32 v3, 64, v3
	v_cmp_lt_i32_e32 vcc, v1, v3
	v_lshrrev_b32_e32 v0, 1, v9
	v_and_b32_e32 v0, 56, v0
	v_cndmask_b32_e32 v1, v9, v1, vcc
	v_lshlrev_b32_e32 v231, 2, v1
	v_xor_b32_e32 v1, 32, v9
	v_cmp_lt_i32_e32 vcc, v1, v3
	v_lshlrev_b32_e32 v192, 2, v0
	s_mov_b32 s7, 0xb000
	v_cndmask_b32_e32 v1, v9, v1, vcc
	v_lshlrev_b32_e32 v232, 2, v1
	v_lshrrev_b32_e32 v1, 1, v8
	v_mul_lo_u32 v8, v11, s6
	v_cmp_gt_u32_e64 s[4:5], 16, v9
	v_lshl_add_u64 v[194:195], s[40:41], 0, v[192:193]
	v_mad_u64_u32 v[8:9], s[40:41], v1, s7, v[8:9]
	v_or_b32_e32 v1, v8, v10
	v_add_lshl_u32 v192, v1, v12, 1
	v_lshrrev_b32_e32 v1, 1, v13
	v_mul_lo_u32 v8, v14, s6
	v_mad_u64_u32 v[8:9], s[6:7], v1, s7, v[8:9]
	s_mov_b64 s[8:9], 0xb0080
	s_waitcnt vmcnt(6)
	s_cmpk_lt_u32 s3, 0x100
	v_cmp_gt_u32_e64 s[10:11], 8, v229
	v_or_b32_e32 v1, v8, v15
	s_cselect_b64 s[48:49], -1, 0
	v_cndmask_b32_e64 v6, 32, 0, s[10:11]
	v_lshl_add_u64 v[196:197], v[192:193], 0, s[8:9]
	v_add_lshl_u32 v192, v1, v17, 1
	s_add_i32 s82, 0, 0x10000
	s_add_i32 s85, 0, 0x14000
	s_mov_b32 s76, 0x18000
	s_mov_b32 s77, 0x8000
	s_lshl_b32 s78, s72, 6
	s_ashr_i32 s79, s34, 31
	s_mov_b32 s80, s34
	s_ashr_i32 s81, s2, 31
	v_lshl_add_u64 v[198:199], v[192:193], 0, s[8:9]
	v_add_u32_e32 v233, s82, v230
	v_add_u32_e32 v234, s85, v230
	v_add_u32_e32 v235, 0, v5
	v_lshlrev_b32_e32 v192, 1, v4
	v_lshlrev_b32_e32 v202, 1, v2
	v_lshlrev_b32_e32 v204, 1, v0
	s_mov_b32 s87, 0x40000
	s_mov_b32 s88, 0x48000
	s_mov_b32 s89, 0x50000
	s_mov_b32 s90, 0x58000
	v_lshlrev_b32_e32 v206, 1, v6
	s_mov_b32 s91, 0
	s_barrier
	s_branch .LBB0_215

.LBB0_220:
	s_add_u32 s95, s52, 0x100
	s_addc_u32 s96, s53, 0
	s_mov_b32 s97, -2
	s_and_b64 vcc, exec, s[48:49]
	s_cbranch_vccz .Lh1p_2
	ds_read_b128 v[88:91], v233
	ds_read_b128 v[92:95], v233 offset:1024
	ds_read_b128 v[112:115], v233 offset:2048
	ds_read_b128 v[116:119], v233 offset:3072
	ds_read_b128 v[132:135], v234
	ds_read_b128 v[136:139], v234 offset:1024
	ds_read_b128 v[152:155], v234 offset:2048
	ds_read_b128 v[156:159], v234 offset:3072
	s_add_u32 s52, s50, 0x100
	s_addc_u32 s53, s51, 0
	s_cmp_eq_u32 s97, 40
	s_cselect_b32 s57, s9, s53
	s_cselect_b32 s56, s8, s52
	s_cselect_b32 s55, s41, s96
	s_cselect_b32 s54, s40, s95
	v_lshl_add_u64 v[216:217], s[50:51], 0, v[196:197]
	s_add_i32 m0, s67, 0xc000
	ds_read_b128 v[160:163], v235
	ds_read_b128 v[164:167], v235 offset:1024
	ds_read_b128 v[168:171], v235 offset:2048
	ds_read_b128 v[172:175], v235 offset:3072
	ds_read_b128 v[176:179], v235 offset:4096
	ds_read_b128 v[180:183], v235 offset:5120
	ds_read_b128 v[208:211], v235 offset:6144
	ds_read_b128 v[212:215], v235 offset:7168
	global_load_lds_dwordx4 v[216:217], off
	v_lshl_add_u64 v[216:217], s[50:51], 0, v[198:199]
	s_add_i32 m0, s67, 0xe000
	s_nop 0
	global_load_lds_dwordx4 v[216:217], off
	s_waitcnt vmcnt(8)
	s_waitcnt lgkmcnt(0)
	s_setprio 1
	v_mfma_f32_16x16x32_bf16 v[148:151], v[88:91], v[160:163], 0
	v_mfma_f32_16x16x32_bf16 v[144:147], v[112:115], v[160:163], 0
	v_mfma_f32_16x16x32_bf16 v[124:127], v[88:91], v[168:171], 0
	v_mfma_f32_16x16x32_bf16 v[120:123], v[112:115], v[168:171], 0
	v_mfma_f32_16x16x32_bf16 v[100:103], v[88:91], v[176:179], 0
	v_mfma_f32_16x16x32_bf16 v[96:99], v[112:115], v[176:179], 0
	v_mfma_f32_16x16x32_bf16 v[76:79], v[88:91], v[208:211], 0
	v_mfma_f32_16x16x32_bf16 v[72:75], v[112:115], v[208:211], 0
	v_mfma_f32_16x16x32_bf16 v[148:151], v[92:95], v[164:167], v[148:151]
	v_mfma_f32_16x16x32_bf16 v[144:147], v[116:119], v[164:167], v[144:147]
	v_mfma_f32_16x16x32_bf16 v[124:127], v[92:95], v[172:175], v[124:127]
	v_mfma_f32_16x16x32_bf16 v[120:123], v[116:119], v[172:175], v[120:123]
	v_mfma_f32_16x16x32_bf16 v[100:103], v[92:95], v[180:183], v[100:103]
	v_mfma_f32_16x16x32_bf16 v[96:99], v[116:119], v[180:183], v[96:99]
	v_mfma_f32_16x16x32_bf16 v[76:79], v[92:95], v[212:215], v[76:79]
	v_mfma_f32_16x16x32_bf16 v[72:75], v[116:119], v[212:215], v[72:75]
	v_mfma_f32_16x16x32_bf16 v[140:143], v[132:135], v[160:163], 0
	v_mfma_f32_16x16x32_bf16 v[128:131], v[152:155], v[160:163], 0
	v_mfma_f32_16x16x32_bf16 v[108:111], v[132:135], v[168:171], 0
	v_mfma_f32_16x16x32_bf16 v[104:107], v[152:155], v[168:171], 0
	v_mfma_f32_16x16x32_bf16 v[84:87], v[132:135], v[176:179], 0
	v_mfma_f32_16x16x32_bf16 v[80:83], v[152:155], v[176:179], 0
	v_mfma_f32_16x16x32_bf16 v[68:71], v[132:135], v[208:211], 0
	v_mfma_f32_16x16x32_bf16 v[64:67], v[152:155], v[208:211], 0
	v_mfma_f32_16x16x32_bf16 v[140:143], v[136:139], v[164:167], v[140:143]
	v_mfma_f32_16x16x32_bf16 v[128:131], v[156:159], v[164:167], v[128:131]
	v_mfma_f32_16x16x32_bf16 v[108:111], v[136:139], v[172:175], v[108:111]
	v_mfma_f32_16x16x32_bf16 v[104:107], v[156:159], v[172:175], v[104:107]
	v_mfma_f32_16x16x32_bf16 v[84:87], v[136:139], v[180:183], v[84:87]
	v_mfma_f32_16x16x32_bf16 v[80:83], v[156:159], v[180:183], v[80:83]
	v_mfma_f32_16x16x32_bf16 v[68:71], v[136:139], v[212:215], v[68:71]
	v_mfma_f32_16x16x32_bf16 v[64:67], v[156:159], v[212:215], v[64:67]
	s_setprio 0
	s_barrier
	s_add_i32 s50, s82, s66
	v_lshl_add_u64 v[216:217], s[54:55], 0, v[186:187]
	s_mov_b32 m0, s50
	ds_read_b128 v[160:163], v235 offset:16384
	ds_read_b128 v[164:167], v235 offset:17408
	ds_read_b128 v[168:171], v235 offset:18432
	ds_read_b128 v[172:175], v235 offset:19456
	ds_read_b128 v[176:179], v235 offset:20480
	ds_read_b128 v[180:183], v235 offset:21504
	ds_read_b128 v[208:211], v235 offset:22528
	ds_read_b128 v[212:215], v235 offset:23552
	global_load_lds_dwordx4 v[216:217], off
	s_add_i32 m0, s50, 0x2000
	s_add_u32 s50, s54, 0xb0000
	v_lshl_add_u64 v[218:219], s[54:55], 0, v[190:191]
	s_addc_u32 s51, s55, 0
	s_add_i32 vcc_lo, s85, s66
	global_load_lds_dwordx4 v[218:219], off
	v_lshl_add_u64 v[220:221], s[50:51], 0, v[186:187]
	s_mov_b32 m0, vcc_lo
	v_lshl_add_u64 v[222:223], s[56:57], 0, v[188:189]
	global_load_lds_dwordx4 v[220:221], off
	v_lshl_add_u64 v[220:221], s[50:51], 0, v[190:191]
	s_add_i32 m0, vcc_lo, 0x2000
	s_nop 0
	global_load_lds_dwordx4 v[220:221], off
	v_lshl_add_u64 v[220:221], s[56:57], 0, v[184:185]
	s_mov_b32 m0, s67
	s_nop 0
	global_load_lds_dwordx4 v[220:221], off
	s_mov_b32 m0, s68
	s_nop 0
	global_load_lds_dwordx4 v[222:223], off
	s_waitcnt vmcnt(8)
	s_waitcnt lgkmcnt(0)
	s_setprio 1
	v_mfma_f32_16x16x32_bf16 v[60:63], v[88:91], v[160:163], 0
	v_mfma_f32_16x16x32_bf16 v[56:59], v[112:115], v[160:163], 0
	v_mfma_f32_16x16x32_bf16 v[44:47], v[88:91], v[168:171], 0
	v_mfma_f32_16x16x32_bf16 v[40:43], v[112:115], v[168:171], 0
	v_mfma_f32_16x16x32_bf16 v[28:31], v[88:91], v[176:179], 0
	v_mfma_f32_16x16x32_bf16 v[24:27], v[112:115], v[176:179], 0
	v_mfma_f32_16x16x32_bf16 v[12:15], v[88:91], v[208:211], 0
	v_mfma_f32_16x16x32_bf16 v[8:11], v[112:115], v[208:211], 0
	v_mfma_f32_16x16x32_bf16 v[60:63], v[92:95], v[164:167], v[60:63]
	v_mfma_f32_16x16x32_bf16 v[56:59], v[116:119], v[164:167], v[56:59]
	v_mfma_f32_16x16x32_bf16 v[44:47], v[92:95], v[172:175], v[44:47]
	v_mfma_f32_16x16x32_bf16 v[40:43], v[116:119], v[172:175], v[40:43]
	v_mfma_f32_16x16x32_bf16 v[28:31], v[92:95], v[180:183], v[28:31]
	v_mfma_f32_16x16x32_bf16 v[24:27], v[116:119], v[180:183], v[24:27]
	v_mfma_f32_16x16x32_bf16 v[12:15], v[92:95], v[212:215], v[12:15]
	v_mfma_f32_16x16x32_bf16 v[8:11], v[116:119], v[212:215], v[8:11]
	v_mfma_f32_16x16x32_bf16 v[52:55], v[132:135], v[160:163], 0
	v_mfma_f32_16x16x32_bf16 v[48:51], v[152:155], v[160:163], 0
	v_mfma_f32_16x16x32_bf16 v[36:39], v[132:135], v[168:171], 0
	v_mfma_f32_16x16x32_bf16 v[32:35], v[152:155], v[168:171], 0
	v_mfma_f32_16x16x32_bf16 v[20:23], v[132:135], v[176:179], 0
	v_mfma_f32_16x16x32_bf16 v[16:19], v[152:155], v[176:179], 0
	v_mfma_f32_16x16x32_bf16 v[4:7], v[132:135], v[208:211], 0
	v_mfma_f32_16x16x32_bf16 v[0:3], v[152:155], v[208:211], 0
	v_mfma_f32_16x16x32_bf16 v[52:55], v[136:139], v[164:167], v[52:55]
	v_mfma_f32_16x16x32_bf16 v[48:51], v[156:159], v[164:167], v[48:51]
	v_mfma_f32_16x16x32_bf16 v[36:39], v[136:139], v[172:175], v[36:39]
	v_mfma_f32_16x16x32_bf16 v[32:35], v[156:159], v[172:175], v[32:35]
	v_mfma_f32_16x16x32_bf16 v[20:23], v[136:139], v[180:183], v[20:23]
	v_mfma_f32_16x16x32_bf16 v[16:19], v[156:159], v[180:183], v[16:19]
	v_mfma_f32_16x16x32_bf16 v[4:7], v[136:139], v[212:215], v[4:7]
	v_mfma_f32_16x16x32_bf16 v[0:3], v[156:159], v[212:215], v[0:3]
	s_setprio 0
	s_barrier
	s_add_i32 vcc_lo, 0, 0x18000
	s_add_i32 vcc_hi, 0, 0x1c000
	v_add_u32_e32 v116, vcc_lo, v230
	v_add_u32_e32 v156, vcc_hi, v230
	ds_read_b128 v[88:91], v116
	ds_read_b128 v[92:95], v116 offset:1024
	ds_read_b128 v[112:115], v116 offset:2048
	ds_read_b128 v[116:119], v116 offset:3072
	ds_read_b128 v[132:135], v156
	ds_read_b128 v[136:139], v156 offset:1024
	ds_read_b128 v[152:155], v156 offset:2048
	ds_read_b128 v[156:159], v156 offset:3072
	s_add_u32 s50, s56, 0xb0000
	s_addc_u32 s51, s57, 0
	s_mov_b32 m0, s69
	v_lshl_add_u64 v[224:225], s[50:51], 0, v[184:185]
	ds_read_b128 v[160:163], v235 offset:32768
	ds_read_b128 v[164:167], v235 offset:33792
	ds_read_b128 v[168:171], v235 offset:34816
	ds_read_b128 v[172:175], v235 offset:35840
	ds_read_b128 v[176:179], v235 offset:36864
	ds_read_b128 v[180:183], v235 offset:37888
	ds_read_b128 v[208:211], v235 offset:38912
	ds_read_b128 v[212:215], v235 offset:39936
	global_load_lds_dwordx4 v[224:225], off
	v_lshl_add_u64 v[224:225], s[50:51], 0, v[188:189]
	s_mov_b32 m0, s70
	s_nop 0
	global_load_lds_dwordx4 v[224:225], off
	s_waitcnt vmcnt(8)
	s_waitcnt lgkmcnt(0)
	s_setprio 1
	v_mfma_f32_16x16x32_bf16 v[148:151], v[88:91], v[160:163], v[148:151]
	v_mfma_f32_16x16x32_bf16 v[144:147], v[112:115], v[160:163], v[144:147]
	v_mfma_f32_16x16x32_bf16 v[124:127], v[88:91], v[168:171], v[124:127]
	v_mfma_f32_16x16x32_bf16 v[120:123], v[112:115], v[168:171], v[120:123]
	v_mfma_f32_16x16x32_bf16 v[100:103], v[88:91], v[176:179], v[100:103]
	v_mfma_f32_16x16x32_bf16 v[96:99], v[112:115], v[176:179], v[96:99]
	v_mfma_f32_16x16x32_bf16 v[76:79], v[88:91], v[208:211], v[76:79]
	v_mfma_f32_16x16x32_bf16 v[72:75], v[112:115], v[208:211], v[72:75]
	v_mfma_f32_16x16x32_bf16 v[148:151], v[92:95], v[164:167], v[148:151]
	v_mfma_f32_16x16x32_bf16 v[144:147], v[116:119], v[164:167], v[144:147]
	v_mfma_f32_16x16x32_bf16 v[124:127], v[92:95], v[172:175], v[124:127]
	v_mfma_f32_16x16x32_bf16 v[120:123], v[116:119], v[172:175], v[120:123]
	v_mfma_f32_16x16x32_bf16 v[100:103], v[92:95], v[180:183], v[100:103]
	v_mfma_f32_16x16x32_bf16 v[96:99], v[116:119], v[180:183], v[96:99]
	v_mfma_f32_16x16x32_bf16 v[76:79], v[92:95], v[212:215], v[76:79]
	v_mfma_f32_16x16x32_bf16 v[72:75], v[116:119], v[212:215], v[72:75]
	v_mfma_f32_16x16x32_bf16 v[140:143], v[132:135], v[160:163], v[140:143]
	v_mfma_f32_16x16x32_bf16 v[128:131], v[152:155], v[160:163], v[128:131]
	v_mfma_f32_16x16x32_bf16 v[108:111], v[132:135], v[168:171], v[108:111]
	v_mfma_f32_16x16x32_bf16 v[104:107], v[152:155], v[168:171], v[104:107]
	v_mfma_f32_16x16x32_bf16 v[84:87], v[132:135], v[176:179], v[84:87]
	v_mfma_f32_16x16x32_bf16 v[80:83], v[152:155], v[176:179], v[80:83]
	v_mfma_f32_16x16x32_bf16 v[68:71], v[132:135], v[208:211], v[68:71]
	v_mfma_f32_16x16x32_bf16 v[64:67], v[152:155], v[208:211], v[64:67]
	v_mfma_f32_16x16x32_bf16 v[140:143], v[136:139], v[164:167], v[140:143]
	v_mfma_f32_16x16x32_bf16 v[128:131], v[156:159], v[164:167], v[128:131]
	v_mfma_f32_16x16x32_bf16 v[108:111], v[136:139], v[172:175], v[108:111]
	v_mfma_f32_16x16x32_bf16 v[104:107], v[156:159], v[172:175], v[104:107]
	v_mfma_f32_16x16x32_bf16 v[84:87], v[136:139], v[180:183], v[84:87]
	v_mfma_f32_16x16x32_bf16 v[80:83], v[156:159], v[180:183], v[80:83]
	v_mfma_f32_16x16x32_bf16 v[68:71], v[136:139], v[212:215], v[68:71]
	v_mfma_f32_16x16x32_bf16 v[64:67], v[156:159], v[212:215], v[64:67]
	s_setprio 0
	s_barrier
	s_add_i32 s50, vcc_lo, s66
	v_lshl_add_u64 v[216:217], v[216:217], 0, s[46:47]
	s_mov_b32 m0, s50
	ds_read_b128 v[160:163], v235 offset:49152
	ds_read_b128 v[164:167], v235 offset:50176
	ds_read_b128 v[168:171], v235 offset:51200
	ds_read_b128 v[172:175], v235 offset:52224
	ds_read_b128 v[176:179], v235 offset:53248
	ds_read_b128 v[180:183], v235 offset:54272
	ds_read_b128 v[208:211], v235 offset:55296
	ds_read_b128 v[212:215], v235 offset:56320
	global_load_lds_dwordx4 v[216:217], off
	s_add_i32 m0, s50, 0x2000
	s_add_u32 s50, s54, 0xb0080
	v_lshl_add_u64 v[216:217], v[218:219], 0, s[46:47]
	s_addc_u32 s51, s55, 0
	s_add_i32 s54, vcc_hi, s66
	global_load_lds_dwordx4 v[216:217], off
	v_lshl_add_u64 v[216:217], s[50:51], 0, v[186:187]
	s_mov_b32 m0, s54
	s_nop 0
	global_load_lds_dwordx4 v[216:217], off
	v_lshl_add_u64 v[216:217], s[50:51], 0, v[190:191]
	s_add_i32 m0, s54, 0x2000
	s_nop 0
	global_load_lds_dwordx4 v[216:217], off
	v_lshl_add_u64 v[216:217], v[220:221], 0, s[46:47]
	s_mov_b32 m0, s74
	s_nop 0
	global_load_lds_dwordx4 v[216:217], off
	v_lshl_add_u64 v[216:217], v[222:223], 0, s[46:47]
	s_mov_b32 m0, s75
	s_nop 0
	global_load_lds_dwordx4 v[216:217], off
	s_waitcnt vmcnt(8)
	s_waitcnt lgkmcnt(0)
	s_setprio 1
	v_mfma_f32_16x16x32_bf16 v[60:63], v[88:91], v[160:163], v[60:63]
	v_mfma_f32_16x16x32_bf16 v[56:59], v[112:115], v[160:163], v[56:59]
	v_mfma_f32_16x16x32_bf16 v[44:47], v[88:91], v[168:171], v[44:47]
	v_mfma_f32_16x16x32_bf16 v[40:43], v[112:115], v[168:171], v[40:43]
	v_mfma_f32_16x16x32_bf16 v[28:31], v[88:91], v[176:179], v[28:31]
	v_mfma_f32_16x16x32_bf16 v[24:27], v[112:115], v[176:179], v[24:27]
	v_mfma_f32_16x16x32_bf16 v[12:15], v[88:91], v[208:211], v[12:15]
	v_mfma_f32_16x16x32_bf16 v[8:11], v[112:115], v[208:211], v[8:11]
	v_mfma_f32_16x16x32_bf16 v[60:63], v[92:95], v[164:167], v[60:63]
	v_mfma_f32_16x16x32_bf16 v[56:59], v[116:119], v[164:167], v[56:59]
	v_mfma_f32_16x16x32_bf16 v[44:47], v[92:95], v[172:175], v[44:47]
	v_mfma_f32_16x16x32_bf16 v[40:43], v[116:119], v[172:175], v[40:43]
	v_mfma_f32_16x16x32_bf16 v[28:31], v[92:95], v[180:183], v[28:31]
	v_mfma_f32_16x16x32_bf16 v[24:27], v[116:119], v[180:183], v[24:27]
	v_mfma_f32_16x16x32_bf16 v[12:15], v[92:95], v[212:215], v[12:15]
	v_mfma_f32_16x16x32_bf16 v[8:11], v[116:119], v[212:215], v[8:11]
	v_mfma_f32_16x16x32_bf16 v[52:55], v[132:135], v[160:163], v[52:55]
	v_mfma_f32_16x16x32_bf16 v[48:51], v[152:155], v[160:163], v[48:51]
	v_mfma_f32_16x16x32_bf16 v[36:39], v[132:135], v[168:171], v[36:39]
	v_mfma_f32_16x16x32_bf16 v[32:35], v[152:155], v[168:171], v[32:35]
	v_mfma_f32_16x16x32_bf16 v[20:23], v[132:135], v[176:179], v[20:23]
	v_mfma_f32_16x16x32_bf16 v[16:19], v[152:155], v[176:179], v[16:19]
	v_mfma_f32_16x16x32_bf16 v[4:7], v[132:135], v[208:211], v[4:7]
	v_mfma_f32_16x16x32_bf16 v[0:3], v[152:155], v[208:211], v[0:3]
	v_mfma_f32_16x16x32_bf16 v[52:55], v[136:139], v[164:167], v[52:55]
	v_mfma_f32_16x16x32_bf16 v[48:51], v[156:159], v[164:167], v[48:51]
	v_mfma_f32_16x16x32_bf16 v[36:39], v[136:139], v[172:175], v[36:39]
	v_mfma_f32_16x16x32_bf16 v[32:35], v[156:159], v[172:175], v[32:35]
	v_mfma_f32_16x16x32_bf16 v[20:23], v[136:139], v[180:183], v[20:23]
	v_mfma_f32_16x16x32_bf16 v[16:19], v[156:159], v[180:183], v[16:19]
	v_mfma_f32_16x16x32_bf16 v[4:7], v[136:139], v[212:215], v[4:7]
	v_mfma_f32_16x16x32_bf16 v[0:3], v[156:159], v[212:215], v[0:3]
	s_setprio 0
	s_barrier
	s_add_i32 s97, s97, 2
	s_add_u32 s95, s95, 0x100
	s_addc_u32 s96, s96, 0
	s_cmp_gt_u32 s97, 41
	s_mov_b64 s[50:51], s[52:53]
.Lh0_2:
	ds_read_b128 v[88:91], v233
	ds_read_b128 v[92:95], v233 offset:1024
	ds_read_b128 v[112:115], v233 offset:2048
	ds_read_b128 v[116:119], v233 offset:3072
	ds_read_b128 v[132:135], v234
	ds_read_b128 v[136:139], v234 offset:1024
	ds_read_b128 v[152:155], v234 offset:2048
	ds_read_b128 v[156:159], v234 offset:3072
	s_add_u32 s52, s50, 0x100
	s_addc_u32 s53, s51, 0
	s_cmp_eq_u32 s97, 40
	s_cselect_b32 s57, s9, s53
	s_cselect_b32 s56, s8, s52
	s_cselect_b32 s55, s41, s96
	s_cselect_b32 s54, s40, s95
	v_lshl_add_u64 v[216:217], s[50:51], 0, v[196:197]
	s_add_i32 m0, s67, 0xc000
	ds_read_b128 v[160:163], v235
	ds_read_b128 v[164:167], v235 offset:1024
	ds_read_b128 v[168:171], v235 offset:2048
	ds_read_b128 v[172:175], v235 offset:3072
	ds_read_b128 v[176:179], v235 offset:4096
	ds_read_b128 v[180:183], v235 offset:5120
	ds_read_b128 v[208:211], v235 offset:6144
	ds_read_b128 v[212:215], v235 offset:7168
	global_load_lds_dwordx4 v[216:217], off
	v_lshl_add_u64 v[216:217], s[50:51], 0, v[198:199]
	s_add_i32 m0, s67, 0xe000
	s_nop 0
	global_load_lds_dwordx4 v[216:217], off
	s_waitcnt vmcnt(8)
	s_waitcnt lgkmcnt(0)
	s_setprio 1
	v_mfma_f32_16x16x32_bf16 v[148:151], v[88:91], v[160:163], v[148:151]
	v_mfma_f32_16x16x32_bf16 v[144:147], v[112:115], v[160:163], v[144:147]
	v_mfma_f32_16x16x32_bf16 v[124:127], v[88:91], v[168:171], v[124:127]
	v_mfma_f32_16x16x32_bf16 v[120:123], v[112:115], v[168:171], v[120:123]
	v_mfma_f32_16x16x32_bf16 v[100:103], v[88:91], v[176:179], v[100:103]
	v_mfma_f32_16x16x32_bf16 v[96:99], v[112:115], v[176:179], v[96:99]
	v_mfma_f32_16x16x32_bf16 v[76:79], v[88:91], v[208:211], v[76:79]
	v_mfma_f32_16x16x32_bf16 v[72:75], v[112:115], v[208:211], v[72:75]
	v_mfma_f32_16x16x32_bf16 v[148:151], v[92:95], v[164:167], v[148:151]
	v_mfma_f32_16x16x32_bf16 v[144:147], v[116:119], v[164:167], v[144:147]
	v_mfma_f32_16x16x32_bf16 v[124:127], v[92:95], v[172:175], v[124:127]
	v_mfma_f32_16x16x32_bf16 v[120:123], v[116:119], v[172:175], v[120:123]
	v_mfma_f32_16x16x32_bf16 v[100:103], v[92:95], v[180:183], v[100:103]
	v_mfma_f32_16x16x32_bf16 v[96:99], v[116:119], v[180:183], v[96:99]
	v_mfma_f32_16x16x32_bf16 v[76:79], v[92:95], v[212:215], v[76:79]
	v_mfma_f32_16x16x32_bf16 v[72:75], v[116:119], v[212:215], v[72:75]
	v_mfma_f32_16x16x32_bf16 v[140:143], v[132:135], v[160:163], v[140:143]
	v_mfma_f32_16x16x32_bf16 v[128:131], v[152:155], v[160:163], v[128:131]
	v_mfma_f32_16x16x32_bf16 v[108:111], v[132:135], v[168:171], v[108:111]
	v_mfma_f32_16x16x32_bf16 v[104:107], v[152:155], v[168:171], v[104:107]
	v_mfma_f32_16x16x32_bf16 v[84:87], v[132:135], v[176:179], v[84:87]
	v_mfma_f32_16x16x32_bf16 v[80:83], v[152:155], v[176:179], v[80:83]
	v_mfma_f32_16x16x32_bf16 v[68:71], v[132:135], v[208:211], v[68:71]
	v_mfma_f32_16x16x32_bf16 v[64:67], v[152:155], v[208:211], v[64:67]
	v_mfma_f32_16x16x32_bf16 v[140:143], v[136:139], v[164:167], v[140:143]
	v_mfma_f32_16x16x32_bf16 v[128:131], v[156:159], v[164:167], v[128:131]
	v_mfma_f32_16x16x32_bf16 v[108:111], v[136:139], v[172:175], v[108:111]
	v_mfma_f32_16x16x32_bf16 v[104:107], v[156:159], v[172:175], v[104:107]
	v_mfma_f32_16x16x32_bf16 v[84:87], v[136:139], v[180:183], v[84:87]
	v_mfma_f32_16x16x32_bf16 v[80:83], v[156:159], v[180:183], v[80:83]
	v_mfma_f32_16x16x32_bf16 v[68:71], v[136:139], v[212:215], v[68:71]
	v_mfma_f32_16x16x32_bf16 v[64:67], v[156:159], v[212:215], v[64:67]
	s_setprio 0
	s_barrier
	s_add_i32 s50, s82, s66
	v_lshl_add_u64 v[216:217], s[54:55], 0, v[186:187]
	s_mov_b32 m0, s50
	ds_read_b128 v[160:163], v235 offset:16384
	ds_read_b128 v[164:167], v235 offset:17408
	ds_read_b128 v[168:171], v235 offset:18432
	ds_read_b128 v[172:175], v235 offset:19456
	ds_read_b128 v[176:179], v235 offset:20480
	ds_read_b128 v[180:183], v235 offset:21504
	ds_read_b128 v[208:211], v235 offset:22528
	ds_read_b128 v[212:215], v235 offset:23552
	global_load_lds_dwordx4 v[216:217], off
	s_add_i32 m0, s50, 0x2000
	s_add_u32 s50, s54, 0xb0000
	v_lshl_add_u64 v[218:219], s[54:55], 0, v[190:191]
	s_addc_u32 s51, s55, 0
	s_add_i32 vcc_lo, s85, s66
	global_load_lds_dwordx4 v[218:219], off
	v_lshl_add_u64 v[220:221], s[50:51], 0, v[186:187]
	s_mov_b32 m0, vcc_lo
	v_lshl_add_u64 v[222:223], s[56:57], 0, v[188:189]
	global_load_lds_dwordx4 v[220:221], off
	v_lshl_add_u64 v[220:221], s[50:51], 0, v[190:191]
	s_add_i32 m0, vcc_lo, 0x2000
	s_nop 0
	global_load_lds_dwordx4 v[220:221], off
	v_lshl_add_u64 v[220:221], s[56:57], 0, v[184:185]
	s_mov_b32 m0, s67
	s_nop 0
	global_load_lds_dwordx4 v[220:221], off
	s_mov_b32 m0, s68
	s_nop 0
	global_load_lds_dwordx4 v[222:223], off
	s_waitcnt vmcnt(8)
	s_waitcnt lgkmcnt(0)
	s_setprio 1
	v_mfma_f32_16x16x32_bf16 v[60:63], v[88:91], v[160:163], v[60:63]
	v_mfma_f32_16x16x32_bf16 v[56:59], v[112:115], v[160:163], v[56:59]
	v_mfma_f32_16x16x32_bf16 v[44:47], v[88:91], v[168:171], v[44:47]
	v_mfma_f32_16x16x32_bf16 v[40:43], v[112:115], v[168:171], v[40:43]
	v_mfma_f32_16x16x32_bf16 v[28:31], v[88:91], v[176:179], v[28:31]
	v_mfma_f32_16x16x32_bf16 v[24:27], v[112:115], v[176:179], v[24:27]
	v_mfma_f32_16x16x32_bf16 v[12:15], v[88:91], v[208:211], v[12:15]
	v_mfma_f32_16x16x32_bf16 v[8:11], v[112:115], v[208:211], v[8:11]
	v_mfma_f32_16x16x32_bf16 v[60:63], v[92:95], v[164:167], v[60:63]
	v_mfma_f32_16x16x32_bf16 v[56:59], v[116:119], v[164:167], v[56:59]
	v_mfma_f32_16x16x32_bf16 v[44:47], v[92:95], v[172:175], v[44:47]
	v_mfma_f32_16x16x32_bf16 v[40:43], v[116:119], v[172:175], v[40:43]
	v_mfma_f32_16x16x32_bf16 v[28:31], v[92:95], v[180:183], v[28:31]
	v_mfma_f32_16x16x32_bf16 v[24:27], v[116:119], v[180:183], v[24:27]
	v_mfma_f32_16x16x32_bf16 v[12:15], v[92:95], v[212:215], v[12:15]
	v_mfma_f32_16x16x32_bf16 v[8:11], v[116:119], v[212:215], v[8:11]
	v_mfma_f32_16x16x32_bf16 v[52:55], v[132:135], v[160:163], v[52:55]
	v_mfma_f32_16x16x32_bf16 v[48:51], v[152:155], v[160:163], v[48:51]
	v_mfma_f32_16x16x32_bf16 v[36:39], v[132:135], v[168:171], v[36:39]
	v_mfma_f32_16x16x32_bf16 v[32:35], v[152:155], v[168:171], v[32:35]
	v_mfma_f32_16x16x32_bf16 v[20:23], v[132:135], v[176:179], v[20:23]
	v_mfma_f32_16x16x32_bf16 v[16:19], v[152:155], v[176:179], v[16:19]
	v_mfma_f32_16x16x32_bf16 v[4:7], v[132:135], v[208:211], v[4:7]
	v_mfma_f32_16x16x32_bf16 v[0:3], v[152:155], v[208:211], v[0:3]
	v_mfma_f32_16x16x32_bf16 v[52:55], v[136:139], v[164:167], v[52:55]
	v_mfma_f32_16x16x32_bf16 v[48:51], v[156:159], v[164:167], v[48:51]
	v_mfma_f32_16x16x32_bf16 v[36:39], v[136:139], v[172:175], v[36:39]
	v_mfma_f32_16x16x32_bf16 v[32:35], v[156:159], v[172:175], v[32:35]
	v_mfma_f32_16x16x32_bf16 v[20:23], v[136:139], v[180:183], v[20:23]
	v_mfma_f32_16x16x32_bf16 v[16:19], v[156:159], v[180:183], v[16:19]
	v_mfma_f32_16x16x32_bf16 v[4:7], v[136:139], v[212:215], v[4:7]
	v_mfma_f32_16x16x32_bf16 v[0:3], v[156:159], v[212:215], v[0:3]
	s_setprio 0
	s_barrier
	s_add_i32 vcc_lo, 0, 0x18000
	s_add_i32 vcc_hi, 0, 0x1c000
	v_add_u32_e32 v116, vcc_lo, v230
	v_add_u32_e32 v156, vcc_hi, v230
	ds_read_b128 v[88:91], v116
	ds_read_b128 v[92:95], v116 offset:1024
	ds_read_b128 v[112:115], v116 offset:2048
	ds_read_b128 v[116:119], v116 offset:3072
	ds_read_b128 v[132:135], v156
	ds_read_b128 v[136:139], v156 offset:1024
	ds_read_b128 v[152:155], v156 offset:2048
	ds_read_b128 v[156:159], v156 offset:3072
	s_add_u32 s50, s56, 0xb0000
	s_addc_u32 s51, s57, 0
	s_mov_b32 m0, s69
	v_lshl_add_u64 v[224:225], s[50:51], 0, v[184:185]
	ds_read_b128 v[160:163], v235 offset:32768
	ds_read_b128 v[164:167], v235 offset:33792
	ds_read_b128 v[168:171], v235 offset:34816
	ds_read_b128 v[172:175], v235 offset:35840
	ds_read_b128 v[176:179], v235 offset:36864
	ds_read_b128 v[180:183], v235 offset:37888
	ds_read_b128 v[208:211], v235 offset:38912
	ds_read_b128 v[212:215], v235 offset:39936
	global_load_lds_dwordx4 v[224:225], off
	v_lshl_add_u64 v[224:225], s[50:51], 0, v[188:189]
	s_mov_b32 m0, s70
	s_nop 0
	global_load_lds_dwordx4 v[224:225], off
	s_waitcnt vmcnt(8)
	s_waitcnt lgkmcnt(0)
	s_setprio 1
	v_mfma_f32_16x16x32_bf16 v[148:151], v[88:91], v[160:163], v[148:151]
	v_mfma_f32_16x16x32_bf16 v[144:147], v[112:115], v[160:163], v[144:147]
	v_mfma_f32_16x16x32_bf16 v[124:127], v[88:91], v[168:171], v[124:127]
	v_mfma_f32_16x16x32_bf16 v[120:123], v[112:115], v[168:171], v[120:123]
	v_mfma_f32_16x16x32_bf16 v[100:103], v[88:91], v[176:179], v[100:103]
	v_mfma_f32_16x16x32_bf16 v[96:99], v[112:115], v[176:179], v[96:99]
	v_mfma_f32_16x16x32_bf16 v[76:79], v[88:91], v[208:211], v[76:79]
	v_mfma_f32_16x16x32_bf16 v[72:75], v[112:115], v[208:211], v[72:75]
	v_mfma_f32_16x16x32_bf16 v[148:151], v[92:95], v[164:167], v[148:151]
	v_mfma_f32_16x16x32_bf16 v[144:147], v[116:119], v[164:167], v[144:147]
	v_mfma_f32_16x16x32_bf16 v[124:127], v[92:95], v[172:175], v[124:127]
	v_mfma_f32_16x16x32_bf16 v[120:123], v[116:119], v[172:175], v[120:123]
	v_mfma_f32_16x16x32_bf16 v[100:103], v[92:95], v[180:183], v[100:103]
	v_mfma_f32_16x16x32_bf16 v[96:99], v[116:119], v[180:183], v[96:99]
	v_mfma_f32_16x16x32_bf16 v[76:79], v[92:95], v[212:215], v[76:79]
	v_mfma_f32_16x16x32_bf16 v[72:75], v[116:119], v[212:215], v[72:75]
	v_mfma_f32_16x16x32_bf16 v[140:143], v[132:135], v[160:163], v[140:143]
	v_mfma_f32_16x16x32_bf16 v[128:131], v[152:155], v[160:163], v[128:131]
	v_mfma_f32_16x16x32_bf16 v[108:111], v[132:135], v[168:171], v[108:111]
	v_mfma_f32_16x16x32_bf16 v[104:107], v[152:155], v[168:171], v[104:107]
	v_mfma_f32_16x16x32_bf16 v[84:87], v[132:135], v[176:179], v[84:87]
	v_mfma_f32_16x16x32_bf16 v[80:83], v[152:155], v[176:179], v[80:83]
	v_mfma_f32_16x16x32_bf16 v[68:71], v[132:135], v[208:211], v[68:71]
	v_mfma_f32_16x16x32_bf16 v[64:67], v[152:155], v[208:211], v[64:67]
	v_mfma_f32_16x16x32_bf16 v[140:143], v[136:139], v[164:167], v[140:143]
	v_mfma_f32_16x16x32_bf16 v[128:131], v[156:159], v[164:167], v[128:131]
	v_mfma_f32_16x16x32_bf16 v[108:111], v[136:139], v[172:175], v[108:111]
	v_mfma_f32_16x16x32_bf16 v[104:107], v[156:159], v[172:175], v[104:107]
	v_mfma_f32_16x16x32_bf16 v[84:87], v[136:139], v[180:183], v[84:87]
	v_mfma_f32_16x16x32_bf16 v[80:83], v[156:159], v[180:183], v[80:83]
	v_mfma_f32_16x16x32_bf16 v[68:71], v[136:139], v[212:215], v[68:71]
	v_mfma_f32_16x16x32_bf16 v[64:67], v[156:159], v[212:215], v[64:67]
	s_setprio 0
	s_barrier
	s_add_i32 s50, vcc_lo, s66
	v_lshl_add_u64 v[216:217], v[216:217], 0, s[46:47]
	s_mov_b32 m0, s50
	ds_read_b128 v[160:163], v235 offset:49152
	ds_read_b128 v[164:167], v235 offset:50176
	ds_read_b128 v[168:171], v235 offset:51200
	ds_read_b128 v[172:175], v235 offset:52224
	ds_read_b128 v[176:179], v235 offset:53248
	ds_read_b128 v[180:183], v235 offset:54272
	ds_read_b128 v[208:211], v235 offset:55296
	ds_read_b128 v[212:215], v235 offset:56320
	global_load_lds_dwordx4 v[216:217], off
	s_add_i32 m0, s50, 0x2000
	s_add_u32 s50, s54, 0xb0080
	v_lshl_add_u64 v[216:217], v[218:219], 0, s[46:47]
	s_addc_u32 s51, s55, 0
	s_add_i32 s54, vcc_hi, s66
	global_load_lds_dwordx4 v[216:217], off
	v_lshl_add_u64 v[216:217], s[50:51], 0, v[186:187]
	s_mov_b32 m0, s54
	s_nop 0
	global_load_lds_dwordx4 v[216:217], off
	v_lshl_add_u64 v[216:217], s[50:51], 0, v[190:191]
	s_add_i32 m0, s54, 0x2000
	s_nop 0
	global_load_lds_dwordx4 v[216:217], off
	v_lshl_add_u64 v[216:217], v[220:221], 0, s[46:47]
	s_mov_b32 m0, s74
	s_nop 0
	global_load_lds_dwordx4 v[216:217], off
	v_lshl_add_u64 v[216:217], v[222:223], 0, s[46:47]
	s_mov_b32 m0, s75
	s_nop 0
	global_load_lds_dwordx4 v[216:217], off
	s_waitcnt vmcnt(8)
	s_waitcnt lgkmcnt(0)
	s_setprio 1
	v_mfma_f32_16x16x32_bf16 v[60:63], v[88:91], v[160:163], v[60:63]
	v_mfma_f32_16x16x32_bf16 v[56:59], v[112:115], v[160:163], v[56:59]
	v_mfma_f32_16x16x32_bf16 v[44:47], v[88:91], v[168:171], v[44:47]
	v_mfma_f32_16x16x32_bf16 v[40:43], v[112:115], v[168:171], v[40:43]
	v_mfma_f32_16x16x32_bf16 v[28:31], v[88:91], v[176:179], v[28:31]
	v_mfma_f32_16x16x32_bf16 v[24:27], v[112:115], v[176:179], v[24:27]
	v_mfma_f32_16x16x32_bf16 v[12:15], v[88:91], v[208:211], v[12:15]
	v_mfma_f32_16x16x32_bf16 v[8:11], v[112:115], v[208:211], v[8:11]
	v_mfma_f32_16x16x32_bf16 v[60:63], v[92:95], v[164:167], v[60:63]
	v_mfma_f32_16x16x32_bf16 v[56:59], v[116:119], v[164:167], v[56:59]
	v_mfma_f32_16x16x32_bf16 v[44:47], v[92:95], v[172:175], v[44:47]
	v_mfma_f32_16x16x32_bf16 v[40:43], v[116:119], v[172:175], v[40:43]
	v_mfma_f32_16x16x32_bf16 v[28:31], v[92:95], v[180:183], v[28:31]
	v_mfma_f32_16x16x32_bf16 v[24:27], v[116:119], v[180:183], v[24:27]
	v_mfma_f32_16x16x32_bf16 v[12:15], v[92:95], v[212:215], v[12:15]
	v_mfma_f32_16x16x32_bf16 v[8:11], v[116:119], v[212:215], v[8:11]
	v_mfma_f32_16x16x32_bf16 v[52:55], v[132:135], v[160:163], v[52:55]
	v_mfma_f32_16x16x32_bf16 v[48:51], v[152:155], v[160:163], v[48:51]
	v_mfma_f32_16x16x32_bf16 v[36:39], v[132:135], v[168:171], v[36:39]
	v_mfma_f32_16x16x32_bf16 v[32:35], v[152:155], v[168:171], v[32:35]
	v_mfma_f32_16x16x32_bf16 v[20:23], v[132:135], v[176:179], v[20:23]
	v_mfma_f32_16x16x32_bf16 v[16:19], v[152:155], v[176:179], v[16:19]
	v_mfma_f32_16x16x32_bf16 v[4:7], v[132:135], v[208:211], v[4:7]
	v_mfma_f32_16x16x32_bf16 v[0:3], v[152:155], v[208:211], v[0:3]
	v_mfma_f32_16x16x32_bf16 v[52:55], v[136:139], v[164:167], v[52:55]
	v_mfma_f32_16x16x32_bf16 v[48:51], v[156:159], v[164:167], v[48:51]
	v_mfma_f32_16x16x32_bf16 v[36:39], v[136:139], v[172:175], v[36:39]
	v_mfma_f32_16x16x32_bf16 v[32:35], v[156:159], v[172:175], v[32:35]
	v_mfma_f32_16x16x32_bf16 v[20:23], v[136:139], v[180:183], v[20:23]
	v_mfma_f32_16x16x32_bf16 v[16:19], v[156:159], v[180:183], v[16:19]
	v_mfma_f32_16x16x32_bf16 v[4:7], v[136:139], v[212:215], v[4:7]
	v_mfma_f32_16x16x32_bf16 v[0:3], v[156:159], v[212:215], v[0:3]
	s_setprio 0
	s_barrier
	s_add_i32 s97, s97, 2
	s_add_u32 s95, s95, 0x100
	s_addc_u32 s96, s96, 0
	s_cmp_gt_u32 s97, 41
	s_mov_b64 s[50:51], s[52:53]
	s_cbranch_scc0 .Lh0_2
	s_branch .Ljoin_2
.Lh1p_2:
	ds_read_b128 v[88:91], v233
	ds_read_b128 v[92:95], v233 offset:1024
	ds_read_b128 v[112:115], v233 offset:2048
	ds_read_b128 v[116:119], v233 offset:3072
	ds_read_b128 v[132:135], v234
	ds_read_b128 v[136:139], v234 offset:1024
	ds_read_b128 v[152:155], v234 offset:2048
	ds_read_b128 v[156:159], v234 offset:3072
	s_add_u32 s52, s50, 0x100
	s_addc_u32 s53, s51, 0
	s_cmp_eq_u32 s97, 40
	s_cselect_b32 s57, s9, s53
	s_cselect_b32 s56, s8, s52
	s_cselect_b32 s55, s41, s96
	s_cselect_b32 s54, s40, s95
	v_lshl_add_u64 v[216:217], s[50:51], 0, v[196:197]
	s_add_i32 m0, s67, 0xc000
	ds_read_b128 v[160:163], v235
	ds_read_b128 v[164:167], v235 offset:1024
	ds_read_b128 v[168:171], v235 offset:2048
	ds_read_b128 v[172:175], v235 offset:3072
	ds_read_b128 v[176:179], v235 offset:4096
	ds_read_b128 v[180:183], v235 offset:5120
	ds_read_b128 v[208:211], v235 offset:6144
	ds_read_b128 v[212:215], v235 offset:7168
	global_load_lds_dwordx4 v[216:217], off
	v_lshl_add_u64 v[216:217], s[50:51], 0, v[198:199]
	s_add_i32 m0, s67, 0xe000
	s_nop 0
	global_load_lds_dwordx4 v[216:217], off
	s_waitcnt vmcnt(8)
	s_waitcnt lgkmcnt(0)
	s_barrier
	s_setprio 2
	v_mfma_f32_16x16x32_bf16 v[148:151], v[88:91], v[160:163], 0
	v_mfma_f32_16x16x32_bf16 v[144:147], v[112:115], v[160:163], 0
	v_mfma_f32_16x16x32_bf16 v[124:127], v[88:91], v[168:171], 0
	v_mfma_f32_16x16x32_bf16 v[120:123], v[112:115], v[168:171], 0
	v_mfma_f32_16x16x32_bf16 v[100:103], v[88:91], v[176:179], 0
	v_mfma_f32_16x16x32_bf16 v[96:99], v[112:115], v[176:179], 0
	v_mfma_f32_16x16x32_bf16 v[76:79], v[88:91], v[208:211], 0
	v_mfma_f32_16x16x32_bf16 v[72:75], v[112:115], v[208:211], 0
	v_mfma_f32_16x16x32_bf16 v[148:151], v[92:95], v[164:167], v[148:151]
	v_mfma_f32_16x16x32_bf16 v[144:147], v[116:119], v[164:167], v[144:147]
	v_mfma_f32_16x16x32_bf16 v[124:127], v[92:95], v[172:175], v[124:127]
	v_mfma_f32_16x16x32_bf16 v[120:123], v[116:119], v[172:175], v[120:123]
	v_mfma_f32_16x16x32_bf16 v[100:103], v[92:95], v[180:183], v[100:103]
	v_mfma_f32_16x16x32_bf16 v[96:99], v[116:119], v[180:183], v[96:99]
	v_mfma_f32_16x16x32_bf16 v[76:79], v[92:95], v[212:215], v[76:79]
	v_mfma_f32_16x16x32_bf16 v[72:75], v[116:119], v[212:215], v[72:75]
	v_mfma_f32_16x16x32_bf16 v[140:143], v[132:135], v[160:163], 0
	v_mfma_f32_16x16x32_bf16 v[128:131], v[152:155], v[160:163], 0
	v_mfma_f32_16x16x32_bf16 v[108:111], v[132:135], v[168:171], 0
	v_mfma_f32_16x16x32_bf16 v[104:107], v[152:155], v[168:171], 0
	v_mfma_f32_16x16x32_bf16 v[84:87], v[132:135], v[176:179], 0
	v_mfma_f32_16x16x32_bf16 v[80:83], v[152:155], v[176:179], 0
	v_mfma_f32_16x16x32_bf16 v[68:71], v[132:135], v[208:211], 0
	v_mfma_f32_16x16x32_bf16 v[64:67], v[152:155], v[208:211], 0
	v_mfma_f32_16x16x32_bf16 v[140:143], v[136:139], v[164:167], v[140:143]
	v_mfma_f32_16x16x32_bf16 v[128:131], v[156:159], v[164:167], v[128:131]
	v_mfma_f32_16x16x32_bf16 v[108:111], v[136:139], v[172:175], v[108:111]
	v_mfma_f32_16x16x32_bf16 v[104:107], v[156:159], v[172:175], v[104:107]
	v_mfma_f32_16x16x32_bf16 v[84:87], v[136:139], v[180:183], v[84:87]
	v_mfma_f32_16x16x32_bf16 v[80:83], v[156:159], v[180:183], v[80:83]
	v_mfma_f32_16x16x32_bf16 v[68:71], v[136:139], v[212:215], v[68:71]
	v_mfma_f32_16x16x32_bf16 v[64:67], v[156:159], v[212:215], v[64:67]
	s_setprio 0
	s_add_i32 s50, s82, s66
	v_lshl_add_u64 v[216:217], s[54:55], 0, v[186:187]
	s_mov_b32 m0, s50
	ds_read_b128 v[160:163], v235 offset:16384
	ds_read_b128 v[164:167], v235 offset:17408
	ds_read_b128 v[168:171], v235 offset:18432
	ds_read_b128 v[172:175], v235 offset:19456
	ds_read_b128 v[176:179], v235 offset:20480
	ds_read_b128 v[180:183], v235 offset:21504
	ds_read_b128 v[208:211], v235 offset:22528
	ds_read_b128 v[212:215], v235 offset:23552
	global_load_lds_dwordx4 v[216:217], off
	s_add_i32 m0, s50, 0x2000
	s_add_u32 s50, s54, 0xb0000
	v_lshl_add_u64 v[218:219], s[54:55], 0, v[190:191]
	s_addc_u32 s51, s55, 0
	s_add_i32 vcc_lo, s85, s66
	global_load_lds_dwordx4 v[218:219], off
	v_lshl_add_u64 v[220:221], s[50:51], 0, v[186:187]
	s_mov_b32 m0, vcc_lo
	v_lshl_add_u64 v[222:223], s[56:57], 0, v[188:189]
	global_load_lds_dwordx4 v[220:221], off
	v_lshl_add_u64 v[220:221], s[50:51], 0, v[190:191]
	s_add_i32 m0, vcc_lo, 0x2000
	s_nop 0
	global_load_lds_dwordx4 v[220:221], off
	v_lshl_add_u64 v[220:221], s[56:57], 0, v[184:185]
	s_mov_b32 m0, s67
	s_nop 0
	global_load_lds_dwordx4 v[220:221], off
	s_mov_b32 m0, s68
	s_nop 0
	global_load_lds_dwordx4 v[222:223], off
	s_waitcnt vmcnt(8)
	s_waitcnt lgkmcnt(0)
	s_barrier
	s_setprio 2
	v_mfma_f32_16x16x32_bf16 v[60:63], v[88:91], v[160:163], 0
	v_mfma_f32_16x16x32_bf16 v[56:59], v[112:115], v[160:163], 0
	v_mfma_f32_16x16x32_bf16 v[44:47], v[88:91], v[168:171], 0
	v_mfma_f32_16x16x32_bf16 v[40:43], v[112:115], v[168:171], 0
	v_mfma_f32_16x16x32_bf16 v[28:31], v[88:91], v[176:179], 0
	v_mfma_f32_16x16x32_bf16 v[24:27], v[112:115], v[176:179], 0
	v_mfma_f32_16x16x32_bf16 v[12:15], v[88:91], v[208:211], 0
	v_mfma_f32_16x16x32_bf16 v[8:11], v[112:115], v[208:211], 0
	v_mfma_f32_16x16x32_bf16 v[60:63], v[92:95], v[164:167], v[60:63]
	v_mfma_f32_16x16x32_bf16 v[56:59], v[116:119], v[164:167], v[56:59]
	v_mfma_f32_16x16x32_bf16 v[44:47], v[92:95], v[172:175], v[44:47]
	v_mfma_f32_16x16x32_bf16 v[40:43], v[116:119], v[172:175], v[40:43]
	v_mfma_f32_16x16x32_bf16 v[28:31], v[92:95], v[180:183], v[28:31]
	v_mfma_f32_16x16x32_bf16 v[24:27], v[116:119], v[180:183], v[24:27]
	v_mfma_f32_16x16x32_bf16 v[12:15], v[92:95], v[212:215], v[12:15]
	v_mfma_f32_16x16x32_bf16 v[8:11], v[116:119], v[212:215], v[8:11]
	v_mfma_f32_16x16x32_bf16 v[52:55], v[132:135], v[160:163], 0
	v_mfma_f32_16x16x32_bf16 v[48:51], v[152:155], v[160:163], 0
	v_mfma_f32_16x16x32_bf16 v[36:39], v[132:135], v[168:171], 0
	v_mfma_f32_16x16x32_bf16 v[32:35], v[152:155], v[168:171], 0
	v_mfma_f32_16x16x32_bf16 v[20:23], v[132:135], v[176:179], 0
	v_mfma_f32_16x16x32_bf16 v[16:19], v[152:155], v[176:179], 0
	v_mfma_f32_16x16x32_bf16 v[4:7], v[132:135], v[208:211], 0
	v_mfma_f32_16x16x32_bf16 v[0:3], v[152:155], v[208:211], 0
	v_mfma_f32_16x16x32_bf16 v[52:55], v[136:139], v[164:167], v[52:55]
	v_mfma_f32_16x16x32_bf16 v[48:51], v[156:159], v[164:167], v[48:51]
	v_mfma_f32_16x16x32_bf16 v[36:39], v[136:139], v[172:175], v[36:39]
	v_mfma_f32_16x16x32_bf16 v[32:35], v[156:159], v[172:175], v[32:35]
	v_mfma_f32_16x16x32_bf16 v[20:23], v[136:139], v[180:183], v[20:23]
	v_mfma_f32_16x16x32_bf16 v[16:19], v[156:159], v[180:183], v[16:19]
	v_mfma_f32_16x16x32_bf16 v[4:7], v[136:139], v[212:215], v[4:7]
	v_mfma_f32_16x16x32_bf16 v[0:3], v[156:159], v[212:215], v[0:3]
	s_setprio 0
	s_add_i32 vcc_lo, 0, 0x18000
	s_add_i32 vcc_hi, 0, 0x1c000
	v_add_u32_e32 v116, vcc_lo, v230
	v_add_u32_e32 v156, vcc_hi, v230
	ds_read_b128 v[88:91], v116
	ds_read_b128 v[92:95], v116 offset:1024
	ds_read_b128 v[112:115], v116 offset:2048
	ds_read_b128 v[116:119], v116 offset:3072
	ds_read_b128 v[132:135], v156
	ds_read_b128 v[136:139], v156 offset:1024
	ds_read_b128 v[152:155], v156 offset:2048
	ds_read_b128 v[156:159], v156 offset:3072
	s_add_u32 s50, s56, 0xb0000
	s_addc_u32 s51, s57, 0
	s_mov_b32 m0, s69
	v_lshl_add_u64 v[224:225], s[50:51], 0, v[184:185]
	ds_read_b128 v[160:163], v235 offset:32768
	ds_read_b128 v[164:167], v235 offset:33792
	ds_read_b128 v[168:171], v235 offset:34816
	ds_read_b128 v[172:175], v235 offset:35840
	ds_read_b128 v[176:179], v235 offset:36864
	ds_read_b128 v[180:183], v235 offset:37888
	ds_read_b128 v[208:211], v235 offset:38912
	ds_read_b128 v[212:215], v235 offset:39936
	global_load_lds_dwordx4 v[224:225], off
	v_lshl_add_u64 v[224:225], s[50:51], 0, v[188:189]
	s_mov_b32 m0, s70
	s_nop 0
	global_load_lds_dwordx4 v[224:225], off
	s_waitcnt vmcnt(8)
	s_waitcnt lgkmcnt(0)
	s_barrier
	s_setprio 2
	v_mfma_f32_16x16x32_bf16 v[148:151], v[88:91], v[160:163], v[148:151]
	v_mfma_f32_16x16x32_bf16 v[144:147], v[112:115], v[160:163], v[144:147]
	v_mfma_f32_16x16x32_bf16 v[124:127], v[88:91], v[168:171], v[124:127]
	v_mfma_f32_16x16x32_bf16 v[120:123], v[112:115], v[168:171], v[120:123]
	v_mfma_f32_16x16x32_bf16 v[100:103], v[88:91], v[176:179], v[100:103]
	v_mfma_f32_16x16x32_bf16 v[96:99], v[112:115], v[176:179], v[96:99]
	v_mfma_f32_16x16x32_bf16 v[76:79], v[88:91], v[208:211], v[76:79]
	v_mfma_f32_16x16x32_bf16 v[72:75], v[112:115], v[208:211], v[72:75]
	v_mfma_f32_16x16x32_bf16 v[148:151], v[92:95], v[164:167], v[148:151]
	v_mfma_f32_16x16x32_bf16 v[144:147], v[116:119], v[164:167], v[144:147]
	v_mfma_f32_16x16x32_bf16 v[124:127], v[92:95], v[172:175], v[124:127]
	v_mfma_f32_16x16x32_bf16 v[120:123], v[116:119], v[172:175], v[120:123]
	v_mfma_f32_16x16x32_bf16 v[100:103], v[92:95], v[180:183], v[100:103]
	v_mfma_f32_16x16x32_bf16 v[96:99], v[116:119], v[180:183], v[96:99]
	v_mfma_f32_16x16x32_bf16 v[76:79], v[92:95], v[212:215], v[76:79]
	v_mfma_f32_16x16x32_bf16 v[72:75], v[116:119], v[212:215], v[72:75]
	v_mfma_f32_16x16x32_bf16 v[140:143], v[132:135], v[160:163], v[140:143]
	v_mfma_f32_16x16x32_bf16 v[128:131], v[152:155], v[160:163], v[128:131]
	v_mfma_f32_16x16x32_bf16 v[108:111], v[132:135], v[168:171], v[108:111]
	v_mfma_f32_16x16x32_bf16 v[104:107], v[152:155], v[168:171], v[104:107]
	v_mfma_f32_16x16x32_bf16 v[84:87], v[132:135], v[176:179], v[84:87]
	v_mfma_f32_16x16x32_bf16 v[80:83], v[152:155], v[176:179], v[80:83]
	v_mfma_f32_16x16x32_bf16 v[68:71], v[132:135], v[208:211], v[68:71]
	v_mfma_f32_16x16x32_bf16 v[64:67], v[152:155], v[208:211], v[64:67]
	v_mfma_f32_16x16x32_bf16 v[140:143], v[136:139], v[164:167], v[140:143]
	v_mfma_f32_16x16x32_bf16 v[128:131], v[156:159], v[164:167], v[128:131]
	v_mfma_f32_16x16x32_bf16 v[108:111], v[136:139], v[172:175], v[108:111]
	v_mfma_f32_16x16x32_bf16 v[104:107], v[156:159], v[172:175], v[104:107]
	v_mfma_f32_16x16x32_bf16 v[84:87], v[136:139], v[180:183], v[84:87]
	v_mfma_f32_16x16x32_bf16 v[80:83], v[156:159], v[180:183], v[80:83]
	v_mfma_f32_16x16x32_bf16 v[68:71], v[136:139], v[212:215], v[68:71]
	v_mfma_f32_16x16x32_bf16 v[64:67], v[156:159], v[212:215], v[64:67]
	s_setprio 0
	s_add_i32 s50, vcc_lo, s66
	v_lshl_add_u64 v[216:217], v[216:217], 0, s[46:47]
	s_mov_b32 m0, s50
	ds_read_b128 v[160:163], v235 offset:49152
	ds_read_b128 v[164:167], v235 offset:50176
	ds_read_b128 v[168:171], v235 offset:51200
	ds_read_b128 v[172:175], v235 offset:52224
	ds_read_b128 v[176:179], v235 offset:53248
	ds_read_b128 v[180:183], v235 offset:54272
	ds_read_b128 v[208:211], v235 offset:55296
	ds_read_b128 v[212:215], v235 offset:56320
	global_load_lds_dwordx4 v[216:217], off
	s_add_i32 m0, s50, 0x2000
	s_add_u32 s50, s54, 0xb0080
	v_lshl_add_u64 v[216:217], v[218:219], 0, s[46:47]
	s_addc_u32 s51, s55, 0
	s_add_i32 s54, vcc_hi, s66
	global_load_lds_dwordx4 v[216:217], off
	v_lshl_add_u64 v[216:217], s[50:51], 0, v[186:187]
	s_mov_b32 m0, s54
	s_nop 0
	global_load_lds_dwordx4 v[216:217], off
	v_lshl_add_u64 v[216:217], s[50:51], 0, v[190:191]
	s_add_i32 m0, s54, 0x2000
	s_nop 0
	global_load_lds_dwordx4 v[216:217], off
	v_lshl_add_u64 v[216:217], v[220:221], 0, s[46:47]
	s_mov_b32 m0, s74
	s_nop 0
	global_load_lds_dwordx4 v[216:217], off
	v_lshl_add_u64 v[216:217], v[222:223], 0, s[46:47]
	s_mov_b32 m0, s75
	s_nop 0
	global_load_lds_dwordx4 v[216:217], off
	s_waitcnt vmcnt(8)
	s_waitcnt lgkmcnt(0)
	s_barrier
	s_setprio 2
	v_mfma_f32_16x16x32_bf16 v[60:63], v[88:91], v[160:163], v[60:63]
	v_mfma_f32_16x16x32_bf16 v[56:59], v[112:115], v[160:163], v[56:59]
	v_mfma_f32_16x16x32_bf16 v[44:47], v[88:91], v[168:171], v[44:47]
	v_mfma_f32_16x16x32_bf16 v[40:43], v[112:115], v[168:171], v[40:43]
	v_mfma_f32_16x16x32_bf16 v[28:31], v[88:91], v[176:179], v[28:31]
	v_mfma_f32_16x16x32_bf16 v[24:27], v[112:115], v[176:179], v[24:27]
	v_mfma_f32_16x16x32_bf16 v[12:15], v[88:91], v[208:211], v[12:15]
	v_mfma_f32_16x16x32_bf16 v[8:11], v[112:115], v[208:211], v[8:11]
	v_mfma_f32_16x16x32_bf16 v[60:63], v[92:95], v[164:167], v[60:63]
	v_mfma_f32_16x16x32_bf16 v[56:59], v[116:119], v[164:167], v[56:59]
	v_mfma_f32_16x16x32_bf16 v[44:47], v[92:95], v[172:175], v[44:47]
	v_mfma_f32_16x16x32_bf16 v[40:43], v[116:119], v[172:175], v[40:43]
	v_mfma_f32_16x16x32_bf16 v[28:31], v[92:95], v[180:183], v[28:31]
	v_mfma_f32_16x16x32_bf16 v[24:27], v[116:119], v[180:183], v[24:27]
	v_mfma_f32_16x16x32_bf16 v[12:15], v[92:95], v[212:215], v[12:15]
	v_mfma_f32_16x16x32_bf16 v[8:11], v[116:119], v[212:215], v[8:11]
	v_mfma_f32_16x16x32_bf16 v[52:55], v[132:135], v[160:163], v[52:55]
	v_mfma_f32_16x16x32_bf16 v[48:51], v[152:155], v[160:163], v[48:51]
	v_mfma_f32_16x16x32_bf16 v[36:39], v[132:135], v[168:171], v[36:39]
	v_mfma_f32_16x16x32_bf16 v[32:35], v[152:155], v[168:171], v[32:35]
	v_mfma_f32_16x16x32_bf16 v[20:23], v[132:135], v[176:179], v[20:23]
	v_mfma_f32_16x16x32_bf16 v[16:19], v[152:155], v[176:179], v[16:19]
	v_mfma_f32_16x16x32_bf16 v[4:7], v[132:135], v[208:211], v[4:7]
	v_mfma_f32_16x16x32_bf16 v[0:3], v[152:155], v[208:211], v[0:3]
	v_mfma_f32_16x16x32_bf16 v[52:55], v[136:139], v[164:167], v[52:55]
	v_mfma_f32_16x16x32_bf16 v[48:51], v[156:159], v[164:167], v[48:51]
	v_mfma_f32_16x16x32_bf16 v[36:39], v[136:139], v[172:175], v[36:39]
	v_mfma_f32_16x16x32_bf16 v[32:35], v[156:159], v[172:175], v[32:35]
	v_mfma_f32_16x16x32_bf16 v[20:23], v[136:139], v[180:183], v[20:23]
	v_mfma_f32_16x16x32_bf16 v[16:19], v[156:159], v[180:183], v[16:19]
	v_mfma_f32_16x16x32_bf16 v[4:7], v[136:139], v[212:215], v[4:7]
	v_mfma_f32_16x16x32_bf16 v[0:3], v[156:159], v[212:215], v[0:3]
	s_setprio 0
	s_add_i32 s97, s97, 2
	s_add_u32 s95, s95, 0x100
	s_addc_u32 s96, s96, 0
	s_cmp_gt_u32 s97, 41
	s_mov_b64 s[50:51], s[52:53]
.Lh1_2:
	ds_read_b128 v[88:91], v233
	ds_read_b128 v[92:95], v233 offset:1024
	ds_read_b128 v[112:115], v233 offset:2048
	ds_read_b128 v[116:119], v233 offset:3072
	ds_read_b128 v[132:135], v234
	ds_read_b128 v[136:139], v234 offset:1024
	ds_read_b128 v[152:155], v234 offset:2048
	ds_read_b128 v[156:159], v234 offset:3072
	s_add_u32 s52, s50, 0x100
	s_addc_u32 s53, s51, 0
	s_cmp_eq_u32 s97, 40
	s_cselect_b32 s57, s9, s53
	s_cselect_b32 s56, s8, s52
	s_cselect_b32 s55, s41, s96
	s_cselect_b32 s54, s40, s95
	v_lshl_add_u64 v[216:217], s[50:51], 0, v[196:197]
	s_add_i32 m0, s67, 0xc000
	ds_read_b128 v[160:163], v235
	ds_read_b128 v[164:167], v235 offset:1024
	ds_read_b128 v[168:171], v235 offset:2048
	ds_read_b128 v[172:175], v235 offset:3072
	ds_read_b128 v[176:179], v235 offset:4096
	ds_read_b128 v[180:183], v235 offset:5120
	ds_read_b128 v[208:211], v235 offset:6144
	ds_read_b128 v[212:215], v235 offset:7168
	global_load_lds_dwordx4 v[216:217], off
	v_lshl_add_u64 v[216:217], s[50:51], 0, v[198:199]
	s_add_i32 m0, s67, 0xe000
	s_nop 0
	global_load_lds_dwordx4 v[216:217], off
	s_waitcnt vmcnt(8)
	s_waitcnt lgkmcnt(0)
	s_barrier
	s_setprio 2
	v_mfma_f32_16x16x32_bf16 v[148:151], v[88:91], v[160:163], v[148:151]
	v_mfma_f32_16x16x32_bf16 v[144:147], v[112:115], v[160:163], v[144:147]
	v_mfma_f32_16x16x32_bf16 v[124:127], v[88:91], v[168:171], v[124:127]
	v_mfma_f32_16x16x32_bf16 v[120:123], v[112:115], v[168:171], v[120:123]
	v_mfma_f32_16x16x32_bf16 v[100:103], v[88:91], v[176:179], v[100:103]
	v_mfma_f32_16x16x32_bf16 v[96:99], v[112:115], v[176:179], v[96:99]
	v_mfma_f32_16x16x32_bf16 v[76:79], v[88:91], v[208:211], v[76:79]
	v_mfma_f32_16x16x32_bf16 v[72:75], v[112:115], v[208:211], v[72:75]
	v_mfma_f32_16x16x32_bf16 v[148:151], v[92:95], v[164:167], v[148:151]
	v_mfma_f32_16x16x32_bf16 v[144:147], v[116:119], v[164:167], v[144:147]
	v_mfma_f32_16x16x32_bf16 v[124:127], v[92:95], v[172:175], v[124:127]
	v_mfma_f32_16x16x32_bf16 v[120:123], v[116:119], v[172:175], v[120:123]
	v_mfma_f32_16x16x32_bf16 v[100:103], v[92:95], v[180:183], v[100:103]
	v_mfma_f32_16x16x32_bf16 v[96:99], v[116:119], v[180:183], v[96:99]
	v_mfma_f32_16x16x32_bf16 v[76:79], v[92:95], v[212:215], v[76:79]
	v_mfma_f32_16x16x32_bf16 v[72:75], v[116:119], v[212:215], v[72:75]
	v_mfma_f32_16x16x32_bf16 v[140:143], v[132:135], v[160:163], v[140:143]
	v_mfma_f32_16x16x32_bf16 v[128:131], v[152:155], v[160:163], v[128:131]
	v_mfma_f32_16x16x32_bf16 v[108:111], v[132:135], v[168:171], v[108:111]
	v_mfma_f32_16x16x32_bf16 v[104:107], v[152:155], v[168:171], v[104:107]
	v_mfma_f32_16x16x32_bf16 v[84:87], v[132:135], v[176:179], v[84:87]
	v_mfma_f32_16x16x32_bf16 v[80:83], v[152:155], v[176:179], v[80:83]
	v_mfma_f32_16x16x32_bf16 v[68:71], v[132:135], v[208:211], v[68:71]
	v_mfma_f32_16x16x32_bf16 v[64:67], v[152:155], v[208:211], v[64:67]
	v_mfma_f32_16x16x32_bf16 v[140:143], v[136:139], v[164:167], v[140:143]
	v_mfma_f32_16x16x32_bf16 v[128:131], v[156:159], v[164:167], v[128:131]
	v_mfma_f32_16x16x32_bf16 v[108:111], v[136:139], v[172:175], v[108:111]
	v_mfma_f32_16x16x32_bf16 v[104:107], v[156:159], v[172:175], v[104:107]
	v_mfma_f32_16x16x32_bf16 v[84:87], v[136:139], v[180:183], v[84:87]
	v_mfma_f32_16x16x32_bf16 v[80:83], v[156:159], v[180:183], v[80:83]
	v_mfma_f32_16x16x32_bf16 v[68:71], v[136:139], v[212:215], v[68:71]
	v_mfma_f32_16x16x32_bf16 v[64:67], v[156:159], v[212:215], v[64:67]
	s_setprio 0
	s_add_i32 s50, s82, s66
	v_lshl_add_u64 v[216:217], s[54:55], 0, v[186:187]
	s_mov_b32 m0, s50
	ds_read_b128 v[160:163], v235 offset:16384
	ds_read_b128 v[164:167], v235 offset:17408
	ds_read_b128 v[168:171], v235 offset:18432
	ds_read_b128 v[172:175], v235 offset:19456
	ds_read_b128 v[176:179], v235 offset:20480
	ds_read_b128 v[180:183], v235 offset:21504
	ds_read_b128 v[208:211], v235 offset:22528
	ds_read_b128 v[212:215], v235 offset:23552
	global_load_lds_dwordx4 v[216:217], off
	s_add_i32 m0, s50, 0x2000
	s_add_u32 s50, s54, 0xb0000
	v_lshl_add_u64 v[218:219], s[54:55], 0, v[190:191]
	s_addc_u32 s51, s55, 0
	s_add_i32 vcc_lo, s85, s66
	global_load_lds_dwordx4 v[218:219], off
	v_lshl_add_u64 v[220:221], s[50:51], 0, v[186:187]
	s_mov_b32 m0, vcc_lo
	v_lshl_add_u64 v[222:223], s[56:57], 0, v[188:189]
	global_load_lds_dwordx4 v[220:221], off
	v_lshl_add_u64 v[220:221], s[50:51], 0, v[190:191]
	s_add_i32 m0, vcc_lo, 0x2000
	s_nop 0
	global_load_lds_dwordx4 v[220:221], off
	v_lshl_add_u64 v[220:221], s[56:57], 0, v[184:185]
	s_mov_b32 m0, s67
	s_nop 0
	global_load_lds_dwordx4 v[220:221], off
	s_mov_b32 m0, s68
	s_nop 0
	global_load_lds_dwordx4 v[222:223], off
	s_waitcnt vmcnt(8)
	s_waitcnt lgkmcnt(0)
	s_barrier
	s_setprio 2
	v_mfma_f32_16x16x32_bf16 v[60:63], v[88:91], v[160:163], v[60:63]
	v_mfma_f32_16x16x32_bf16 v[56:59], v[112:115], v[160:163], v[56:59]
	v_mfma_f32_16x16x32_bf16 v[44:47], v[88:91], v[168:171], v[44:47]
	v_mfma_f32_16x16x32_bf16 v[40:43], v[112:115], v[168:171], v[40:43]
	v_mfma_f32_16x16x32_bf16 v[28:31], v[88:91], v[176:179], v[28:31]
	v_mfma_f32_16x16x32_bf16 v[24:27], v[112:115], v[176:179], v[24:27]
	v_mfma_f32_16x16x32_bf16 v[12:15], v[88:91], v[208:211], v[12:15]
	v_mfma_f32_16x16x32_bf16 v[8:11], v[112:115], v[208:211], v[8:11]
	v_mfma_f32_16x16x32_bf16 v[60:63], v[92:95], v[164:167], v[60:63]
	v_mfma_f32_16x16x32_bf16 v[56:59], v[116:119], v[164:167], v[56:59]
	v_mfma_f32_16x16x32_bf16 v[44:47], v[92:95], v[172:175], v[44:47]
	v_mfma_f32_16x16x32_bf16 v[40:43], v[116:119], v[172:175], v[40:43]
	v_mfma_f32_16x16x32_bf16 v[28:31], v[92:95], v[180:183], v[28:31]
	v_mfma_f32_16x16x32_bf16 v[24:27], v[116:119], v[180:183], v[24:27]
	v_mfma_f32_16x16x32_bf16 v[12:15], v[92:95], v[212:215], v[12:15]
	v_mfma_f32_16x16x32_bf16 v[8:11], v[116:119], v[212:215], v[8:11]
	v_mfma_f32_16x16x32_bf16 v[52:55], v[132:135], v[160:163], v[52:55]
	v_mfma_f32_16x16x32_bf16 v[48:51], v[152:155], v[160:163], v[48:51]
	v_mfma_f32_16x16x32_bf16 v[36:39], v[132:135], v[168:171], v[36:39]
	v_mfma_f32_16x16x32_bf16 v[32:35], v[152:155], v[168:171], v[32:35]
	v_mfma_f32_16x16x32_bf16 v[20:23], v[132:135], v[176:179], v[20:23]
	v_mfma_f32_16x16x32_bf16 v[16:19], v[152:155], v[176:179], v[16:19]
	v_mfma_f32_16x16x32_bf16 v[4:7], v[132:135], v[208:211], v[4:7]
	v_mfma_f32_16x16x32_bf16 v[0:3], v[152:155], v[208:211], v[0:3]
	v_mfma_f32_16x16x32_bf16 v[52:55], v[136:139], v[164:167], v[52:55]
	v_mfma_f32_16x16x32_bf16 v[48:51], v[156:159], v[164:167], v[48:51]
	v_mfma_f32_16x16x32_bf16 v[36:39], v[136:139], v[172:175], v[36:39]
	v_mfma_f32_16x16x32_bf16 v[32:35], v[156:159], v[172:175], v[32:35]
	v_mfma_f32_16x16x32_bf16 v[20:23], v[136:139], v[180:183], v[20:23]
	v_mfma_f32_16x16x32_bf16 v[16:19], v[156:159], v[180:183], v[16:19]
	v_mfma_f32_16x16x32_bf16 v[4:7], v[136:139], v[212:215], v[4:7]
	v_mfma_f32_16x16x32_bf16 v[0:3], v[156:159], v[212:215], v[0:3]
	s_setprio 0
	s_add_i32 vcc_lo, 0, 0x18000
	s_add_i32 vcc_hi, 0, 0x1c000
	v_add_u32_e32 v116, vcc_lo, v230
	v_add_u32_e32 v156, vcc_hi, v230
	ds_read_b128 v[88:91], v116
	ds_read_b128 v[92:95], v116 offset:1024
	ds_read_b128 v[112:115], v116 offset:2048
	ds_read_b128 v[116:119], v116 offset:3072
	ds_read_b128 v[132:135], v156
	ds_read_b128 v[136:139], v156 offset:1024
	ds_read_b128 v[152:155], v156 offset:2048
	ds_read_b128 v[156:159], v156 offset:3072
	s_add_u32 s50, s56, 0xb0000
	s_addc_u32 s51, s57, 0
	s_mov_b32 m0, s69
	v_lshl_add_u64 v[224:225], s[50:51], 0, v[184:185]
	ds_read_b128 v[160:163], v235 offset:32768
	ds_read_b128 v[164:167], v235 offset:33792
	ds_read_b128 v[168:171], v235 offset:34816
	ds_read_b128 v[172:175], v235 offset:35840
	ds_read_b128 v[176:179], v235 offset:36864
	ds_read_b128 v[180:183], v235 offset:37888
	ds_read_b128 v[208:211], v235 offset:38912
	ds_read_b128 v[212:215], v235 offset:39936
	global_load_lds_dwordx4 v[224:225], off
	v_lshl_add_u64 v[224:225], s[50:51], 0, v[188:189]
	s_mov_b32 m0, s70
	s_nop 0
	global_load_lds_dwordx4 v[224:225], off
	s_waitcnt vmcnt(8)
	s_waitcnt lgkmcnt(0)
	s_barrier
	s_setprio 2
	v_mfma_f32_16x16x32_bf16 v[148:151], v[88:91], v[160:163], v[148:151]
	v_mfma_f32_16x16x32_bf16 v[144:147], v[112:115], v[160:163], v[144:147]
	v_mfma_f32_16x16x32_bf16 v[124:127], v[88:91], v[168:171], v[124:127]
	v_mfma_f32_16x16x32_bf16 v[120:123], v[112:115], v[168:171], v[120:123]
	v_mfma_f32_16x16x32_bf16 v[100:103], v[88:91], v[176:179], v[100:103]
	v_mfma_f32_16x16x32_bf16 v[96:99], v[112:115], v[176:179], v[96:99]
	v_mfma_f32_16x16x32_bf16 v[76:79], v[88:91], v[208:211], v[76:79]
	v_mfma_f32_16x16x32_bf16 v[72:75], v[112:115], v[208:211], v[72:75]
	v_mfma_f32_16x16x32_bf16 v[148:151], v[92:95], v[164:167], v[148:151]
	v_mfma_f32_16x16x32_bf16 v[144:147], v[116:119], v[164:167], v[144:147]
	v_mfma_f32_16x16x32_bf16 v[124:127], v[92:95], v[172:175], v[124:127]
	v_mfma_f32_16x16x32_bf16 v[120:123], v[116:119], v[172:175], v[120:123]
	v_mfma_f32_16x16x32_bf16 v[100:103], v[92:95], v[180:183], v[100:103]
	v_mfma_f32_16x16x32_bf16 v[96:99], v[116:119], v[180:183], v[96:99]
	v_mfma_f32_16x16x32_bf16 v[76:79], v[92:95], v[212:215], v[76:79]
	v_mfma_f32_16x16x32_bf16 v[72:75], v[116:119], v[212:215], v[72:75]
	v_mfma_f32_16x16x32_bf16 v[140:143], v[132:135], v[160:163], v[140:143]
	v_mfma_f32_16x16x32_bf16 v[128:131], v[152:155], v[160:163], v[128:131]
	v_mfma_f32_16x16x32_bf16 v[108:111], v[132:135], v[168:171], v[108:111]
	v_mfma_f32_16x16x32_bf16 v[104:107], v[152:155], v[168:171], v[104:107]
	v_mfma_f32_16x16x32_bf16 v[84:87], v[132:135], v[176:179], v[84:87]
	v_mfma_f32_16x16x32_bf16 v[80:83], v[152:155], v[176:179], v[80:83]
	v_mfma_f32_16x16x32_bf16 v[68:71], v[132:135], v[208:211], v[68:71]
	v_mfma_f32_16x16x32_bf16 v[64:67], v[152:155], v[208:211], v[64:67]
	v_mfma_f32_16x16x32_bf16 v[140:143], v[136:139], v[164:167], v[140:143]
	v_mfma_f32_16x16x32_bf16 v[128:131], v[156:159], v[164:167], v[128:131]
	v_mfma_f32_16x16x32_bf16 v[108:111], v[136:139], v[172:175], v[108:111]
	v_mfma_f32_16x16x32_bf16 v[104:107], v[156:159], v[172:175], v[104:107]
	v_mfma_f32_16x16x32_bf16 v[84:87], v[136:139], v[180:183], v[84:87]
	v_mfma_f32_16x16x32_bf16 v[80:83], v[156:159], v[180:183], v[80:83]
	v_mfma_f32_16x16x32_bf16 v[68:71], v[136:139], v[212:215], v[68:71]
	v_mfma_f32_16x16x32_bf16 v[64:67], v[156:159], v[212:215], v[64:67]
	s_setprio 0
	s_add_i32 s50, vcc_lo, s66
	v_lshl_add_u64 v[216:217], v[216:217], 0, s[46:47]
	s_mov_b32 m0, s50
	ds_read_b128 v[160:163], v235 offset:49152
	ds_read_b128 v[164:167], v235 offset:50176
	ds_read_b128 v[168:171], v235 offset:51200
	ds_read_b128 v[172:175], v235 offset:52224
	ds_read_b128 v[176:179], v235 offset:53248
	ds_read_b128 v[180:183], v235 offset:54272
	ds_read_b128 v[208:211], v235 offset:55296
	ds_read_b128 v[212:215], v235 offset:56320
	global_load_lds_dwordx4 v[216:217], off
	s_add_i32 m0, s50, 0x2000
	s_add_u32 s50, s54, 0xb0080
	v_lshl_add_u64 v[216:217], v[218:219], 0, s[46:47]
	s_addc_u32 s51, s55, 0
	s_add_i32 s54, vcc_hi, s66
	global_load_lds_dwordx4 v[216:217], off
	v_lshl_add_u64 v[216:217], s[50:51], 0, v[186:187]
	s_mov_b32 m0, s54
	s_nop 0
	global_load_lds_dwordx4 v[216:217], off
	v_lshl_add_u64 v[216:217], s[50:51], 0, v[190:191]
	s_add_i32 m0, s54, 0x2000
	s_nop 0
	global_load_lds_dwordx4 v[216:217], off
	v_lshl_add_u64 v[216:217], v[220:221], 0, s[46:47]
	s_mov_b32 m0, s74
	s_nop 0
	global_load_lds_dwordx4 v[216:217], off
	v_lshl_add_u64 v[216:217], v[222:223], 0, s[46:47]
	s_mov_b32 m0, s75
	s_nop 0
	global_load_lds_dwordx4 v[216:217], off
	s_waitcnt vmcnt(8)
	s_waitcnt lgkmcnt(0)
	s_barrier
	s_setprio 2
	v_mfma_f32_16x16x32_bf16 v[60:63], v[88:91], v[160:163], v[60:63]
	v_mfma_f32_16x16x32_bf16 v[56:59], v[112:115], v[160:163], v[56:59]
	v_mfma_f32_16x16x32_bf16 v[44:47], v[88:91], v[168:171], v[44:47]
	v_mfma_f32_16x16x32_bf16 v[40:43], v[112:115], v[168:171], v[40:43]
	v_mfma_f32_16x16x32_bf16 v[28:31], v[88:91], v[176:179], v[28:31]
	v_mfma_f32_16x16x32_bf16 v[24:27], v[112:115], v[176:179], v[24:27]
	v_mfma_f32_16x16x32_bf16 v[12:15], v[88:91], v[208:211], v[12:15]
	v_mfma_f32_16x16x32_bf16 v[8:11], v[112:115], v[208:211], v[8:11]
	v_mfma_f32_16x16x32_bf16 v[60:63], v[92:95], v[164:167], v[60:63]
	v_mfma_f32_16x16x32_bf16 v[56:59], v[116:119], v[164:167], v[56:59]
	v_mfma_f32_16x16x32_bf16 v[44:47], v[92:95], v[172:175], v[44:47]
	v_mfma_f32_16x16x32_bf16 v[40:43], v[116:119], v[172:175], v[40:43]
	v_mfma_f32_16x16x32_bf16 v[28:31], v[92:95], v[180:183], v[28:31]
	v_mfma_f32_16x16x32_bf16 v[24:27], v[116:119], v[180:183], v[24:27]
	v_mfma_f32_16x16x32_bf16 v[12:15], v[92:95], v[212:215], v[12:15]
	v_mfma_f32_16x16x32_bf16 v[8:11], v[116:119], v[212:215], v[8:11]
	v_mfma_f32_16x16x32_bf16 v[52:55], v[132:135], v[160:163], v[52:55]
	v_mfma_f32_16x16x32_bf16 v[48:51], v[152:155], v[160:163], v[48:51]
	v_mfma_f32_16x16x32_bf16 v[36:39], v[132:135], v[168:171], v[36:39]
	v_mfma_f32_16x16x32_bf16 v[32:35], v[152:155], v[168:171], v[32:35]
	v_mfma_f32_16x16x32_bf16 v[20:23], v[132:135], v[176:179], v[20:23]
	v_mfma_f32_16x16x32_bf16 v[16:19], v[152:155], v[176:179], v[16:19]
	v_mfma_f32_16x16x32_bf16 v[4:7], v[132:135], v[208:211], v[4:7]
	v_mfma_f32_16x16x32_bf16 v[0:3], v[152:155], v[208:211], v[0:3]
	v_mfma_f32_16x16x32_bf16 v[52:55], v[136:139], v[164:167], v[52:55]
	v_mfma_f32_16x16x32_bf16 v[48:51], v[156:159], v[164:167], v[48:51]
	v_mfma_f32_16x16x32_bf16 v[36:39], v[136:139], v[172:175], v[36:39]
	v_mfma_f32_16x16x32_bf16 v[32:35], v[156:159], v[172:175], v[32:35]
	v_mfma_f32_16x16x32_bf16 v[20:23], v[136:139], v[180:183], v[20:23]
	v_mfma_f32_16x16x32_bf16 v[16:19], v[156:159], v[180:183], v[16:19]
	v_mfma_f32_16x16x32_bf16 v[4:7], v[136:139], v[212:215], v[4:7]
	v_mfma_f32_16x16x32_bf16 v[0:3], v[156:159], v[212:215], v[0:3]
	s_setprio 0
	s_add_i32 s97, s97, 2
	s_add_u32 s95, s95, 0x100
	s_addc_u32 s96, s96, 0
	s_cmp_gt_u32 s97, 41
	s_mov_b64 s[50:51], s[52:53]
	s_cbranch_scc0 .Lh1_2
.Ljoin_2:
	s_and_b64 vcc, exec, s[48:49]
	s_cbranch_vccz .LBB0_224
.LBB0_224:
	s_lshl_b32 s50, s36, 8
	s_or_b32 s50, s50, s78
	s_ashr_i32 s51, s50, 31
	v_lshl_add_u64 v[116:117], s[50:51], 2, v[194:195]
	s_lshl_b32 s52, s94, 8
	global_load_dwordx4 v[88:91], v[116:117], off
	global_load_dwordx4 v[92:95], v[116:117], off offset:16
	global_load_dwordx4 v[112:115], v[116:117], off offset:128
	s_add_i32 s52, s52, s73
	v_or_b32_e32 v208, s52, v229
	v_ashrrev_i32_e32 v209, 31, v208
	v_lshl_add_u64 v[132:133], v[208:209], 2, s[44:45]
	global_load_dword v154, v[132:133], off
	v_or_b32_e32 v134, 0x80, v229
	global_load_dwordx4 v[116:119], v[116:117], off offset:144
	s_ashr_i32 s53, s52, 31
	v_add_u32_e32 v134, s52, v134
	s_lshl_b64 s[52:53], s[52:53], 11
	s_add_u32 s52, s62, s52
	s_addc_u32 s53, s63, s53
	s_lshl_b64 s[50:51], s[50:51], 1
	s_add_u32 s50, s52, s50
	s_addc_u32 s51, s53, s51
	v_mov_b32_e32 v203, v193
	v_ashrrev_i32_e32 v135, 31, v134
	v_lshl_add_u64 v[218:219], s[50:51], 0, v[192:193]
	v_mov_b32_e32 v205, v193
	v_lshl_add_u64 v[134:135], v[134:135], 2, s[44:45]
	global_load_dword v242, v[132:133], off offset:64
	global_load_dword v241, v[132:133], off offset:128
	global_load_dword v240, v[132:133], off offset:192
	global_load_dword v239, v[134:135], off
	global_load_dword v238, v[134:135], off offset:64
	global_load_dword v237, v[134:135], off offset:128
	global_load_dword v236, v[134:135], off offset:192
	v_lshl_add_u64 v[132:133], v[218:219], 0, v[202:203]
	v_lshl_add_u64 v[252:253], v[132:133], 0, v[204:205]
	s_movk_i32 s50, 0x4000
	v_add_co_u32_e32 v132, vcc, s50, v252
	s_mov_b32 s50, 0xc000
	s_nop 0
	v_addc_co_u32_e32 v133, vcc, 0, v253, vcc
	global_load_dwordx4 v[244:247], v[252:253], off
	global_load_dwordx4 v[248:251], v[132:133], off
	v_add_co_u32_e32 v134, vcc, s77, v252
	v_mov_b32_e32 v207, v193
	s_nop 0
	v_addc_co_u32_e32 v135, vcc, 0, v253, vcc
	v_add_co_u32_e32 v136, vcc, s50, v252
	s_mov_b32 s50, 0x14000
	s_nop 0
	v_addc_co_u32_e32 v137, vcc, 0, v253, vcc
	v_add_co_u32_e32 v138, vcc, s71, v252
	v_lshl_add_u64 v[218:219], v[218:219], 0, v[206:207]
	s_nop 0
	v_addc_co_u32_e32 v139, vcc, 0, v253, vcc
	v_add_co_u32_e32 v132, vcc, s50, v252
	s_mov_b32 s50, 0x1c000
	s_nop 0
	v_addc_co_u32_e32 v133, vcc, 0, v253, vcc
	v_add_co_u32_e32 v152, vcc, s76, v252
	global_load_dwordx4 v[180:183], v[134:135], off
	global_load_dwordx4 v[176:179], v[136:137], off
	global_load_dwordx4 v[172:175], v[138:139], off
	global_load_dwordx4 v[168:171], v[132:133], off
	v_addc_co_u32_e32 v153, vcc, 0, v253, vcc
	v_mov_b32_e32 v243, v193
	v_lshl_add_u64 v[218:219], v[218:219], 0, v[204:205]
	s_waitcnt vmcnt(0)
	v_rcp_f32_e32 v224, v88
	v_add_co_u32_e32 v88, vcc, s50, v252
	v_rcp_f32_e32 v225, v89
	s_nop 0
	v_addc_co_u32_e32 v89, vcc, 0, v253, vcc
	global_load_dwordx4 v[164:167], v[152:153], off
	global_load_dwordx4 v[160:163], v[88:89], off
	v_add_co_u32_e32 v88, vcc, s87, v252
	s_mov_b32 s50, 0x44000
	s_nop 0
	v_addc_co_u32_e32 v89, vcc, 0, v253, vcc
	v_rcp_f32_e32 v226, v90
	v_add_co_u32_e32 v90, vcc, s50, v252
	v_rcp_f32_e32 v227, v91
	s_nop 0
	v_addc_co_u32_e32 v91, vcc, 0, v253, vcc
	v_rcp_f32_e32 v200, v154
	global_load_dwordx4 v[156:159], v[88:89], off
	global_load_dwordx4 v[152:155], v[90:91], off
	v_add_co_u32_e32 v88, vcc, s88, v252
	s_mov_b32 s50, 0x4c000
	s_nop 0
	v_addc_co_u32_e32 v89, vcc, 0, v253, vcc
	v_add_co_u32_e32 v90, vcc, s50, v252
	s_mov_b32 s50, 0x54000
	s_nop 0
	v_addc_co_u32_e32 v91, vcc, 0, v253, vcc
	global_load_dwordx4 v[136:139], v[88:89], off
	global_load_dwordx4 v[132:135], v[90:91], off
	v_add_co_u32_e32 v88, vcc, s89, v252
	v_rcp_f32_e32 v212, v112
	s_nop 0
	v_addc_co_u32_e32 v89, vcc, 0, v253, vcc
	v_add_co_u32_e32 v90, vcc, s50, v252
	v_rcp_f32_e32 v213, v113
	s_nop 0
	v_addc_co_u32_e32 v91, vcc, 0, v253, vcc
	v_rcp_f32_e32 v216, v114
	v_rcp_f32_e32 v217, v115
	v_rcp_f32_e32 v210, v116
	v_rcp_f32_e32 v211, v117
	v_rcp_f32_e32 v214, v118
	v_rcp_f32_e32 v215, v119
	global_load_dwordx4 v[116:119], v[88:89], off
	global_load_dwordx4 v[112:115], v[90:91], off
	v_add_co_u32_e32 v88, vcc, s90, v252
	s_mov_b32 s50, 0x5c000
	s_nop 0
	v_addc_co_u32_e32 v89, vcc, 0, v253, vcc
	v_add_co_u32_e32 v90, vcc, s50, v252
	v_rcp_f32_e32 v220, v92
	s_nop 0
	v_addc_co_u32_e32 v91, vcc, 0, v253, vcc
	v_rcp_f32_e32 v221, v93
	v_rcp_f32_e32 v222, v94
	v_rcp_f32_e32 v223, v95
	global_load_dwordx4 v[92:95], v[88:89], off
	s_nop 0
	global_load_dwordx4 v[88:91], v[90:91], off
	v_cndmask_b32_e64 v207, v244, v248, s[10:11]
	v_cndmask_b32_e64 v205, v245, v249, s[10:11]
	v_cndmask_b32_e64 v203, v246, v250, s[10:11]
	v_mov_b32_dpp v243, v207 row_ror:8 row_mask:0xf bank_mask:0xf
	v_mov_b32_e32 v207, v193
	v_cndmask_b32_e64 v201, v247, v251, s[10:11]
	s_lshl_b32 s50, s36, 2
	v_mov_b32_dpp v207, v205 row_ror:8 row_mask:0xf bank_mask:0xf
	v_mov_b32_e32 v205, v193
	s_ashr_i32 s51, s50, 31
	s_nop 0
	v_mov_b32_dpp v205, v203 row_ror:8 row_mask:0xf bank_mask:0xf
	v_mov_b32_e32 v203, v193
	v_cndmask_b32_e64 v252, v205, v246, s[10:11]
	v_cndmask_b32_e64 v205, v250, v205, s[10:11]
	v_mov_b32_dpp v203, v201 row_ror:8 row_mask:0xf bank_mask:0xf
	v_cndmask_b32_e64 v201, v203, v247, s[10:11]
	v_cndmask_b32_e64 v247, v207, v245, s[10:11]
	v_cndmask_b32_e64 v245, v243, v244, s[10:11]
	v_lshlrev_b32_e32 v244, 16, v245
	v_and_b32_e32 v245, 0xffff0000, v245
	v_lshlrev_b32_e32 v246, 16, v247
	v_and_b32_e32 v247, 0xffff0000, v247
	v_pk_mul_f32 v[244:245], v[224:225], v[244:245]
	v_cndmask_b32_e64 v203, v251, v203, s[10:11]
	v_cndmask_b32_e64 v207, v249, v207, s[10:11]
	v_cndmask_b32_e64 v243, v248, v243, s[10:11]
	v_lshlrev_b32_e32 v248, 16, v252
	v_and_b32_e32 v249, 0xffff0000, v252
	v_lshlrev_b32_e32 v250, 16, v201
	v_and_b32_e32 v251, 0xffff0000, v201
	v_pk_mul_f32 v[246:247], v[226:227], v[246:247]
	v_pk_mul_f32 v[244:245], v[200:201], v[244:245] op_sel_hi:[0,1]
	v_pk_mul_f32 v[246:247], v[200:201], v[246:247] op_sel_hi:[0,1]
	v_pk_mul_f32 v[250:251], v[222:223], v[250:251]
	v_pk_mul_f32 v[248:249], v[220:221], v[248:249]
	v_pk_fma_f32 v[148:149], v[148:149], 0.5, v[244:245] op_sel_hi:[1,0,1]
	v_pk_mul_f32 v[248:249], v[200:201], v[248:249] op_sel_hi:[0,1]
	v_pk_mul_f32 v[250:251], v[200:201], v[250:251] op_sel_hi:[0,1]
	v_pk_fma_f32 v[150:151], v[150:151], 0.5, v[246:247] op_sel_hi:[1,0,1]
	v_cvt_pk_bf16_f32 v201, v148, v149
	v_mul_f32_e32 v149, v149, v149
	v_pk_fma_f32 v[144:145], v[144:145], 0.5, v[248:249] op_sel_hi:[1,0,1]
	v_fmac_f32_e32 v149, v148, v148
	v_mul_f32_e32 v148, v151, v151
	v_cvt_pk_bf16_f32 v244, v150, v151
	v_cvt_pk_bf16_f32 v245, v144, v145
	v_fmac_f32_e32 v148, v150, v150
	v_mul_f32_e32 v145, v145, v145
	v_pk_fma_f32 v[146:147], v[146:147], 0.5, v[250:251] op_sel_hi:[1,0,1]
	v_add_f32_e32 v148, v149, v148
	v_fmac_f32_e32 v145, v144, v144
	v_add_f32_e32 v144, v145, v148
	v_mul_f32_e32 v145, v147, v147
	v_fmac_f32_e32 v145, v146, v146
	v_add_f32_e32 v247, v145, v144
	v_lshlrev_b32_e32 v144, 16, v243
	v_and_b32_e32 v145, 0xffff0000, v243
	v_cvt_pk_bf16_f32 v246, v146, v147
	v_lshlrev_b32_e32 v146, 16, v207
	v_and_b32_e32 v147, 0xffff0000, v207
	v_pk_mul_f32 v[144:145], v[212:213], v[144:145]
	v_lshlrev_b32_e32 v148, 16, v205
	v_and_b32_e32 v149, 0xffff0000, v205
	v_pk_mul_f32 v[146:147], v[216:217], v[146:147]
	v_pk_mul_f32 v[144:145], v[200:201], v[144:145] op_sel_hi:[0,1]
	v_pk_mul_f32 v[146:147], v[200:201], v[146:147] op_sel_hi:[0,1]
	v_pk_mul_f32 v[148:149], v[210:211], v[148:149]
	v_pk_fma_f32 v[140:141], v[140:141], 0.5, v[144:145] op_sel_hi:[1,0,1]
	v_lshlrev_b32_e32 v150, 16, v203
	v_and_b32_e32 v151, 0xffff0000, v203
	v_pk_mul_f32 v[148:149], v[200:201], v[148:149] op_sel_hi:[0,1]
	v_pk_fma_f32 v[142:143], v[142:143], 0.5, v[146:147] op_sel_hi:[1,0,1]
	v_cvt_pk_bf16_f32 v144, v140, v141
	v_mul_f32_e32 v141, v141, v141
	v_pk_mul_f32 v[150:151], v[214:215], v[150:151]
	v_pk_fma_f32 v[128:129], v[128:129], 0.5, v[148:149] op_sel_hi:[1,0,1]
	v_fmac_f32_e32 v141, v140, v140
	v_mul_f32_e32 v140, v143, v143
	v_pk_mul_f32 v[150:151], v[200:201], v[150:151] op_sel_hi:[0,1]
	v_cvt_pk_bf16_f32 v145, v142, v143
	v_cvt_pk_bf16_f32 v146, v128, v129
	v_fmac_f32_e32 v140, v142, v142
	v_mul_f32_e32 v129, v129, v129
	v_pk_fma_f32 v[130:131], v[130:131], 0.5, v[150:151] op_sel_hi:[1,0,1]
	v_add_f32_e32 v140, v141, v140
	v_fmac_f32_e32 v129, v128, v128
	v_add_f32_e32 v128, v129, v140
	v_mul_f32_e32 v129, v131, v131
	v_fmac_f32_e32 v129, v130, v130
	v_add_f32_e32 v128, v129, v128
	v_cvt_pk_bf16_f32 v147, v130, v131
	v_add_f32_e32 v148, v247, v128
	v_cndmask_b32_e64 v128, v246, v147, s[10:11]
	v_cndmask_b32_e64 v129, v245, v146, s[10:11]
	v_cndmask_b32_e64 v130, v244, v145, s[10:11]
	v_cndmask_b32_e64 v131, v201, v144, s[10:11]
	v_mov_b32_e32 v140, v193
	v_mov_b32_e32 v141, v193
	v_mov_b32_e32 v142, v193
	v_mov_b32_e32 v143, v193
	v_mov_b32_dpp v140, v131 row_ror:8 row_mask:0xf bank_mask:0xf
	v_mov_b32_dpp v141, v130 row_ror:8 row_mask:0xf bank_mask:0xf
	v_mov_b32_dpp v142, v129 row_ror:8 row_mask:0xf bank_mask:0xf
	v_mov_b32_dpp v143, v128 row_ror:8 row_mask:0xf bank_mask:0xf
	v_cndmask_b32_e64 v128, v140, v201, s[10:11]
	v_cndmask_b32_e64 v129, v141, v244, s[10:11]
	v_cndmask_b32_e64 v130, v142, v245, s[10:11]
	v_cndmask_b32_e64 v131, v143, v246, s[10:11]
	global_store_dwordx4 v[218:219], v[128:131], off
	ds_bpermute_b32 v128, v231, v148
	v_cndmask_b32_e64 v140, v144, v140, s[10:11]
	v_add_co_u32_e32 v130, vcc, 0x4000, v218
	v_cndmask_b32_e64 v141, v145, v141, s[10:11]
	s_waitcnt lgkmcnt(0)
	v_add_f32_e32 v128, v148, v128
	ds_bpermute_b32 v129, v232, v128
	v_cndmask_b32_e64 v142, v146, v142, s[10:11]
	v_cndmask_b32_e64 v143, v147, v143, s[10:11]
	v_addc_co_u32_e32 v131, vcc, 0, v219, vcc
	global_store_dwordx4 v[130:131], v[140:143], off
	s_and_saveexec_b64 s[52:53], s[4:5]
	s_cbranch_execz .LBB0_226
	v_lshlrev_b64 v[130:131], 6, v[208:209]
	v_lshl_add_u64 v[130:131], s[42:43], 0, v[130:131]
	v_lshl_add_u64 v[130:131], s[50:51], 2, v[130:131]
	s_lshl_b32 s36, s72, 2
	v_lshl_add_u64 v[130:131], v[130:131], 0, s[36:37]
	s_waitcnt lgkmcnt(0)
	v_add_f32_e32 v128, v128, v129
	global_store_dword v[130:131], v128, off

.LBB0_240:
	s_or_b64 exec, exec, s[52:53]
	s_and_b64 vcc, exec, s[6:7]
	s_mov_b64 s[6:7], -1
	s_cbranch_vccnz .LBB0_214
	s_andn2_b64 vcc, exec, s[38:39]
	s_cbranch_vccnz .LBB0_213
	s_branch .LBB0_213

.LBB0_307:
	s_add_u32 s79, s30, 0x13000000
	s_addc_u32 s80, s31, 0
	s_add_u32 s36, s30, 0x18000000
	s_mov_b64 s[38:39], 0x80
	s_addc_u32 s37, s31, 0
	s_bfe_u32 s10, s3, 0x20006
	s_add_i32 m0, s75, 0x18000
	v_lshl_add_u64 v[6:7], v[6:7], 0, s[38:39]
	s_lshl_b32 s81, s5, 6
	s_lshl_b32 s5, s5, 13
	s_lshl_b32 s40, s10, 12
	s_nop 0
	global_load_lds_dwordx4 v[6:7], off
	v_lshl_add_u64 v[2:3], v[2:3], 0, s[38:39]
	s_add_i32 m0, s75, 0x1a000
	s_add_i32 s87, s75, 0x8000
	s_add_i32 s88, s75, 0xa000
	global_load_lds_dwordx4 v[2:3], off
	v_lshl_add_u64 v[0:1], v[0:1], 0, s[38:39]
	s_mov_b32 m0, s87
	s_add_u32 s6, s54, 0x40080
	global_load_lds_dwordx4 v[0:1], off
	v_lshl_add_u64 v[0:1], v[4:5], 0, s[38:39]
	s_mov_b32 m0, s88
	s_addc_u32 s7, s55, 0
	global_load_lds_dwordx4 v[0:1], off
	s_add_i32 m0, s75, 0x1c000
	v_lshl_add_u64 v[0:1], s[6:7], 0, v[148:149]
	global_load_lds_dwordx4 v[0:1], off
	v_lshl_add_u64 v[0:1], s[6:7], 0, v[144:145]
	s_add_i32 m0, s75, 0x1e000
	v_and_b32_e32 v155, 15, v9
	global_load_lds_dwordx4 v[0:1], off
	v_lshrrev_b32_e32 v0, 1, v9
	v_lshlrev_b32_e32 v3, 2, v9
	v_and_b32_e32 v154, 56, v0
	v_and_b32_e32 v0, 48, v9
	v_lshlrev_b32_e32 v2, 6, v155
	v_and_b32_e32 v3, 32, v3
	v_and_b32_e32 v1, 0x400, v14
	v_bitop3_b32 v0, v2, v3, v0 bitop3:0x36
	v_or3_b32 v3, v1, s5, v0
	v_or3_b32 v157, v1, s40, v0
	v_and_b32_e32 v1, 64, v9
	v_xor_b32_e32 v0, 16, v9
	v_add_u32_e32 v1, 64, v1
	v_cmp_lt_i32_e32 vcc, v0, v1
	s_cmpk_lt_u32 s3, 0x100
	s_cselect_b64 s[40:41], -1, 0
	v_cndmask_b32_e32 v0, v9, v0, vcc
	v_lshlrev_b32_e32 v173, 2, v0
	v_xor_b32_e32 v0, 32, v9
	v_cmp_lt_i32_e32 vcc, v0, v1
	s_lshl_b32 s89, s10, 6
	v_lshlrev_b32_e32 v1, 9, v9
	v_and_b32_e32 v2, 0xe00, v1
	v_or_b32_e32 v1, s89, v154
	v_or_b32_e32 v177, 0xfffffc00, v1
	v_lshlrev_b32_e32 v1, 14, v12
	v_and_b32_e32 v1, 0xffff8000, v1
	v_lshl_add_u32 v1, v13, 11, v1
	v_and_b32_e32 v4, 1, v12
	v_lshl_or_b32 v1, v4, 6, v1
	v_lshl_add_u32 v162, v15, 1, v1
	v_lshlrev_b32_e32 v1, 14, v8
	v_cndmask_b32_e32 v0, v9, v0, vcc
	s_ashr_i32 s90, s34, 31
	v_and_b32_e32 v1, 0xffff8000, v1
	s_sext_i32_i8 s66, s4
	s_waitcnt vmcnt(6)
	v_lshlrev_b32_e32 v175, 2, v0
	v_lshlrev_b32_e32 v0, 10, v9
	s_add_u32 s4, s30, s89
	v_lshl_add_u32 v1, v10, 11, v1
	v_and_b32_e32 v4, 1, v8
	v_and_b32_e32 v0, 0x1c00, v0
	v_cmp_gt_u32_e64 s[6:7], 8, v155
	v_and_b32_e32 v152, 0x70, v9
	s_addc_u32 s5, s31, 0
	v_lshl_or_b32 v1, v4, 6, v1
	s_add_i32 s92, 0, 0x10000
	s_add_i32 s93, 0, 0x14000
	v_cndmask_b32_e64 v156, 32, 0, s[6:7]
	s_mov_b32 s91, s34
	v_lshl_add_u64 v[158:159], s[42:43], 0, v[152:153]
	v_lshl_add_u64 v[160:161], s[4:5], 0, v[152:153]
	v_mov_b32_e32 v163, v153
	v_lshl_add_u32 v164, v11, 1, v1
	v_mov_b32_e32 v165, v153
	v_mov_b64_e32 v[166:167], 0xf00
	v_mov_b64_e32 v[168:169], 0xeff
	v_add_u32_e32 v179, s92, v157
	v_add_u32_e32 v181, s93, v157
	v_add_u32_e32 v183, 0, v3
	v_mov_b32_e32 v185, 0x358637bd
	s_mov_b32 s94, 0x1cfff000
	s_mov_b32 s95, 0x1d007000
	s_mov_b32 s96, 0x1d00f000
	s_mov_b32 s97, 0x1d017000
	s_mov_b32 s85, 0x1d03f000
	s_mov_b32 s58, 0x1d047000
	s_mov_b32 s59, 0x1d04f000
	v_lshlrev_b32_e32 v170, 1, v0
	v_lshlrev_b32_e32 v152, 1, v2
	v_mov_b32_e32 v187, 0x3e38aa3b
	s_mov_b32 s82, 0
	s_barrier
	s_branch .LBB0_310

.LBB0_312:
	s_ashr_i32 s43, s42, 31
	s_lshl_b64 s[46:47], s[42:43], 19
	s_add_u32 s46, s62, s46
	s_addc_u32 s47, s63, s47
	s_and_b64 s[48:49], s[4:5], exec
	s_cselect_b32 s10, s47, s53
	s_cselect_b32 s43, s46, s52
	s_ashr_i32 s45, s44, 31
	s_lshl_b64 s[48:49], s[44:45], 19
	s_add_u32 s48, s70, s48
	s_addc_u32 s49, s71, s49
	s_and_b64 s[56:57], s[4:5], exec
	s_cselect_b32 s45, s49, s55
	s_cselect_b32 s51, s48, s54
	s_add_u32 s52, s52, 0x40080
	s_addc_u32 s53, s53, 0
	s_add_u32 s67, s54, 0x100
	s_addc_u32 s68, s55, 0
	s_mov_b32 s69, -2
	s_and_b64 vcc, exec, s[40:41]
	s_cbranch_vccz .Lh1p_3
	ds_read_b128 v[128:131], v179
	ds_read_b128 v[132:135], v179 offset:1024
	ds_read_b128 v[136:139], v179 offset:2048
	ds_read_b128 v[140:143], v179 offset:3072
	ds_read_b128 v[188:191], v181
	ds_read_b128 v[192:195], v181 offset:1024
	ds_read_b128 v[196:199], v181 offset:2048
	ds_read_b128 v[200:203], v181 offset:3072
	s_add_u32 s54, s52, 0xfffc0080
	s_addc_u32 s55, s53, -1
	s_cmp_eq_u32 s69, 12
	s_cselect_b32 s57, s10, s55
	s_cselect_b32 s56, s43, s54
	s_cselect_b32 s55, s45, s68
	s_cselect_b32 s54, s51, s67
	v_lshl_add_u64 v[238:239], s[52:53], 0, v[162:163]
	s_add_i32 m0, s75, 0xc000
	ds_read_b128 v[204:207], v183
	ds_read_b128 v[208:211], v183 offset:1024
	ds_read_b128 v[212:215], v183 offset:2048
	ds_read_b128 v[216:219], v183 offset:3072
	ds_read_b128 v[220:223], v183 offset:4096
	ds_read_b128 v[224:227], v183 offset:5120
	ds_read_b128 v[230:233], v183 offset:6144
	ds_read_b128 v[234:237], v183 offset:7168
	global_load_lds_dwordx4 v[238:239], off
	v_lshl_add_u64 v[238:239], s[52:53], 0, v[164:165]
	s_add_i32 m0, s75, 0xe000
	s_nop 0
	global_load_lds_dwordx4 v[238:239], off
	s_waitcnt vmcnt(8)
	s_waitcnt lgkmcnt(0)
	s_setprio 1
	v_mfma_f32_16x16x32_bf16 v[124:127], v[128:131], v[204:207], 0
	v_mfma_f32_16x16x32_bf16 v[120:123], v[136:139], v[204:207], 0
	v_mfma_f32_16x16x32_bf16 v[108:111], v[128:131], v[212:215], 0
	v_mfma_f32_16x16x32_bf16 v[104:107], v[136:139], v[212:215], 0
	v_mfma_f32_16x16x32_bf16 v[92:95], v[128:131], v[220:223], 0
	v_mfma_f32_16x16x32_bf16 v[88:91], v[136:139], v[220:223], 0
	v_mfma_f32_16x16x32_bf16 v[76:79], v[128:131], v[230:233], 0
	v_mfma_f32_16x16x32_bf16 v[72:75], v[136:139], v[230:233], 0
	v_mfma_f32_16x16x32_bf16 v[124:127], v[132:135], v[208:211], v[124:127]
	v_mfma_f32_16x16x32_bf16 v[120:123], v[140:143], v[208:211], v[120:123]
	v_mfma_f32_16x16x32_bf16 v[108:111], v[132:135], v[216:219], v[108:111]
	v_mfma_f32_16x16x32_bf16 v[104:107], v[140:143], v[216:219], v[104:107]
	v_mfma_f32_16x16x32_bf16 v[92:95], v[132:135], v[224:227], v[92:95]
	v_mfma_f32_16x16x32_bf16 v[88:91], v[140:143], v[224:227], v[88:91]
	v_mfma_f32_16x16x32_bf16 v[76:79], v[132:135], v[234:237], v[76:79]
	v_mfma_f32_16x16x32_bf16 v[72:75], v[140:143], v[234:237], v[72:75]
	v_mfma_f32_16x16x32_bf16 v[116:119], v[188:191], v[204:207], 0
	v_mfma_f32_16x16x32_bf16 v[112:115], v[196:199], v[204:207], 0
	v_mfma_f32_16x16x32_bf16 v[100:103], v[188:191], v[212:215], 0
	v_mfma_f32_16x16x32_bf16 v[96:99], v[196:199], v[212:215], 0
	v_mfma_f32_16x16x32_bf16 v[84:87], v[188:191], v[220:223], 0
	v_mfma_f32_16x16x32_bf16 v[80:83], v[196:199], v[220:223], 0
	v_mfma_f32_16x16x32_bf16 v[68:71], v[188:191], v[230:233], 0
	v_mfma_f32_16x16x32_bf16 v[64:67], v[196:199], v[230:233], 0
	v_mfma_f32_16x16x32_bf16 v[116:119], v[192:195], v[208:211], v[116:119]
	v_mfma_f32_16x16x32_bf16 v[112:115], v[200:203], v[208:211], v[112:115]
	v_mfma_f32_16x16x32_bf16 v[100:103], v[192:195], v[216:219], v[100:103]
	v_mfma_f32_16x16x32_bf16 v[96:99], v[200:203], v[216:219], v[96:99]
	v_mfma_f32_16x16x32_bf16 v[84:87], v[192:195], v[224:227], v[84:87]
	v_mfma_f32_16x16x32_bf16 v[80:83], v[200:203], v[224:227], v[80:83]
	v_mfma_f32_16x16x32_bf16 v[68:71], v[192:195], v[234:237], v[68:71]
	v_mfma_f32_16x16x32_bf16 v[64:67], v[200:203], v[234:237], v[64:67]
	s_setprio 0
	s_barrier
	s_add_i32 vcc_lo, s92, s72
	v_lshl_add_u64 v[238:239], s[54:55], 0, v[148:149]
	s_mov_b32 m0, vcc_lo
	ds_read_b128 v[204:207], v183 offset:16384
	ds_read_b128 v[208:211], v183 offset:17408
	ds_read_b128 v[212:215], v183 offset:18432
	ds_read_b128 v[216:219], v183 offset:19456
	ds_read_b128 v[220:223], v183 offset:20480
	ds_read_b128 v[224:227], v183 offset:21504
	ds_read_b128 v[230:233], v183 offset:22528
	ds_read_b128 v[234:237], v183 offset:23552
	global_load_lds_dwordx4 v[238:239], off
	s_add_i32 m0, vcc_lo, 0x2000
	s_add_u32 vcc_lo, s54, 0x40000
	v_lshl_add_u64 v[240:241], s[54:55], 0, v[144:145]
	s_addc_u32 vcc_hi, s55, 0
	s_add_i32 s83, s93, s72
	global_load_lds_dwordx4 v[240:241], off
	v_lshl_add_u64 v[242:243], vcc, 0, v[148:149]
	s_mov_b32 m0, s83
	v_lshl_add_u64 v[244:245], s[56:57], 0, v[146:147]
	global_load_lds_dwordx4 v[242:243], off
	v_lshl_add_u64 v[242:243], vcc, 0, v[144:145]
	s_add_i32 m0, s83, 0x2000
	s_nop 0
	global_load_lds_dwordx4 v[242:243], off
	v_lshl_add_u64 v[242:243], s[56:57], 0, v[150:151]
	s_mov_b32 m0, s75
	s_nop 0
	global_load_lds_dwordx4 v[242:243], off
	s_mov_b32 m0, s76
	s_nop 0
	global_load_lds_dwordx4 v[244:245], off
	s_waitcnt vmcnt(8)
	s_waitcnt lgkmcnt(0)
	s_setprio 1
	v_mfma_f32_16x16x32_bf16 v[60:63], v[128:131], v[204:207], 0
	v_mfma_f32_16x16x32_bf16 v[56:59], v[136:139], v[204:207], 0
	v_mfma_f32_16x16x32_bf16 v[44:47], v[128:131], v[212:215], 0
	v_mfma_f32_16x16x32_bf16 v[40:43], v[136:139], v[212:215], 0
	v_mfma_f32_16x16x32_bf16 v[28:31], v[128:131], v[220:223], 0
	v_mfma_f32_16x16x32_bf16 v[24:27], v[136:139], v[220:223], 0
	v_mfma_f32_16x16x32_bf16 v[12:15], v[128:131], v[230:233], 0
	v_mfma_f32_16x16x32_bf16 v[8:11], v[136:139], v[230:233], 0
	v_mfma_f32_16x16x32_bf16 v[60:63], v[132:135], v[208:211], v[60:63]
	v_mfma_f32_16x16x32_bf16 v[56:59], v[140:143], v[208:211], v[56:59]
	v_mfma_f32_16x16x32_bf16 v[44:47], v[132:135], v[216:219], v[44:47]
	v_mfma_f32_16x16x32_bf16 v[40:43], v[140:143], v[216:219], v[40:43]
	v_mfma_f32_16x16x32_bf16 v[28:31], v[132:135], v[224:227], v[28:31]
	v_mfma_f32_16x16x32_bf16 v[24:27], v[140:143], v[224:227], v[24:27]
	v_mfma_f32_16x16x32_bf16 v[12:15], v[132:135], v[234:237], v[12:15]
	v_mfma_f32_16x16x32_bf16 v[8:11], v[140:143], v[234:237], v[8:11]
	v_mfma_f32_16x16x32_bf16 v[52:55], v[188:191], v[204:207], 0
	v_mfma_f32_16x16x32_bf16 v[48:51], v[196:199], v[204:207], 0
	v_mfma_f32_16x16x32_bf16 v[36:39], v[188:191], v[212:215], 0
	v_mfma_f32_16x16x32_bf16 v[32:35], v[196:199], v[212:215], 0
	v_mfma_f32_16x16x32_bf16 v[20:23], v[188:191], v[220:223], 0
	v_mfma_f32_16x16x32_bf16 v[16:19], v[196:199], v[220:223], 0
	v_mfma_f32_16x16x32_bf16 v[4:7], v[188:191], v[230:233], 0
	v_mfma_f32_16x16x32_bf16 v[0:3], v[196:199], v[230:233], 0
	v_mfma_f32_16x16x32_bf16 v[52:55], v[192:195], v[208:211], v[52:55]
	v_mfma_f32_16x16x32_bf16 v[48:51], v[200:203], v[208:211], v[48:51]
	v_mfma_f32_16x16x32_bf16 v[36:39], v[192:195], v[216:219], v[36:39]
	v_mfma_f32_16x16x32_bf16 v[32:35], v[200:203], v[216:219], v[32:35]
	v_mfma_f32_16x16x32_bf16 v[20:23], v[192:195], v[224:227], v[20:23]
	v_mfma_f32_16x16x32_bf16 v[16:19], v[200:203], v[224:227], v[16:19]
	v_mfma_f32_16x16x32_bf16 v[4:7], v[192:195], v[234:237], v[4:7]
	v_mfma_f32_16x16x32_bf16 v[0:3], v[200:203], v[234:237], v[0:3]
	s_setprio 0
	s_barrier
	s_add_i32 s83, 0, 0x18000
	s_add_i32 vcc_lo, 0, 0x1c000
	v_add_u32_e32 v140, s83, v157
	v_add_u32_e32 v171, vcc_lo, v157
	ds_read_b128 v[128:131], v140
	ds_read_b128 v[132:135], v140 offset:1024
	ds_read_b128 v[136:139], v140 offset:2048
	ds_read_b128 v[140:143], v140 offset:3072
	ds_read_b128 v[188:191], v171
	ds_read_b128 v[192:195], v171 offset:1024
	ds_read_b128 v[196:199], v171 offset:2048
	ds_read_b128 v[200:203], v171 offset:3072
	s_add_u32 s56, s56, 0x40000
	s_addc_u32 s57, s57, 0
	s_mov_b32 m0, s77
	v_lshl_add_u64 v[246:247], s[56:57], 0, v[150:151]
	ds_read_b128 v[204:207], v183 offset:32768
	ds_read_b128 v[208:211], v183 offset:33792
	ds_read_b128 v[212:215], v183 offset:34816
	ds_read_b128 v[216:219], v183 offset:35840
	ds_read_b128 v[220:223], v183 offset:36864
	ds_read_b128 v[224:227], v183 offset:37888
	ds_read_b128 v[230:233], v183 offset:38912
	ds_read_b128 v[234:237], v183 offset:39936
	global_load_lds_dwordx4 v[246:247], off
	v_lshl_add_u64 v[246:247], s[56:57], 0, v[146:147]
	s_mov_b32 m0, s78
	s_nop 0
	global_load_lds_dwordx4 v[246:247], off
	s_waitcnt vmcnt(8)
	s_waitcnt lgkmcnt(0)
	s_setprio 1
	v_mfma_f32_16x16x32_bf16 v[124:127], v[128:131], v[204:207], v[124:127]
	v_mfma_f32_16x16x32_bf16 v[120:123], v[136:139], v[204:207], v[120:123]
	v_mfma_f32_16x16x32_bf16 v[108:111], v[128:131], v[212:215], v[108:111]
	v_mfma_f32_16x16x32_bf16 v[104:107], v[136:139], v[212:215], v[104:107]
	v_mfma_f32_16x16x32_bf16 v[92:95], v[128:131], v[220:223], v[92:95]
	v_mfma_f32_16x16x32_bf16 v[88:91], v[136:139], v[220:223], v[88:91]
	v_mfma_f32_16x16x32_bf16 v[76:79], v[128:131], v[230:233], v[76:79]
	v_mfma_f32_16x16x32_bf16 v[72:75], v[136:139], v[230:233], v[72:75]
	v_mfma_f32_16x16x32_bf16 v[124:127], v[132:135], v[208:211], v[124:127]
	v_mfma_f32_16x16x32_bf16 v[120:123], v[140:143], v[208:211], v[120:123]
	v_mfma_f32_16x16x32_bf16 v[108:111], v[132:135], v[216:219], v[108:111]
	v_mfma_f32_16x16x32_bf16 v[104:107], v[140:143], v[216:219], v[104:107]
	v_mfma_f32_16x16x32_bf16 v[92:95], v[132:135], v[224:227], v[92:95]
	v_mfma_f32_16x16x32_bf16 v[88:91], v[140:143], v[224:227], v[88:91]
	v_mfma_f32_16x16x32_bf16 v[76:79], v[132:135], v[234:237], v[76:79]
	v_mfma_f32_16x16x32_bf16 v[72:75], v[140:143], v[234:237], v[72:75]
	v_mfma_f32_16x16x32_bf16 v[116:119], v[188:191], v[204:207], v[116:119]
	v_mfma_f32_16x16x32_bf16 v[112:115], v[196:199], v[204:207], v[112:115]
	v_mfma_f32_16x16x32_bf16 v[100:103], v[188:191], v[212:215], v[100:103]
	v_mfma_f32_16x16x32_bf16 v[96:99], v[196:199], v[212:215], v[96:99]
	v_mfma_f32_16x16x32_bf16 v[84:87], v[188:191], v[220:223], v[84:87]
	v_mfma_f32_16x16x32_bf16 v[80:83], v[196:199], v[220:223], v[80:83]
	v_mfma_f32_16x16x32_bf16 v[68:71], v[188:191], v[230:233], v[68:71]
	v_mfma_f32_16x16x32_bf16 v[64:67], v[196:199], v[230:233], v[64:67]
	v_mfma_f32_16x16x32_bf16 v[116:119], v[192:195], v[208:211], v[116:119]
	v_mfma_f32_16x16x32_bf16 v[112:115], v[200:203], v[208:211], v[112:115]
	v_mfma_f32_16x16x32_bf16 v[100:103], v[192:195], v[216:219], v[100:103]
	v_mfma_f32_16x16x32_bf16 v[96:99], v[200:203], v[216:219], v[96:99]
	v_mfma_f32_16x16x32_bf16 v[84:87], v[192:195], v[224:227], v[84:87]
	v_mfma_f32_16x16x32_bf16 v[80:83], v[200:203], v[224:227], v[80:83]
	v_mfma_f32_16x16x32_bf16 v[68:71], v[192:195], v[234:237], v[68:71]
	v_mfma_f32_16x16x32_bf16 v[64:67], v[200:203], v[234:237], v[64:67]
	s_setprio 0
	s_barrier
	s_add_i32 s56, s83, s72
	v_lshl_add_u64 v[238:239], v[238:239], 0, s[38:39]
	s_mov_b32 m0, s56
	ds_read_b128 v[204:207], v183 offset:49152
	ds_read_b128 v[208:211], v183 offset:50176
	ds_read_b128 v[212:215], v183 offset:51200
	ds_read_b128 v[216:219], v183 offset:52224
	ds_read_b128 v[220:223], v183 offset:53248
	ds_read_b128 v[224:227], v183 offset:54272
	ds_read_b128 v[230:233], v183 offset:55296
	ds_read_b128 v[234:237], v183 offset:56320
	global_load_lds_dwordx4 v[238:239], off
	s_add_i32 m0, s56, 0x2000
	s_add_u32 s54, s54, 0x40080
	v_lshl_add_u64 v[238:239], v[240:241], 0, s[38:39]
	s_addc_u32 s55, s55, 0
	s_add_i32 s56, vcc_lo, s72
	global_load_lds_dwordx4 v[238:239], off
	v_lshl_add_u64 v[238:239], s[54:55], 0, v[148:149]
	s_mov_b32 m0, s56
	s_nop 0
	global_load_lds_dwordx4 v[238:239], off
	v_lshl_add_u64 v[238:239], s[54:55], 0, v[144:145]
	s_add_i32 m0, s56, 0x2000
	s_nop 0
	global_load_lds_dwordx4 v[238:239], off
	v_lshl_add_u64 v[238:239], v[242:243], 0, s[38:39]
	s_mov_b32 m0, s87
	s_nop 0
	global_load_lds_dwordx4 v[238:239], off
	v_lshl_add_u64 v[238:239], v[244:245], 0, s[38:39]
	s_mov_b32 m0, s88
	s_nop 0
	global_load_lds_dwordx4 v[238:239], off
	s_waitcnt vmcnt(8)
	s_waitcnt lgkmcnt(0)
	s_setprio 1
	v_mfma_f32_16x16x32_bf16 v[60:63], v[128:131], v[204:207], v[60:63]
	v_mfma_f32_16x16x32_bf16 v[56:59], v[136:139], v[204:207], v[56:59]
	v_mfma_f32_16x16x32_bf16 v[44:47], v[128:131], v[212:215], v[44:47]
	v_mfma_f32_16x16x32_bf16 v[40:43], v[136:139], v[212:215], v[40:43]
	v_mfma_f32_16x16x32_bf16 v[28:31], v[128:131], v[220:223], v[28:31]
	v_mfma_f32_16x16x32_bf16 v[24:27], v[136:139], v[220:223], v[24:27]
	v_mfma_f32_16x16x32_bf16 v[12:15], v[128:131], v[230:233], v[12:15]
	v_mfma_f32_16x16x32_bf16 v[8:11], v[136:139], v[230:233], v[8:11]
	v_mfma_f32_16x16x32_bf16 v[60:63], v[132:135], v[208:211], v[60:63]
	v_mfma_f32_16x16x32_bf16 v[56:59], v[140:143], v[208:211], v[56:59]
	v_mfma_f32_16x16x32_bf16 v[44:47], v[132:135], v[216:219], v[44:47]
	v_mfma_f32_16x16x32_bf16 v[40:43], v[140:143], v[216:219], v[40:43]
	v_mfma_f32_16x16x32_bf16 v[28:31], v[132:135], v[224:227], v[28:31]
	v_mfma_f32_16x16x32_bf16 v[24:27], v[140:143], v[224:227], v[24:27]
	v_mfma_f32_16x16x32_bf16 v[12:15], v[132:135], v[234:237], v[12:15]
	v_mfma_f32_16x16x32_bf16 v[8:11], v[140:143], v[234:237], v[8:11]
	v_mfma_f32_16x16x32_bf16 v[52:55], v[188:191], v[204:207], v[52:55]
	v_mfma_f32_16x16x32_bf16 v[48:51], v[196:199], v[204:207], v[48:51]
	v_mfma_f32_16x16x32_bf16 v[36:39], v[188:191], v[212:215], v[36:39]
	v_mfma_f32_16x16x32_bf16 v[32:35], v[196:199], v[212:215], v[32:35]
	v_mfma_f32_16x16x32_bf16 v[20:23], v[188:191], v[220:223], v[20:23]
	v_mfma_f32_16x16x32_bf16 v[16:19], v[196:199], v[220:223], v[16:19]
	v_mfma_f32_16x16x32_bf16 v[4:7], v[188:191], v[230:233], v[4:7]
	v_mfma_f32_16x16x32_bf16 v[0:3], v[196:199], v[230:233], v[0:3]
	v_mfma_f32_16x16x32_bf16 v[52:55], v[192:195], v[208:211], v[52:55]
	v_mfma_f32_16x16x32_bf16 v[48:51], v[200:203], v[208:211], v[48:51]
	v_mfma_f32_16x16x32_bf16 v[36:39], v[192:195], v[216:219], v[36:39]
	v_mfma_f32_16x16x32_bf16 v[32:35], v[200:203], v[216:219], v[32:35]
	v_mfma_f32_16x16x32_bf16 v[20:23], v[192:195], v[224:227], v[20:23]
	v_mfma_f32_16x16x32_bf16 v[16:19], v[200:203], v[224:227], v[16:19]
	v_mfma_f32_16x16x32_bf16 v[4:7], v[192:195], v[234:237], v[4:7]
	v_mfma_f32_16x16x32_bf16 v[0:3], v[200:203], v[234:237], v[0:3]
	s_setprio 0
	s_barrier
	s_add_i32 s69, s69, 2
	s_add_u32 s52, s52, 0x100
	s_addc_u32 s53, s53, 0
	s_add_u32 s67, s67, 0x100
	s_addc_u32 s68, s68, 0
	s_cmp_gt_u32 s69, 13
.Lh0_3:
	ds_read_b128 v[128:131], v179
	ds_read_b128 v[132:135], v179 offset:1024
	ds_read_b128 v[136:139], v179 offset:2048
	ds_read_b128 v[140:143], v179 offset:3072
	ds_read_b128 v[188:191], v181
	ds_read_b128 v[192:195], v181 offset:1024
	ds_read_b128 v[196:199], v181 offset:2048
	ds_read_b128 v[200:203], v181 offset:3072
	s_add_u32 s54, s52, 0xfffc0080
	s_addc_u32 s55, s53, -1
	s_cmp_eq_u32 s69, 12
	s_cselect_b32 s57, s10, s55
	s_cselect_b32 s56, s43, s54
	s_cselect_b32 s55, s45, s68
	s_cselect_b32 s54, s51, s67
	v_lshl_add_u64 v[238:239], s[52:53], 0, v[162:163]
	s_add_i32 m0, s75, 0xc000
	ds_read_b128 v[204:207], v183
	ds_read_b128 v[208:211], v183 offset:1024
	ds_read_b128 v[212:215], v183 offset:2048
	ds_read_b128 v[216:219], v183 offset:3072
	ds_read_b128 v[220:223], v183 offset:4096
	ds_read_b128 v[224:227], v183 offset:5120
	ds_read_b128 v[230:233], v183 offset:6144
	ds_read_b128 v[234:237], v183 offset:7168
	global_load_lds_dwordx4 v[238:239], off
	v_lshl_add_u64 v[238:239], s[52:53], 0, v[164:165]
	s_add_i32 m0, s75, 0xe000
	s_nop 0
	global_load_lds_dwordx4 v[238:239], off
	s_waitcnt vmcnt(8)
	s_waitcnt lgkmcnt(0)
	s_setprio 1
	v_mfma_f32_16x16x32_bf16 v[124:127], v[128:131], v[204:207], v[124:127]
	v_mfma_f32_16x16x32_bf16 v[120:123], v[136:139], v[204:207], v[120:123]
	v_mfma_f32_16x16x32_bf16 v[108:111], v[128:131], v[212:215], v[108:111]
	v_mfma_f32_16x16x32_bf16 v[104:107], v[136:139], v[212:215], v[104:107]
	v_mfma_f32_16x16x32_bf16 v[92:95], v[128:131], v[220:223], v[92:95]
	v_mfma_f32_16x16x32_bf16 v[88:91], v[136:139], v[220:223], v[88:91]
	v_mfma_f32_16x16x32_bf16 v[76:79], v[128:131], v[230:233], v[76:79]
	v_mfma_f32_16x16x32_bf16 v[72:75], v[136:139], v[230:233], v[72:75]
	v_mfma_f32_16x16x32_bf16 v[124:127], v[132:135], v[208:211], v[124:127]
	v_mfma_f32_16x16x32_bf16 v[120:123], v[140:143], v[208:211], v[120:123]
	v_mfma_f32_16x16x32_bf16 v[108:111], v[132:135], v[216:219], v[108:111]
	v_mfma_f32_16x16x32_bf16 v[104:107], v[140:143], v[216:219], v[104:107]
	v_mfma_f32_16x16x32_bf16 v[92:95], v[132:135], v[224:227], v[92:95]
	v_mfma_f32_16x16x32_bf16 v[88:91], v[140:143], v[224:227], v[88:91]
	v_mfma_f32_16x16x32_bf16 v[76:79], v[132:135], v[234:237], v[76:79]
	v_mfma_f32_16x16x32_bf16 v[72:75], v[140:143], v[234:237], v[72:75]
	v_mfma_f32_16x16x32_bf16 v[116:119], v[188:191], v[204:207], v[116:119]
	v_mfma_f32_16x16x32_bf16 v[112:115], v[196:199], v[204:207], v[112:115]
	v_mfma_f32_16x16x32_bf16 v[100:103], v[188:191], v[212:215], v[100:103]
	v_mfma_f32_16x16x32_bf16 v[96:99], v[196:199], v[212:215], v[96:99]
	v_mfma_f32_16x16x32_bf16 v[84:87], v[188:191], v[220:223], v[84:87]
	v_mfma_f32_16x16x32_bf16 v[80:83], v[196:199], v[220:223], v[80:83]
	v_mfma_f32_16x16x32_bf16 v[68:71], v[188:191], v[230:233], v[68:71]
	v_mfma_f32_16x16x32_bf16 v[64:67], v[196:199], v[230:233], v[64:67]
	v_mfma_f32_16x16x32_bf16 v[116:119], v[192:195], v[208:211], v[116:119]
	v_mfma_f32_16x16x32_bf16 v[112:115], v[200:203], v[208:211], v[112:115]
	v_mfma_f32_16x16x32_bf16 v[100:103], v[192:195], v[216:219], v[100:103]
	v_mfma_f32_16x16x32_bf16 v[96:99], v[200:203], v[216:219], v[96:99]
	v_mfma_f32_16x16x32_bf16 v[84:87], v[192:195], v[224:227], v[84:87]
	v_mfma_f32_16x16x32_bf16 v[80:83], v[200:203], v[224:227], v[80:83]
	v_mfma_f32_16x16x32_bf16 v[68:71], v[192:195], v[234:237], v[68:71]
	v_mfma_f32_16x16x32_bf16 v[64:67], v[200:203], v[234:237], v[64:67]
	s_setprio 0
	s_barrier
	s_add_i32 vcc_lo, s92, s72
	v_lshl_add_u64 v[238:239], s[54:55], 0, v[148:149]
	s_mov_b32 m0, vcc_lo
	ds_read_b128 v[204:207], v183 offset:16384
	ds_read_b128 v[208:211], v183 offset:17408
	ds_read_b128 v[212:215], v183 offset:18432
	ds_read_b128 v[216:219], v183 offset:19456
	ds_read_b128 v[220:223], v183 offset:20480
	ds_read_b128 v[224:227], v183 offset:21504
	ds_read_b128 v[230:233], v183 offset:22528
	ds_read_b128 v[234:237], v183 offset:23552
	global_load_lds_dwordx4 v[238:239], off
	s_add_i32 m0, vcc_lo, 0x2000
	s_add_u32 vcc_lo, s54, 0x40000
	v_lshl_add_u64 v[240:241], s[54:55], 0, v[144:145]
	s_addc_u32 vcc_hi, s55, 0
	s_add_i32 s83, s93, s72
	global_load_lds_dwordx4 v[240:241], off
	v_lshl_add_u64 v[242:243], vcc, 0, v[148:149]
	s_mov_b32 m0, s83
	v_lshl_add_u64 v[244:245], s[56:57], 0, v[146:147]
	global_load_lds_dwordx4 v[242:243], off
	v_lshl_add_u64 v[242:243], vcc, 0, v[144:145]
	s_add_i32 m0, s83, 0x2000
	s_nop 0
	global_load_lds_dwordx4 v[242:243], off
	v_lshl_add_u64 v[242:243], s[56:57], 0, v[150:151]
	s_mov_b32 m0, s75
	s_nop 0
	global_load_lds_dwordx4 v[242:243], off
	s_mov_b32 m0, s76
	s_nop 0
	global_load_lds_dwordx4 v[244:245], off
	s_waitcnt vmcnt(8)
	s_waitcnt lgkmcnt(0)
	s_setprio 1
	v_mfma_f32_16x16x32_bf16 v[60:63], v[128:131], v[204:207], v[60:63]
	v_mfma_f32_16x16x32_bf16 v[56:59], v[136:139], v[204:207], v[56:59]
	v_mfma_f32_16x16x32_bf16 v[44:47], v[128:131], v[212:215], v[44:47]
	v_mfma_f32_16x16x32_bf16 v[40:43], v[136:139], v[212:215], v[40:43]
	v_mfma_f32_16x16x32_bf16 v[28:31], v[128:131], v[220:223], v[28:31]
	v_mfma_f32_16x16x32_bf16 v[24:27], v[136:139], v[220:223], v[24:27]
	v_mfma_f32_16x16x32_bf16 v[12:15], v[128:131], v[230:233], v[12:15]
	v_mfma_f32_16x16x32_bf16 v[8:11], v[136:139], v[230:233], v[8:11]
	v_mfma_f32_16x16x32_bf16 v[60:63], v[132:135], v[208:211], v[60:63]
	v_mfma_f32_16x16x32_bf16 v[56:59], v[140:143], v[208:211], v[56:59]
	v_mfma_f32_16x16x32_bf16 v[44:47], v[132:135], v[216:219], v[44:47]
	v_mfma_f32_16x16x32_bf16 v[40:43], v[140:143], v[216:219], v[40:43]
	v_mfma_f32_16x16x32_bf16 v[28:31], v[132:135], v[224:227], v[28:31]
	v_mfma_f32_16x16x32_bf16 v[24:27], v[140:143], v[224:227], v[24:27]
	v_mfma_f32_16x16x32_bf16 v[12:15], v[132:135], v[234:237], v[12:15]
	v_mfma_f32_16x16x32_bf16 v[8:11], v[140:143], v[234:237], v[8:11]
	v_mfma_f32_16x16x32_bf16 v[52:55], v[188:191], v[204:207], v[52:55]
	v_mfma_f32_16x16x32_bf16 v[48:51], v[196:199], v[204:207], v[48:51]
	v_mfma_f32_16x16x32_bf16 v[36:39], v[188:191], v[212:215], v[36:39]
	v_mfma_f32_16x16x32_bf16 v[32:35], v[196:199], v[212:215], v[32:35]
	v_mfma_f32_16x16x32_bf16 v[20:23], v[188:191], v[220:223], v[20:23]
	v_mfma_f32_16x16x32_bf16 v[16:19], v[196:199], v[220:223], v[16:19]
	v_mfma_f32_16x16x32_bf16 v[4:7], v[188:191], v[230:233], v[4:7]
	v_mfma_f32_16x16x32_bf16 v[0:3], v[196:199], v[230:233], v[0:3]
	v_mfma_f32_16x16x32_bf16 v[52:55], v[192:195], v[208:211], v[52:55]
	v_mfma_f32_16x16x32_bf16 v[48:51], v[200:203], v[208:211], v[48:51]
	v_mfma_f32_16x16x32_bf16 v[36:39], v[192:195], v[216:219], v[36:39]
	v_mfma_f32_16x16x32_bf16 v[32:35], v[200:203], v[216:219], v[32:35]
	v_mfma_f32_16x16x32_bf16 v[20:23], v[192:195], v[224:227], v[20:23]
	v_mfma_f32_16x16x32_bf16 v[16:19], v[200:203], v[224:227], v[16:19]
	v_mfma_f32_16x16x32_bf16 v[4:7], v[192:195], v[234:237], v[4:7]
	v_mfma_f32_16x16x32_bf16 v[0:3], v[200:203], v[234:237], v[0:3]
	s_setprio 0
	s_barrier
	s_add_i32 s83, 0, 0x18000
	s_add_i32 vcc_lo, 0, 0x1c000
	v_add_u32_e32 v140, s83, v157
	v_add_u32_e32 v171, vcc_lo, v157
	ds_read_b128 v[128:131], v140
	ds_read_b128 v[132:135], v140 offset:1024
	ds_read_b128 v[136:139], v140 offset:2048
	ds_read_b128 v[140:143], v140 offset:3072
	ds_read_b128 v[188:191], v171
	ds_read_b128 v[192:195], v171 offset:1024
	ds_read_b128 v[196:199], v171 offset:2048
	ds_read_b128 v[200:203], v171 offset:3072
	s_add_u32 s56, s56, 0x40000
	s_addc_u32 s57, s57, 0
	s_mov_b32 m0, s77
	v_lshl_add_u64 v[246:247], s[56:57], 0, v[150:151]
	ds_read_b128 v[204:207], v183 offset:32768
	ds_read_b128 v[208:211], v183 offset:33792
	ds_read_b128 v[212:215], v183 offset:34816
	ds_read_b128 v[216:219], v183 offset:35840
	ds_read_b128 v[220:223], v183 offset:36864
	ds_read_b128 v[224:227], v183 offset:37888
	ds_read_b128 v[230:233], v183 offset:38912
	ds_read_b128 v[234:237], v183 offset:39936
	global_load_lds_dwordx4 v[246:247], off
	v_lshl_add_u64 v[246:247], s[56:57], 0, v[146:147]
	s_mov_b32 m0, s78
	s_nop 0
	global_load_lds_dwordx4 v[246:247], off
	s_waitcnt vmcnt(8)
	s_waitcnt lgkmcnt(0)
	s_setprio 1
	v_mfma_f32_16x16x32_bf16 v[124:127], v[128:131], v[204:207], v[124:127]
	v_mfma_f32_16x16x32_bf16 v[120:123], v[136:139], v[204:207], v[120:123]
	v_mfma_f32_16x16x32_bf16 v[108:111], v[128:131], v[212:215], v[108:111]
	v_mfma_f32_16x16x32_bf16 v[104:107], v[136:139], v[212:215], v[104:107]
	v_mfma_f32_16x16x32_bf16 v[92:95], v[128:131], v[220:223], v[92:95]
	v_mfma_f32_16x16x32_bf16 v[88:91], v[136:139], v[220:223], v[88:91]
	v_mfma_f32_16x16x32_bf16 v[76:79], v[128:131], v[230:233], v[76:79]
	v_mfma_f32_16x16x32_bf16 v[72:75], v[136:139], v[230:233], v[72:75]
	v_mfma_f32_16x16x32_bf16 v[124:127], v[132:135], v[208:211], v[124:127]
	v_mfma_f32_16x16x32_bf16 v[120:123], v[140:143], v[208:211], v[120:123]
	v_mfma_f32_16x16x32_bf16 v[108:111], v[132:135], v[216:219], v[108:111]
	v_mfma_f32_16x16x32_bf16 v[104:107], v[140:143], v[216:219], v[104:107]
	v_mfma_f32_16x16x32_bf16 v[92:95], v[132:135], v[224:227], v[92:95]
	v_mfma_f32_16x16x32_bf16 v[88:91], v[140:143], v[224:227], v[88:91]
	v_mfma_f32_16x16x32_bf16 v[76:79], v[132:135], v[234:237], v[76:79]
	v_mfma_f32_16x16x32_bf16 v[72:75], v[140:143], v[234:237], v[72:75]
	v_mfma_f32_16x16x32_bf16 v[116:119], v[188:191], v[204:207], v[116:119]
	v_mfma_f32_16x16x32_bf16 v[112:115], v[196:199], v[204:207], v[112:115]
	v_mfma_f32_16x16x32_bf16 v[100:103], v[188:191], v[212:215], v[100:103]
	v_mfma_f32_16x16x32_bf16 v[96:99], v[196:199], v[212:215], v[96:99]
	v_mfma_f32_16x16x32_bf16 v[84:87], v[188:191], v[220:223], v[84:87]
	v_mfma_f32_16x16x32_bf16 v[80:83], v[196:199], v[220:223], v[80:83]
	v_mfma_f32_16x16x32_bf16 v[68:71], v[188:191], v[230:233], v[68:71]
	v_mfma_f32_16x16x32_bf16 v[64:67], v[196:199], v[230:233], v[64:67]
	v_mfma_f32_16x16x32_bf16 v[116:119], v[192:195], v[208:211], v[116:119]
	v_mfma_f32_16x16x32_bf16 v[112:115], v[200:203], v[208:211], v[112:115]
	v_mfma_f32_16x16x32_bf16 v[100:103], v[192:195], v[216:219], v[100:103]
	v_mfma_f32_16x16x32_bf16 v[96:99], v[200:203], v[216:219], v[96:99]
	v_mfma_f32_16x16x32_bf16 v[84:87], v[192:195], v[224:227], v[84:87]
	v_mfma_f32_16x16x32_bf16 v[80:83], v[200:203], v[224:227], v[80:83]
	v_mfma_f32_16x16x32_bf16 v[68:71], v[192:195], v[234:237], v[68:71]
	v_mfma_f32_16x16x32_bf16 v[64:67], v[200:203], v[234:237], v[64:67]
	s_setprio 0
	s_barrier
	s_add_i32 s56, s83, s72
	v_lshl_add_u64 v[238:239], v[238:239], 0, s[38:39]
	s_mov_b32 m0, s56
	ds_read_b128 v[204:207], v183 offset:49152
	ds_read_b128 v[208:211], v183 offset:50176
	ds_read_b128 v[212:215], v183 offset:51200
	ds_read_b128 v[216:219], v183 offset:52224
	ds_read_b128 v[220:223], v183 offset:53248
	ds_read_b128 v[224:227], v183 offset:54272
	ds_read_b128 v[230:233], v183 offset:55296
	ds_read_b128 v[234:237], v183 offset:56320
	global_load_lds_dwordx4 v[238:239], off
	s_add_i32 m0, s56, 0x2000
	s_add_u32 s54, s54, 0x40080
	v_lshl_add_u64 v[238:239], v[240:241], 0, s[38:39]
	s_addc_u32 s55, s55, 0
	s_add_i32 s56, vcc_lo, s72
	global_load_lds_dwordx4 v[238:239], off
	v_lshl_add_u64 v[238:239], s[54:55], 0, v[148:149]
	s_mov_b32 m0, s56
	s_nop 0
	global_load_lds_dwordx4 v[238:239], off
	v_lshl_add_u64 v[238:239], s[54:55], 0, v[144:145]
	s_add_i32 m0, s56, 0x2000
	s_nop 0
	global_load_lds_dwordx4 v[238:239], off
	v_lshl_add_u64 v[238:239], v[242:243], 0, s[38:39]
	s_mov_b32 m0, s87
	s_nop 0
	global_load_lds_dwordx4 v[238:239], off
	v_lshl_add_u64 v[238:239], v[244:245], 0, s[38:39]
	s_mov_b32 m0, s88
	s_nop 0
	global_load_lds_dwordx4 v[238:239], off
	s_waitcnt vmcnt(8)
	s_waitcnt lgkmcnt(0)
	s_setprio 1
	v_mfma_f32_16x16x32_bf16 v[60:63], v[128:131], v[204:207], v[60:63]
	v_mfma_f32_16x16x32_bf16 v[56:59], v[136:139], v[204:207], v[56:59]
	v_mfma_f32_16x16x32_bf16 v[44:47], v[128:131], v[212:215], v[44:47]
	v_mfma_f32_16x16x32_bf16 v[40:43], v[136:139], v[212:215], v[40:43]
	v_mfma_f32_16x16x32_bf16 v[28:31], v[128:131], v[220:223], v[28:31]
	v_mfma_f32_16x16x32_bf16 v[24:27], v[136:139], v[220:223], v[24:27]
	v_mfma_f32_16x16x32_bf16 v[12:15], v[128:131], v[230:233], v[12:15]
	v_mfma_f32_16x16x32_bf16 v[8:11], v[136:139], v[230:233], v[8:11]
	v_mfma_f32_16x16x32_bf16 v[60:63], v[132:135], v[208:211], v[60:63]
	v_mfma_f32_16x16x32_bf16 v[56:59], v[140:143], v[208:211], v[56:59]
	v_mfma_f32_16x16x32_bf16 v[44:47], v[132:135], v[216:219], v[44:47]
	v_mfma_f32_16x16x32_bf16 v[40:43], v[140:143], v[216:219], v[40:43]
	v_mfma_f32_16x16x32_bf16 v[28:31], v[132:135], v[224:227], v[28:31]
	v_mfma_f32_16x16x32_bf16 v[24:27], v[140:143], v[224:227], v[24:27]
	v_mfma_f32_16x16x32_bf16 v[12:15], v[132:135], v[234:237], v[12:15]
	v_mfma_f32_16x16x32_bf16 v[8:11], v[140:143], v[234:237], v[8:11]
	v_mfma_f32_16x16x32_bf16 v[52:55], v[188:191], v[204:207], v[52:55]
	v_mfma_f32_16x16x32_bf16 v[48:51], v[196:199], v[204:207], v[48:51]
	v_mfma_f32_16x16x32_bf16 v[36:39], v[188:191], v[212:215], v[36:39]
	v_mfma_f32_16x16x32_bf16 v[32:35], v[196:199], v[212:215], v[32:35]
	v_mfma_f32_16x16x32_bf16 v[20:23], v[188:191], v[220:223], v[20:23]
	v_mfma_f32_16x16x32_bf16 v[16:19], v[196:199], v[220:223], v[16:19]
	v_mfma_f32_16x16x32_bf16 v[4:7], v[188:191], v[230:233], v[4:7]
	v_mfma_f32_16x16x32_bf16 v[0:3], v[196:199], v[230:233], v[0:3]
	v_mfma_f32_16x16x32_bf16 v[52:55], v[192:195], v[208:211], v[52:55]
	v_mfma_f32_16x16x32_bf16 v[48:51], v[200:203], v[208:211], v[48:51]
	v_mfma_f32_16x16x32_bf16 v[36:39], v[192:195], v[216:219], v[36:39]
	v_mfma_f32_16x16x32_bf16 v[32:35], v[200:203], v[216:219], v[32:35]
	v_mfma_f32_16x16x32_bf16 v[20:23], v[192:195], v[224:227], v[20:23]
	v_mfma_f32_16x16x32_bf16 v[16:19], v[200:203], v[224:227], v[16:19]
	v_mfma_f32_16x16x32_bf16 v[4:7], v[192:195], v[234:237], v[4:7]
	v_mfma_f32_16x16x32_bf16 v[0:3], v[200:203], v[234:237], v[0:3]
	s_setprio 0
	s_barrier
	s_add_i32 s69, s69, 2
	s_add_u32 s52, s52, 0x100
	s_addc_u32 s53, s53, 0
	s_add_u32 s67, s67, 0x100
	s_addc_u32 s68, s68, 0
	s_cmp_gt_u32 s69, 13
	s_cbranch_scc0 .Lh0_3
	s_branch .Ljoin_3
.Lh1p_3:
	ds_read_b128 v[128:131], v179
	ds_read_b128 v[132:135], v179 offset:1024
	ds_read_b128 v[136:139], v179 offset:2048
	ds_read_b128 v[140:143], v179 offset:3072
	ds_read_b128 v[188:191], v181
	ds_read_b128 v[192:195], v181 offset:1024
	ds_read_b128 v[196:199], v181 offset:2048
	ds_read_b128 v[200:203], v181 offset:3072
	s_add_u32 s54, s52, 0xfffc0080
	s_addc_u32 s55, s53, -1
	s_cmp_eq_u32 s69, 12
	s_cselect_b32 s57, s10, s55
	s_cselect_b32 s56, s43, s54
	s_cselect_b32 s55, s45, s68
	s_cselect_b32 s54, s51, s67
	v_lshl_add_u64 v[238:239], s[52:53], 0, v[162:163]
	s_add_i32 m0, s75, 0xc000
	ds_read_b128 v[204:207], v183
	ds_read_b128 v[208:211], v183 offset:1024
	ds_read_b128 v[212:215], v183 offset:2048
	ds_read_b128 v[216:219], v183 offset:3072
	ds_read_b128 v[220:223], v183 offset:4096
	ds_read_b128 v[224:227], v183 offset:5120
	ds_read_b128 v[230:233], v183 offset:6144
	ds_read_b128 v[234:237], v183 offset:7168
	global_load_lds_dwordx4 v[238:239], off
	v_lshl_add_u64 v[238:239], s[52:53], 0, v[164:165]
	s_add_i32 m0, s75, 0xe000
	s_nop 0
	global_load_lds_dwordx4 v[238:239], off
	s_waitcnt vmcnt(8)
	s_waitcnt lgkmcnt(0)
	s_barrier
	s_setprio 2
	v_mfma_f32_16x16x32_bf16 v[124:127], v[128:131], v[204:207], 0
	v_mfma_f32_16x16x32_bf16 v[120:123], v[136:139], v[204:207], 0
	v_mfma_f32_16x16x32_bf16 v[108:111], v[128:131], v[212:215], 0
	v_mfma_f32_16x16x32_bf16 v[104:107], v[136:139], v[212:215], 0
	v_mfma_f32_16x16x32_bf16 v[92:95], v[128:131], v[220:223], 0
	v_mfma_f32_16x16x32_bf16 v[88:91], v[136:139], v[220:223], 0
	v_mfma_f32_16x16x32_bf16 v[76:79], v[128:131], v[230:233], 0
	v_mfma_f32_16x16x32_bf16 v[72:75], v[136:139], v[230:233], 0
	v_mfma_f32_16x16x32_bf16 v[124:127], v[132:135], v[208:211], v[124:127]
	v_mfma_f32_16x16x32_bf16 v[120:123], v[140:143], v[208:211], v[120:123]
	v_mfma_f32_16x16x32_bf16 v[108:111], v[132:135], v[216:219], v[108:111]
	v_mfma_f32_16x16x32_bf16 v[104:107], v[140:143], v[216:219], v[104:107]
	v_mfma_f32_16x16x32_bf16 v[92:95], v[132:135], v[224:227], v[92:95]
	v_mfma_f32_16x16x32_bf16 v[88:91], v[140:143], v[224:227], v[88:91]
	v_mfma_f32_16x16x32_bf16 v[76:79], v[132:135], v[234:237], v[76:79]
	v_mfma_f32_16x16x32_bf16 v[72:75], v[140:143], v[234:237], v[72:75]
	v_mfma_f32_16x16x32_bf16 v[116:119], v[188:191], v[204:207], 0
	v_mfma_f32_16x16x32_bf16 v[112:115], v[196:199], v[204:207], 0
	v_mfma_f32_16x16x32_bf16 v[100:103], v[188:191], v[212:215], 0
	v_mfma_f32_16x16x32_bf16 v[96:99], v[196:199], v[212:215], 0
	v_mfma_f32_16x16x32_bf16 v[84:87], v[188:191], v[220:223], 0
	v_mfma_f32_16x16x32_bf16 v[80:83], v[196:199], v[220:223], 0
	v_mfma_f32_16x16x32_bf16 v[68:71], v[188:191], v[230:233], 0
	v_mfma_f32_16x16x32_bf16 v[64:67], v[196:199], v[230:233], 0
	v_mfma_f32_16x16x32_bf16 v[116:119], v[192:195], v[208:211], v[116:119]
	v_mfma_f32_16x16x32_bf16 v[112:115], v[200:203], v[208:211], v[112:115]
	v_mfma_f32_16x16x32_bf16 v[100:103], v[192:195], v[216:219], v[100:103]
	v_mfma_f32_16x16x32_bf16 v[96:99], v[200:203], v[216:219], v[96:99]
	v_mfma_f32_16x16x32_bf16 v[84:87], v[192:195], v[224:227], v[84:87]
	v_mfma_f32_16x16x32_bf16 v[80:83], v[200:203], v[224:227], v[80:83]
	v_mfma_f32_16x16x32_bf16 v[68:71], v[192:195], v[234:237], v[68:71]
	v_mfma_f32_16x16x32_bf16 v[64:67], v[200:203], v[234:237], v[64:67]
	s_setprio 0
	s_add_i32 vcc_lo, s92, s72
	v_lshl_add_u64 v[238:239], s[54:55], 0, v[148:149]
	s_mov_b32 m0, vcc_lo
	ds_read_b128 v[204:207], v183 offset:16384
	ds_read_b128 v[208:211], v183 offset:17408
	ds_read_b128 v[212:215], v183 offset:18432
	ds_read_b128 v[216:219], v183 offset:19456
	ds_read_b128 v[220:223], v183 offset:20480
	ds_read_b128 v[224:227], v183 offset:21504
	ds_read_b128 v[230:233], v183 offset:22528
	ds_read_b128 v[234:237], v183 offset:23552
	global_load_lds_dwordx4 v[238:239], off
	s_add_i32 m0, vcc_lo, 0x2000
	s_add_u32 vcc_lo, s54, 0x40000
	v_lshl_add_u64 v[240:241], s[54:55], 0, v[144:145]
	s_addc_u32 vcc_hi, s55, 0
	s_add_i32 s83, s93, s72
	global_load_lds_dwordx4 v[240:241], off
	v_lshl_add_u64 v[242:243], vcc, 0, v[148:149]
	s_mov_b32 m0, s83
	v_lshl_add_u64 v[244:245], s[56:57], 0, v[146:147]
	global_load_lds_dwordx4 v[242:243], off
	v_lshl_add_u64 v[242:243], vcc, 0, v[144:145]
	s_add_i32 m0, s83, 0x2000
	s_nop 0
	global_load_lds_dwordx4 v[242:243], off
	v_lshl_add_u64 v[242:243], s[56:57], 0, v[150:151]
	s_mov_b32 m0, s75
	s_nop 0
	global_load_lds_dwordx4 v[242:243], off
	s_mov_b32 m0, s76
	s_nop 0
	global_load_lds_dwordx4 v[244:245], off
	s_waitcnt vmcnt(8)
	s_waitcnt lgkmcnt(0)
	s_barrier
	s_setprio 2
	v_mfma_f32_16x16x32_bf16 v[60:63], v[128:131], v[204:207], 0
	v_mfma_f32_16x16x32_bf16 v[56:59], v[136:139], v[204:207], 0
	v_mfma_f32_16x16x32_bf16 v[44:47], v[128:131], v[212:215], 0
	v_mfma_f32_16x16x32_bf16 v[40:43], v[136:139], v[212:215], 0
	v_mfma_f32_16x16x32_bf16 v[28:31], v[128:131], v[220:223], 0
	v_mfma_f32_16x16x32_bf16 v[24:27], v[136:139], v[220:223], 0
	v_mfma_f32_16x16x32_bf16 v[12:15], v[128:131], v[230:233], 0
	v_mfma_f32_16x16x32_bf16 v[8:11], v[136:139], v[230:233], 0
	v_mfma_f32_16x16x32_bf16 v[60:63], v[132:135], v[208:211], v[60:63]
	v_mfma_f32_16x16x32_bf16 v[56:59], v[140:143], v[208:211], v[56:59]
	v_mfma_f32_16x16x32_bf16 v[44:47], v[132:135], v[216:219], v[44:47]
	v_mfma_f32_16x16x32_bf16 v[40:43], v[140:143], v[216:219], v[40:43]
	v_mfma_f32_16x16x32_bf16 v[28:31], v[132:135], v[224:227], v[28:31]
	v_mfma_f32_16x16x32_bf16 v[24:27], v[140:143], v[224:227], v[24:27]
	v_mfma_f32_16x16x32_bf16 v[12:15], v[132:135], v[234:237], v[12:15]
	v_mfma_f32_16x16x32_bf16 v[8:11], v[140:143], v[234:237], v[8:11]
	v_mfma_f32_16x16x32_bf16 v[52:55], v[188:191], v[204:207], 0
	v_mfma_f32_16x16x32_bf16 v[48:51], v[196:199], v[204:207], 0
	v_mfma_f32_16x16x32_bf16 v[36:39], v[188:191], v[212:215], 0
	v_mfma_f32_16x16x32_bf16 v[32:35], v[196:199], v[212:215], 0
	v_mfma_f32_16x16x32_bf16 v[20:23], v[188:191], v[220:223], 0
	v_mfma_f32_16x16x32_bf16 v[16:19], v[196:199], v[220:223], 0
	v_mfma_f32_16x16x32_bf16 v[4:7], v[188:191], v[230:233], 0
	v_mfma_f32_16x16x32_bf16 v[0:3], v[196:199], v[230:233], 0
	v_mfma_f32_16x16x32_bf16 v[52:55], v[192:195], v[208:211], v[52:55]
	v_mfma_f32_16x16x32_bf16 v[48:51], v[200:203], v[208:211], v[48:51]
	v_mfma_f32_16x16x32_bf16 v[36:39], v[192:195], v[216:219], v[36:39]
	v_mfma_f32_16x16x32_bf16 v[32:35], v[200:203], v[216:219], v[32:35]
	v_mfma_f32_16x16x32_bf16 v[20:23], v[192:195], v[224:227], v[20:23]
	v_mfma_f32_16x16x32_bf16 v[16:19], v[200:203], v[224:227], v[16:19]
	v_mfma_f32_16x16x32_bf16 v[4:7], v[192:195], v[234:237], v[4:7]
	v_mfma_f32_16x16x32_bf16 v[0:3], v[200:203], v[234:237], v[0:3]
	s_setprio 0
	s_add_i32 s83, 0, 0x18000
	s_add_i32 vcc_lo, 0, 0x1c000
	v_add_u32_e32 v140, s83, v157
	v_add_u32_e32 v171, vcc_lo, v157
	ds_read_b128 v[128:131], v140
	ds_read_b128 v[132:135], v140 offset:1024
	ds_read_b128 v[136:139], v140 offset:2048
	ds_read_b128 v[140:143], v140 offset:3072
	ds_read_b128 v[188:191], v171
	ds_read_b128 v[192:195], v171 offset:1024
	ds_read_b128 v[196:199], v171 offset:2048
	ds_read_b128 v[200:203], v171 offset:3072
	s_add_u32 s56, s56, 0x40000
	s_addc_u32 s57, s57, 0
	s_mov_b32 m0, s77
	v_lshl_add_u64 v[246:247], s[56:57], 0, v[150:151]
	ds_read_b128 v[204:207], v183 offset:32768
	ds_read_b128 v[208:211], v183 offset:33792
	ds_read_b128 v[212:215], v183 offset:34816
	ds_read_b128 v[216:219], v183 offset:35840
	ds_read_b128 v[220:223], v183 offset:36864
	ds_read_b128 v[224:227], v183 offset:37888
	ds_read_b128 v[230:233], v183 offset:38912
	ds_read_b128 v[234:237], v183 offset:39936
	global_load_lds_dwordx4 v[246:247], off
	v_lshl_add_u64 v[246:247], s[56:57], 0, v[146:147]
	s_mov_b32 m0, s78
	s_nop 0
	global_load_lds_dwordx4 v[246:247], off
	s_waitcnt vmcnt(8)
	s_waitcnt lgkmcnt(0)
	s_barrier
	s_setprio 2
	v_mfma_f32_16x16x32_bf16 v[124:127], v[128:131], v[204:207], v[124:127]
	v_mfma_f32_16x16x32_bf16 v[120:123], v[136:139], v[204:207], v[120:123]
	v_mfma_f32_16x16x32_bf16 v[108:111], v[128:131], v[212:215], v[108:111]
	v_mfma_f32_16x16x32_bf16 v[104:107], v[136:139], v[212:215], v[104:107]
	v_mfma_f32_16x16x32_bf16 v[92:95], v[128:131], v[220:223], v[92:95]
	v_mfma_f32_16x16x32_bf16 v[88:91], v[136:139], v[220:223], v[88:91]
	v_mfma_f32_16x16x32_bf16 v[76:79], v[128:131], v[230:233], v[76:79]
	v_mfma_f32_16x16x32_bf16 v[72:75], v[136:139], v[230:233], v[72:75]
	v_mfma_f32_16x16x32_bf16 v[124:127], v[132:135], v[208:211], v[124:127]
	v_mfma_f32_16x16x32_bf16 v[120:123], v[140:143], v[208:211], v[120:123]
	v_mfma_f32_16x16x32_bf16 v[108:111], v[132:135], v[216:219], v[108:111]
	v_mfma_f32_16x16x32_bf16 v[104:107], v[140:143], v[216:219], v[104:107]
	v_mfma_f32_16x16x32_bf16 v[92:95], v[132:135], v[224:227], v[92:95]
	v_mfma_f32_16x16x32_bf16 v[88:91], v[140:143], v[224:227], v[88:91]
	v_mfma_f32_16x16x32_bf16 v[76:79], v[132:135], v[234:237], v[76:79]
	v_mfma_f32_16x16x32_bf16 v[72:75], v[140:143], v[234:237], v[72:75]
	v_mfma_f32_16x16x32_bf16 v[116:119], v[188:191], v[204:207], v[116:119]
	v_mfma_f32_16x16x32_bf16 v[112:115], v[196:199], v[204:207], v[112:115]
	v_mfma_f32_16x16x32_bf16 v[100:103], v[188:191], v[212:215], v[100:103]
	v_mfma_f32_16x16x32_bf16 v[96:99], v[196:199], v[212:215], v[96:99]
	v_mfma_f32_16x16x32_bf16 v[84:87], v[188:191], v[220:223], v[84:87]
	v_mfma_f32_16x16x32_bf16 v[80:83], v[196:199], v[220:223], v[80:83]
	v_mfma_f32_16x16x32_bf16 v[68:71], v[188:191], v[230:233], v[68:71]
	v_mfma_f32_16x16x32_bf16 v[64:67], v[196:199], v[230:233], v[64:67]
	v_mfma_f32_16x16x32_bf16 v[116:119], v[192:195], v[208:211], v[116:119]
	v_mfma_f32_16x16x32_bf16 v[112:115], v[200:203], v[208:211], v[112:115]
	v_mfma_f32_16x16x32_bf16 v[100:103], v[192:195], v[216:219], v[100:103]
	v_mfma_f32_16x16x32_bf16 v[96:99], v[200:203], v[216:219], v[96:99]
	v_mfma_f32_16x16x32_bf16 v[84:87], v[192:195], v[224:227], v[84:87]
	v_mfma_f32_16x16x32_bf16 v[80:83], v[200:203], v[224:227], v[80:83]
	v_mfma_f32_16x16x32_bf16 v[68:71], v[192:195], v[234:237], v[68:71]
	v_mfma_f32_16x16x32_bf16 v[64:67], v[200:203], v[234:237], v[64:67]
	s_setprio 0
	s_add_i32 s56, s83, s72
	v_lshl_add_u64 v[238:239], v[238:239], 0, s[38:39]
	s_mov_b32 m0, s56
	ds_read_b128 v[204:207], v183 offset:49152
	ds_read_b128 v[208:211], v183 offset:50176
	ds_read_b128 v[212:215], v183 offset:51200
	ds_read_b128 v[216:219], v183 offset:52224
	ds_read_b128 v[220:223], v183 offset:53248
	ds_read_b128 v[224:227], v183 offset:54272
	ds_read_b128 v[230:233], v183 offset:55296
	ds_read_b128 v[234:237], v183 offset:56320
	global_load_lds_dwordx4 v[238:239], off
	s_add_i32 m0, s56, 0x2000
	s_add_u32 s54, s54, 0x40080
	v_lshl_add_u64 v[238:239], v[240:241], 0, s[38:39]
	s_addc_u32 s55, s55, 0
	s_add_i32 s56, vcc_lo, s72
	global_load_lds_dwordx4 v[238:239], off
	v_lshl_add_u64 v[238:239], s[54:55], 0, v[148:149]
	s_mov_b32 m0, s56
	s_nop 0
	global_load_lds_dwordx4 v[238:239], off
	v_lshl_add_u64 v[238:239], s[54:55], 0, v[144:145]
	s_add_i32 m0, s56, 0x2000
	s_nop 0
	global_load_lds_dwordx4 v[238:239], off
	v_lshl_add_u64 v[238:239], v[242:243], 0, s[38:39]
	s_mov_b32 m0, s87
	s_nop 0
	global_load_lds_dwordx4 v[238:239], off
	v_lshl_add_u64 v[238:239], v[244:245], 0, s[38:39]
	s_mov_b32 m0, s88
	s_nop 0
	global_load_lds_dwordx4 v[238:239], off
	s_waitcnt vmcnt(8)
	s_waitcnt lgkmcnt(0)
	s_barrier
	s_setprio 2
	v_mfma_f32_16x16x32_bf16 v[60:63], v[128:131], v[204:207], v[60:63]
	v_mfma_f32_16x16x32_bf16 v[56:59], v[136:139], v[204:207], v[56:59]
	v_mfma_f32_16x16x32_bf16 v[44:47], v[128:131], v[212:215], v[44:47]
	v_mfma_f32_16x16x32_bf16 v[40:43], v[136:139], v[212:215], v[40:43]
	v_mfma_f32_16x16x32_bf16 v[28:31], v[128:131], v[220:223], v[28:31]
	v_mfma_f32_16x16x32_bf16 v[24:27], v[136:139], v[220:223], v[24:27]
	v_mfma_f32_16x16x32_bf16 v[12:15], v[128:131], v[230:233], v[12:15]
	v_mfma_f32_16x16x32_bf16 v[8:11], v[136:139], v[230:233], v[8:11]
	v_mfma_f32_16x16x32_bf16 v[60:63], v[132:135], v[208:211], v[60:63]
	v_mfma_f32_16x16x32_bf16 v[56:59], v[140:143], v[208:211], v[56:59]
	v_mfma_f32_16x16x32_bf16 v[44:47], v[132:135], v[216:219], v[44:47]
	v_mfma_f32_16x16x32_bf16 v[40:43], v[140:143], v[216:219], v[40:43]
	v_mfma_f32_16x16x32_bf16 v[28:31], v[132:135], v[224:227], v[28:31]
	v_mfma_f32_16x16x32_bf16 v[24:27], v[140:143], v[224:227], v[24:27]
	v_mfma_f32_16x16x32_bf16 v[12:15], v[132:135], v[234:237], v[12:15]
	v_mfma_f32_16x16x32_bf16 v[8:11], v[140:143], v[234:237], v[8:11]
	v_mfma_f32_16x16x32_bf16 v[52:55], v[188:191], v[204:207], v[52:55]
	v_mfma_f32_16x16x32_bf16 v[48:51], v[196:199], v[204:207], v[48:51]
	v_mfma_f32_16x16x32_bf16 v[36:39], v[188:191], v[212:215], v[36:39]
	v_mfma_f32_16x16x32_bf16 v[32:35], v[196:199], v[212:215], v[32:35]
	v_mfma_f32_16x16x32_bf16 v[20:23], v[188:191], v[220:223], v[20:23]
	v_mfma_f32_16x16x32_bf16 v[16:19], v[196:199], v[220:223], v[16:19]
	v_mfma_f32_16x16x32_bf16 v[4:7], v[188:191], v[230:233], v[4:7]
	v_mfma_f32_16x16x32_bf16 v[0:3], v[196:199], v[230:233], v[0:3]
	v_mfma_f32_16x16x32_bf16 v[52:55], v[192:195], v[208:211], v[52:55]
	v_mfma_f32_16x16x32_bf16 v[48:51], v[200:203], v[208:211], v[48:51]
	v_mfma_f32_16x16x32_bf16 v[36:39], v[192:195], v[216:219], v[36:39]
	v_mfma_f32_16x16x32_bf16 v[32:35], v[200:203], v[216:219], v[32:35]
	v_mfma_f32_16x16x32_bf16 v[20:23], v[192:195], v[224:227], v[20:23]
	v_mfma_f32_16x16x32_bf16 v[16:19], v[200:203], v[224:227], v[16:19]
	v_mfma_f32_16x16x32_bf16 v[4:7], v[192:195], v[234:237], v[4:7]
	v_mfma_f32_16x16x32_bf16 v[0:3], v[200:203], v[234:237], v[0:3]
	s_setprio 0
	s_add_i32 s69, s69, 2
	s_add_u32 s52, s52, 0x100
	s_addc_u32 s53, s53, 0
	s_add_u32 s67, s67, 0x100
	s_addc_u32 s68, s68, 0
	s_cmp_gt_u32 s69, 13
.Lh1_3:
	ds_read_b128 v[128:131], v179
	ds_read_b128 v[132:135], v179 offset:1024
	ds_read_b128 v[136:139], v179 offset:2048
	ds_read_b128 v[140:143], v179 offset:3072
	ds_read_b128 v[188:191], v181
	ds_read_b128 v[192:195], v181 offset:1024
	ds_read_b128 v[196:199], v181 offset:2048
	ds_read_b128 v[200:203], v181 offset:3072
	s_add_u32 s54, s52, 0xfffc0080
	s_addc_u32 s55, s53, -1
	s_cmp_eq_u32 s69, 12
	s_cselect_b32 s57, s10, s55
	s_cselect_b32 s56, s43, s54
	s_cselect_b32 s55, s45, s68
	s_cselect_b32 s54, s51, s67
	v_lshl_add_u64 v[238:239], s[52:53], 0, v[162:163]
	s_add_i32 m0, s75, 0xc000
	ds_read_b128 v[204:207], v183
	ds_read_b128 v[208:211], v183 offset:1024
	ds_read_b128 v[212:215], v183 offset:2048
	ds_read_b128 v[216:219], v183 offset:3072
	ds_read_b128 v[220:223], v183 offset:4096
	ds_read_b128 v[224:227], v183 offset:5120
	ds_read_b128 v[230:233], v183 offset:6144
	ds_read_b128 v[234:237], v183 offset:7168
	global_load_lds_dwordx4 v[238:239], off
	v_lshl_add_u64 v[238:239], s[52:53], 0, v[164:165]
	s_add_i32 m0, s75, 0xe000
	s_nop 0
	global_load_lds_dwordx4 v[238:239], off
	s_waitcnt vmcnt(8)
	s_waitcnt lgkmcnt(0)
	s_barrier
	s_setprio 2
	v_mfma_f32_16x16x32_bf16 v[124:127], v[128:131], v[204:207], v[124:127]
	v_mfma_f32_16x16x32_bf16 v[120:123], v[136:139], v[204:207], v[120:123]
	v_mfma_f32_16x16x32_bf16 v[108:111], v[128:131], v[212:215], v[108:111]
	v_mfma_f32_16x16x32_bf16 v[104:107], v[136:139], v[212:215], v[104:107]
	v_mfma_f32_16x16x32_bf16 v[92:95], v[128:131], v[220:223], v[92:95]
	v_mfma_f32_16x16x32_bf16 v[88:91], v[136:139], v[220:223], v[88:91]
	v_mfma_f32_16x16x32_bf16 v[76:79], v[128:131], v[230:233], v[76:79]
	v_mfma_f32_16x16x32_bf16 v[72:75], v[136:139], v[230:233], v[72:75]
	v_mfma_f32_16x16x32_bf16 v[124:127], v[132:135], v[208:211], v[124:127]
	v_mfma_f32_16x16x32_bf16 v[120:123], v[140:143], v[208:211], v[120:123]
	v_mfma_f32_16x16x32_bf16 v[108:111], v[132:135], v[216:219], v[108:111]
	v_mfma_f32_16x16x32_bf16 v[104:107], v[140:143], v[216:219], v[104:107]
	v_mfma_f32_16x16x32_bf16 v[92:95], v[132:135], v[224:227], v[92:95]
	v_mfma_f32_16x16x32_bf16 v[88:91], v[140:143], v[224:227], v[88:91]
	v_mfma_f32_16x16x32_bf16 v[76:79], v[132:135], v[234:237], v[76:79]
	v_mfma_f32_16x16x32_bf16 v[72:75], v[140:143], v[234:237], v[72:75]
	v_mfma_f32_16x16x32_bf16 v[116:119], v[188:191], v[204:207], v[116:119]
	v_mfma_f32_16x16x32_bf16 v[112:115], v[196:199], v[204:207], v[112:115]
	v_mfma_f32_16x16x32_bf16 v[100:103], v[188:191], v[212:215], v[100:103]
	v_mfma_f32_16x16x32_bf16 v[96:99], v[196:199], v[212:215], v[96:99]
	v_mfma_f32_16x16x32_bf16 v[84:87], v[188:191], v[220:223], v[84:87]
	v_mfma_f32_16x16x32_bf16 v[80:83], v[196:199], v[220:223], v[80:83]
	v_mfma_f32_16x16x32_bf16 v[68:71], v[188:191], v[230:233], v[68:71]
	v_mfma_f32_16x16x32_bf16 v[64:67], v[196:199], v[230:233], v[64:67]
	v_mfma_f32_16x16x32_bf16 v[116:119], v[192:195], v[208:211], v[116:119]
	v_mfma_f32_16x16x32_bf16 v[112:115], v[200:203], v[208:211], v[112:115]
	v_mfma_f32_16x16x32_bf16 v[100:103], v[192:195], v[216:219], v[100:103]
	v_mfma_f32_16x16x32_bf16 v[96:99], v[200:203], v[216:219], v[96:99]
	v_mfma_f32_16x16x32_bf16 v[84:87], v[192:195], v[224:227], v[84:87]
	v_mfma_f32_16x16x32_bf16 v[80:83], v[200:203], v[224:227], v[80:83]
	v_mfma_f32_16x16x32_bf16 v[68:71], v[192:195], v[234:237], v[68:71]
	v_mfma_f32_16x16x32_bf16 v[64:67], v[200:203], v[234:237], v[64:67]
	s_setprio 0
	s_add_i32 vcc_lo, s92, s72
	v_lshl_add_u64 v[238:239], s[54:55], 0, v[148:149]
	s_mov_b32 m0, vcc_lo
	ds_read_b128 v[204:207], v183 offset:16384
	ds_read_b128 v[208:211], v183 offset:17408
	ds_read_b128 v[212:215], v183 offset:18432
	ds_read_b128 v[216:219], v183 offset:19456
	ds_read_b128 v[220:223], v183 offset:20480
	ds_read_b128 v[224:227], v183 offset:21504
	ds_read_b128 v[230:233], v183 offset:22528
	ds_read_b128 v[234:237], v183 offset:23552
	global_load_lds_dwordx4 v[238:239], off
	s_add_i32 m0, vcc_lo, 0x2000
	s_add_u32 vcc_lo, s54, 0x40000
	v_lshl_add_u64 v[240:241], s[54:55], 0, v[144:145]
	s_addc_u32 vcc_hi, s55, 0
	s_add_i32 s83, s93, s72
	global_load_lds_dwordx4 v[240:241], off
	v_lshl_add_u64 v[242:243], vcc, 0, v[148:149]
	s_mov_b32 m0, s83
	v_lshl_add_u64 v[244:245], s[56:57], 0, v[146:147]
	global_load_lds_dwordx4 v[242:243], off
	v_lshl_add_u64 v[242:243], vcc, 0, v[144:145]
	s_add_i32 m0, s83, 0x2000
	s_nop 0
	global_load_lds_dwordx4 v[242:243], off
	v_lshl_add_u64 v[242:243], s[56:57], 0, v[150:151]
	s_mov_b32 m0, s75
	s_nop 0
	global_load_lds_dwordx4 v[242:243], off
	s_mov_b32 m0, s76
	s_nop 0
	global_load_lds_dwordx4 v[244:245], off
	s_waitcnt vmcnt(8)
	s_waitcnt lgkmcnt(0)
	s_barrier
	s_setprio 2
	v_mfma_f32_16x16x32_bf16 v[60:63], v[128:131], v[204:207], v[60:63]
	v_mfma_f32_16x16x32_bf16 v[56:59], v[136:139], v[204:207], v[56:59]
	v_mfma_f32_16x16x32_bf16 v[44:47], v[128:131], v[212:215], v[44:47]
	v_mfma_f32_16x16x32_bf16 v[40:43], v[136:139], v[212:215], v[40:43]
	v_mfma_f32_16x16x32_bf16 v[28:31], v[128:131], v[220:223], v[28:31]
	v_mfma_f32_16x16x32_bf16 v[24:27], v[136:139], v[220:223], v[24:27]
	v_mfma_f32_16x16x32_bf16 v[12:15], v[128:131], v[230:233], v[12:15]
	v_mfma_f32_16x16x32_bf16 v[8:11], v[136:139], v[230:233], v[8:11]
	v_mfma_f32_16x16x32_bf16 v[60:63], v[132:135], v[208:211], v[60:63]
	v_mfma_f32_16x16x32_bf16 v[56:59], v[140:143], v[208:211], v[56:59]
	v_mfma_f32_16x16x32_bf16 v[44:47], v[132:135], v[216:219], v[44:47]
	v_mfma_f32_16x16x32_bf16 v[40:43], v[140:143], v[216:219], v[40:43]
	v_mfma_f32_16x16x32_bf16 v[28:31], v[132:135], v[224:227], v[28:31]
	v_mfma_f32_16x16x32_bf16 v[24:27], v[140:143], v[224:227], v[24:27]
	v_mfma_f32_16x16x32_bf16 v[12:15], v[132:135], v[234:237], v[12:15]
	v_mfma_f32_16x16x32_bf16 v[8:11], v[140:143], v[234:237], v[8:11]
	v_mfma_f32_16x16x32_bf16 v[52:55], v[188:191], v[204:207], v[52:55]
	v_mfma_f32_16x16x32_bf16 v[48:51], v[196:199], v[204:207], v[48:51]
	v_mfma_f32_16x16x32_bf16 v[36:39], v[188:191], v[212:215], v[36:39]
	v_mfma_f32_16x16x32_bf16 v[32:35], v[196:199], v[212:215], v[32:35]
	v_mfma_f32_16x16x32_bf16 v[20:23], v[188:191], v[220:223], v[20:23]
	v_mfma_f32_16x16x32_bf16 v[16:19], v[196:199], v[220:223], v[16:19]
	v_mfma_f32_16x16x32_bf16 v[4:7], v[188:191], v[230:233], v[4:7]
	v_mfma_f32_16x16x32_bf16 v[0:3], v[196:199], v[230:233], v[0:3]
	v_mfma_f32_16x16x32_bf16 v[52:55], v[192:195], v[208:211], v[52:55]
	v_mfma_f32_16x16x32_bf16 v[48:51], v[200:203], v[208:211], v[48:51]
	v_mfma_f32_16x16x32_bf16 v[36:39], v[192:195], v[216:219], v[36:39]
	v_mfma_f32_16x16x32_bf16 v[32:35], v[200:203], v[216:219], v[32:35]
	v_mfma_f32_16x16x32_bf16 v[20:23], v[192:195], v[224:227], v[20:23]
	v_mfma_f32_16x16x32_bf16 v[16:19], v[200:203], v[224:227], v[16:19]
	v_mfma_f32_16x16x32_bf16 v[4:7], v[192:195], v[234:237], v[4:7]
	v_mfma_f32_16x16x32_bf16 v[0:3], v[200:203], v[234:237], v[0:3]
	s_setprio 0
	s_add_i32 s83, 0, 0x18000
	s_add_i32 vcc_lo, 0, 0x1c000
	v_add_u32_e32 v140, s83, v157
	v_add_u32_e32 v171, vcc_lo, v157
	ds_read_b128 v[128:131], v140
	ds_read_b128 v[132:135], v140 offset:1024
	ds_read_b128 v[136:139], v140 offset:2048
	ds_read_b128 v[140:143], v140 offset:3072
	ds_read_b128 v[188:191], v171
	ds_read_b128 v[192:195], v171 offset:1024
	ds_read_b128 v[196:199], v171 offset:2048
	ds_read_b128 v[200:203], v171 offset:3072
	s_add_u32 s56, s56, 0x40000
	s_addc_u32 s57, s57, 0
	s_mov_b32 m0, s77
	v_lshl_add_u64 v[246:247], s[56:57], 0, v[150:151]
	ds_read_b128 v[204:207], v183 offset:32768
	ds_read_b128 v[208:211], v183 offset:33792
	ds_read_b128 v[212:215], v183 offset:34816
	ds_read_b128 v[216:219], v183 offset:35840
	ds_read_b128 v[220:223], v183 offset:36864
	ds_read_b128 v[224:227], v183 offset:37888
	ds_read_b128 v[230:233], v183 offset:38912
	ds_read_b128 v[234:237], v183 offset:39936
	global_load_lds_dwordx4 v[246:247], off
	v_lshl_add_u64 v[246:247], s[56:57], 0, v[146:147]
	s_mov_b32 m0, s78
	s_nop 0
	global_load_lds_dwordx4 v[246:247], off
	s_waitcnt vmcnt(8)
	s_waitcnt lgkmcnt(0)
	s_barrier
	s_setprio 2
	v_mfma_f32_16x16x32_bf16 v[124:127], v[128:131], v[204:207], v[124:127]
	v_mfma_f32_16x16x32_bf16 v[120:123], v[136:139], v[204:207], v[120:123]
	v_mfma_f32_16x16x32_bf16 v[108:111], v[128:131], v[212:215], v[108:111]
	v_mfma_f32_16x16x32_bf16 v[104:107], v[136:139], v[212:215], v[104:107]
	v_mfma_f32_16x16x32_bf16 v[92:95], v[128:131], v[220:223], v[92:95]
	v_mfma_f32_16x16x32_bf16 v[88:91], v[136:139], v[220:223], v[88:91]
	v_mfma_f32_16x16x32_bf16 v[76:79], v[128:131], v[230:233], v[76:79]
	v_mfma_f32_16x16x32_bf16 v[72:75], v[136:139], v[230:233], v[72:75]
	v_mfma_f32_16x16x32_bf16 v[124:127], v[132:135], v[208:211], v[124:127]
	v_mfma_f32_16x16x32_bf16 v[120:123], v[140:143], v[208:211], v[120:123]
	v_mfma_f32_16x16x32_bf16 v[108:111], v[132:135], v[216:219], v[108:111]
	v_mfma_f32_16x16x32_bf16 v[104:107], v[140:143], v[216:219], v[104:107]
	v_mfma_f32_16x16x32_bf16 v[92:95], v[132:135], v[224:227], v[92:95]
	v_mfma_f32_16x16x32_bf16 v[88:91], v[140:143], v[224:227], v[88:91]
	v_mfma_f32_16x16x32_bf16 v[76:79], v[132:135], v[234:237], v[76:79]
	v_mfma_f32_16x16x32_bf16 v[72:75], v[140:143], v[234:237], v[72:75]
	v_mfma_f32_16x16x32_bf16 v[116:119], v[188:191], v[204:207], v[116:119]
	v_mfma_f32_16x16x32_bf16 v[112:115], v[196:199], v[204:207], v[112:115]
	v_mfma_f32_16x16x32_bf16 v[100:103], v[188:191], v[212:215], v[100:103]
	v_mfma_f32_16x16x32_bf16 v[96:99], v[196:199], v[212:215], v[96:99]
	v_mfma_f32_16x16x32_bf16 v[84:87], v[188:191], v[220:223], v[84:87]
	v_mfma_f32_16x16x32_bf16 v[80:83], v[196:199], v[220:223], v[80:83]
	v_mfma_f32_16x16x32_bf16 v[68:71], v[188:191], v[230:233], v[68:71]
	v_mfma_f32_16x16x32_bf16 v[64:67], v[196:199], v[230:233], v[64:67]
	v_mfma_f32_16x16x32_bf16 v[116:119], v[192:195], v[208:211], v[116:119]
	v_mfma_f32_16x16x32_bf16 v[112:115], v[200:203], v[208:211], v[112:115]
	v_mfma_f32_16x16x32_bf16 v[100:103], v[192:195], v[216:219], v[100:103]
	v_mfma_f32_16x16x32_bf16 v[96:99], v[200:203], v[216:219], v[96:99]
	v_mfma_f32_16x16x32_bf16 v[84:87], v[192:195], v[224:227], v[84:87]
	v_mfma_f32_16x16x32_bf16 v[80:83], v[200:203], v[224:227], v[80:83]
	v_mfma_f32_16x16x32_bf16 v[68:71], v[192:195], v[234:237], v[68:71]
	v_mfma_f32_16x16x32_bf16 v[64:67], v[200:203], v[234:237], v[64:67]
	s_setprio 0
	s_add_i32 s56, s83, s72
	v_lshl_add_u64 v[238:239], v[238:239], 0, s[38:39]
	s_mov_b32 m0, s56
	ds_read_b128 v[204:207], v183 offset:49152
	ds_read_b128 v[208:211], v183 offset:50176
	ds_read_b128 v[212:215], v183 offset:51200
	ds_read_b128 v[216:219], v183 offset:52224
	ds_read_b128 v[220:223], v183 offset:53248
	ds_read_b128 v[224:227], v183 offset:54272
	ds_read_b128 v[230:233], v183 offset:55296
	ds_read_b128 v[234:237], v183 offset:56320
	global_load_lds_dwordx4 v[238:239], off
	s_add_i32 m0, s56, 0x2000
	s_add_u32 s54, s54, 0x40080
	v_lshl_add_u64 v[238:239], v[240:241], 0, s[38:39]
	s_addc_u32 s55, s55, 0
	s_add_i32 s56, vcc_lo, s72
	global_load_lds_dwordx4 v[238:239], off
	v_lshl_add_u64 v[238:239], s[54:55], 0, v[148:149]
	s_mov_b32 m0, s56
	s_nop 0
	global_load_lds_dwordx4 v[238:239], off
	v_lshl_add_u64 v[238:239], s[54:55], 0, v[144:145]
	s_add_i32 m0, s56, 0x2000
	s_nop 0
	global_load_lds_dwordx4 v[238:239], off
	v_lshl_add_u64 v[238:239], v[242:243], 0, s[38:39]
	s_mov_b32 m0, s87
	s_nop 0
	global_load_lds_dwordx4 v[238:239], off
	v_lshl_add_u64 v[238:239], v[244:245], 0, s[38:39]
	s_mov_b32 m0, s88
	s_nop 0
	global_load_lds_dwordx4 v[238:239], off
	s_waitcnt vmcnt(8)
	s_waitcnt lgkmcnt(0)
	s_barrier
	s_setprio 2
	v_mfma_f32_16x16x32_bf16 v[60:63], v[128:131], v[204:207], v[60:63]
	v_mfma_f32_16x16x32_bf16 v[56:59], v[136:139], v[204:207], v[56:59]
	v_mfma_f32_16x16x32_bf16 v[44:47], v[128:131], v[212:215], v[44:47]
	v_mfma_f32_16x16x32_bf16 v[40:43], v[136:139], v[212:215], v[40:43]
	v_mfma_f32_16x16x32_bf16 v[28:31], v[128:131], v[220:223], v[28:31]
	v_mfma_f32_16x16x32_bf16 v[24:27], v[136:139], v[220:223], v[24:27]
	v_mfma_f32_16x16x32_bf16 v[12:15], v[128:131], v[230:233], v[12:15]
	v_mfma_f32_16x16x32_bf16 v[8:11], v[136:139], v[230:233], v[8:11]
	v_mfma_f32_16x16x32_bf16 v[60:63], v[132:135], v[208:211], v[60:63]
	v_mfma_f32_16x16x32_bf16 v[56:59], v[140:143], v[208:211], v[56:59]
	v_mfma_f32_16x16x32_bf16 v[44:47], v[132:135], v[216:219], v[44:47]
	v_mfma_f32_16x16x32_bf16 v[40:43], v[140:143], v[216:219], v[40:43]
	v_mfma_f32_16x16x32_bf16 v[28:31], v[132:135], v[224:227], v[28:31]
	v_mfma_f32_16x16x32_bf16 v[24:27], v[140:143], v[224:227], v[24:27]
	v_mfma_f32_16x16x32_bf16 v[12:15], v[132:135], v[234:237], v[12:15]
	v_mfma_f32_16x16x32_bf16 v[8:11], v[140:143], v[234:237], v[8:11]
	v_mfma_f32_16x16x32_bf16 v[52:55], v[188:191], v[204:207], v[52:55]
	v_mfma_f32_16x16x32_bf16 v[48:51], v[196:199], v[204:207], v[48:51]
	v_mfma_f32_16x16x32_bf16 v[36:39], v[188:191], v[212:215], v[36:39]
	v_mfma_f32_16x16x32_bf16 v[32:35], v[196:199], v[212:215], v[32:35]
	v_mfma_f32_16x16x32_bf16 v[20:23], v[188:191], v[220:223], v[20:23]
	v_mfma_f32_16x16x32_bf16 v[16:19], v[196:199], v[220:223], v[16:19]
	v_mfma_f32_16x16x32_bf16 v[4:7], v[188:191], v[230:233], v[4:7]
	v_mfma_f32_16x16x32_bf16 v[0:3], v[196:199], v[230:233], v[0:3]
	v_mfma_f32_16x16x32_bf16 v[52:55], v[192:195], v[208:211], v[52:55]
	v_mfma_f32_16x16x32_bf16 v[48:51], v[200:203], v[208:211], v[48:51]
	v_mfma_f32_16x16x32_bf16 v[36:39], v[192:195], v[216:219], v[36:39]
	v_mfma_f32_16x16x32_bf16 v[32:35], v[200:203], v[216:219], v[32:35]
	v_mfma_f32_16x16x32_bf16 v[20:23], v[192:195], v[224:227], v[20:23]
	v_mfma_f32_16x16x32_bf16 v[16:19], v[200:203], v[224:227], v[16:19]
	v_mfma_f32_16x16x32_bf16 v[4:7], v[192:195], v[234:237], v[4:7]
	v_mfma_f32_16x16x32_bf16 v[0:3], v[200:203], v[234:237], v[0:3]
	s_setprio 0
	s_add_i32 s69, s69, 2
	s_add_u32 s52, s52, 0x100
	s_addc_u32 s53, s53, 0
	s_add_u32 s67, s67, 0x100
	s_addc_u32 s68, s68, 0
	s_cmp_gt_u32 s69, 13
	s_cbranch_scc0 .Lh1_3
.Ljoin_3:
	s_and_b64 vcc, exec, s[40:41]
	s_cbranch_vccz .LBB0_316

.LBB0_329:
	s_andn2_b64 vcc, exec, s[26:27]
	s_cbranch_vccnz .LBB0_308
	s_branch .LBB0_308

.LBB0_662:
	s_mov_b64 s[18:19], 0x80
	s_bfe_u32 s66, s3, 0x20006
	s_add_i32 m0, s53, 0x18000
	v_lshl_add_u64 v[6:7], v[6:7], 0, s[18:19]
	s_lshl_b32 s67, s4, 6
	s_lshl_b32 s6, s4, 13
	s_lshl_b32 s7, s66, 12
	s_nop 0
	global_load_lds_dwordx4 v[6:7], off
	v_lshl_add_u64 v[4:5], v[4:5], 0, s[18:19]
	s_add_i32 m0, s53, 0x1a000
	s_add_i32 s68, s53, 0x8000
	s_add_i32 s69, s53, 0xa000
	global_load_lds_dwordx4 v[4:5], off
	v_lshl_add_u64 v[2:3], v[2:3], 0, s[18:19]
	s_mov_b32 m0, s68
	s_add_u32 s4, s46, 0x40080
	global_load_lds_dwordx4 v[2:3], off
	v_lshl_add_u64 v[0:1], v[0:1], 0, s[18:19]
	s_mov_b32 m0, s69
	s_addc_u32 s5, s47, 0
	global_load_lds_dwordx4 v[0:1], off
	s_add_i32 m0, s53, 0x1c000
	v_lshl_add_u64 v[0:1], s[4:5], 0, v[186:187]
	global_load_lds_dwordx4 v[0:1], off
	v_lshl_add_u64 v[0:1], s[4:5], 0, v[190:191]
	s_add_i32 m0, s53, 0x1e000
	v_and_b32_e32 v212, 15, v9
	global_load_lds_dwordx4 v[0:1], off
	v_lshlrev_b32_e32 v2, 2, v9
	v_and_b32_e32 v1, 48, v9
	v_lshlrev_b32_e32 v4, 6, v212
	v_and_b32_e32 v2, 32, v2
	v_and_b32_e32 v3, 0x400, v14
	v_bitop3_b32 v1, v4, v2, v1 bitop3:0x36
	v_or3_b32 v5, v3, s6, v1
	v_or3_b32 v213, v3, s7, v1
	v_lshlrev_b32_e32 v1, 10, v9
	v_and_b32_e32 v3, 64, v9
	v_and_b32_e32 v4, 0x1c00, v1
	v_xor_b32_e32 v1, 16, v9
	v_add_u32_e32 v3, 64, v3
	v_cmp_lt_i32_e32 vcc, v1, v3
	v_lshrrev_b32_e32 v0, 1, v9
	s_waitcnt vmcnt(6)
	s_cmpk_lt_u32 s3, 0x100
	v_cndmask_b32_e32 v1, v9, v1, vcc
	v_lshlrev_b32_e32 v214, 2, v1
	v_xor_b32_e32 v1, 32, v9
	v_cmp_lt_i32_e32 vcc, v1, v3
	v_and_b32_e32 v3, 1, v8
	v_cmp_gt_u32_e64 s[8:9], 8, v212
	v_cndmask_b32_e32 v1, v9, v1, vcc
	v_lshlrev_b32_e32 v215, 2, v1
	v_lshlrev_b32_e32 v1, 14, v8
	v_and_b32_e32 v1, 0xffff8000, v1
	v_lshl_add_u32 v1, v10, 11, v1
	v_lshl_or_b32 v1, v3, 6, v1
	v_lshl_add_u32 v194, v11, 1, v1
	v_lshlrev_b32_e32 v1, 14, v12
	v_and_b32_e32 v1, 0xffff8000, v1
	v_lshl_add_u32 v1, v13, 11, v1
	v_and_b32_e32 v3, 1, v12
	v_and_b32_e32 v0, 56, v0
	s_cselect_b64 s[20:21], -1, 0
	v_cndmask_b32_e64 v6, 32, 0, s[8:9]
	v_lshl_or_b32 v1, v3, 6, v1
	s_add_i32 s78, 0, 0x10000
	s_add_i32 s79, 0, 0x14000
	s_mov_b32 s70, 0x18000
	s_mov_b32 s71, 0x8000
	s_mov_b32 s72, 0x1c000
	s_lshl_b32 s73, s66, 6
	v_cmp_gt_u32_e64 s[4:5], 16, v9
	s_ashr_i32 s74, s34, 31
	s_mov_b32 s75, s34
	s_ashr_i32 s76, s2, 31
	v_mov_b32_e32 v195, v193
	v_lshl_add_u32 v196, v15, 1, v1
	v_mov_b32_e32 v197, v193
	v_mov_b64_e32 v[198:199], 0x500
	v_mov_b64_e32 v[200:201], 0x4ff
	s_movk_i32 s77, 0xa1
	v_add_u32_e32 v216, s78, v213
	v_add_u32_e32 v217, s79, v213
	v_add_u32_e32 v218, 0, v5
	s_mov_b32 s80, 0xc000
	v_lshlrev_b32_e32 v192, 1, v4
	v_lshlrev_b32_e32 v202, 1, v2
	v_lshlrev_b32_e32 v204, 1, v0
	s_mov_b32 s81, 0x40000
	s_mov_b32 s82, 0x44000
	s_mov_b32 s85, 0x48000
	s_mov_b32 s86, 0x4c000
	s_mov_b32 s87, 0x50000
	s_mov_b32 s88, 0x54000
	s_mov_b32 s89, 0x58000
	s_mov_b32 s90, 0x5c000
	v_lshlrev_b32_e32 v206, 1, v6
	s_mov_b32 s91, 0
	s_barrier
	s_branch .LBB0_665

.LBB0_667:
	s_ashr_i32 s23, s22, 31
	s_lshl_b64 s[38:39], s[22:23], 19
	s_add_u32 s38, s26, s38
	s_addc_u32 s39, s27, s39
	s_and_b64 s[40:41], s[6:7], exec
	s_cselect_b32 s23, s39, s45
	s_cselect_b32 s43, s38, s44
	s_ashr_i32 s37, s36, 31
	s_lshl_b64 s[40:41], s[36:37], 19
	s_add_u32 s40, s50, s40
	s_addc_u32 s41, s51, s41
	s_and_b64 s[48:49], s[6:7], exec
	s_cselect_b32 s37, s41, s47
	s_cselect_b32 s92, s40, s46
	s_add_u32 s44, s44, 0x40080
	s_addc_u32 s45, s45, 0
	s_add_u32 s93, s46, 0x100
	s_addc_u32 s94, s47, 0
	s_mov_b32 s95, -2
	s_waitcnt lgkmcnt(0)
	s_and_b64 vcc, exec, s[20:21]
	s_cbranch_vccz .Lh1p_4
	ds_read_b128 v[80:83], v216
	ds_read_b128 v[84:87], v216 offset:1024
	ds_read_b128 v[104:107], v216 offset:2048
	ds_read_b128 v[108:111], v216 offset:3072
	ds_read_b128 v[128:131], v217
	ds_read_b128 v[132:135], v217 offset:1024
	ds_read_b128 v[152:155], v217 offset:2048
	ds_read_b128 v[156:159], v217 offset:3072
	s_add_u32 s46, s44, 0xfffc0080
	s_addc_u32 s47, s45, -1
	s_cmp_eq_u32 s95, 12
	s_cselect_b32 s49, s23, s47
	s_cselect_b32 s48, s43, s46
	s_cselect_b32 s47, s37, s94
	s_cselect_b32 s46, s92, s93
	v_lshl_add_u64 v[224:225], s[44:45], 0, v[194:195]
	s_add_i32 m0, s53, 0xc000
	ds_read_b128 v[160:163], v218
	ds_read_b128 v[164:167], v218 offset:1024
	ds_read_b128 v[168:171], v218 offset:2048
	ds_read_b128 v[172:175], v218 offset:3072
	ds_read_b128 v[176:179], v218 offset:4096
	ds_read_b128 v[180:183], v218 offset:5120
	ds_read_b128 v[208:211], v218 offset:6144
	ds_read_b128 v[220:223], v218 offset:7168
	global_load_lds_dwordx4 v[224:225], off
	v_lshl_add_u64 v[224:225], s[44:45], 0, v[196:197]
	s_add_i32 m0, s53, 0xe000
	s_nop 0
	global_load_lds_dwordx4 v[224:225], off
	s_waitcnt vmcnt(8)
	s_waitcnt lgkmcnt(0)
	s_setprio 1
	v_mfma_f32_16x16x32_bf16 v[148:151], v[80:83], v[160:163], 0
	v_mfma_f32_16x16x32_bf16 v[144:147], v[104:107], v[160:163], 0
	v_mfma_f32_16x16x32_bf16 v[124:127], v[80:83], v[168:171], 0
	v_mfma_f32_16x16x32_bf16 v[120:123], v[104:107], v[168:171], 0
	v_mfma_f32_16x16x32_bf16 v[100:103], v[80:83], v[176:179], 0
	v_mfma_f32_16x16x32_bf16 v[96:99], v[104:107], v[176:179], 0
	v_mfma_f32_16x16x32_bf16 v[76:79], v[80:83], v[208:211], 0
	v_mfma_f32_16x16x32_bf16 v[72:75], v[104:107], v[208:211], 0
	v_mfma_f32_16x16x32_bf16 v[148:151], v[84:87], v[164:167], v[148:151]
	v_mfma_f32_16x16x32_bf16 v[144:147], v[108:111], v[164:167], v[144:147]
	v_mfma_f32_16x16x32_bf16 v[124:127], v[84:87], v[172:175], v[124:127]
	v_mfma_f32_16x16x32_bf16 v[120:123], v[108:111], v[172:175], v[120:123]
	v_mfma_f32_16x16x32_bf16 v[100:103], v[84:87], v[180:183], v[100:103]
	v_mfma_f32_16x16x32_bf16 v[96:99], v[108:111], v[180:183], v[96:99]
	v_mfma_f32_16x16x32_bf16 v[76:79], v[84:87], v[220:223], v[76:79]
	v_mfma_f32_16x16x32_bf16 v[72:75], v[108:111], v[220:223], v[72:75]
	v_mfma_f32_16x16x32_bf16 v[140:143], v[128:131], v[160:163], 0
	v_mfma_f32_16x16x32_bf16 v[136:139], v[152:155], v[160:163], 0
	v_mfma_f32_16x16x32_bf16 v[116:119], v[128:131], v[168:171], 0
	v_mfma_f32_16x16x32_bf16 v[112:115], v[152:155], v[168:171], 0
	v_mfma_f32_16x16x32_bf16 v[92:95], v[128:131], v[176:179], 0
	v_mfma_f32_16x16x32_bf16 v[88:91], v[152:155], v[176:179], 0
	v_mfma_f32_16x16x32_bf16 v[68:71], v[128:131], v[208:211], 0
	v_mfma_f32_16x16x32_bf16 v[64:67], v[152:155], v[208:211], 0
	v_mfma_f32_16x16x32_bf16 v[140:143], v[132:135], v[164:167], v[140:143]
	v_mfma_f32_16x16x32_bf16 v[136:139], v[156:159], v[164:167], v[136:139]
	v_mfma_f32_16x16x32_bf16 v[116:119], v[132:135], v[172:175], v[116:119]
	v_mfma_f32_16x16x32_bf16 v[112:115], v[156:159], v[172:175], v[112:115]
	v_mfma_f32_16x16x32_bf16 v[92:95], v[132:135], v[180:183], v[92:95]
	v_mfma_f32_16x16x32_bf16 v[88:91], v[156:159], v[180:183], v[88:91]
	v_mfma_f32_16x16x32_bf16 v[68:71], v[132:135], v[220:223], v[68:71]
	v_mfma_f32_16x16x32_bf16 v[64:67], v[156:159], v[220:223], v[64:67]
	s_setprio 0
	s_barrier
	s_add_i32 s83, s78, s52
	v_lshl_add_u64 v[224:225], s[46:47], 0, v[186:187]
	s_mov_b32 m0, s83
	ds_read_b128 v[160:163], v218 offset:16384
	ds_read_b128 v[164:167], v218 offset:17408
	ds_read_b128 v[168:171], v218 offset:18432
	ds_read_b128 v[172:175], v218 offset:19456
	ds_read_b128 v[176:179], v218 offset:20480
	ds_read_b128 v[180:183], v218 offset:21504
	ds_read_b128 v[208:211], v218 offset:22528
	ds_read_b128 v[220:223], v218 offset:23552
	global_load_lds_dwordx4 v[224:225], off
	s_add_i32 m0, s83, 0x2000
	s_add_u32 s96, s46, 0x40000
	v_lshl_add_u64 v[226:227], s[46:47], 0, v[190:191]
	s_addc_u32 s97, s47, 0
	s_add_i32 s83, s79, s52
	global_load_lds_dwordx4 v[226:227], off
	v_lshl_add_u64 v[230:231], s[96:97], 0, v[186:187]
	s_mov_b32 m0, s83
	v_lshl_add_u64 v[232:233], s[48:49], 0, v[188:189]
	global_load_lds_dwordx4 v[230:231], off
	v_lshl_add_u64 v[230:231], s[96:97], 0, v[190:191]
	s_add_i32 m0, s83, 0x2000
	s_nop 0
	global_load_lds_dwordx4 v[230:231], off
	v_lshl_add_u64 v[230:231], s[48:49], 0, v[184:185]
	s_mov_b32 m0, s53
	s_nop 0
	global_load_lds_dwordx4 v[230:231], off
	s_mov_b32 m0, s54
	s_nop 0
	global_load_lds_dwordx4 v[232:233], off
	s_waitcnt vmcnt(8)
	s_waitcnt lgkmcnt(0)
	s_setprio 1
	v_mfma_f32_16x16x32_bf16 v[60:63], v[80:83], v[160:163], 0
	v_mfma_f32_16x16x32_bf16 v[56:59], v[104:107], v[160:163], 0
	v_mfma_f32_16x16x32_bf16 v[44:47], v[80:83], v[168:171], 0
	v_mfma_f32_16x16x32_bf16 v[40:43], v[104:107], v[168:171], 0
	v_mfma_f32_16x16x32_bf16 v[28:31], v[80:83], v[176:179], 0
	v_mfma_f32_16x16x32_bf16 v[24:27], v[104:107], v[176:179], 0
	v_mfma_f32_16x16x32_bf16 v[12:15], v[80:83], v[208:211], 0
	v_mfma_f32_16x16x32_bf16 v[8:11], v[104:107], v[208:211], 0
	v_mfma_f32_16x16x32_bf16 v[60:63], v[84:87], v[164:167], v[60:63]
	v_mfma_f32_16x16x32_bf16 v[56:59], v[108:111], v[164:167], v[56:59]
	v_mfma_f32_16x16x32_bf16 v[44:47], v[84:87], v[172:175], v[44:47]
	v_mfma_f32_16x16x32_bf16 v[40:43], v[108:111], v[172:175], v[40:43]
	v_mfma_f32_16x16x32_bf16 v[28:31], v[84:87], v[180:183], v[28:31]
	v_mfma_f32_16x16x32_bf16 v[24:27], v[108:111], v[180:183], v[24:27]
	v_mfma_f32_16x16x32_bf16 v[12:15], v[84:87], v[220:223], v[12:15]
	v_mfma_f32_16x16x32_bf16 v[8:11], v[108:111], v[220:223], v[8:11]
	v_mfma_f32_16x16x32_bf16 v[52:55], v[128:131], v[160:163], 0
	v_mfma_f32_16x16x32_bf16 v[48:51], v[152:155], v[160:163], 0
	v_mfma_f32_16x16x32_bf16 v[36:39], v[128:131], v[168:171], 0
	v_mfma_f32_16x16x32_bf16 v[32:35], v[152:155], v[168:171], 0
	v_mfma_f32_16x16x32_bf16 v[20:23], v[128:131], v[176:179], 0
	v_mfma_f32_16x16x32_bf16 v[16:19], v[152:155], v[176:179], 0
	v_mfma_f32_16x16x32_bf16 v[4:7], v[128:131], v[208:211], 0
	v_mfma_f32_16x16x32_bf16 v[0:3], v[152:155], v[208:211], 0
	v_mfma_f32_16x16x32_bf16 v[52:55], v[132:135], v[164:167], v[52:55]
	v_mfma_f32_16x16x32_bf16 v[48:51], v[156:159], v[164:167], v[48:51]
	v_mfma_f32_16x16x32_bf16 v[36:39], v[132:135], v[172:175], v[36:39]
	v_mfma_f32_16x16x32_bf16 v[32:35], v[156:159], v[172:175], v[32:35]
	v_mfma_f32_16x16x32_bf16 v[20:23], v[132:135], v[180:183], v[20:23]
	v_mfma_f32_16x16x32_bf16 v[16:19], v[156:159], v[180:183], v[16:19]
	v_mfma_f32_16x16x32_bf16 v[4:7], v[132:135], v[220:223], v[4:7]
	v_mfma_f32_16x16x32_bf16 v[0:3], v[156:159], v[220:223], v[0:3]
	s_setprio 0
	s_barrier
	s_add_i32 s83, 0, 0x18000
	s_add_i32 s96, 0, 0x1c000
	v_add_u32_e32 v108, s83, v213
	v_add_u32_e32 v156, s96, v213
	ds_read_b128 v[80:83], v108
	ds_read_b128 v[84:87], v108 offset:1024
	ds_read_b128 v[104:107], v108 offset:2048
	ds_read_b128 v[108:111], v108 offset:3072
	ds_read_b128 v[128:131], v156
	ds_read_b128 v[132:135], v156 offset:1024
	ds_read_b128 v[152:155], v156 offset:2048
	ds_read_b128 v[156:159], v156 offset:3072
	s_add_u32 s48, s48, 0x40000
	s_addc_u32 s49, s49, 0
	s_mov_b32 m0, s55
	v_lshl_add_u64 v[234:235], s[48:49], 0, v[184:185]
	ds_read_b128 v[160:163], v218 offset:32768
	ds_read_b128 v[164:167], v218 offset:33792
	ds_read_b128 v[168:171], v218 offset:34816
	ds_read_b128 v[172:175], v218 offset:35840
	ds_read_b128 v[176:179], v218 offset:36864
	ds_read_b128 v[180:183], v218 offset:37888
	ds_read_b128 v[208:211], v218 offset:38912
	ds_read_b128 v[220:223], v218 offset:39936
	global_load_lds_dwordx4 v[234:235], off
	v_lshl_add_u64 v[234:235], s[48:49], 0, v[188:189]
	s_mov_b32 m0, s56
	s_nop 0
	global_load_lds_dwordx4 v[234:235], off
	s_waitcnt vmcnt(8)
	s_waitcnt lgkmcnt(0)
	s_setprio 1
	v_mfma_f32_16x16x32_bf16 v[148:151], v[80:83], v[160:163], v[148:151]
	v_mfma_f32_16x16x32_bf16 v[144:147], v[104:107], v[160:163], v[144:147]
	v_mfma_f32_16x16x32_bf16 v[124:127], v[80:83], v[168:171], v[124:127]
	v_mfma_f32_16x16x32_bf16 v[120:123], v[104:107], v[168:171], v[120:123]
	v_mfma_f32_16x16x32_bf16 v[100:103], v[80:83], v[176:179], v[100:103]
	v_mfma_f32_16x16x32_bf16 v[96:99], v[104:107], v[176:179], v[96:99]
	v_mfma_f32_16x16x32_bf16 v[76:79], v[80:83], v[208:211], v[76:79]
	v_mfma_f32_16x16x32_bf16 v[72:75], v[104:107], v[208:211], v[72:75]
	v_mfma_f32_16x16x32_bf16 v[148:151], v[84:87], v[164:167], v[148:151]
	v_mfma_f32_16x16x32_bf16 v[144:147], v[108:111], v[164:167], v[144:147]
	v_mfma_f32_16x16x32_bf16 v[124:127], v[84:87], v[172:175], v[124:127]
	v_mfma_f32_16x16x32_bf16 v[120:123], v[108:111], v[172:175], v[120:123]
	v_mfma_f32_16x16x32_bf16 v[100:103], v[84:87], v[180:183], v[100:103]
	v_mfma_f32_16x16x32_bf16 v[96:99], v[108:111], v[180:183], v[96:99]
	v_mfma_f32_16x16x32_bf16 v[76:79], v[84:87], v[220:223], v[76:79]
	v_mfma_f32_16x16x32_bf16 v[72:75], v[108:111], v[220:223], v[72:75]
	v_mfma_f32_16x16x32_bf16 v[140:143], v[128:131], v[160:163], v[140:143]
	v_mfma_f32_16x16x32_bf16 v[136:139], v[152:155], v[160:163], v[136:139]
	v_mfma_f32_16x16x32_bf16 v[116:119], v[128:131], v[168:171], v[116:119]
	v_mfma_f32_16x16x32_bf16 v[112:115], v[152:155], v[168:171], v[112:115]
	v_mfma_f32_16x16x32_bf16 v[92:95], v[128:131], v[176:179], v[92:95]
	v_mfma_f32_16x16x32_bf16 v[88:91], v[152:155], v[176:179], v[88:91]
	v_mfma_f32_16x16x32_bf16 v[68:71], v[128:131], v[208:211], v[68:71]
	v_mfma_f32_16x16x32_bf16 v[64:67], v[152:155], v[208:211], v[64:67]
	v_mfma_f32_16x16x32_bf16 v[140:143], v[132:135], v[164:167], v[140:143]
	v_mfma_f32_16x16x32_bf16 v[136:139], v[156:159], v[164:167], v[136:139]
	v_mfma_f32_16x16x32_bf16 v[116:119], v[132:135], v[172:175], v[116:119]
	v_mfma_f32_16x16x32_bf16 v[112:115], v[156:159], v[172:175], v[112:115]
	v_mfma_f32_16x16x32_bf16 v[92:95], v[132:135], v[180:183], v[92:95]
	v_mfma_f32_16x16x32_bf16 v[88:91], v[156:159], v[180:183], v[88:91]
	v_mfma_f32_16x16x32_bf16 v[68:71], v[132:135], v[220:223], v[68:71]
	v_mfma_f32_16x16x32_bf16 v[64:67], v[156:159], v[220:223], v[64:67]
	s_setprio 0
	s_barrier
	s_add_i32 s48, s83, s52
	v_lshl_add_u64 v[224:225], v[224:225], 0, s[18:19]
	s_mov_b32 m0, s48
	ds_read_b128 v[160:163], v218 offset:49152
	ds_read_b128 v[164:167], v218 offset:50176
	ds_read_b128 v[168:171], v218 offset:51200
	ds_read_b128 v[172:175], v218 offset:52224
	ds_read_b128 v[176:179], v218 offset:53248
	ds_read_b128 v[180:183], v218 offset:54272
	ds_read_b128 v[208:211], v218 offset:55296
	ds_read_b128 v[220:223], v218 offset:56320
	global_load_lds_dwordx4 v[224:225], off
	s_add_i32 m0, s48, 0x2000
	s_add_u32 s46, s46, 0x40080
	v_lshl_add_u64 v[224:225], v[226:227], 0, s[18:19]
	s_addc_u32 s47, s47, 0
	s_add_i32 s48, s96, s52
	global_load_lds_dwordx4 v[224:225], off
	v_lshl_add_u64 v[224:225], s[46:47], 0, v[186:187]
	s_mov_b32 m0, s48
	s_nop 0
	global_load_lds_dwordx4 v[224:225], off
	v_lshl_add_u64 v[224:225], s[46:47], 0, v[190:191]
	s_add_i32 m0, s48, 0x2000
	s_nop 0
	global_load_lds_dwordx4 v[224:225], off
	v_lshl_add_u64 v[224:225], v[230:231], 0, s[18:19]
	s_mov_b32 m0, s68
	s_nop 0
	global_load_lds_dwordx4 v[224:225], off
	v_lshl_add_u64 v[224:225], v[232:233], 0, s[18:19]
	s_mov_b32 m0, s69
	s_nop 0
	global_load_lds_dwordx4 v[224:225], off
	s_waitcnt vmcnt(8)
	s_waitcnt lgkmcnt(0)
	s_setprio 1
	v_mfma_f32_16x16x32_bf16 v[60:63], v[80:83], v[160:163], v[60:63]
	v_mfma_f32_16x16x32_bf16 v[56:59], v[104:107], v[160:163], v[56:59]
	v_mfma_f32_16x16x32_bf16 v[44:47], v[80:83], v[168:171], v[44:47]
	v_mfma_f32_16x16x32_bf16 v[40:43], v[104:107], v[168:171], v[40:43]
	v_mfma_f32_16x16x32_bf16 v[28:31], v[80:83], v[176:179], v[28:31]
	v_mfma_f32_16x16x32_bf16 v[24:27], v[104:107], v[176:179], v[24:27]
	v_mfma_f32_16x16x32_bf16 v[12:15], v[80:83], v[208:211], v[12:15]
	v_mfma_f32_16x16x32_bf16 v[8:11], v[104:107], v[208:211], v[8:11]
	v_mfma_f32_16x16x32_bf16 v[60:63], v[84:87], v[164:167], v[60:63]
	v_mfma_f32_16x16x32_bf16 v[56:59], v[108:111], v[164:167], v[56:59]
	v_mfma_f32_16x16x32_bf16 v[44:47], v[84:87], v[172:175], v[44:47]
	v_mfma_f32_16x16x32_bf16 v[40:43], v[108:111], v[172:175], v[40:43]
	v_mfma_f32_16x16x32_bf16 v[28:31], v[84:87], v[180:183], v[28:31]
	v_mfma_f32_16x16x32_bf16 v[24:27], v[108:111], v[180:183], v[24:27]
	v_mfma_f32_16x16x32_bf16 v[12:15], v[84:87], v[220:223], v[12:15]
	v_mfma_f32_16x16x32_bf16 v[8:11], v[108:111], v[220:223], v[8:11]
	v_mfma_f32_16x16x32_bf16 v[52:55], v[128:131], v[160:163], v[52:55]
	v_mfma_f32_16x16x32_bf16 v[48:51], v[152:155], v[160:163], v[48:51]
	v_mfma_f32_16x16x32_bf16 v[36:39], v[128:131], v[168:171], v[36:39]
	v_mfma_f32_16x16x32_bf16 v[32:35], v[152:155], v[168:171], v[32:35]
	v_mfma_f32_16x16x32_bf16 v[20:23], v[128:131], v[176:179], v[20:23]
	v_mfma_f32_16x16x32_bf16 v[16:19], v[152:155], v[176:179], v[16:19]
	v_mfma_f32_16x16x32_bf16 v[4:7], v[128:131], v[208:211], v[4:7]
	v_mfma_f32_16x16x32_bf16 v[0:3], v[152:155], v[208:211], v[0:3]
	v_mfma_f32_16x16x32_bf16 v[52:55], v[132:135], v[164:167], v[52:55]
	v_mfma_f32_16x16x32_bf16 v[48:51], v[156:159], v[164:167], v[48:51]
	v_mfma_f32_16x16x32_bf16 v[36:39], v[132:135], v[172:175], v[36:39]
	v_mfma_f32_16x16x32_bf16 v[32:35], v[156:159], v[172:175], v[32:35]
	v_mfma_f32_16x16x32_bf16 v[20:23], v[132:135], v[180:183], v[20:23]
	v_mfma_f32_16x16x32_bf16 v[16:19], v[156:159], v[180:183], v[16:19]
	v_mfma_f32_16x16x32_bf16 v[4:7], v[132:135], v[220:223], v[4:7]
	v_mfma_f32_16x16x32_bf16 v[0:3], v[156:159], v[220:223], v[0:3]
	s_setprio 0
	s_barrier
	s_add_i32 s95, s95, 2
	s_add_u32 s44, s44, 0x100
	s_addc_u32 s45, s45, 0
	s_add_u32 s93, s93, 0x100
	s_addc_u32 s94, s94, 0
	s_cmp_gt_u32 s95, 13
.Lh0_4:
	ds_read_b128 v[80:83], v216
	ds_read_b128 v[84:87], v216 offset:1024
	ds_read_b128 v[104:107], v216 offset:2048
	ds_read_b128 v[108:111], v216 offset:3072
	ds_read_b128 v[128:131], v217
	ds_read_b128 v[132:135], v217 offset:1024
	ds_read_b128 v[152:155], v217 offset:2048
	ds_read_b128 v[156:159], v217 offset:3072
	s_add_u32 s46, s44, 0xfffc0080
	s_addc_u32 s47, s45, -1
	s_cmp_eq_u32 s95, 12
	s_cselect_b32 s49, s23, s47
	s_cselect_b32 s48, s43, s46
	s_cselect_b32 s47, s37, s94
	s_cselect_b32 s46, s92, s93
	v_lshl_add_u64 v[224:225], s[44:45], 0, v[194:195]
	s_add_i32 m0, s53, 0xc000
	ds_read_b128 v[160:163], v218
	ds_read_b128 v[164:167], v218 offset:1024
	ds_read_b128 v[168:171], v218 offset:2048
	ds_read_b128 v[172:175], v218 offset:3072
	ds_read_b128 v[176:179], v218 offset:4096
	ds_read_b128 v[180:183], v218 offset:5120
	ds_read_b128 v[208:211], v218 offset:6144
	ds_read_b128 v[220:223], v218 offset:7168
	global_load_lds_dwordx4 v[224:225], off
	v_lshl_add_u64 v[224:225], s[44:45], 0, v[196:197]
	s_add_i32 m0, s53, 0xe000
	s_nop 0
	global_load_lds_dwordx4 v[224:225], off
	s_waitcnt vmcnt(8)
	s_waitcnt lgkmcnt(0)
	s_setprio 1
	v_mfma_f32_16x16x32_bf16 v[148:151], v[80:83], v[160:163], v[148:151]
	v_mfma_f32_16x16x32_bf16 v[144:147], v[104:107], v[160:163], v[144:147]
	v_mfma_f32_16x16x32_bf16 v[124:127], v[80:83], v[168:171], v[124:127]
	v_mfma_f32_16x16x32_bf16 v[120:123], v[104:107], v[168:171], v[120:123]
	v_mfma_f32_16x16x32_bf16 v[100:103], v[80:83], v[176:179], v[100:103]
	v_mfma_f32_16x16x32_bf16 v[96:99], v[104:107], v[176:179], v[96:99]
	v_mfma_f32_16x16x32_bf16 v[76:79], v[80:83], v[208:211], v[76:79]
	v_mfma_f32_16x16x32_bf16 v[72:75], v[104:107], v[208:211], v[72:75]
	v_mfma_f32_16x16x32_bf16 v[148:151], v[84:87], v[164:167], v[148:151]
	v_mfma_f32_16x16x32_bf16 v[144:147], v[108:111], v[164:167], v[144:147]
	v_mfma_f32_16x16x32_bf16 v[124:127], v[84:87], v[172:175], v[124:127]
	v_mfma_f32_16x16x32_bf16 v[120:123], v[108:111], v[172:175], v[120:123]
	v_mfma_f32_16x16x32_bf16 v[100:103], v[84:87], v[180:183], v[100:103]
	v_mfma_f32_16x16x32_bf16 v[96:99], v[108:111], v[180:183], v[96:99]
	v_mfma_f32_16x16x32_bf16 v[76:79], v[84:87], v[220:223], v[76:79]
	v_mfma_f32_16x16x32_bf16 v[72:75], v[108:111], v[220:223], v[72:75]
	v_mfma_f32_16x16x32_bf16 v[140:143], v[128:131], v[160:163], v[140:143]
	v_mfma_f32_16x16x32_bf16 v[136:139], v[152:155], v[160:163], v[136:139]
	v_mfma_f32_16x16x32_bf16 v[116:119], v[128:131], v[168:171], v[116:119]
	v_mfma_f32_16x16x32_bf16 v[112:115], v[152:155], v[168:171], v[112:115]
	v_mfma_f32_16x16x32_bf16 v[92:95], v[128:131], v[176:179], v[92:95]
	v_mfma_f32_16x16x32_bf16 v[88:91], v[152:155], v[176:179], v[88:91]
	v_mfma_f32_16x16x32_bf16 v[68:71], v[128:131], v[208:211], v[68:71]
	v_mfma_f32_16x16x32_bf16 v[64:67], v[152:155], v[208:211], v[64:67]
	v_mfma_f32_16x16x32_bf16 v[140:143], v[132:135], v[164:167], v[140:143]
	v_mfma_f32_16x16x32_bf16 v[136:139], v[156:159], v[164:167], v[136:139]
	v_mfma_f32_16x16x32_bf16 v[116:119], v[132:135], v[172:175], v[116:119]
	v_mfma_f32_16x16x32_bf16 v[112:115], v[156:159], v[172:175], v[112:115]
	v_mfma_f32_16x16x32_bf16 v[92:95], v[132:135], v[180:183], v[92:95]
	v_mfma_f32_16x16x32_bf16 v[88:91], v[156:159], v[180:183], v[88:91]
	v_mfma_f32_16x16x32_bf16 v[68:71], v[132:135], v[220:223], v[68:71]
	v_mfma_f32_16x16x32_bf16 v[64:67], v[156:159], v[220:223], v[64:67]
	s_setprio 0
	s_barrier
	s_add_i32 s83, s78, s52
	v_lshl_add_u64 v[224:225], s[46:47], 0, v[186:187]
	s_mov_b32 m0, s83
	ds_read_b128 v[160:163], v218 offset:16384
	ds_read_b128 v[164:167], v218 offset:17408
	ds_read_b128 v[168:171], v218 offset:18432
	ds_read_b128 v[172:175], v218 offset:19456
	ds_read_b128 v[176:179], v218 offset:20480
	ds_read_b128 v[180:183], v218 offset:21504
	ds_read_b128 v[208:211], v218 offset:22528
	ds_read_b128 v[220:223], v218 offset:23552
	global_load_lds_dwordx4 v[224:225], off
	s_add_i32 m0, s83, 0x2000
	s_add_u32 s96, s46, 0x40000
	v_lshl_add_u64 v[226:227], s[46:47], 0, v[190:191]
	s_addc_u32 s97, s47, 0
	s_add_i32 s83, s79, s52
	global_load_lds_dwordx4 v[226:227], off
	v_lshl_add_u64 v[230:231], s[96:97], 0, v[186:187]
	s_mov_b32 m0, s83
	v_lshl_add_u64 v[232:233], s[48:49], 0, v[188:189]
	global_load_lds_dwordx4 v[230:231], off
	v_lshl_add_u64 v[230:231], s[96:97], 0, v[190:191]
	s_add_i32 m0, s83, 0x2000
	s_nop 0
	global_load_lds_dwordx4 v[230:231], off
	v_lshl_add_u64 v[230:231], s[48:49], 0, v[184:185]
	s_mov_b32 m0, s53
	s_nop 0
	global_load_lds_dwordx4 v[230:231], off
	s_mov_b32 m0, s54
	s_nop 0
	global_load_lds_dwordx4 v[232:233], off
	s_waitcnt vmcnt(8)
	s_waitcnt lgkmcnt(0)
	s_setprio 1
	v_mfma_f32_16x16x32_bf16 v[60:63], v[80:83], v[160:163], v[60:63]
	v_mfma_f32_16x16x32_bf16 v[56:59], v[104:107], v[160:163], v[56:59]
	v_mfma_f32_16x16x32_bf16 v[44:47], v[80:83], v[168:171], v[44:47]
	v_mfma_f32_16x16x32_bf16 v[40:43], v[104:107], v[168:171], v[40:43]
	v_mfma_f32_16x16x32_bf16 v[28:31], v[80:83], v[176:179], v[28:31]
	v_mfma_f32_16x16x32_bf16 v[24:27], v[104:107], v[176:179], v[24:27]
	v_mfma_f32_16x16x32_bf16 v[12:15], v[80:83], v[208:211], v[12:15]
	v_mfma_f32_16x16x32_bf16 v[8:11], v[104:107], v[208:211], v[8:11]
	v_mfma_f32_16x16x32_bf16 v[60:63], v[84:87], v[164:167], v[60:63]
	v_mfma_f32_16x16x32_bf16 v[56:59], v[108:111], v[164:167], v[56:59]
	v_mfma_f32_16x16x32_bf16 v[44:47], v[84:87], v[172:175], v[44:47]
	v_mfma_f32_16x16x32_bf16 v[40:43], v[108:111], v[172:175], v[40:43]
	v_mfma_f32_16x16x32_bf16 v[28:31], v[84:87], v[180:183], v[28:31]
	v_mfma_f32_16x16x32_bf16 v[24:27], v[108:111], v[180:183], v[24:27]
	v_mfma_f32_16x16x32_bf16 v[12:15], v[84:87], v[220:223], v[12:15]
	v_mfma_f32_16x16x32_bf16 v[8:11], v[108:111], v[220:223], v[8:11]
	v_mfma_f32_16x16x32_bf16 v[52:55], v[128:131], v[160:163], v[52:55]
	v_mfma_f32_16x16x32_bf16 v[48:51], v[152:155], v[160:163], v[48:51]
	v_mfma_f32_16x16x32_bf16 v[36:39], v[128:131], v[168:171], v[36:39]
	v_mfma_f32_16x16x32_bf16 v[32:35], v[152:155], v[168:171], v[32:35]
	v_mfma_f32_16x16x32_bf16 v[20:23], v[128:131], v[176:179], v[20:23]
	v_mfma_f32_16x16x32_bf16 v[16:19], v[152:155], v[176:179], v[16:19]
	v_mfma_f32_16x16x32_bf16 v[4:7], v[128:131], v[208:211], v[4:7]
	v_mfma_f32_16x16x32_bf16 v[0:3], v[152:155], v[208:211], v[0:3]
	v_mfma_f32_16x16x32_bf16 v[52:55], v[132:135], v[164:167], v[52:55]
	v_mfma_f32_16x16x32_bf16 v[48:51], v[156:159], v[164:167], v[48:51]
	v_mfma_f32_16x16x32_bf16 v[36:39], v[132:135], v[172:175], v[36:39]
	v_mfma_f32_16x16x32_bf16 v[32:35], v[156:159], v[172:175], v[32:35]
	v_mfma_f32_16x16x32_bf16 v[20:23], v[132:135], v[180:183], v[20:23]
	v_mfma_f32_16x16x32_bf16 v[16:19], v[156:159], v[180:183], v[16:19]
	v_mfma_f32_16x16x32_bf16 v[4:7], v[132:135], v[220:223], v[4:7]
	v_mfma_f32_16x16x32_bf16 v[0:3], v[156:159], v[220:223], v[0:3]
	s_setprio 0
	s_barrier
	s_add_i32 s83, 0, 0x18000
	s_add_i32 s96, 0, 0x1c000
	v_add_u32_e32 v108, s83, v213
	v_add_u32_e32 v156, s96, v213
	ds_read_b128 v[80:83], v108
	ds_read_b128 v[84:87], v108 offset:1024
	ds_read_b128 v[104:107], v108 offset:2048
	ds_read_b128 v[108:111], v108 offset:3072
	ds_read_b128 v[128:131], v156
	ds_read_b128 v[132:135], v156 offset:1024
	ds_read_b128 v[152:155], v156 offset:2048
	ds_read_b128 v[156:159], v156 offset:3072
	s_add_u32 s48, s48, 0x40000
	s_addc_u32 s49, s49, 0
	s_mov_b32 m0, s55
	v_lshl_add_u64 v[234:235], s[48:49], 0, v[184:185]
	ds_read_b128 v[160:163], v218 offset:32768
	ds_read_b128 v[164:167], v218 offset:33792
	ds_read_b128 v[168:171], v218 offset:34816
	ds_read_b128 v[172:175], v218 offset:35840
	ds_read_b128 v[176:179], v218 offset:36864
	ds_read_b128 v[180:183], v218 offset:37888
	ds_read_b128 v[208:211], v218 offset:38912
	ds_read_b128 v[220:223], v218 offset:39936
	global_load_lds_dwordx4 v[234:235], off
	v_lshl_add_u64 v[234:235], s[48:49], 0, v[188:189]
	s_mov_b32 m0, s56
	s_nop 0
	global_load_lds_dwordx4 v[234:235], off
	s_waitcnt vmcnt(8)
	s_waitcnt lgkmcnt(0)
	s_setprio 1
	v_mfma_f32_16x16x32_bf16 v[148:151], v[80:83], v[160:163], v[148:151]
	v_mfma_f32_16x16x32_bf16 v[144:147], v[104:107], v[160:163], v[144:147]
	v_mfma_f32_16x16x32_bf16 v[124:127], v[80:83], v[168:171], v[124:127]
	v_mfma_f32_16x16x32_bf16 v[120:123], v[104:107], v[168:171], v[120:123]
	v_mfma_f32_16x16x32_bf16 v[100:103], v[80:83], v[176:179], v[100:103]
	v_mfma_f32_16x16x32_bf16 v[96:99], v[104:107], v[176:179], v[96:99]
	v_mfma_f32_16x16x32_bf16 v[76:79], v[80:83], v[208:211], v[76:79]
	v_mfma_f32_16x16x32_bf16 v[72:75], v[104:107], v[208:211], v[72:75]
	v_mfma_f32_16x16x32_bf16 v[148:151], v[84:87], v[164:167], v[148:151]
	v_mfma_f32_16x16x32_bf16 v[144:147], v[108:111], v[164:167], v[144:147]
	v_mfma_f32_16x16x32_bf16 v[124:127], v[84:87], v[172:175], v[124:127]
	v_mfma_f32_16x16x32_bf16 v[120:123], v[108:111], v[172:175], v[120:123]
	v_mfma_f32_16x16x32_bf16 v[100:103], v[84:87], v[180:183], v[100:103]
	v_mfma_f32_16x16x32_bf16 v[96:99], v[108:111], v[180:183], v[96:99]
	v_mfma_f32_16x16x32_bf16 v[76:79], v[84:87], v[220:223], v[76:79]
	v_mfma_f32_16x16x32_bf16 v[72:75], v[108:111], v[220:223], v[72:75]
	v_mfma_f32_16x16x32_bf16 v[140:143], v[128:131], v[160:163], v[140:143]
	v_mfma_f32_16x16x32_bf16 v[136:139], v[152:155], v[160:163], v[136:139]
	v_mfma_f32_16x16x32_bf16 v[116:119], v[128:131], v[168:171], v[116:119]
	v_mfma_f32_16x16x32_bf16 v[112:115], v[152:155], v[168:171], v[112:115]
	v_mfma_f32_16x16x32_bf16 v[92:95], v[128:131], v[176:179], v[92:95]
	v_mfma_f32_16x16x32_bf16 v[88:91], v[152:155], v[176:179], v[88:91]
	v_mfma_f32_16x16x32_bf16 v[68:71], v[128:131], v[208:211], v[68:71]
	v_mfma_f32_16x16x32_bf16 v[64:67], v[152:155], v[208:211], v[64:67]
	v_mfma_f32_16x16x32_bf16 v[140:143], v[132:135], v[164:167], v[140:143]
	v_mfma_f32_16x16x32_bf16 v[136:139], v[156:159], v[164:167], v[136:139]
	v_mfma_f32_16x16x32_bf16 v[116:119], v[132:135], v[172:175], v[116:119]
	v_mfma_f32_16x16x32_bf16 v[112:115], v[156:159], v[172:175], v[112:115]
	v_mfma_f32_16x16x32_bf16 v[92:95], v[132:135], v[180:183], v[92:95]
	v_mfma_f32_16x16x32_bf16 v[88:91], v[156:159], v[180:183], v[88:91]
	v_mfma_f32_16x16x32_bf16 v[68:71], v[132:135], v[220:223], v[68:71]
	v_mfma_f32_16x16x32_bf16 v[64:67], v[156:159], v[220:223], v[64:67]
	s_setprio 0
	s_barrier
	s_add_i32 s48, s83, s52
	v_lshl_add_u64 v[224:225], v[224:225], 0, s[18:19]
	s_mov_b32 m0, s48
	ds_read_b128 v[160:163], v218 offset:49152
	ds_read_b128 v[164:167], v218 offset:50176
	ds_read_b128 v[168:171], v218 offset:51200
	ds_read_b128 v[172:175], v218 offset:52224
	ds_read_b128 v[176:179], v218 offset:53248
	ds_read_b128 v[180:183], v218 offset:54272
	ds_read_b128 v[208:211], v218 offset:55296
	ds_read_b128 v[220:223], v218 offset:56320
	global_load_lds_dwordx4 v[224:225], off
	s_add_i32 m0, s48, 0x2000
	s_add_u32 s46, s46, 0x40080
	v_lshl_add_u64 v[224:225], v[226:227], 0, s[18:19]
	s_addc_u32 s47, s47, 0
	s_add_i32 s48, s96, s52
	global_load_lds_dwordx4 v[224:225], off
	v_lshl_add_u64 v[224:225], s[46:47], 0, v[186:187]
	s_mov_b32 m0, s48
	s_nop 0
	global_load_lds_dwordx4 v[224:225], off
	v_lshl_add_u64 v[224:225], s[46:47], 0, v[190:191]
	s_add_i32 m0, s48, 0x2000
	s_nop 0
	global_load_lds_dwordx4 v[224:225], off
	v_lshl_add_u64 v[224:225], v[230:231], 0, s[18:19]
	s_mov_b32 m0, s68
	s_nop 0
	global_load_lds_dwordx4 v[224:225], off
	v_lshl_add_u64 v[224:225], v[232:233], 0, s[18:19]
	s_mov_b32 m0, s69
	s_nop 0
	global_load_lds_dwordx4 v[224:225], off
	s_waitcnt vmcnt(8)
	s_waitcnt lgkmcnt(0)
	s_setprio 1
	v_mfma_f32_16x16x32_bf16 v[60:63], v[80:83], v[160:163], v[60:63]
	v_mfma_f32_16x16x32_bf16 v[56:59], v[104:107], v[160:163], v[56:59]
	v_mfma_f32_16x16x32_bf16 v[44:47], v[80:83], v[168:171], v[44:47]
	v_mfma_f32_16x16x32_bf16 v[40:43], v[104:107], v[168:171], v[40:43]
	v_mfma_f32_16x16x32_bf16 v[28:31], v[80:83], v[176:179], v[28:31]
	v_mfma_f32_16x16x32_bf16 v[24:27], v[104:107], v[176:179], v[24:27]
	v_mfma_f32_16x16x32_bf16 v[12:15], v[80:83], v[208:211], v[12:15]
	v_mfma_f32_16x16x32_bf16 v[8:11], v[104:107], v[208:211], v[8:11]
	v_mfma_f32_16x16x32_bf16 v[60:63], v[84:87], v[164:167], v[60:63]
	v_mfma_f32_16x16x32_bf16 v[56:59], v[108:111], v[164:167], v[56:59]
	v_mfma_f32_16x16x32_bf16 v[44:47], v[84:87], v[172:175], v[44:47]
	v_mfma_f32_16x16x32_bf16 v[40:43], v[108:111], v[172:175], v[40:43]
	v_mfma_f32_16x16x32_bf16 v[28:31], v[84:87], v[180:183], v[28:31]
	v_mfma_f32_16x16x32_bf16 v[24:27], v[108:111], v[180:183], v[24:27]
	v_mfma_f32_16x16x32_bf16 v[12:15], v[84:87], v[220:223], v[12:15]
	v_mfma_f32_16x16x32_bf16 v[8:11], v[108:111], v[220:223], v[8:11]
	v_mfma_f32_16x16x32_bf16 v[52:55], v[128:131], v[160:163], v[52:55]
	v_mfma_f32_16x16x32_bf16 v[48:51], v[152:155], v[160:163], v[48:51]
	v_mfma_f32_16x16x32_bf16 v[36:39], v[128:131], v[168:171], v[36:39]
	v_mfma_f32_16x16x32_bf16 v[32:35], v[152:155], v[168:171], v[32:35]
	v_mfma_f32_16x16x32_bf16 v[20:23], v[128:131], v[176:179], v[20:23]
	v_mfma_f32_16x16x32_bf16 v[16:19], v[152:155], v[176:179], v[16:19]
	v_mfma_f32_16x16x32_bf16 v[4:7], v[128:131], v[208:211], v[4:7]
	v_mfma_f32_16x16x32_bf16 v[0:3], v[152:155], v[208:211], v[0:3]
	v_mfma_f32_16x16x32_bf16 v[52:55], v[132:135], v[164:167], v[52:55]
	v_mfma_f32_16x16x32_bf16 v[48:51], v[156:159], v[164:167], v[48:51]
	v_mfma_f32_16x16x32_bf16 v[36:39], v[132:135], v[172:175], v[36:39]
	v_mfma_f32_16x16x32_bf16 v[32:35], v[156:159], v[172:175], v[32:35]
	v_mfma_f32_16x16x32_bf16 v[20:23], v[132:135], v[180:183], v[20:23]
	v_mfma_f32_16x16x32_bf16 v[16:19], v[156:159], v[180:183], v[16:19]
	v_mfma_f32_16x16x32_bf16 v[4:7], v[132:135], v[220:223], v[4:7]
	v_mfma_f32_16x16x32_bf16 v[0:3], v[156:159], v[220:223], v[0:3]
	s_setprio 0
	s_barrier
	s_add_i32 s95, s95, 2
	s_add_u32 s44, s44, 0x100
	s_addc_u32 s45, s45, 0
	s_add_u32 s93, s93, 0x100
	s_addc_u32 s94, s94, 0
	s_cmp_gt_u32 s95, 13
	s_cbranch_scc0 .Lh0_4
	s_branch .Ljoin_4
.Lh1p_4:
	ds_read_b128 v[80:83], v216
	ds_read_b128 v[84:87], v216 offset:1024
	ds_read_b128 v[104:107], v216 offset:2048
	ds_read_b128 v[108:111], v216 offset:3072
	ds_read_b128 v[128:131], v217
	ds_read_b128 v[132:135], v217 offset:1024
	ds_read_b128 v[152:155], v217 offset:2048
	ds_read_b128 v[156:159], v217 offset:3072
	s_add_u32 s46, s44, 0xfffc0080
	s_addc_u32 s47, s45, -1
	s_cmp_eq_u32 s95, 12
	s_cselect_b32 s49, s23, s47
	s_cselect_b32 s48, s43, s46
	s_cselect_b32 s47, s37, s94
	s_cselect_b32 s46, s92, s93
	v_lshl_add_u64 v[224:225], s[44:45], 0, v[194:195]
	s_add_i32 m0, s53, 0xc000
	ds_read_b128 v[160:163], v218
	ds_read_b128 v[164:167], v218 offset:1024
	ds_read_b128 v[168:171], v218 offset:2048
	ds_read_b128 v[172:175], v218 offset:3072
	ds_read_b128 v[176:179], v218 offset:4096
	ds_read_b128 v[180:183], v218 offset:5120
	ds_read_b128 v[208:211], v218 offset:6144
	ds_read_b128 v[220:223], v218 offset:7168
	global_load_lds_dwordx4 v[224:225], off
	v_lshl_add_u64 v[224:225], s[44:45], 0, v[196:197]
	s_add_i32 m0, s53, 0xe000
	s_nop 0
	global_load_lds_dwordx4 v[224:225], off
	s_waitcnt vmcnt(8)
	s_waitcnt lgkmcnt(0)
	s_barrier
	s_setprio 2
	v_mfma_f32_16x16x32_bf16 v[148:151], v[80:83], v[160:163], 0
	v_mfma_f32_16x16x32_bf16 v[144:147], v[104:107], v[160:163], 0
	v_mfma_f32_16x16x32_bf16 v[124:127], v[80:83], v[168:171], 0
	v_mfma_f32_16x16x32_bf16 v[120:123], v[104:107], v[168:171], 0
	v_mfma_f32_16x16x32_bf16 v[100:103], v[80:83], v[176:179], 0
	v_mfma_f32_16x16x32_bf16 v[96:99], v[104:107], v[176:179], 0
	v_mfma_f32_16x16x32_bf16 v[76:79], v[80:83], v[208:211], 0
	v_mfma_f32_16x16x32_bf16 v[72:75], v[104:107], v[208:211], 0
	v_mfma_f32_16x16x32_bf16 v[148:151], v[84:87], v[164:167], v[148:151]
	v_mfma_f32_16x16x32_bf16 v[144:147], v[108:111], v[164:167], v[144:147]
	v_mfma_f32_16x16x32_bf16 v[124:127], v[84:87], v[172:175], v[124:127]
	v_mfma_f32_16x16x32_bf16 v[120:123], v[108:111], v[172:175], v[120:123]
	v_mfma_f32_16x16x32_bf16 v[100:103], v[84:87], v[180:183], v[100:103]
	v_mfma_f32_16x16x32_bf16 v[96:99], v[108:111], v[180:183], v[96:99]
	v_mfma_f32_16x16x32_bf16 v[76:79], v[84:87], v[220:223], v[76:79]
	v_mfma_f32_16x16x32_bf16 v[72:75], v[108:111], v[220:223], v[72:75]
	v_mfma_f32_16x16x32_bf16 v[140:143], v[128:131], v[160:163], 0
	v_mfma_f32_16x16x32_bf16 v[136:139], v[152:155], v[160:163], 0
	v_mfma_f32_16x16x32_bf16 v[116:119], v[128:131], v[168:171], 0
	v_mfma_f32_16x16x32_bf16 v[112:115], v[152:155], v[168:171], 0
	v_mfma_f32_16x16x32_bf16 v[92:95], v[128:131], v[176:179], 0
	v_mfma_f32_16x16x32_bf16 v[88:91], v[152:155], v[176:179], 0
	v_mfma_f32_16x16x32_bf16 v[68:71], v[128:131], v[208:211], 0
	v_mfma_f32_16x16x32_bf16 v[64:67], v[152:155], v[208:211], 0
	v_mfma_f32_16x16x32_bf16 v[140:143], v[132:135], v[164:167], v[140:143]
	v_mfma_f32_16x16x32_bf16 v[136:139], v[156:159], v[164:167], v[136:139]
	v_mfma_f32_16x16x32_bf16 v[116:119], v[132:135], v[172:175], v[116:119]
	v_mfma_f32_16x16x32_bf16 v[112:115], v[156:159], v[172:175], v[112:115]
	v_mfma_f32_16x16x32_bf16 v[92:95], v[132:135], v[180:183], v[92:95]
	v_mfma_f32_16x16x32_bf16 v[88:91], v[156:159], v[180:183], v[88:91]
	v_mfma_f32_16x16x32_bf16 v[68:71], v[132:135], v[220:223], v[68:71]
	v_mfma_f32_16x16x32_bf16 v[64:67], v[156:159], v[220:223], v[64:67]
	s_setprio 0
	s_add_i32 s83, s78, s52
	v_lshl_add_u64 v[224:225], s[46:47], 0, v[186:187]
	s_mov_b32 m0, s83
	ds_read_b128 v[160:163], v218 offset:16384
	ds_read_b128 v[164:167], v218 offset:17408
	ds_read_b128 v[168:171], v218 offset:18432
	ds_read_b128 v[172:175], v218 offset:19456
	ds_read_b128 v[176:179], v218 offset:20480
	ds_read_b128 v[180:183], v218 offset:21504
	ds_read_b128 v[208:211], v218 offset:22528
	ds_read_b128 v[220:223], v218 offset:23552
	global_load_lds_dwordx4 v[224:225], off
	s_add_i32 m0, s83, 0x2000
	s_add_u32 s96, s46, 0x40000
	v_lshl_add_u64 v[226:227], s[46:47], 0, v[190:191]
	s_addc_u32 s97, s47, 0
	s_add_i32 s83, s79, s52
	global_load_lds_dwordx4 v[226:227], off
	v_lshl_add_u64 v[230:231], s[96:97], 0, v[186:187]
	s_mov_b32 m0, s83
	v_lshl_add_u64 v[232:233], s[48:49], 0, v[188:189]
	global_load_lds_dwordx4 v[230:231], off
	v_lshl_add_u64 v[230:231], s[96:97], 0, v[190:191]
	s_add_i32 m0, s83, 0x2000
	s_nop 0
	global_load_lds_dwordx4 v[230:231], off
	v_lshl_add_u64 v[230:231], s[48:49], 0, v[184:185]
	s_mov_b32 m0, s53
	s_nop 0
	global_load_lds_dwordx4 v[230:231], off
	s_mov_b32 m0, s54
	s_nop 0
	global_load_lds_dwordx4 v[232:233], off
	s_waitcnt vmcnt(8)
	s_waitcnt lgkmcnt(0)
	s_barrier
	s_setprio 2
	v_mfma_f32_16x16x32_bf16 v[60:63], v[80:83], v[160:163], 0
	v_mfma_f32_16x16x32_bf16 v[56:59], v[104:107], v[160:163], 0
	v_mfma_f32_16x16x32_bf16 v[44:47], v[80:83], v[168:171], 0
	v_mfma_f32_16x16x32_bf16 v[40:43], v[104:107], v[168:171], 0
	v_mfma_f32_16x16x32_bf16 v[28:31], v[80:83], v[176:179], 0
	v_mfma_f32_16x16x32_bf16 v[24:27], v[104:107], v[176:179], 0
	v_mfma_f32_16x16x32_bf16 v[12:15], v[80:83], v[208:211], 0
	v_mfma_f32_16x16x32_bf16 v[8:11], v[104:107], v[208:211], 0
	v_mfma_f32_16x16x32_bf16 v[60:63], v[84:87], v[164:167], v[60:63]
	v_mfma_f32_16x16x32_bf16 v[56:59], v[108:111], v[164:167], v[56:59]
	v_mfma_f32_16x16x32_bf16 v[44:47], v[84:87], v[172:175], v[44:47]
	v_mfma_f32_16x16x32_bf16 v[40:43], v[108:111], v[172:175], v[40:43]
	v_mfma_f32_16x16x32_bf16 v[28:31], v[84:87], v[180:183], v[28:31]
	v_mfma_f32_16x16x32_bf16 v[24:27], v[108:111], v[180:183], v[24:27]
	v_mfma_f32_16x16x32_bf16 v[12:15], v[84:87], v[220:223], v[12:15]
	v_mfma_f32_16x16x32_bf16 v[8:11], v[108:111], v[220:223], v[8:11]
	v_mfma_f32_16x16x32_bf16 v[52:55], v[128:131], v[160:163], 0
	v_mfma_f32_16x16x32_bf16 v[48:51], v[152:155], v[160:163], 0
	v_mfma_f32_16x16x32_bf16 v[36:39], v[128:131], v[168:171], 0
	v_mfma_f32_16x16x32_bf16 v[32:35], v[152:155], v[168:171], 0
	v_mfma_f32_16x16x32_bf16 v[20:23], v[128:131], v[176:179], 0
	v_mfma_f32_16x16x32_bf16 v[16:19], v[152:155], v[176:179], 0
	v_mfma_f32_16x16x32_bf16 v[4:7], v[128:131], v[208:211], 0
	v_mfma_f32_16x16x32_bf16 v[0:3], v[152:155], v[208:211], 0
	v_mfma_f32_16x16x32_bf16 v[52:55], v[132:135], v[164:167], v[52:55]
	v_mfma_f32_16x16x32_bf16 v[48:51], v[156:159], v[164:167], v[48:51]
	v_mfma_f32_16x16x32_bf16 v[36:39], v[132:135], v[172:175], v[36:39]
	v_mfma_f32_16x16x32_bf16 v[32:35], v[156:159], v[172:175], v[32:35]
	v_mfma_f32_16x16x32_bf16 v[20:23], v[132:135], v[180:183], v[20:23]
	v_mfma_f32_16x16x32_bf16 v[16:19], v[156:159], v[180:183], v[16:19]
	v_mfma_f32_16x16x32_bf16 v[4:7], v[132:135], v[220:223], v[4:7]
	v_mfma_f32_16x16x32_bf16 v[0:3], v[156:159], v[220:223], v[0:3]
	s_setprio 0
	s_add_i32 s83, 0, 0x18000
	s_add_i32 s96, 0, 0x1c000
	v_add_u32_e32 v108, s83, v213
	v_add_u32_e32 v156, s96, v213
	ds_read_b128 v[80:83], v108
	ds_read_b128 v[84:87], v108 offset:1024
	ds_read_b128 v[104:107], v108 offset:2048
	ds_read_b128 v[108:111], v108 offset:3072
	ds_read_b128 v[128:131], v156
	ds_read_b128 v[132:135], v156 offset:1024
	ds_read_b128 v[152:155], v156 offset:2048
	ds_read_b128 v[156:159], v156 offset:3072
	s_add_u32 s48, s48, 0x40000
	s_addc_u32 s49, s49, 0
	s_mov_b32 m0, s55
	v_lshl_add_u64 v[234:235], s[48:49], 0, v[184:185]
	ds_read_b128 v[160:163], v218 offset:32768
	ds_read_b128 v[164:167], v218 offset:33792
	ds_read_b128 v[168:171], v218 offset:34816
	ds_read_b128 v[172:175], v218 offset:35840
	ds_read_b128 v[176:179], v218 offset:36864
	ds_read_b128 v[180:183], v218 offset:37888
	ds_read_b128 v[208:211], v218 offset:38912
	ds_read_b128 v[220:223], v218 offset:39936
	global_load_lds_dwordx4 v[234:235], off
	v_lshl_add_u64 v[234:235], s[48:49], 0, v[188:189]
	s_mov_b32 m0, s56
	s_nop 0
	global_load_lds_dwordx4 v[234:235], off
	s_waitcnt vmcnt(8)
	s_waitcnt lgkmcnt(0)
	s_barrier
	s_setprio 2
	v_mfma_f32_16x16x32_bf16 v[148:151], v[80:83], v[160:163], v[148:151]
	v_mfma_f32_16x16x32_bf16 v[144:147], v[104:107], v[160:163], v[144:147]
	v_mfma_f32_16x16x32_bf16 v[124:127], v[80:83], v[168:171], v[124:127]
	v_mfma_f32_16x16x32_bf16 v[120:123], v[104:107], v[168:171], v[120:123]
	v_mfma_f32_16x16x32_bf16 v[100:103], v[80:83], v[176:179], v[100:103]
	v_mfma_f32_16x16x32_bf16 v[96:99], v[104:107], v[176:179], v[96:99]
	v_mfma_f32_16x16x32_bf16 v[76:79], v[80:83], v[208:211], v[76:79]
	v_mfma_f32_16x16x32_bf16 v[72:75], v[104:107], v[208:211], v[72:75]
	v_mfma_f32_16x16x32_bf16 v[148:151], v[84:87], v[164:167], v[148:151]
	v_mfma_f32_16x16x32_bf16 v[144:147], v[108:111], v[164:167], v[144:147]
	v_mfma_f32_16x16x32_bf16 v[124:127], v[84:87], v[172:175], v[124:127]
	v_mfma_f32_16x16x32_bf16 v[120:123], v[108:111], v[172:175], v[120:123]
	v_mfma_f32_16x16x32_bf16 v[100:103], v[84:87], v[180:183], v[100:103]
	v_mfma_f32_16x16x32_bf16 v[96:99], v[108:111], v[180:183], v[96:99]
	v_mfma_f32_16x16x32_bf16 v[76:79], v[84:87], v[220:223], v[76:79]
	v_mfma_f32_16x16x32_bf16 v[72:75], v[108:111], v[220:223], v[72:75]
	v_mfma_f32_16x16x32_bf16 v[140:143], v[128:131], v[160:163], v[140:143]
	v_mfma_f32_16x16x32_bf16 v[136:139], v[152:155], v[160:163], v[136:139]
	v_mfma_f32_16x16x32_bf16 v[116:119], v[128:131], v[168:171], v[116:119]
	v_mfma_f32_16x16x32_bf16 v[112:115], v[152:155], v[168:171], v[112:115]
	v_mfma_f32_16x16x32_bf16 v[92:95], v[128:131], v[176:179], v[92:95]
	v_mfma_f32_16x16x32_bf16 v[88:91], v[152:155], v[176:179], v[88:91]
	v_mfma_f32_16x16x32_bf16 v[68:71], v[128:131], v[208:211], v[68:71]
	v_mfma_f32_16x16x32_bf16 v[64:67], v[152:155], v[208:211], v[64:67]
	v_mfma_f32_16x16x32_bf16 v[140:143], v[132:135], v[164:167], v[140:143]
	v_mfma_f32_16x16x32_bf16 v[136:139], v[156:159], v[164:167], v[136:139]
	v_mfma_f32_16x16x32_bf16 v[116:119], v[132:135], v[172:175], v[116:119]
	v_mfma_f32_16x16x32_bf16 v[112:115], v[156:159], v[172:175], v[112:115]
	v_mfma_f32_16x16x32_bf16 v[92:95], v[132:135], v[180:183], v[92:95]
	v_mfma_f32_16x16x32_bf16 v[88:91], v[156:159], v[180:183], v[88:91]
	v_mfma_f32_16x16x32_bf16 v[68:71], v[132:135], v[220:223], v[68:71]
	v_mfma_f32_16x16x32_bf16 v[64:67], v[156:159], v[220:223], v[64:67]
	s_setprio 0
	s_add_i32 s48, s83, s52
	v_lshl_add_u64 v[224:225], v[224:225], 0, s[18:19]
	s_mov_b32 m0, s48
	ds_read_b128 v[160:163], v218 offset:49152
	ds_read_b128 v[164:167], v218 offset:50176
	ds_read_b128 v[168:171], v218 offset:51200
	ds_read_b128 v[172:175], v218 offset:52224
	ds_read_b128 v[176:179], v218 offset:53248
	ds_read_b128 v[180:183], v218 offset:54272
	ds_read_b128 v[208:211], v218 offset:55296
	ds_read_b128 v[220:223], v218 offset:56320
	global_load_lds_dwordx4 v[224:225], off
	s_add_i32 m0, s48, 0x2000
	s_add_u32 s46, s46, 0x40080
	v_lshl_add_u64 v[224:225], v[226:227], 0, s[18:19]
	s_addc_u32 s47, s47, 0
	s_add_i32 s48, s96, s52
	global_load_lds_dwordx4 v[224:225], off
	v_lshl_add_u64 v[224:225], s[46:47], 0, v[186:187]
	s_mov_b32 m0, s48
	s_nop 0
	global_load_lds_dwordx4 v[224:225], off
	v_lshl_add_u64 v[224:225], s[46:47], 0, v[190:191]
	s_add_i32 m0, s48, 0x2000
	s_nop 0
	global_load_lds_dwordx4 v[224:225], off
	v_lshl_add_u64 v[224:225], v[230:231], 0, s[18:19]
	s_mov_b32 m0, s68
	s_nop 0
	global_load_lds_dwordx4 v[224:225], off
	v_lshl_add_u64 v[224:225], v[232:233], 0, s[18:19]
	s_mov_b32 m0, s69
	s_nop 0
	global_load_lds_dwordx4 v[224:225], off
	s_waitcnt vmcnt(8)
	s_waitcnt lgkmcnt(0)
	s_barrier
	s_setprio 2
	v_mfma_f32_16x16x32_bf16 v[60:63], v[80:83], v[160:163], v[60:63]
	v_mfma_f32_16x16x32_bf16 v[56:59], v[104:107], v[160:163], v[56:59]
	v_mfma_f32_16x16x32_bf16 v[44:47], v[80:83], v[168:171], v[44:47]
	v_mfma_f32_16x16x32_bf16 v[40:43], v[104:107], v[168:171], v[40:43]
	v_mfma_f32_16x16x32_bf16 v[28:31], v[80:83], v[176:179], v[28:31]
	v_mfma_f32_16x16x32_bf16 v[24:27], v[104:107], v[176:179], v[24:27]
	v_mfma_f32_16x16x32_bf16 v[12:15], v[80:83], v[208:211], v[12:15]
	v_mfma_f32_16x16x32_bf16 v[8:11], v[104:107], v[208:211], v[8:11]
	v_mfma_f32_16x16x32_bf16 v[60:63], v[84:87], v[164:167], v[60:63]
	v_mfma_f32_16x16x32_bf16 v[56:59], v[108:111], v[164:167], v[56:59]
	v_mfma_f32_16x16x32_bf16 v[44:47], v[84:87], v[172:175], v[44:47]
	v_mfma_f32_16x16x32_bf16 v[40:43], v[108:111], v[172:175], v[40:43]
	v_mfma_f32_16x16x32_bf16 v[28:31], v[84:87], v[180:183], v[28:31]
	v_mfma_f32_16x16x32_bf16 v[24:27], v[108:111], v[180:183], v[24:27]
	v_mfma_f32_16x16x32_bf16 v[12:15], v[84:87], v[220:223], v[12:15]
	v_mfma_f32_16x16x32_bf16 v[8:11], v[108:111], v[220:223], v[8:11]
	v_mfma_f32_16x16x32_bf16 v[52:55], v[128:131], v[160:163], v[52:55]
	v_mfma_f32_16x16x32_bf16 v[48:51], v[152:155], v[160:163], v[48:51]
	v_mfma_f32_16x16x32_bf16 v[36:39], v[128:131], v[168:171], v[36:39]
	v_mfma_f32_16x16x32_bf16 v[32:35], v[152:155], v[168:171], v[32:35]
	v_mfma_f32_16x16x32_bf16 v[20:23], v[128:131], v[176:179], v[20:23]
	v_mfma_f32_16x16x32_bf16 v[16:19], v[152:155], v[176:179], v[16:19]
	v_mfma_f32_16x16x32_bf16 v[4:7], v[128:131], v[208:211], v[4:7]
	v_mfma_f32_16x16x32_bf16 v[0:3], v[152:155], v[208:211], v[0:3]
	v_mfma_f32_16x16x32_bf16 v[52:55], v[132:135], v[164:167], v[52:55]
	v_mfma_f32_16x16x32_bf16 v[48:51], v[156:159], v[164:167], v[48:51]
	v_mfma_f32_16x16x32_bf16 v[36:39], v[132:135], v[172:175], v[36:39]
	v_mfma_f32_16x16x32_bf16 v[32:35], v[156:159], v[172:175], v[32:35]
	v_mfma_f32_16x16x32_bf16 v[20:23], v[132:135], v[180:183], v[20:23]
	v_mfma_f32_16x16x32_bf16 v[16:19], v[156:159], v[180:183], v[16:19]
	v_mfma_f32_16x16x32_bf16 v[4:7], v[132:135], v[220:223], v[4:7]
	v_mfma_f32_16x16x32_bf16 v[0:3], v[156:159], v[220:223], v[0:3]
	s_setprio 0
	s_add_i32 s95, s95, 2
	s_add_u32 s44, s44, 0x100
	s_addc_u32 s45, s45, 0
	s_add_u32 s93, s93, 0x100
	s_addc_u32 s94, s94, 0
	s_cmp_gt_u32 s95, 13
.Lh1_4:
	ds_read_b128 v[80:83], v216
	ds_read_b128 v[84:87], v216 offset:1024
	ds_read_b128 v[104:107], v216 offset:2048
	ds_read_b128 v[108:111], v216 offset:3072
	ds_read_b128 v[128:131], v217
	ds_read_b128 v[132:135], v217 offset:1024
	ds_read_b128 v[152:155], v217 offset:2048
	ds_read_b128 v[156:159], v217 offset:3072
	s_add_u32 s46, s44, 0xfffc0080
	s_addc_u32 s47, s45, -1
	s_cmp_eq_u32 s95, 12
	s_cselect_b32 s49, s23, s47
	s_cselect_b32 s48, s43, s46
	s_cselect_b32 s47, s37, s94
	s_cselect_b32 s46, s92, s93
	v_lshl_add_u64 v[224:225], s[44:45], 0, v[194:195]
	s_add_i32 m0, s53, 0xc000
	ds_read_b128 v[160:163], v218
	ds_read_b128 v[164:167], v218 offset:1024
	ds_read_b128 v[168:171], v218 offset:2048
	ds_read_b128 v[172:175], v218 offset:3072
	ds_read_b128 v[176:179], v218 offset:4096
	ds_read_b128 v[180:183], v218 offset:5120
	ds_read_b128 v[208:211], v218 offset:6144
	ds_read_b128 v[220:223], v218 offset:7168
	global_load_lds_dwordx4 v[224:225], off
	v_lshl_add_u64 v[224:225], s[44:45], 0, v[196:197]
	s_add_i32 m0, s53, 0xe000
	s_nop 0
	global_load_lds_dwordx4 v[224:225], off
	s_waitcnt vmcnt(8)
	s_waitcnt lgkmcnt(0)
	s_barrier
	s_setprio 2
	v_mfma_f32_16x16x32_bf16 v[148:151], v[80:83], v[160:163], v[148:151]
	v_mfma_f32_16x16x32_bf16 v[144:147], v[104:107], v[160:163], v[144:147]
	v_mfma_f32_16x16x32_bf16 v[124:127], v[80:83], v[168:171], v[124:127]
	v_mfma_f32_16x16x32_bf16 v[120:123], v[104:107], v[168:171], v[120:123]
	v_mfma_f32_16x16x32_bf16 v[100:103], v[80:83], v[176:179], v[100:103]
	v_mfma_f32_16x16x32_bf16 v[96:99], v[104:107], v[176:179], v[96:99]
	v_mfma_f32_16x16x32_bf16 v[76:79], v[80:83], v[208:211], v[76:79]
	v_mfma_f32_16x16x32_bf16 v[72:75], v[104:107], v[208:211], v[72:75]
	v_mfma_f32_16x16x32_bf16 v[148:151], v[84:87], v[164:167], v[148:151]
	v_mfma_f32_16x16x32_bf16 v[144:147], v[108:111], v[164:167], v[144:147]
	v_mfma_f32_16x16x32_bf16 v[124:127], v[84:87], v[172:175], v[124:127]
	v_mfma_f32_16x16x32_bf16 v[120:123], v[108:111], v[172:175], v[120:123]
	v_mfma_f32_16x16x32_bf16 v[100:103], v[84:87], v[180:183], v[100:103]
	v_mfma_f32_16x16x32_bf16 v[96:99], v[108:111], v[180:183], v[96:99]
	v_mfma_f32_16x16x32_bf16 v[76:79], v[84:87], v[220:223], v[76:79]
	v_mfma_f32_16x16x32_bf16 v[72:75], v[108:111], v[220:223], v[72:75]
	v_mfma_f32_16x16x32_bf16 v[140:143], v[128:131], v[160:163], v[140:143]
	v_mfma_f32_16x16x32_bf16 v[136:139], v[152:155], v[160:163], v[136:139]
	v_mfma_f32_16x16x32_bf16 v[116:119], v[128:131], v[168:171], v[116:119]
	v_mfma_f32_16x16x32_bf16 v[112:115], v[152:155], v[168:171], v[112:115]
	v_mfma_f32_16x16x32_bf16 v[92:95], v[128:131], v[176:179], v[92:95]
	v_mfma_f32_16x16x32_bf16 v[88:91], v[152:155], v[176:179], v[88:91]
	v_mfma_f32_16x16x32_bf16 v[68:71], v[128:131], v[208:211], v[68:71]
	v_mfma_f32_16x16x32_bf16 v[64:67], v[152:155], v[208:211], v[64:67]
	v_mfma_f32_16x16x32_bf16 v[140:143], v[132:135], v[164:167], v[140:143]
	v_mfma_f32_16x16x32_bf16 v[136:139], v[156:159], v[164:167], v[136:139]
	v_mfma_f32_16x16x32_bf16 v[116:119], v[132:135], v[172:175], v[116:119]
	v_mfma_f32_16x16x32_bf16 v[112:115], v[156:159], v[172:175], v[112:115]
	v_mfma_f32_16x16x32_bf16 v[92:95], v[132:135], v[180:183], v[92:95]
	v_mfma_f32_16x16x32_bf16 v[88:91], v[156:159], v[180:183], v[88:91]
	v_mfma_f32_16x16x32_bf16 v[68:71], v[132:135], v[220:223], v[68:71]
	v_mfma_f32_16x16x32_bf16 v[64:67], v[156:159], v[220:223], v[64:67]
	s_setprio 0
	s_add_i32 s83, s78, s52
	v_lshl_add_u64 v[224:225], s[46:47], 0, v[186:187]
	s_mov_b32 m0, s83
	ds_read_b128 v[160:163], v218 offset:16384
	ds_read_b128 v[164:167], v218 offset:17408
	ds_read_b128 v[168:171], v218 offset:18432
	ds_read_b128 v[172:175], v218 offset:19456
	ds_read_b128 v[176:179], v218 offset:20480
	ds_read_b128 v[180:183], v218 offset:21504
	ds_read_b128 v[208:211], v218 offset:22528
	ds_read_b128 v[220:223], v218 offset:23552
	global_load_lds_dwordx4 v[224:225], off
	s_add_i32 m0, s83, 0x2000
	s_add_u32 s96, s46, 0x40000
	v_lshl_add_u64 v[226:227], s[46:47], 0, v[190:191]
	s_addc_u32 s97, s47, 0
	s_add_i32 s83, s79, s52
	global_load_lds_dwordx4 v[226:227], off
	v_lshl_add_u64 v[230:231], s[96:97], 0, v[186:187]
	s_mov_b32 m0, s83
	v_lshl_add_u64 v[232:233], s[48:49], 0, v[188:189]
	global_load_lds_dwordx4 v[230:231], off
	v_lshl_add_u64 v[230:231], s[96:97], 0, v[190:191]
	s_add_i32 m0, s83, 0x2000
	s_nop 0
	global_load_lds_dwordx4 v[230:231], off
	v_lshl_add_u64 v[230:231], s[48:49], 0, v[184:185]
	s_mov_b32 m0, s53
	s_nop 0
	global_load_lds_dwordx4 v[230:231], off
	s_mov_b32 m0, s54
	s_nop 0
	global_load_lds_dwordx4 v[232:233], off
	s_waitcnt vmcnt(8)
	s_waitcnt lgkmcnt(0)
	s_barrier
	s_setprio 2
	v_mfma_f32_16x16x32_bf16 v[60:63], v[80:83], v[160:163], v[60:63]
	v_mfma_f32_16x16x32_bf16 v[56:59], v[104:107], v[160:163], v[56:59]
	v_mfma_f32_16x16x32_bf16 v[44:47], v[80:83], v[168:171], v[44:47]
	v_mfma_f32_16x16x32_bf16 v[40:43], v[104:107], v[168:171], v[40:43]
	v_mfma_f32_16x16x32_bf16 v[28:31], v[80:83], v[176:179], v[28:31]
	v_mfma_f32_16x16x32_bf16 v[24:27], v[104:107], v[176:179], v[24:27]
	v_mfma_f32_16x16x32_bf16 v[12:15], v[80:83], v[208:211], v[12:15]
	v_mfma_f32_16x16x32_bf16 v[8:11], v[104:107], v[208:211], v[8:11]
	v_mfma_f32_16x16x32_bf16 v[60:63], v[84:87], v[164:167], v[60:63]
	v_mfma_f32_16x16x32_bf16 v[56:59], v[108:111], v[164:167], v[56:59]
	v_mfma_f32_16x16x32_bf16 v[44:47], v[84:87], v[172:175], v[44:47]
	v_mfma_f32_16x16x32_bf16 v[40:43], v[108:111], v[172:175], v[40:43]
	v_mfma_f32_16x16x32_bf16 v[28:31], v[84:87], v[180:183], v[28:31]
	v_mfma_f32_16x16x32_bf16 v[24:27], v[108:111], v[180:183], v[24:27]
	v_mfma_f32_16x16x32_bf16 v[12:15], v[84:87], v[220:223], v[12:15]
	v_mfma_f32_16x16x32_bf16 v[8:11], v[108:111], v[220:223], v[8:11]
	v_mfma_f32_16x16x32_bf16 v[52:55], v[128:131], v[160:163], v[52:55]
	v_mfma_f32_16x16x32_bf16 v[48:51], v[152:155], v[160:163], v[48:51]
	v_mfma_f32_16x16x32_bf16 v[36:39], v[128:131], v[168:171], v[36:39]
	v_mfma_f32_16x16x32_bf16 v[32:35], v[152:155], v[168:171], v[32:35]
	v_mfma_f32_16x16x32_bf16 v[20:23], v[128:131], v[176:179], v[20:23]
	v_mfma_f32_16x16x32_bf16 v[16:19], v[152:155], v[176:179], v[16:19]
	v_mfma_f32_16x16x32_bf16 v[4:7], v[128:131], v[208:211], v[4:7]
	v_mfma_f32_16x16x32_bf16 v[0:3], v[152:155], v[208:211], v[0:3]
	v_mfma_f32_16x16x32_bf16 v[52:55], v[132:135], v[164:167], v[52:55]
	v_mfma_f32_16x16x32_bf16 v[48:51], v[156:159], v[164:167], v[48:51]
	v_mfma_f32_16x16x32_bf16 v[36:39], v[132:135], v[172:175], v[36:39]
	v_mfma_f32_16x16x32_bf16 v[32:35], v[156:159], v[172:175], v[32:35]
	v_mfma_f32_16x16x32_bf16 v[20:23], v[132:135], v[180:183], v[20:23]
	v_mfma_f32_16x16x32_bf16 v[16:19], v[156:159], v[180:183], v[16:19]
	v_mfma_f32_16x16x32_bf16 v[4:7], v[132:135], v[220:223], v[4:7]
	v_mfma_f32_16x16x32_bf16 v[0:3], v[156:159], v[220:223], v[0:3]
	s_setprio 0
	s_add_i32 s83, 0, 0x18000
	s_add_i32 s96, 0, 0x1c000
	v_add_u32_e32 v108, s83, v213
	v_add_u32_e32 v156, s96, v213
	ds_read_b128 v[80:83], v108
	ds_read_b128 v[84:87], v108 offset:1024
	ds_read_b128 v[104:107], v108 offset:2048
	ds_read_b128 v[108:111], v108 offset:3072
	ds_read_b128 v[128:131], v156
	ds_read_b128 v[132:135], v156 offset:1024
	ds_read_b128 v[152:155], v156 offset:2048
	ds_read_b128 v[156:159], v156 offset:3072
	s_add_u32 s48, s48, 0x40000
	s_addc_u32 s49, s49, 0
	s_mov_b32 m0, s55
	v_lshl_add_u64 v[234:235], s[48:49], 0, v[184:185]
	ds_read_b128 v[160:163], v218 offset:32768
	ds_read_b128 v[164:167], v218 offset:33792
	ds_read_b128 v[168:171], v218 offset:34816
	ds_read_b128 v[172:175], v218 offset:35840
	ds_read_b128 v[176:179], v218 offset:36864
	ds_read_b128 v[180:183], v218 offset:37888
	ds_read_b128 v[208:211], v218 offset:38912
	ds_read_b128 v[220:223], v218 offset:39936
	global_load_lds_dwordx4 v[234:235], off
	v_lshl_add_u64 v[234:235], s[48:49], 0, v[188:189]
	s_mov_b32 m0, s56
	s_nop 0
	global_load_lds_dwordx4 v[234:235], off
	s_waitcnt vmcnt(8)
	s_waitcnt lgkmcnt(0)
	s_barrier
	s_setprio 2
	v_mfma_f32_16x16x32_bf16 v[148:151], v[80:83], v[160:163], v[148:151]
	v_mfma_f32_16x16x32_bf16 v[144:147], v[104:107], v[160:163], v[144:147]
	v_mfma_f32_16x16x32_bf16 v[124:127], v[80:83], v[168:171], v[124:127]
	v_mfma_f32_16x16x32_bf16 v[120:123], v[104:107], v[168:171], v[120:123]
	v_mfma_f32_16x16x32_bf16 v[100:103], v[80:83], v[176:179], v[100:103]
	v_mfma_f32_16x16x32_bf16 v[96:99], v[104:107], v[176:179], v[96:99]
	v_mfma_f32_16x16x32_bf16 v[76:79], v[80:83], v[208:211], v[76:79]
	v_mfma_f32_16x16x32_bf16 v[72:75], v[104:107], v[208:211], v[72:75]
	v_mfma_f32_16x16x32_bf16 v[148:151], v[84:87], v[164:167], v[148:151]
	v_mfma_f32_16x16x32_bf16 v[144:147], v[108:111], v[164:167], v[144:147]
	v_mfma_f32_16x16x32_bf16 v[124:127], v[84:87], v[172:175], v[124:127]
	v_mfma_f32_16x16x32_bf16 v[120:123], v[108:111], v[172:175], v[120:123]
	v_mfma_f32_16x16x32_bf16 v[100:103], v[84:87], v[180:183], v[100:103]
	v_mfma_f32_16x16x32_bf16 v[96:99], v[108:111], v[180:183], v[96:99]
	v_mfma_f32_16x16x32_bf16 v[76:79], v[84:87], v[220:223], v[76:79]
	v_mfma_f32_16x16x32_bf16 v[72:75], v[108:111], v[220:223], v[72:75]
	v_mfma_f32_16x16x32_bf16 v[140:143], v[128:131], v[160:163], v[140:143]
	v_mfma_f32_16x16x32_bf16 v[136:139], v[152:155], v[160:163], v[136:139]
	v_mfma_f32_16x16x32_bf16 v[116:119], v[128:131], v[168:171], v[116:119]
	v_mfma_f32_16x16x32_bf16 v[112:115], v[152:155], v[168:171], v[112:115]
	v_mfma_f32_16x16x32_bf16 v[92:95], v[128:131], v[176:179], v[92:95]
	v_mfma_f32_16x16x32_bf16 v[88:91], v[152:155], v[176:179], v[88:91]
	v_mfma_f32_16x16x32_bf16 v[68:71], v[128:131], v[208:211], v[68:71]
	v_mfma_f32_16x16x32_bf16 v[64:67], v[152:155], v[208:211], v[64:67]
	v_mfma_f32_16x16x32_bf16 v[140:143], v[132:135], v[164:167], v[140:143]
	v_mfma_f32_16x16x32_bf16 v[136:139], v[156:159], v[164:167], v[136:139]
	v_mfma_f32_16x16x32_bf16 v[116:119], v[132:135], v[172:175], v[116:119]
	v_mfma_f32_16x16x32_bf16 v[112:115], v[156:159], v[172:175], v[112:115]
	v_mfma_f32_16x16x32_bf16 v[92:95], v[132:135], v[180:183], v[92:95]
	v_mfma_f32_16x16x32_bf16 v[88:91], v[156:159], v[180:183], v[88:91]
	v_mfma_f32_16x16x32_bf16 v[68:71], v[132:135], v[220:223], v[68:71]
	v_mfma_f32_16x16x32_bf16 v[64:67], v[156:159], v[220:223], v[64:67]
	s_setprio 0
	s_add_i32 s48, s83, s52
	v_lshl_add_u64 v[224:225], v[224:225], 0, s[18:19]
	s_mov_b32 m0, s48
	ds_read_b128 v[160:163], v218 offset:49152
	ds_read_b128 v[164:167], v218 offset:50176
	ds_read_b128 v[168:171], v218 offset:51200
	ds_read_b128 v[172:175], v218 offset:52224
	ds_read_b128 v[176:179], v218 offset:53248
	ds_read_b128 v[180:183], v218 offset:54272
	ds_read_b128 v[208:211], v218 offset:55296
	ds_read_b128 v[220:223], v218 offset:56320
	global_load_lds_dwordx4 v[224:225], off
	s_add_i32 m0, s48, 0x2000
	s_add_u32 s46, s46, 0x40080
	v_lshl_add_u64 v[224:225], v[226:227], 0, s[18:19]
	s_addc_u32 s47, s47, 0
	s_add_i32 s48, s96, s52
	global_load_lds_dwordx4 v[224:225], off
	v_lshl_add_u64 v[224:225], s[46:47], 0, v[186:187]
	s_mov_b32 m0, s48
	s_nop 0
	global_load_lds_dwordx4 v[224:225], off
	v_lshl_add_u64 v[224:225], s[46:47], 0, v[190:191]
	s_add_i32 m0, s48, 0x2000
	s_nop 0
	global_load_lds_dwordx4 v[224:225], off
	v_lshl_add_u64 v[224:225], v[230:231], 0, s[18:19]
	s_mov_b32 m0, s68
	s_nop 0
	global_load_lds_dwordx4 v[224:225], off
	v_lshl_add_u64 v[224:225], v[232:233], 0, s[18:19]
	s_mov_b32 m0, s69
	s_nop 0
	global_load_lds_dwordx4 v[224:225], off
	s_waitcnt vmcnt(8)
	s_waitcnt lgkmcnt(0)
	s_barrier
	s_setprio 2
	v_mfma_f32_16x16x32_bf16 v[60:63], v[80:83], v[160:163], v[60:63]
	v_mfma_f32_16x16x32_bf16 v[56:59], v[104:107], v[160:163], v[56:59]
	v_mfma_f32_16x16x32_bf16 v[44:47], v[80:83], v[168:171], v[44:47]
	v_mfma_f32_16x16x32_bf16 v[40:43], v[104:107], v[168:171], v[40:43]
	v_mfma_f32_16x16x32_bf16 v[28:31], v[80:83], v[176:179], v[28:31]
	v_mfma_f32_16x16x32_bf16 v[24:27], v[104:107], v[176:179], v[24:27]
	v_mfma_f32_16x16x32_bf16 v[12:15], v[80:83], v[208:211], v[12:15]
	v_mfma_f32_16x16x32_bf16 v[8:11], v[104:107], v[208:211], v[8:11]
	v_mfma_f32_16x16x32_bf16 v[60:63], v[84:87], v[164:167], v[60:63]
	v_mfma_f32_16x16x32_bf16 v[56:59], v[108:111], v[164:167], v[56:59]
	v_mfma_f32_16x16x32_bf16 v[44:47], v[84:87], v[172:175], v[44:47]
	v_mfma_f32_16x16x32_bf16 v[40:43], v[108:111], v[172:175], v[40:43]
	v_mfma_f32_16x16x32_bf16 v[28:31], v[84:87], v[180:183], v[28:31]
	v_mfma_f32_16x16x32_bf16 v[24:27], v[108:111], v[180:183], v[24:27]
	v_mfma_f32_16x16x32_bf16 v[12:15], v[84:87], v[220:223], v[12:15]
	v_mfma_f32_16x16x32_bf16 v[8:11], v[108:111], v[220:223], v[8:11]
	v_mfma_f32_16x16x32_bf16 v[52:55], v[128:131], v[160:163], v[52:55]
	v_mfma_f32_16x16x32_bf16 v[48:51], v[152:155], v[160:163], v[48:51]
	v_mfma_f32_16x16x32_bf16 v[36:39], v[128:131], v[168:171], v[36:39]
	v_mfma_f32_16x16x32_bf16 v[32:35], v[152:155], v[168:171], v[32:35]
	v_mfma_f32_16x16x32_bf16 v[20:23], v[128:131], v[176:179], v[20:23]
	v_mfma_f32_16x16x32_bf16 v[16:19], v[152:155], v[176:179], v[16:19]
	v_mfma_f32_16x16x32_bf16 v[4:7], v[128:131], v[208:211], v[4:7]
	v_mfma_f32_16x16x32_bf16 v[0:3], v[152:155], v[208:211], v[0:3]
	v_mfma_f32_16x16x32_bf16 v[52:55], v[132:135], v[164:167], v[52:55]
	v_mfma_f32_16x16x32_bf16 v[48:51], v[156:159], v[164:167], v[48:51]
	v_mfma_f32_16x16x32_bf16 v[36:39], v[132:135], v[172:175], v[36:39]
	v_mfma_f32_16x16x32_bf16 v[32:35], v[156:159], v[172:175], v[32:35]
	v_mfma_f32_16x16x32_bf16 v[20:23], v[132:135], v[180:183], v[20:23]
	v_mfma_f32_16x16x32_bf16 v[16:19], v[156:159], v[180:183], v[16:19]
	v_mfma_f32_16x16x32_bf16 v[4:7], v[132:135], v[220:223], v[4:7]
	v_mfma_f32_16x16x32_bf16 v[0:3], v[156:159], v[220:223], v[0:3]
	s_setprio 0
	s_add_i32 s95, s95, 2
	s_add_u32 s44, s44, 0x100
	s_addc_u32 s45, s45, 0
	s_add_u32 s93, s93, 0x100
	s_addc_u32 s94, s94, 0
	s_cmp_gt_u32 s95, 13
	s_cbranch_scc0 .Lh1_4
.Ljoin_4:
	s_and_b64 vcc, exec, s[20:21]
	s_cbranch_vccz .LBB0_671

.LBB0_687:
	s_or_b64 exec, exec, s[44:45]
	s_andn2_b64 vcc, exec, s[6:7]
	s_mov_b64 s[6:7], -1
	s_cbranch_vccnz .LBB0_664
	s_andn2_b64 vcc, exec, s[16:17]
	s_cbranch_vccnz .LBB0_663
	s_branch .LBB0_663

.LBB0_751:
	s_lshl_b32 s6, s71, 5
	s_mov_b64 s[14:15], 0x80
	s_and_b32 s18, s6, 0x60
	s_add_i32 m0, s27, 0x18000
	v_lshl_add_u64 v[6:7], v[6:7], 0, s[14:15]
	s_lshl_b32 s16, s5, 13
	s_lshr_b32 s17, s18, 3
	s_nop 0
	global_load_lds_dwordx4 v[6:7], off
	v_lshl_add_u64 v[4:5], v[4:5], 0, s[14:15]
	s_add_i32 m0, s27, 0x1a000
	s_add_i32 s49, s27, 0x8000
	s_add_i32 s50, s27, 0xa000
	global_load_lds_dwordx4 v[4:5], off
	v_lshl_add_u64 v[0:1], v[0:1], 0, s[14:15]
	s_mov_b32 m0, s49
	s_add_u32 s6, s36, 0x40080
	global_load_lds_dwordx4 v[0:1], off
	v_lshl_add_u64 v[0:1], v[2:3], 0, s[14:15]
	s_mov_b32 m0, s50
	s_addc_u32 s7, s37, 0
	global_load_lds_dwordx4 v[0:1], off
	s_add_i32 m0, s27, 0x1c000
	v_lshl_add_u64 v[0:1], s[6:7], 0, v[132:133]
	global_load_lds_dwordx4 v[0:1], off
	v_lshl_add_u64 v[0:1], s[6:7], 0, v[128:129]
	s_add_i32 m0, s27, 0x1e000
	v_lshrrev_b32_e32 v2, 6, v9
	global_load_lds_dwordx4 v[0:1], off
	v_and_b32_e32 v0, 15, v9
	v_lshlrev_b32_e32 v5, 2, v9
	v_lshl_or_b32 v153, s5, 6, v0
	v_and_b32_e32 v3, 48, v9
	v_lshlrev_b32_e32 v4, 10, v2
	v_lshlrev_b32_e32 v0, 6, v0
	v_and_b32_e32 v5, 32, v5
	v_or_b32_e32 v2, s17, v2
	v_bitop3_b32 v6, v0, v5, v3 bitop3:0x36
	v_or_b32_e32 v0, v0, v3
	v_lshlrev_b32_e32 v2, 10, v2
	v_bitop3_b32 v157, v0, v2, v5 bitop3:0xde
	v_and_b32_e32 v2, 64, v9
	v_xor_b32_e32 v0, 16, v9
	v_add_u32_e32 v2, 64, v2
	v_cmp_lt_i32_e32 vcc, v0, v2
	v_lshrrev_b32_e32 v1, 1, v9
	v_and_b32_e32 v1, 56, v1
	v_cndmask_b32_e32 v0, v9, v0, vcc
	v_lshlrev_b32_e32 v161, 2, v0
	v_xor_b32_e32 v0, 32, v9
	v_cmp_lt_i32_e32 vcc, v0, v2
	v_add_u32_e32 v171, s18, v1
	v_mov_b32_e32 v1, v133
	v_cndmask_b32_e32 v0, v9, v0, vcc
	v_lshlrev_b32_e32 v165, 2, v0
	v_and_b32_e32 v0, 0x70, v9
	v_lshl_add_u64 v[136:137], s[10:11], 0, v[0:1]
	v_lshlrev_b32_e32 v0, 14, v12
	v_and_b32_e32 v0, 0xffff8000, v0
	v_lshl_add_u32 v0, v13, 11, v0
	v_and_b32_e32 v1, 1, v12
	v_lshl_or_b32 v0, v1, 6, v0
	v_lshl_add_u32 v138, v14, 1, v0
	v_lshlrev_b32_e32 v0, 14, v8
	v_and_b32_e32 v0, 0xffff8000, v0
	s_waitcnt vmcnt(6)
	s_cmpk_lt_u32 s3, 0x100
	v_lshl_add_u32 v0, v10, 11, v0
	v_and_b32_e32 v1, 1, v8
	v_or3_b32 v4, v4, s16, v6
	s_cselect_b64 s[16:17], -1, 0
	v_lshl_or_b32 v0, v1, 6, v0
	s_add_i32 s53, 0, 0x10000
	s_add_i32 s54, 0, 0x14000
	s_sext_i32_i16 s56, s4
	s_ashr_i32 s51, s34, 31
	s_mov_b32 s52, s34
	v_mov_b32_e32 v139, v133
	v_lshl_add_u32 v140, v11, 1, v0
	v_mov_b32_e32 v141, v133
	v_mov_b64_e32 v[142:143], 0x1b80
	v_mov_b64_e32 v[144:145], 0x1b7f
	v_add_u32_e32 v172, s53, v157
	v_add_u32_e32 v173, s54, v157
	v_add_u32_e32 v174, 0, v4
	v_mov_b32_e32 v175, 0x358637bd
	s_movk_i32 s55, 0x1600
	s_barrier
	s_branch .LBB0_754

.LBB0_758:
	s_ashr_i32 s19, s18, 31
	s_lshl_b64 s[20:21], s[18:19], 19
	s_add_u32 s20, s62, s20
	s_addc_u32 s21, s63, s21
	s_and_b64 s[22:23], s[4:5], exec
	s_cselect_b32 s19, s21, s39
	s_cselect_b32 s57, s20, s38
	s_ashr_i32 s11, s10, 31
	s_lshl_b64 s[22:23], s[10:11], 19
	s_add_u32 s22, s40, s22
	s_addc_u32 s23, s41, s23
	s_and_b64 s[4:5], s[4:5], exec
	s_cselect_b32 s11, s23, s37
	s_cselect_b32 s58, s22, s36
	s_add_u32 s4, s38, 0x40080
	s_addc_u32 s5, s39, 0
	s_add_u32 s59, s36, 0x100
	s_addc_u32 s66, s37, 0
	s_mov_b32 s67, -2
	s_and_b64 vcc, exec, s[16:17]
	s_cbranch_vccz .Lh1p_5
	ds_read_b128 v[146:149], v172
	ds_read_b128 v[166:169], v172 offset:1024
	ds_read_b128 v[176:179], v172 offset:2048
	ds_read_b128 v[180:183], v172 offset:3072
	ds_read_b128 v[184:187], v173
	ds_read_b128 v[188:191], v173 offset:1024
	ds_read_b128 v[192:195], v173 offset:2048
	ds_read_b128 v[196:199], v173 offset:3072
	s_add_u32 s36, s4, 0xfffc0080
	s_addc_u32 s37, s5, -1
	s_cmp_eq_u32 s67, 12
	s_cselect_b32 s39, s19, s37
	s_cselect_b32 s38, s57, s36
	s_cselect_b32 s37, s11, s66
	s_cselect_b32 s36, s58, s59
	v_lshl_add_u64 v[150:151], s[4:5], 0, v[138:139]
	s_add_i32 m0, s27, 0xc000
	ds_read_b128 v[200:203], v174
	ds_read_b128 v[204:207], v174 offset:1024
	ds_read_b128 v[208:211], v174 offset:2048
	ds_read_b128 v[212:215], v174 offset:3072
	ds_read_b128 v[216:219], v174 offset:4096
	ds_read_b128 v[220:223], v174 offset:5120
	ds_read_b128 v[224:227], v174 offset:6144
	ds_read_b128 v[230:233], v174 offset:7168
	global_load_lds_dwordx4 v[150:151], off
	v_lshl_add_u64 v[150:151], s[4:5], 0, v[140:141]
	s_add_i32 m0, s27, 0xe000
	s_nop 0
	global_load_lds_dwordx4 v[150:151], off
	s_waitcnt vmcnt(8)
	s_waitcnt lgkmcnt(0)
	s_setprio 1
	v_mfma_f32_16x16x32_bf16 v[124:127], v[146:149], v[200:203], 0
	v_mfma_f32_16x16x32_bf16 v[120:123], v[176:179], v[200:203], 0
	v_mfma_f32_16x16x32_bf16 v[108:111], v[146:149], v[208:211], 0
	v_mfma_f32_16x16x32_bf16 v[104:107], v[176:179], v[208:211], 0
	v_mfma_f32_16x16x32_bf16 v[92:95], v[146:149], v[216:219], 0
	v_mfma_f32_16x16x32_bf16 v[88:91], v[176:179], v[216:219], 0
	v_mfma_f32_16x16x32_bf16 v[76:79], v[146:149], v[224:227], 0
	v_mfma_f32_16x16x32_bf16 v[72:75], v[176:179], v[224:227], 0
	v_mfma_f32_16x16x32_bf16 v[124:127], v[166:169], v[204:207], v[124:127]
	v_mfma_f32_16x16x32_bf16 v[120:123], v[180:183], v[204:207], v[120:123]
	v_mfma_f32_16x16x32_bf16 v[108:111], v[166:169], v[212:215], v[108:111]
	v_mfma_f32_16x16x32_bf16 v[104:107], v[180:183], v[212:215], v[104:107]
	v_mfma_f32_16x16x32_bf16 v[92:95], v[166:169], v[220:223], v[92:95]
	v_mfma_f32_16x16x32_bf16 v[88:91], v[180:183], v[220:223], v[88:91]
	v_mfma_f32_16x16x32_bf16 v[76:79], v[166:169], v[230:233], v[76:79]
	v_mfma_f32_16x16x32_bf16 v[72:75], v[180:183], v[230:233], v[72:75]
	v_mfma_f32_16x16x32_bf16 v[116:119], v[184:187], v[200:203], 0
	v_mfma_f32_16x16x32_bf16 v[112:115], v[192:195], v[200:203], 0
	v_mfma_f32_16x16x32_bf16 v[100:103], v[184:187], v[208:211], 0
	v_mfma_f32_16x16x32_bf16 v[96:99], v[192:195], v[208:211], 0
	v_mfma_f32_16x16x32_bf16 v[84:87], v[184:187], v[216:219], 0
	v_mfma_f32_16x16x32_bf16 v[80:83], v[192:195], v[216:219], 0
	v_mfma_f32_16x16x32_bf16 v[68:71], v[184:187], v[224:227], 0
	v_mfma_f32_16x16x32_bf16 v[64:67], v[192:195], v[224:227], 0
	v_mfma_f32_16x16x32_bf16 v[116:119], v[188:191], v[204:207], v[116:119]
	v_mfma_f32_16x16x32_bf16 v[112:115], v[196:199], v[204:207], v[112:115]
	v_mfma_f32_16x16x32_bf16 v[100:103], v[188:191], v[212:215], v[100:103]
	v_mfma_f32_16x16x32_bf16 v[96:99], v[196:199], v[212:215], v[96:99]
	v_mfma_f32_16x16x32_bf16 v[84:87], v[188:191], v[220:223], v[84:87]
	v_mfma_f32_16x16x32_bf16 v[80:83], v[196:199], v[220:223], v[80:83]
	v_mfma_f32_16x16x32_bf16 v[68:71], v[188:191], v[230:233], v[68:71]
	v_mfma_f32_16x16x32_bf16 v[64:67], v[196:199], v[230:233], v[64:67]
	s_setprio 0
	s_barrier
	s_add_i32 s68, s53, s42
	v_lshl_add_u64 v[150:151], s[36:37], 0, v[132:133]
	s_mov_b32 m0, s68
	ds_read_b128 v[200:203], v174 offset:16384
	ds_read_b128 v[204:207], v174 offset:17408
	ds_read_b128 v[208:211], v174 offset:18432
	ds_read_b128 v[212:215], v174 offset:19456
	ds_read_b128 v[216:219], v174 offset:20480
	ds_read_b128 v[220:223], v174 offset:21504
	ds_read_b128 v[224:227], v174 offset:22528
	ds_read_b128 v[230:233], v174 offset:23552
	global_load_lds_dwordx4 v[150:151], off
	s_add_i32 m0, s68, 0x2000
	s_add_u32 s68, s36, 0x40000
	v_lshl_add_u64 v[154:155], s[36:37], 0, v[128:129]
	s_addc_u32 s69, s37, 0
	s_add_i32 s70, s54, s42
	global_load_lds_dwordx4 v[154:155], off
	v_lshl_add_u64 v[158:159], s[68:69], 0, v[132:133]
	s_mov_b32 m0, s70
	v_lshl_add_u64 v[162:163], s[38:39], 0, v[130:131]
	global_load_lds_dwordx4 v[158:159], off
	v_lshl_add_u64 v[158:159], s[68:69], 0, v[128:129]
	s_add_i32 m0, s70, 0x2000
	s_nop 0
	global_load_lds_dwordx4 v[158:159], off
	v_lshl_add_u64 v[158:159], s[38:39], 0, v[134:135]
	s_mov_b32 m0, s27
	s_nop 0
	global_load_lds_dwordx4 v[158:159], off
	s_mov_b32 m0, s45
	s_nop 0
	global_load_lds_dwordx4 v[162:163], off
	s_waitcnt vmcnt(8)
	s_waitcnt lgkmcnt(0)
	s_setprio 1
	v_mfma_f32_16x16x32_bf16 v[60:63], v[146:149], v[200:203], 0
	v_mfma_f32_16x16x32_bf16 v[56:59], v[176:179], v[200:203], 0
	v_mfma_f32_16x16x32_bf16 v[44:47], v[146:149], v[208:211], 0
	v_mfma_f32_16x16x32_bf16 v[40:43], v[176:179], v[208:211], 0
	v_mfma_f32_16x16x32_bf16 v[28:31], v[146:149], v[216:219], 0
	v_mfma_f32_16x16x32_bf16 v[24:27], v[176:179], v[216:219], 0
	v_mfma_f32_16x16x32_bf16 v[12:15], v[146:149], v[224:227], 0
	v_mfma_f32_16x16x32_bf16 v[8:11], v[176:179], v[224:227], 0
	v_mfma_f32_16x16x32_bf16 v[60:63], v[166:169], v[204:207], v[60:63]
	v_mfma_f32_16x16x32_bf16 v[56:59], v[180:183], v[204:207], v[56:59]
	v_mfma_f32_16x16x32_bf16 v[44:47], v[166:169], v[212:215], v[44:47]
	v_mfma_f32_16x16x32_bf16 v[40:43], v[180:183], v[212:215], v[40:43]
	v_mfma_f32_16x16x32_bf16 v[28:31], v[166:169], v[220:223], v[28:31]
	v_mfma_f32_16x16x32_bf16 v[24:27], v[180:183], v[220:223], v[24:27]
	v_mfma_f32_16x16x32_bf16 v[12:15], v[166:169], v[230:233], v[12:15]
	v_mfma_f32_16x16x32_bf16 v[8:11], v[180:183], v[230:233], v[8:11]
	v_mfma_f32_16x16x32_bf16 v[52:55], v[184:187], v[200:203], 0
	v_mfma_f32_16x16x32_bf16 v[48:51], v[192:195], v[200:203], 0
	v_mfma_f32_16x16x32_bf16 v[36:39], v[184:187], v[208:211], 0
	v_mfma_f32_16x16x32_bf16 v[32:35], v[192:195], v[208:211], 0
	v_mfma_f32_16x16x32_bf16 v[20:23], v[184:187], v[216:219], 0
	v_mfma_f32_16x16x32_bf16 v[16:19], v[192:195], v[216:219], 0
	v_mfma_f32_16x16x32_bf16 v[4:7], v[184:187], v[224:227], 0
	v_mfma_f32_16x16x32_bf16 v[0:3], v[192:195], v[224:227], 0
	v_mfma_f32_16x16x32_bf16 v[52:55], v[188:191], v[204:207], v[52:55]
	v_mfma_f32_16x16x32_bf16 v[48:51], v[196:199], v[204:207], v[48:51]
	v_mfma_f32_16x16x32_bf16 v[36:39], v[188:191], v[212:215], v[36:39]
	v_mfma_f32_16x16x32_bf16 v[32:35], v[196:199], v[212:215], v[32:35]
	v_mfma_f32_16x16x32_bf16 v[20:23], v[188:191], v[220:223], v[20:23]
	v_mfma_f32_16x16x32_bf16 v[16:19], v[196:199], v[220:223], v[16:19]
	v_mfma_f32_16x16x32_bf16 v[4:7], v[188:191], v[230:233], v[4:7]
	v_mfma_f32_16x16x32_bf16 v[0:3], v[196:199], v[230:233], v[0:3]
	s_setprio 0
	s_barrier
	s_add_i32 s68, 0, 0x18000
	v_add_u32_e32 v152, s68, v157
	s_add_i32 s69, 0, 0x1c000
	ds_read_b128 v[146:149], v152
	ds_read_b128 v[166:169], v152 offset:1024
	ds_read_b128 v[176:179], v152 offset:2048
	ds_read_b128 v[180:183], v152 offset:3072
	v_add_u32_e32 v152, s69, v157
	ds_read_b128 v[184:187], v152
	ds_read_b128 v[188:191], v152 offset:1024
	ds_read_b128 v[192:195], v152 offset:2048
	ds_read_b128 v[196:199], v152 offset:3072
	s_add_u32 s38, s38, 0x40000
	s_addc_u32 s39, s39, 0
	s_mov_b32 m0, s46
	v_lshl_add_u64 v[234:235], s[38:39], 0, v[134:135]
	ds_read_b128 v[200:203], v174 offset:32768
	ds_read_b128 v[204:207], v174 offset:33792
	ds_read_b128 v[208:211], v174 offset:34816
	ds_read_b128 v[212:215], v174 offset:35840
	ds_read_b128 v[216:219], v174 offset:36864
	ds_read_b128 v[220:223], v174 offset:37888
	ds_read_b128 v[224:227], v174 offset:38912
	ds_read_b128 v[230:233], v174 offset:39936
	global_load_lds_dwordx4 v[234:235], off
	v_lshl_add_u64 v[234:235], s[38:39], 0, v[130:131]
	s_mov_b32 m0, s47
	s_nop 0
	global_load_lds_dwordx4 v[234:235], off
	s_waitcnt vmcnt(8)
	s_waitcnt lgkmcnt(0)
	s_setprio 1
	v_mfma_f32_16x16x32_bf16 v[124:127], v[146:149], v[200:203], v[124:127]
	v_mfma_f32_16x16x32_bf16 v[120:123], v[176:179], v[200:203], v[120:123]
	v_mfma_f32_16x16x32_bf16 v[108:111], v[146:149], v[208:211], v[108:111]
	v_mfma_f32_16x16x32_bf16 v[104:107], v[176:179], v[208:211], v[104:107]
	v_mfma_f32_16x16x32_bf16 v[92:95], v[146:149], v[216:219], v[92:95]
	v_mfma_f32_16x16x32_bf16 v[88:91], v[176:179], v[216:219], v[88:91]
	v_mfma_f32_16x16x32_bf16 v[76:79], v[146:149], v[224:227], v[76:79]
	v_mfma_f32_16x16x32_bf16 v[72:75], v[176:179], v[224:227], v[72:75]
	v_mfma_f32_16x16x32_bf16 v[124:127], v[166:169], v[204:207], v[124:127]
	v_mfma_f32_16x16x32_bf16 v[120:123], v[180:183], v[204:207], v[120:123]
	v_mfma_f32_16x16x32_bf16 v[108:111], v[166:169], v[212:215], v[108:111]
	v_mfma_f32_16x16x32_bf16 v[104:107], v[180:183], v[212:215], v[104:107]
	v_mfma_f32_16x16x32_bf16 v[92:95], v[166:169], v[220:223], v[92:95]
	v_mfma_f32_16x16x32_bf16 v[88:91], v[180:183], v[220:223], v[88:91]
	v_mfma_f32_16x16x32_bf16 v[76:79], v[166:169], v[230:233], v[76:79]
	v_mfma_f32_16x16x32_bf16 v[72:75], v[180:183], v[230:233], v[72:75]
	v_mfma_f32_16x16x32_bf16 v[116:119], v[184:187], v[200:203], v[116:119]
	v_mfma_f32_16x16x32_bf16 v[112:115], v[192:195], v[200:203], v[112:115]
	v_mfma_f32_16x16x32_bf16 v[100:103], v[184:187], v[208:211], v[100:103]
	v_mfma_f32_16x16x32_bf16 v[96:99], v[192:195], v[208:211], v[96:99]
	v_mfma_f32_16x16x32_bf16 v[84:87], v[184:187], v[216:219], v[84:87]
	v_mfma_f32_16x16x32_bf16 v[80:83], v[192:195], v[216:219], v[80:83]
	v_mfma_f32_16x16x32_bf16 v[68:71], v[184:187], v[224:227], v[68:71]
	v_mfma_f32_16x16x32_bf16 v[64:67], v[192:195], v[224:227], v[64:67]
	v_mfma_f32_16x16x32_bf16 v[116:119], v[188:191], v[204:207], v[116:119]
	v_mfma_f32_16x16x32_bf16 v[112:115], v[196:199], v[204:207], v[112:115]
	v_mfma_f32_16x16x32_bf16 v[100:103], v[188:191], v[212:215], v[100:103]
	v_mfma_f32_16x16x32_bf16 v[96:99], v[196:199], v[212:215], v[96:99]
	v_mfma_f32_16x16x32_bf16 v[84:87], v[188:191], v[220:223], v[84:87]
	v_mfma_f32_16x16x32_bf16 v[80:83], v[196:199], v[220:223], v[80:83]
	v_mfma_f32_16x16x32_bf16 v[68:71], v[188:191], v[230:233], v[68:71]
	v_mfma_f32_16x16x32_bf16 v[64:67], v[196:199], v[230:233], v[64:67]
	s_setprio 0
	s_barrier
	s_add_i32 s38, s68, s42
	v_lshl_add_u64 v[150:151], v[150:151], 0, s[14:15]
	s_mov_b32 m0, s38
	ds_read_b128 v[200:203], v174 offset:49152
	ds_read_b128 v[204:207], v174 offset:50176
	ds_read_b128 v[208:211], v174 offset:51200
	ds_read_b128 v[212:215], v174 offset:52224
	ds_read_b128 v[216:219], v174 offset:53248
	ds_read_b128 v[220:223], v174 offset:54272
	ds_read_b128 v[224:227], v174 offset:55296
	ds_read_b128 v[230:233], v174 offset:56320
	global_load_lds_dwordx4 v[150:151], off
	s_add_i32 m0, s38, 0x2000
	s_add_u32 s36, s36, 0x40080
	v_lshl_add_u64 v[150:151], v[154:155], 0, s[14:15]
	s_addc_u32 s37, s37, 0
	s_add_i32 s38, s69, s42
	global_load_lds_dwordx4 v[150:151], off
	v_lshl_add_u64 v[150:151], s[36:37], 0, v[132:133]
	s_mov_b32 m0, s38
	s_nop 0
	global_load_lds_dwordx4 v[150:151], off
	v_lshl_add_u64 v[150:151], s[36:37], 0, v[128:129]
	s_add_i32 m0, s38, 0x2000
	s_nop 0
	global_load_lds_dwordx4 v[150:151], off
	v_lshl_add_u64 v[150:151], v[158:159], 0, s[14:15]
	s_mov_b32 m0, s49
	s_nop 0
	global_load_lds_dwordx4 v[150:151], off
	v_lshl_add_u64 v[150:151], v[162:163], 0, s[14:15]
	s_mov_b32 m0, s50
	s_nop 0
	global_load_lds_dwordx4 v[150:151], off
	s_waitcnt vmcnt(8)
	s_waitcnt lgkmcnt(0)
	s_setprio 1
	v_mfma_f32_16x16x32_bf16 v[60:63], v[146:149], v[200:203], v[60:63]
	v_mfma_f32_16x16x32_bf16 v[56:59], v[176:179], v[200:203], v[56:59]
	v_mfma_f32_16x16x32_bf16 v[44:47], v[146:149], v[208:211], v[44:47]
	v_mfma_f32_16x16x32_bf16 v[40:43], v[176:179], v[208:211], v[40:43]
	v_mfma_f32_16x16x32_bf16 v[28:31], v[146:149], v[216:219], v[28:31]
	v_mfma_f32_16x16x32_bf16 v[24:27], v[176:179], v[216:219], v[24:27]
	v_mfma_f32_16x16x32_bf16 v[12:15], v[146:149], v[224:227], v[12:15]
	v_mfma_f32_16x16x32_bf16 v[8:11], v[176:179], v[224:227], v[8:11]
	v_mfma_f32_16x16x32_bf16 v[60:63], v[166:169], v[204:207], v[60:63]
	v_mfma_f32_16x16x32_bf16 v[56:59], v[180:183], v[204:207], v[56:59]
	v_mfma_f32_16x16x32_bf16 v[44:47], v[166:169], v[212:215], v[44:47]
	v_mfma_f32_16x16x32_bf16 v[40:43], v[180:183], v[212:215], v[40:43]
	v_mfma_f32_16x16x32_bf16 v[28:31], v[166:169], v[220:223], v[28:31]
	v_mfma_f32_16x16x32_bf16 v[24:27], v[180:183], v[220:223], v[24:27]
	v_mfma_f32_16x16x32_bf16 v[12:15], v[166:169], v[230:233], v[12:15]
	v_mfma_f32_16x16x32_bf16 v[8:11], v[180:183], v[230:233], v[8:11]
	v_mfma_f32_16x16x32_bf16 v[52:55], v[184:187], v[200:203], v[52:55]
	v_mfma_f32_16x16x32_bf16 v[48:51], v[192:195], v[200:203], v[48:51]
	v_mfma_f32_16x16x32_bf16 v[36:39], v[184:187], v[208:211], v[36:39]
	v_mfma_f32_16x16x32_bf16 v[32:35], v[192:195], v[208:211], v[32:35]
	v_mfma_f32_16x16x32_bf16 v[20:23], v[184:187], v[216:219], v[20:23]
	v_mfma_f32_16x16x32_bf16 v[16:19], v[192:195], v[216:219], v[16:19]
	v_mfma_f32_16x16x32_bf16 v[4:7], v[184:187], v[224:227], v[4:7]
	v_mfma_f32_16x16x32_bf16 v[0:3], v[192:195], v[224:227], v[0:3]
	v_mfma_f32_16x16x32_bf16 v[52:55], v[188:191], v[204:207], v[52:55]
	v_mfma_f32_16x16x32_bf16 v[48:51], v[196:199], v[204:207], v[48:51]
	v_mfma_f32_16x16x32_bf16 v[36:39], v[188:191], v[212:215], v[36:39]
	v_mfma_f32_16x16x32_bf16 v[32:35], v[196:199], v[212:215], v[32:35]
	v_mfma_f32_16x16x32_bf16 v[20:23], v[188:191], v[220:223], v[20:23]
	v_mfma_f32_16x16x32_bf16 v[16:19], v[196:199], v[220:223], v[16:19]
	v_mfma_f32_16x16x32_bf16 v[4:7], v[188:191], v[230:233], v[4:7]
	v_mfma_f32_16x16x32_bf16 v[0:3], v[196:199], v[230:233], v[0:3]
	s_setprio 0
	s_barrier
	s_add_i32 s67, s67, 2
	s_add_u32 s4, s4, 0x100
	s_addc_u32 s5, s5, 0
	s_add_u32 s59, s59, 0x100
	s_addc_u32 s66, s66, 0
	s_cmp_gt_u32 s67, 13
.Lh0_5:
	ds_read_b128 v[146:149], v172
	ds_read_b128 v[166:169], v172 offset:1024
	ds_read_b128 v[176:179], v172 offset:2048
	ds_read_b128 v[180:183], v172 offset:3072
	ds_read_b128 v[184:187], v173
	ds_read_b128 v[188:191], v173 offset:1024
	ds_read_b128 v[192:195], v173 offset:2048
	ds_read_b128 v[196:199], v173 offset:3072
	s_add_u32 s36, s4, 0xfffc0080
	s_addc_u32 s37, s5, -1
	s_cmp_eq_u32 s67, 12
	s_cselect_b32 s39, s19, s37
	s_cselect_b32 s38, s57, s36
	s_cselect_b32 s37, s11, s66
	s_cselect_b32 s36, s58, s59
	v_lshl_add_u64 v[150:151], s[4:5], 0, v[138:139]
	s_add_i32 m0, s27, 0xc000
	ds_read_b128 v[200:203], v174
	ds_read_b128 v[204:207], v174 offset:1024
	ds_read_b128 v[208:211], v174 offset:2048
	ds_read_b128 v[212:215], v174 offset:3072
	ds_read_b128 v[216:219], v174 offset:4096
	ds_read_b128 v[220:223], v174 offset:5120
	ds_read_b128 v[224:227], v174 offset:6144
	ds_read_b128 v[230:233], v174 offset:7168
	global_load_lds_dwordx4 v[150:151], off
	v_lshl_add_u64 v[150:151], s[4:5], 0, v[140:141]
	s_add_i32 m0, s27, 0xe000
	s_nop 0
	global_load_lds_dwordx4 v[150:151], off
	s_waitcnt vmcnt(8)
	s_waitcnt lgkmcnt(0)
	s_setprio 1
	v_mfma_f32_16x16x32_bf16 v[124:127], v[146:149], v[200:203], v[124:127]
	v_mfma_f32_16x16x32_bf16 v[120:123], v[176:179], v[200:203], v[120:123]
	v_mfma_f32_16x16x32_bf16 v[108:111], v[146:149], v[208:211], v[108:111]
	v_mfma_f32_16x16x32_bf16 v[104:107], v[176:179], v[208:211], v[104:107]
	v_mfma_f32_16x16x32_bf16 v[92:95], v[146:149], v[216:219], v[92:95]
	v_mfma_f32_16x16x32_bf16 v[88:91], v[176:179], v[216:219], v[88:91]
	v_mfma_f32_16x16x32_bf16 v[76:79], v[146:149], v[224:227], v[76:79]
	v_mfma_f32_16x16x32_bf16 v[72:75], v[176:179], v[224:227], v[72:75]
	v_mfma_f32_16x16x32_bf16 v[124:127], v[166:169], v[204:207], v[124:127]
	v_mfma_f32_16x16x32_bf16 v[120:123], v[180:183], v[204:207], v[120:123]
	v_mfma_f32_16x16x32_bf16 v[108:111], v[166:169], v[212:215], v[108:111]
	v_mfma_f32_16x16x32_bf16 v[104:107], v[180:183], v[212:215], v[104:107]
	v_mfma_f32_16x16x32_bf16 v[92:95], v[166:169], v[220:223], v[92:95]
	v_mfma_f32_16x16x32_bf16 v[88:91], v[180:183], v[220:223], v[88:91]
	v_mfma_f32_16x16x32_bf16 v[76:79], v[166:169], v[230:233], v[76:79]
	v_mfma_f32_16x16x32_bf16 v[72:75], v[180:183], v[230:233], v[72:75]
	v_mfma_f32_16x16x32_bf16 v[116:119], v[184:187], v[200:203], v[116:119]
	v_mfma_f32_16x16x32_bf16 v[112:115], v[192:195], v[200:203], v[112:115]
	v_mfma_f32_16x16x32_bf16 v[100:103], v[184:187], v[208:211], v[100:103]
	v_mfma_f32_16x16x32_bf16 v[96:99], v[192:195], v[208:211], v[96:99]
	v_mfma_f32_16x16x32_bf16 v[84:87], v[184:187], v[216:219], v[84:87]
	v_mfma_f32_16x16x32_bf16 v[80:83], v[192:195], v[216:219], v[80:83]
	v_mfma_f32_16x16x32_bf16 v[68:71], v[184:187], v[224:227], v[68:71]
	v_mfma_f32_16x16x32_bf16 v[64:67], v[192:195], v[224:227], v[64:67]
	v_mfma_f32_16x16x32_bf16 v[116:119], v[188:191], v[204:207], v[116:119]
	v_mfma_f32_16x16x32_bf16 v[112:115], v[196:199], v[204:207], v[112:115]
	v_mfma_f32_16x16x32_bf16 v[100:103], v[188:191], v[212:215], v[100:103]
	v_mfma_f32_16x16x32_bf16 v[96:99], v[196:199], v[212:215], v[96:99]
	v_mfma_f32_16x16x32_bf16 v[84:87], v[188:191], v[220:223], v[84:87]
	v_mfma_f32_16x16x32_bf16 v[80:83], v[196:199], v[220:223], v[80:83]
	v_mfma_f32_16x16x32_bf16 v[68:71], v[188:191], v[230:233], v[68:71]
	v_mfma_f32_16x16x32_bf16 v[64:67], v[196:199], v[230:233], v[64:67]
	s_setprio 0
	s_barrier
	s_add_i32 s68, s53, s42
	v_lshl_add_u64 v[150:151], s[36:37], 0, v[132:133]
	s_mov_b32 m0, s68
	ds_read_b128 v[200:203], v174 offset:16384
	ds_read_b128 v[204:207], v174 offset:17408
	ds_read_b128 v[208:211], v174 offset:18432
	ds_read_b128 v[212:215], v174 offset:19456
	ds_read_b128 v[216:219], v174 offset:20480
	ds_read_b128 v[220:223], v174 offset:21504
	ds_read_b128 v[224:227], v174 offset:22528
	ds_read_b128 v[230:233], v174 offset:23552
	global_load_lds_dwordx4 v[150:151], off
	s_add_i32 m0, s68, 0x2000
	s_add_u32 s68, s36, 0x40000
	v_lshl_add_u64 v[154:155], s[36:37], 0, v[128:129]
	s_addc_u32 s69, s37, 0
	s_add_i32 s70, s54, s42
	global_load_lds_dwordx4 v[154:155], off
	v_lshl_add_u64 v[158:159], s[68:69], 0, v[132:133]
	s_mov_b32 m0, s70
	v_lshl_add_u64 v[162:163], s[38:39], 0, v[130:131]
	global_load_lds_dwordx4 v[158:159], off
	v_lshl_add_u64 v[158:159], s[68:69], 0, v[128:129]
	s_add_i32 m0, s70, 0x2000
	s_nop 0
	global_load_lds_dwordx4 v[158:159], off
	v_lshl_add_u64 v[158:159], s[38:39], 0, v[134:135]
	s_mov_b32 m0, s27
	s_nop 0
	global_load_lds_dwordx4 v[158:159], off
	s_mov_b32 m0, s45
	s_nop 0
	global_load_lds_dwordx4 v[162:163], off
	s_waitcnt vmcnt(8)
	s_waitcnt lgkmcnt(0)
	s_setprio 1
	v_mfma_f32_16x16x32_bf16 v[60:63], v[146:149], v[200:203], v[60:63]
	v_mfma_f32_16x16x32_bf16 v[56:59], v[176:179], v[200:203], v[56:59]
	v_mfma_f32_16x16x32_bf16 v[44:47], v[146:149], v[208:211], v[44:47]
	v_mfma_f32_16x16x32_bf16 v[40:43], v[176:179], v[208:211], v[40:43]
	v_mfma_f32_16x16x32_bf16 v[28:31], v[146:149], v[216:219], v[28:31]
	v_mfma_f32_16x16x32_bf16 v[24:27], v[176:179], v[216:219], v[24:27]
	v_mfma_f32_16x16x32_bf16 v[12:15], v[146:149], v[224:227], v[12:15]
	v_mfma_f32_16x16x32_bf16 v[8:11], v[176:179], v[224:227], v[8:11]
	v_mfma_f32_16x16x32_bf16 v[60:63], v[166:169], v[204:207], v[60:63]
	v_mfma_f32_16x16x32_bf16 v[56:59], v[180:183], v[204:207], v[56:59]
	v_mfma_f32_16x16x32_bf16 v[44:47], v[166:169], v[212:215], v[44:47]
	v_mfma_f32_16x16x32_bf16 v[40:43], v[180:183], v[212:215], v[40:43]
	v_mfma_f32_16x16x32_bf16 v[28:31], v[166:169], v[220:223], v[28:31]
	v_mfma_f32_16x16x32_bf16 v[24:27], v[180:183], v[220:223], v[24:27]
	v_mfma_f32_16x16x32_bf16 v[12:15], v[166:169], v[230:233], v[12:15]
	v_mfma_f32_16x16x32_bf16 v[8:11], v[180:183], v[230:233], v[8:11]
	v_mfma_f32_16x16x32_bf16 v[52:55], v[184:187], v[200:203], v[52:55]
	v_mfma_f32_16x16x32_bf16 v[48:51], v[192:195], v[200:203], v[48:51]
	v_mfma_f32_16x16x32_bf16 v[36:39], v[184:187], v[208:211], v[36:39]
	v_mfma_f32_16x16x32_bf16 v[32:35], v[192:195], v[208:211], v[32:35]
	v_mfma_f32_16x16x32_bf16 v[20:23], v[184:187], v[216:219], v[20:23]
	v_mfma_f32_16x16x32_bf16 v[16:19], v[192:195], v[216:219], v[16:19]
	v_mfma_f32_16x16x32_bf16 v[4:7], v[184:187], v[224:227], v[4:7]
	v_mfma_f32_16x16x32_bf16 v[0:3], v[192:195], v[224:227], v[0:3]
	v_mfma_f32_16x16x32_bf16 v[52:55], v[188:191], v[204:207], v[52:55]
	v_mfma_f32_16x16x32_bf16 v[48:51], v[196:199], v[204:207], v[48:51]
	v_mfma_f32_16x16x32_bf16 v[36:39], v[188:191], v[212:215], v[36:39]
	v_mfma_f32_16x16x32_bf16 v[32:35], v[196:199], v[212:215], v[32:35]
	v_mfma_f32_16x16x32_bf16 v[20:23], v[188:191], v[220:223], v[20:23]
	v_mfma_f32_16x16x32_bf16 v[16:19], v[196:199], v[220:223], v[16:19]
	v_mfma_f32_16x16x32_bf16 v[4:7], v[188:191], v[230:233], v[4:7]
	v_mfma_f32_16x16x32_bf16 v[0:3], v[196:199], v[230:233], v[0:3]
	s_setprio 0
	s_barrier
	s_add_i32 s68, 0, 0x18000
	v_add_u32_e32 v152, s68, v157
	s_add_i32 s69, 0, 0x1c000
	ds_read_b128 v[146:149], v152
	ds_read_b128 v[166:169], v152 offset:1024
	ds_read_b128 v[176:179], v152 offset:2048
	ds_read_b128 v[180:183], v152 offset:3072
	v_add_u32_e32 v152, s69, v157
	ds_read_b128 v[184:187], v152
	ds_read_b128 v[188:191], v152 offset:1024
	ds_read_b128 v[192:195], v152 offset:2048
	ds_read_b128 v[196:199], v152 offset:3072
	s_add_u32 s38, s38, 0x40000
	s_addc_u32 s39, s39, 0
	s_mov_b32 m0, s46
	v_lshl_add_u64 v[234:235], s[38:39], 0, v[134:135]
	ds_read_b128 v[200:203], v174 offset:32768
	ds_read_b128 v[204:207], v174 offset:33792
	ds_read_b128 v[208:211], v174 offset:34816
	ds_read_b128 v[212:215], v174 offset:35840
	ds_read_b128 v[216:219], v174 offset:36864
	ds_read_b128 v[220:223], v174 offset:37888
	ds_read_b128 v[224:227], v174 offset:38912
	ds_read_b128 v[230:233], v174 offset:39936
	global_load_lds_dwordx4 v[234:235], off
	v_lshl_add_u64 v[234:235], s[38:39], 0, v[130:131]
	s_mov_b32 m0, s47
	s_nop 0
	global_load_lds_dwordx4 v[234:235], off
	s_waitcnt vmcnt(8)
	s_waitcnt lgkmcnt(0)
	s_setprio 1
	v_mfma_f32_16x16x32_bf16 v[124:127], v[146:149], v[200:203], v[124:127]
	v_mfma_f32_16x16x32_bf16 v[120:123], v[176:179], v[200:203], v[120:123]
	v_mfma_f32_16x16x32_bf16 v[108:111], v[146:149], v[208:211], v[108:111]
	v_mfma_f32_16x16x32_bf16 v[104:107], v[176:179], v[208:211], v[104:107]
	v_mfma_f32_16x16x32_bf16 v[92:95], v[146:149], v[216:219], v[92:95]
	v_mfma_f32_16x16x32_bf16 v[88:91], v[176:179], v[216:219], v[88:91]
	v_mfma_f32_16x16x32_bf16 v[76:79], v[146:149], v[224:227], v[76:79]
	v_mfma_f32_16x16x32_bf16 v[72:75], v[176:179], v[224:227], v[72:75]
	v_mfma_f32_16x16x32_bf16 v[124:127], v[166:169], v[204:207], v[124:127]
	v_mfma_f32_16x16x32_bf16 v[120:123], v[180:183], v[204:207], v[120:123]
	v_mfma_f32_16x16x32_bf16 v[108:111], v[166:169], v[212:215], v[108:111]
	v_mfma_f32_16x16x32_bf16 v[104:107], v[180:183], v[212:215], v[104:107]
	v_mfma_f32_16x16x32_bf16 v[92:95], v[166:169], v[220:223], v[92:95]
	v_mfma_f32_16x16x32_bf16 v[88:91], v[180:183], v[220:223], v[88:91]
	v_mfma_f32_16x16x32_bf16 v[76:79], v[166:169], v[230:233], v[76:79]
	v_mfma_f32_16x16x32_bf16 v[72:75], v[180:183], v[230:233], v[72:75]
	v_mfma_f32_16x16x32_bf16 v[116:119], v[184:187], v[200:203], v[116:119]
	v_mfma_f32_16x16x32_bf16 v[112:115], v[192:195], v[200:203], v[112:115]
	v_mfma_f32_16x16x32_bf16 v[100:103], v[184:187], v[208:211], v[100:103]
	v_mfma_f32_16x16x32_bf16 v[96:99], v[192:195], v[208:211], v[96:99]
	v_mfma_f32_16x16x32_bf16 v[84:87], v[184:187], v[216:219], v[84:87]
	v_mfma_f32_16x16x32_bf16 v[80:83], v[192:195], v[216:219], v[80:83]
	v_mfma_f32_16x16x32_bf16 v[68:71], v[184:187], v[224:227], v[68:71]
	v_mfma_f32_16x16x32_bf16 v[64:67], v[192:195], v[224:227], v[64:67]
	v_mfma_f32_16x16x32_bf16 v[116:119], v[188:191], v[204:207], v[116:119]
	v_mfma_f32_16x16x32_bf16 v[112:115], v[196:199], v[204:207], v[112:115]
	v_mfma_f32_16x16x32_bf16 v[100:103], v[188:191], v[212:215], v[100:103]
	v_mfma_f32_16x16x32_bf16 v[96:99], v[196:199], v[212:215], v[96:99]
	v_mfma_f32_16x16x32_bf16 v[84:87], v[188:191], v[220:223], v[84:87]
	v_mfma_f32_16x16x32_bf16 v[80:83], v[196:199], v[220:223], v[80:83]
	v_mfma_f32_16x16x32_bf16 v[68:71], v[188:191], v[230:233], v[68:71]
	v_mfma_f32_16x16x32_bf16 v[64:67], v[196:199], v[230:233], v[64:67]
	s_setprio 0
	s_barrier
	s_add_i32 s38, s68, s42
	v_lshl_add_u64 v[150:151], v[150:151], 0, s[14:15]
	s_mov_b32 m0, s38
	ds_read_b128 v[200:203], v174 offset:49152
	ds_read_b128 v[204:207], v174 offset:50176
	ds_read_b128 v[208:211], v174 offset:51200
	ds_read_b128 v[212:215], v174 offset:52224
	ds_read_b128 v[216:219], v174 offset:53248
	ds_read_b128 v[220:223], v174 offset:54272
	ds_read_b128 v[224:227], v174 offset:55296
	ds_read_b128 v[230:233], v174 offset:56320
	global_load_lds_dwordx4 v[150:151], off
	s_add_i32 m0, s38, 0x2000
	s_add_u32 s36, s36, 0x40080
	v_lshl_add_u64 v[150:151], v[154:155], 0, s[14:15]
	s_addc_u32 s37, s37, 0
	s_add_i32 s38, s69, s42
	global_load_lds_dwordx4 v[150:151], off
	v_lshl_add_u64 v[150:151], s[36:37], 0, v[132:133]
	s_mov_b32 m0, s38
	s_nop 0
	global_load_lds_dwordx4 v[150:151], off
	v_lshl_add_u64 v[150:151], s[36:37], 0, v[128:129]
	s_add_i32 m0, s38, 0x2000
	s_nop 0
	global_load_lds_dwordx4 v[150:151], off
	v_lshl_add_u64 v[150:151], v[158:159], 0, s[14:15]
	s_mov_b32 m0, s49
	s_nop 0
	global_load_lds_dwordx4 v[150:151], off
	v_lshl_add_u64 v[150:151], v[162:163], 0, s[14:15]
	s_mov_b32 m0, s50
	s_nop 0
	global_load_lds_dwordx4 v[150:151], off
	s_waitcnt vmcnt(8)
	s_waitcnt lgkmcnt(0)
	s_setprio 1
	v_mfma_f32_16x16x32_bf16 v[60:63], v[146:149], v[200:203], v[60:63]
	v_mfma_f32_16x16x32_bf16 v[56:59], v[176:179], v[200:203], v[56:59]
	v_mfma_f32_16x16x32_bf16 v[44:47], v[146:149], v[208:211], v[44:47]
	v_mfma_f32_16x16x32_bf16 v[40:43], v[176:179], v[208:211], v[40:43]
	v_mfma_f32_16x16x32_bf16 v[28:31], v[146:149], v[216:219], v[28:31]
	v_mfma_f32_16x16x32_bf16 v[24:27], v[176:179], v[216:219], v[24:27]
	v_mfma_f32_16x16x32_bf16 v[12:15], v[146:149], v[224:227], v[12:15]
	v_mfma_f32_16x16x32_bf16 v[8:11], v[176:179], v[224:227], v[8:11]
	v_mfma_f32_16x16x32_bf16 v[60:63], v[166:169], v[204:207], v[60:63]
	v_mfma_f32_16x16x32_bf16 v[56:59], v[180:183], v[204:207], v[56:59]
	v_mfma_f32_16x16x32_bf16 v[44:47], v[166:169], v[212:215], v[44:47]
	v_mfma_f32_16x16x32_bf16 v[40:43], v[180:183], v[212:215], v[40:43]
	v_mfma_f32_16x16x32_bf16 v[28:31], v[166:169], v[220:223], v[28:31]
	v_mfma_f32_16x16x32_bf16 v[24:27], v[180:183], v[220:223], v[24:27]
	v_mfma_f32_16x16x32_bf16 v[12:15], v[166:169], v[230:233], v[12:15]
	v_mfma_f32_16x16x32_bf16 v[8:11], v[180:183], v[230:233], v[8:11]
	v_mfma_f32_16x16x32_bf16 v[52:55], v[184:187], v[200:203], v[52:55]
	v_mfma_f32_16x16x32_bf16 v[48:51], v[192:195], v[200:203], v[48:51]
	v_mfma_f32_16x16x32_bf16 v[36:39], v[184:187], v[208:211], v[36:39]
	v_mfma_f32_16x16x32_bf16 v[32:35], v[192:195], v[208:211], v[32:35]
	v_mfma_f32_16x16x32_bf16 v[20:23], v[184:187], v[216:219], v[20:23]
	v_mfma_f32_16x16x32_bf16 v[16:19], v[192:195], v[216:219], v[16:19]
	v_mfma_f32_16x16x32_bf16 v[4:7], v[184:187], v[224:227], v[4:7]
	v_mfma_f32_16x16x32_bf16 v[0:3], v[192:195], v[224:227], v[0:3]
	v_mfma_f32_16x16x32_bf16 v[52:55], v[188:191], v[204:207], v[52:55]
	v_mfma_f32_16x16x32_bf16 v[48:51], v[196:199], v[204:207], v[48:51]
	v_mfma_f32_16x16x32_bf16 v[36:39], v[188:191], v[212:215], v[36:39]
	v_mfma_f32_16x16x32_bf16 v[32:35], v[196:199], v[212:215], v[32:35]
	v_mfma_f32_16x16x32_bf16 v[20:23], v[188:191], v[220:223], v[20:23]
	v_mfma_f32_16x16x32_bf16 v[16:19], v[196:199], v[220:223], v[16:19]
	v_mfma_f32_16x16x32_bf16 v[4:7], v[188:191], v[230:233], v[4:7]
	v_mfma_f32_16x16x32_bf16 v[0:3], v[196:199], v[230:233], v[0:3]
	s_setprio 0
	s_barrier
	s_add_i32 s67, s67, 2
	s_add_u32 s4, s4, 0x100
	s_addc_u32 s5, s5, 0
	s_add_u32 s59, s59, 0x100
	s_addc_u32 s66, s66, 0
	s_cmp_gt_u32 s67, 13
	s_cbranch_scc0 .Lh0_5
	s_branch .Ljoin_5
.Lh1p_5:
	ds_read_b128 v[146:149], v172
	ds_read_b128 v[166:169], v172 offset:1024
	ds_read_b128 v[176:179], v172 offset:2048
	ds_read_b128 v[180:183], v172 offset:3072
	ds_read_b128 v[184:187], v173
	ds_read_b128 v[188:191], v173 offset:1024
	ds_read_b128 v[192:195], v173 offset:2048
	ds_read_b128 v[196:199], v173 offset:3072
	s_add_u32 s36, s4, 0xfffc0080
	s_addc_u32 s37, s5, -1
	s_cmp_eq_u32 s67, 12
	s_cselect_b32 s39, s19, s37
	s_cselect_b32 s38, s57, s36
	s_cselect_b32 s37, s11, s66
	s_cselect_b32 s36, s58, s59
	v_lshl_add_u64 v[150:151], s[4:5], 0, v[138:139]
	s_add_i32 m0, s27, 0xc000
	ds_read_b128 v[200:203], v174
	ds_read_b128 v[204:207], v174 offset:1024
	ds_read_b128 v[208:211], v174 offset:2048
	ds_read_b128 v[212:215], v174 offset:3072
	ds_read_b128 v[216:219], v174 offset:4096
	ds_read_b128 v[220:223], v174 offset:5120
	ds_read_b128 v[224:227], v174 offset:6144
	ds_read_b128 v[230:233], v174 offset:7168
	global_load_lds_dwordx4 v[150:151], off
	v_lshl_add_u64 v[150:151], s[4:5], 0, v[140:141]
	s_add_i32 m0, s27, 0xe000
	s_nop 0
	global_load_lds_dwordx4 v[150:151], off
	s_waitcnt vmcnt(8)
	s_waitcnt lgkmcnt(0)
	s_barrier
	s_setprio 2
	v_mfma_f32_16x16x32_bf16 v[124:127], v[146:149], v[200:203], 0
	v_mfma_f32_16x16x32_bf16 v[120:123], v[176:179], v[200:203], 0
	v_mfma_f32_16x16x32_bf16 v[108:111], v[146:149], v[208:211], 0
	v_mfma_f32_16x16x32_bf16 v[104:107], v[176:179], v[208:211], 0
	v_mfma_f32_16x16x32_bf16 v[92:95], v[146:149], v[216:219], 0
	v_mfma_f32_16x16x32_bf16 v[88:91], v[176:179], v[216:219], 0
	v_mfma_f32_16x16x32_bf16 v[76:79], v[146:149], v[224:227], 0
	v_mfma_f32_16x16x32_bf16 v[72:75], v[176:179], v[224:227], 0
	v_mfma_f32_16x16x32_bf16 v[124:127], v[166:169], v[204:207], v[124:127]
	v_mfma_f32_16x16x32_bf16 v[120:123], v[180:183], v[204:207], v[120:123]
	v_mfma_f32_16x16x32_bf16 v[108:111], v[166:169], v[212:215], v[108:111]
	v_mfma_f32_16x16x32_bf16 v[104:107], v[180:183], v[212:215], v[104:107]
	v_mfma_f32_16x16x32_bf16 v[92:95], v[166:169], v[220:223], v[92:95]
	v_mfma_f32_16x16x32_bf16 v[88:91], v[180:183], v[220:223], v[88:91]
	v_mfma_f32_16x16x32_bf16 v[76:79], v[166:169], v[230:233], v[76:79]
	v_mfma_f32_16x16x32_bf16 v[72:75], v[180:183], v[230:233], v[72:75]
	v_mfma_f32_16x16x32_bf16 v[116:119], v[184:187], v[200:203], 0
	v_mfma_f32_16x16x32_bf16 v[112:115], v[192:195], v[200:203], 0
	v_mfma_f32_16x16x32_bf16 v[100:103], v[184:187], v[208:211], 0
	v_mfma_f32_16x16x32_bf16 v[96:99], v[192:195], v[208:211], 0
	v_mfma_f32_16x16x32_bf16 v[84:87], v[184:187], v[216:219], 0
	v_mfma_f32_16x16x32_bf16 v[80:83], v[192:195], v[216:219], 0
	v_mfma_f32_16x16x32_bf16 v[68:71], v[184:187], v[224:227], 0
	v_mfma_f32_16x16x32_bf16 v[64:67], v[192:195], v[224:227], 0
	v_mfma_f32_16x16x32_bf16 v[116:119], v[188:191], v[204:207], v[116:119]
	v_mfma_f32_16x16x32_bf16 v[112:115], v[196:199], v[204:207], v[112:115]
	v_mfma_f32_16x16x32_bf16 v[100:103], v[188:191], v[212:215], v[100:103]
	v_mfma_f32_16x16x32_bf16 v[96:99], v[196:199], v[212:215], v[96:99]
	v_mfma_f32_16x16x32_bf16 v[84:87], v[188:191], v[220:223], v[84:87]
	v_mfma_f32_16x16x32_bf16 v[80:83], v[196:199], v[220:223], v[80:83]
	v_mfma_f32_16x16x32_bf16 v[68:71], v[188:191], v[230:233], v[68:71]
	v_mfma_f32_16x16x32_bf16 v[64:67], v[196:199], v[230:233], v[64:67]
	s_setprio 0
	s_add_i32 s68, s53, s42
	v_lshl_add_u64 v[150:151], s[36:37], 0, v[132:133]
	s_mov_b32 m0, s68
	ds_read_b128 v[200:203], v174 offset:16384
	ds_read_b128 v[204:207], v174 offset:17408
	ds_read_b128 v[208:211], v174 offset:18432
	ds_read_b128 v[212:215], v174 offset:19456
	ds_read_b128 v[216:219], v174 offset:20480
	ds_read_b128 v[220:223], v174 offset:21504
	ds_read_b128 v[224:227], v174 offset:22528
	ds_read_b128 v[230:233], v174 offset:23552
	global_load_lds_dwordx4 v[150:151], off
	s_add_i32 m0, s68, 0x2000
	s_add_u32 s68, s36, 0x40000
	v_lshl_add_u64 v[154:155], s[36:37], 0, v[128:129]
	s_addc_u32 s69, s37, 0
	s_add_i32 s70, s54, s42
	global_load_lds_dwordx4 v[154:155], off
	v_lshl_add_u64 v[158:159], s[68:69], 0, v[132:133]
	s_mov_b32 m0, s70
	v_lshl_add_u64 v[162:163], s[38:39], 0, v[130:131]
	global_load_lds_dwordx4 v[158:159], off
	v_lshl_add_u64 v[158:159], s[68:69], 0, v[128:129]
	s_add_i32 m0, s70, 0x2000
	s_nop 0
	global_load_lds_dwordx4 v[158:159], off
	v_lshl_add_u64 v[158:159], s[38:39], 0, v[134:135]
	s_mov_b32 m0, s27
	s_nop 0
	global_load_lds_dwordx4 v[158:159], off
	s_mov_b32 m0, s45
	s_nop 0
	global_load_lds_dwordx4 v[162:163], off
	s_waitcnt vmcnt(8)
	s_waitcnt lgkmcnt(0)
	s_barrier
	s_setprio 2
	v_mfma_f32_16x16x32_bf16 v[60:63], v[146:149], v[200:203], 0
	v_mfma_f32_16x16x32_bf16 v[56:59], v[176:179], v[200:203], 0
	v_mfma_f32_16x16x32_bf16 v[44:47], v[146:149], v[208:211], 0
	v_mfma_f32_16x16x32_bf16 v[40:43], v[176:179], v[208:211], 0
	v_mfma_f32_16x16x32_bf16 v[28:31], v[146:149], v[216:219], 0
	v_mfma_f32_16x16x32_bf16 v[24:27], v[176:179], v[216:219], 0
	v_mfma_f32_16x16x32_bf16 v[12:15], v[146:149], v[224:227], 0
	v_mfma_f32_16x16x32_bf16 v[8:11], v[176:179], v[224:227], 0
	v_mfma_f32_16x16x32_bf16 v[60:63], v[166:169], v[204:207], v[60:63]
	v_mfma_f32_16x16x32_bf16 v[56:59], v[180:183], v[204:207], v[56:59]
	v_mfma_f32_16x16x32_bf16 v[44:47], v[166:169], v[212:215], v[44:47]
	v_mfma_f32_16x16x32_bf16 v[40:43], v[180:183], v[212:215], v[40:43]
	v_mfma_f32_16x16x32_bf16 v[28:31], v[166:169], v[220:223], v[28:31]
	v_mfma_f32_16x16x32_bf16 v[24:27], v[180:183], v[220:223], v[24:27]
	v_mfma_f32_16x16x32_bf16 v[12:15], v[166:169], v[230:233], v[12:15]
	v_mfma_f32_16x16x32_bf16 v[8:11], v[180:183], v[230:233], v[8:11]
	v_mfma_f32_16x16x32_bf16 v[52:55], v[184:187], v[200:203], 0
	v_mfma_f32_16x16x32_bf16 v[48:51], v[192:195], v[200:203], 0
	v_mfma_f32_16x16x32_bf16 v[36:39], v[184:187], v[208:211], 0
	v_mfma_f32_16x16x32_bf16 v[32:35], v[192:195], v[208:211], 0
	v_mfma_f32_16x16x32_bf16 v[20:23], v[184:187], v[216:219], 0
	v_mfma_f32_16x16x32_bf16 v[16:19], v[192:195], v[216:219], 0
	v_mfma_f32_16x16x32_bf16 v[4:7], v[184:187], v[224:227], 0
	v_mfma_f32_16x16x32_bf16 v[0:3], v[192:195], v[224:227], 0
	v_mfma_f32_16x16x32_bf16 v[52:55], v[188:191], v[204:207], v[52:55]
	v_mfma_f32_16x16x32_bf16 v[48:51], v[196:199], v[204:207], v[48:51]
	v_mfma_f32_16x16x32_bf16 v[36:39], v[188:191], v[212:215], v[36:39]
	v_mfma_f32_16x16x32_bf16 v[32:35], v[196:199], v[212:215], v[32:35]
	v_mfma_f32_16x16x32_bf16 v[20:23], v[188:191], v[220:223], v[20:23]
	v_mfma_f32_16x16x32_bf16 v[16:19], v[196:199], v[220:223], v[16:19]
	v_mfma_f32_16x16x32_bf16 v[4:7], v[188:191], v[230:233], v[4:7]
	v_mfma_f32_16x16x32_bf16 v[0:3], v[196:199], v[230:233], v[0:3]
	s_setprio 0
	s_add_i32 s68, 0, 0x18000
	v_add_u32_e32 v152, s68, v157
	s_add_i32 s69, 0, 0x1c000
	ds_read_b128 v[146:149], v152
	ds_read_b128 v[166:169], v152 offset:1024
	ds_read_b128 v[176:179], v152 offset:2048
	ds_read_b128 v[180:183], v152 offset:3072
	v_add_u32_e32 v152, s69, v157
	ds_read_b128 v[184:187], v152
	ds_read_b128 v[188:191], v152 offset:1024
	ds_read_b128 v[192:195], v152 offset:2048
	ds_read_b128 v[196:199], v152 offset:3072
	s_add_u32 s38, s38, 0x40000
	s_addc_u32 s39, s39, 0
	s_mov_b32 m0, s46
	v_lshl_add_u64 v[234:235], s[38:39], 0, v[134:135]
	ds_read_b128 v[200:203], v174 offset:32768
	ds_read_b128 v[204:207], v174 offset:33792
	ds_read_b128 v[208:211], v174 offset:34816
	ds_read_b128 v[212:215], v174 offset:35840
	ds_read_b128 v[216:219], v174 offset:36864
	ds_read_b128 v[220:223], v174 offset:37888
	ds_read_b128 v[224:227], v174 offset:38912
	ds_read_b128 v[230:233], v174 offset:39936
	global_load_lds_dwordx4 v[234:235], off
	v_lshl_add_u64 v[234:235], s[38:39], 0, v[130:131]
	s_mov_b32 m0, s47
	s_nop 0
	global_load_lds_dwordx4 v[234:235], off
	s_waitcnt vmcnt(8)
	s_waitcnt lgkmcnt(0)
	s_barrier
	s_setprio 2
	v_mfma_f32_16x16x32_bf16 v[124:127], v[146:149], v[200:203], v[124:127]
	v_mfma_f32_16x16x32_bf16 v[120:123], v[176:179], v[200:203], v[120:123]
	v_mfma_f32_16x16x32_bf16 v[108:111], v[146:149], v[208:211], v[108:111]
	v_mfma_f32_16x16x32_bf16 v[104:107], v[176:179], v[208:211], v[104:107]
	v_mfma_f32_16x16x32_bf16 v[92:95], v[146:149], v[216:219], v[92:95]
	v_mfma_f32_16x16x32_bf16 v[88:91], v[176:179], v[216:219], v[88:91]
	v_mfma_f32_16x16x32_bf16 v[76:79], v[146:149], v[224:227], v[76:79]
	v_mfma_f32_16x16x32_bf16 v[72:75], v[176:179], v[224:227], v[72:75]
	v_mfma_f32_16x16x32_bf16 v[124:127], v[166:169], v[204:207], v[124:127]
	v_mfma_f32_16x16x32_bf16 v[120:123], v[180:183], v[204:207], v[120:123]
	v_mfma_f32_16x16x32_bf16 v[108:111], v[166:169], v[212:215], v[108:111]
	v_mfma_f32_16x16x32_bf16 v[104:107], v[180:183], v[212:215], v[104:107]
	v_mfma_f32_16x16x32_bf16 v[92:95], v[166:169], v[220:223], v[92:95]
	v_mfma_f32_16x16x32_bf16 v[88:91], v[180:183], v[220:223], v[88:91]
	v_mfma_f32_16x16x32_bf16 v[76:79], v[166:169], v[230:233], v[76:79]
	v_mfma_f32_16x16x32_bf16 v[72:75], v[180:183], v[230:233], v[72:75]
	v_mfma_f32_16x16x32_bf16 v[116:119], v[184:187], v[200:203], v[116:119]
	v_mfma_f32_16x16x32_bf16 v[112:115], v[192:195], v[200:203], v[112:115]
	v_mfma_f32_16x16x32_bf16 v[100:103], v[184:187], v[208:211], v[100:103]
	v_mfma_f32_16x16x32_bf16 v[96:99], v[192:195], v[208:211], v[96:99]
	v_mfma_f32_16x16x32_bf16 v[84:87], v[184:187], v[216:219], v[84:87]
	v_mfma_f32_16x16x32_bf16 v[80:83], v[192:195], v[216:219], v[80:83]
	v_mfma_f32_16x16x32_bf16 v[68:71], v[184:187], v[224:227], v[68:71]
	v_mfma_f32_16x16x32_bf16 v[64:67], v[192:195], v[224:227], v[64:67]
	v_mfma_f32_16x16x32_bf16 v[116:119], v[188:191], v[204:207], v[116:119]
	v_mfma_f32_16x16x32_bf16 v[112:115], v[196:199], v[204:207], v[112:115]
	v_mfma_f32_16x16x32_bf16 v[100:103], v[188:191], v[212:215], v[100:103]
	v_mfma_f32_16x16x32_bf16 v[96:99], v[196:199], v[212:215], v[96:99]
	v_mfma_f32_16x16x32_bf16 v[84:87], v[188:191], v[220:223], v[84:87]
	v_mfma_f32_16x16x32_bf16 v[80:83], v[196:199], v[220:223], v[80:83]
	v_mfma_f32_16x16x32_bf16 v[68:71], v[188:191], v[230:233], v[68:71]
	v_mfma_f32_16x16x32_bf16 v[64:67], v[196:199], v[230:233], v[64:67]
	s_setprio 0
	s_add_i32 s38, s68, s42
	v_lshl_add_u64 v[150:151], v[150:151], 0, s[14:15]
	s_mov_b32 m0, s38
	ds_read_b128 v[200:203], v174 offset:49152
	ds_read_b128 v[204:207], v174 offset:50176
	ds_read_b128 v[208:211], v174 offset:51200
	ds_read_b128 v[212:215], v174 offset:52224
	ds_read_b128 v[216:219], v174 offset:53248
	ds_read_b128 v[220:223], v174 offset:54272
	ds_read_b128 v[224:227], v174 offset:55296
	ds_read_b128 v[230:233], v174 offset:56320
	global_load_lds_dwordx4 v[150:151], off
	s_add_i32 m0, s38, 0x2000
	s_add_u32 s36, s36, 0x40080
	v_lshl_add_u64 v[150:151], v[154:155], 0, s[14:15]
	s_addc_u32 s37, s37, 0
	s_add_i32 s38, s69, s42
	global_load_lds_dwordx4 v[150:151], off
	v_lshl_add_u64 v[150:151], s[36:37], 0, v[132:133]
	s_mov_b32 m0, s38
	s_nop 0
	global_load_lds_dwordx4 v[150:151], off
	v_lshl_add_u64 v[150:151], s[36:37], 0, v[128:129]
	s_add_i32 m0, s38, 0x2000
	s_nop 0
	global_load_lds_dwordx4 v[150:151], off
	v_lshl_add_u64 v[150:151], v[158:159], 0, s[14:15]
	s_mov_b32 m0, s49
	s_nop 0
	global_load_lds_dwordx4 v[150:151], off
	v_lshl_add_u64 v[150:151], v[162:163], 0, s[14:15]
	s_mov_b32 m0, s50
	s_nop 0
	global_load_lds_dwordx4 v[150:151], off
	s_waitcnt vmcnt(8)
	s_waitcnt lgkmcnt(0)
	s_barrier
	s_setprio 2
	v_mfma_f32_16x16x32_bf16 v[60:63], v[146:149], v[200:203], v[60:63]
	v_mfma_f32_16x16x32_bf16 v[56:59], v[176:179], v[200:203], v[56:59]
	v_mfma_f32_16x16x32_bf16 v[44:47], v[146:149], v[208:211], v[44:47]
	v_mfma_f32_16x16x32_bf16 v[40:43], v[176:179], v[208:211], v[40:43]
	v_mfma_f32_16x16x32_bf16 v[28:31], v[146:149], v[216:219], v[28:31]
	v_mfma_f32_16x16x32_bf16 v[24:27], v[176:179], v[216:219], v[24:27]
	v_mfma_f32_16x16x32_bf16 v[12:15], v[146:149], v[224:227], v[12:15]
	v_mfma_f32_16x16x32_bf16 v[8:11], v[176:179], v[224:227], v[8:11]
	v_mfma_f32_16x16x32_bf16 v[60:63], v[166:169], v[204:207], v[60:63]
	v_mfma_f32_16x16x32_bf16 v[56:59], v[180:183], v[204:207], v[56:59]
	v_mfma_f32_16x16x32_bf16 v[44:47], v[166:169], v[212:215], v[44:47]
	v_mfma_f32_16x16x32_bf16 v[40:43], v[180:183], v[212:215], v[40:43]
	v_mfma_f32_16x16x32_bf16 v[28:31], v[166:169], v[220:223], v[28:31]
	v_mfma_f32_16x16x32_bf16 v[24:27], v[180:183], v[220:223], v[24:27]
	v_mfma_f32_16x16x32_bf16 v[12:15], v[166:169], v[230:233], v[12:15]
	v_mfma_f32_16x16x32_bf16 v[8:11], v[180:183], v[230:233], v[8:11]
	v_mfma_f32_16x16x32_bf16 v[52:55], v[184:187], v[200:203], v[52:55]
	v_mfma_f32_16x16x32_bf16 v[48:51], v[192:195], v[200:203], v[48:51]
	v_mfma_f32_16x16x32_bf16 v[36:39], v[184:187], v[208:211], v[36:39]
	v_mfma_f32_16x16x32_bf16 v[32:35], v[192:195], v[208:211], v[32:35]
	v_mfma_f32_16x16x32_bf16 v[20:23], v[184:187], v[216:219], v[20:23]
	v_mfma_f32_16x16x32_bf16 v[16:19], v[192:195], v[216:219], v[16:19]
	v_mfma_f32_16x16x32_bf16 v[4:7], v[184:187], v[224:227], v[4:7]
	v_mfma_f32_16x16x32_bf16 v[0:3], v[192:195], v[224:227], v[0:3]
	v_mfma_f32_16x16x32_bf16 v[52:55], v[188:191], v[204:207], v[52:55]
	v_mfma_f32_16x16x32_bf16 v[48:51], v[196:199], v[204:207], v[48:51]
	v_mfma_f32_16x16x32_bf16 v[36:39], v[188:191], v[212:215], v[36:39]
	v_mfma_f32_16x16x32_bf16 v[32:35], v[196:199], v[212:215], v[32:35]
	v_mfma_f32_16x16x32_bf16 v[20:23], v[188:191], v[220:223], v[20:23]
	v_mfma_f32_16x16x32_bf16 v[16:19], v[196:199], v[220:223], v[16:19]
	v_mfma_f32_16x16x32_bf16 v[4:7], v[188:191], v[230:233], v[4:7]
	v_mfma_f32_16x16x32_bf16 v[0:3], v[196:199], v[230:233], v[0:3]
	s_setprio 0
	s_add_i32 s67, s67, 2
	s_add_u32 s4, s4, 0x100
	s_addc_u32 s5, s5, 0
	s_add_u32 s59, s59, 0x100
	s_addc_u32 s66, s66, 0
	s_cmp_gt_u32 s67, 13
.Lh1_5:
	ds_read_b128 v[146:149], v172
	ds_read_b128 v[166:169], v172 offset:1024
	ds_read_b128 v[176:179], v172 offset:2048
	ds_read_b128 v[180:183], v172 offset:3072
	ds_read_b128 v[184:187], v173
	ds_read_b128 v[188:191], v173 offset:1024
	ds_read_b128 v[192:195], v173 offset:2048
	ds_read_b128 v[196:199], v173 offset:3072
	s_add_u32 s36, s4, 0xfffc0080
	s_addc_u32 s37, s5, -1
	s_cmp_eq_u32 s67, 12
	s_cselect_b32 s39, s19, s37
	s_cselect_b32 s38, s57, s36
	s_cselect_b32 s37, s11, s66
	s_cselect_b32 s36, s58, s59
	v_lshl_add_u64 v[150:151], s[4:5], 0, v[138:139]
	s_add_i32 m0, s27, 0xc000
	ds_read_b128 v[200:203], v174
	ds_read_b128 v[204:207], v174 offset:1024
	ds_read_b128 v[208:211], v174 offset:2048
	ds_read_b128 v[212:215], v174 offset:3072
	ds_read_b128 v[216:219], v174 offset:4096
	ds_read_b128 v[220:223], v174 offset:5120
	ds_read_b128 v[224:227], v174 offset:6144
	ds_read_b128 v[230:233], v174 offset:7168
	global_load_lds_dwordx4 v[150:151], off
	v_lshl_add_u64 v[150:151], s[4:5], 0, v[140:141]
	s_add_i32 m0, s27, 0xe000
	s_nop 0
	global_load_lds_dwordx4 v[150:151], off
	s_waitcnt vmcnt(8)
	s_waitcnt lgkmcnt(0)
	s_barrier
	s_setprio 2
	v_mfma_f32_16x16x32_bf16 v[124:127], v[146:149], v[200:203], v[124:127]
	v_mfma_f32_16x16x32_bf16 v[120:123], v[176:179], v[200:203], v[120:123]
	v_mfma_f32_16x16x32_bf16 v[108:111], v[146:149], v[208:211], v[108:111]
	v_mfma_f32_16x16x32_bf16 v[104:107], v[176:179], v[208:211], v[104:107]
	v_mfma_f32_16x16x32_bf16 v[92:95], v[146:149], v[216:219], v[92:95]
	v_mfma_f32_16x16x32_bf16 v[88:91], v[176:179], v[216:219], v[88:91]
	v_mfma_f32_16x16x32_bf16 v[76:79], v[146:149], v[224:227], v[76:79]
	v_mfma_f32_16x16x32_bf16 v[72:75], v[176:179], v[224:227], v[72:75]
	v_mfma_f32_16x16x32_bf16 v[124:127], v[166:169], v[204:207], v[124:127]
	v_mfma_f32_16x16x32_bf16 v[120:123], v[180:183], v[204:207], v[120:123]
	v_mfma_f32_16x16x32_bf16 v[108:111], v[166:169], v[212:215], v[108:111]
	v_mfma_f32_16x16x32_bf16 v[104:107], v[180:183], v[212:215], v[104:107]
	v_mfma_f32_16x16x32_bf16 v[92:95], v[166:169], v[220:223], v[92:95]
	v_mfma_f32_16x16x32_bf16 v[88:91], v[180:183], v[220:223], v[88:91]
	v_mfma_f32_16x16x32_bf16 v[76:79], v[166:169], v[230:233], v[76:79]
	v_mfma_f32_16x16x32_bf16 v[72:75], v[180:183], v[230:233], v[72:75]
	v_mfma_f32_16x16x32_bf16 v[116:119], v[184:187], v[200:203], v[116:119]
	v_mfma_f32_16x16x32_bf16 v[112:115], v[192:195], v[200:203], v[112:115]
	v_mfma_f32_16x16x32_bf16 v[100:103], v[184:187], v[208:211], v[100:103]
	v_mfma_f32_16x16x32_bf16 v[96:99], v[192:195], v[208:211], v[96:99]
	v_mfma_f32_16x16x32_bf16 v[84:87], v[184:187], v[216:219], v[84:87]
	v_mfma_f32_16x16x32_bf16 v[80:83], v[192:195], v[216:219], v[80:83]
	v_mfma_f32_16x16x32_bf16 v[68:71], v[184:187], v[224:227], v[68:71]
	v_mfma_f32_16x16x32_bf16 v[64:67], v[192:195], v[224:227], v[64:67]
	v_mfma_f32_16x16x32_bf16 v[116:119], v[188:191], v[204:207], v[116:119]
	v_mfma_f32_16x16x32_bf16 v[112:115], v[196:199], v[204:207], v[112:115]
	v_mfma_f32_16x16x32_bf16 v[100:103], v[188:191], v[212:215], v[100:103]
	v_mfma_f32_16x16x32_bf16 v[96:99], v[196:199], v[212:215], v[96:99]
	v_mfma_f32_16x16x32_bf16 v[84:87], v[188:191], v[220:223], v[84:87]
	v_mfma_f32_16x16x32_bf16 v[80:83], v[196:199], v[220:223], v[80:83]
	v_mfma_f32_16x16x32_bf16 v[68:71], v[188:191], v[230:233], v[68:71]
	v_mfma_f32_16x16x32_bf16 v[64:67], v[196:199], v[230:233], v[64:67]
	s_setprio 0
	s_add_i32 s68, s53, s42
	v_lshl_add_u64 v[150:151], s[36:37], 0, v[132:133]
	s_mov_b32 m0, s68
	ds_read_b128 v[200:203], v174 offset:16384
	ds_read_b128 v[204:207], v174 offset:17408
	ds_read_b128 v[208:211], v174 offset:18432
	ds_read_b128 v[212:215], v174 offset:19456
	ds_read_b128 v[216:219], v174 offset:20480
	ds_read_b128 v[220:223], v174 offset:21504
	ds_read_b128 v[224:227], v174 offset:22528
	ds_read_b128 v[230:233], v174 offset:23552
	global_load_lds_dwordx4 v[150:151], off
	s_add_i32 m0, s68, 0x2000
	s_add_u32 s68, s36, 0x40000
	v_lshl_add_u64 v[154:155], s[36:37], 0, v[128:129]
	s_addc_u32 s69, s37, 0
	s_add_i32 s70, s54, s42
	global_load_lds_dwordx4 v[154:155], off
	v_lshl_add_u64 v[158:159], s[68:69], 0, v[132:133]
	s_mov_b32 m0, s70
	v_lshl_add_u64 v[162:163], s[38:39], 0, v[130:131]
	global_load_lds_dwordx4 v[158:159], off
	v_lshl_add_u64 v[158:159], s[68:69], 0, v[128:129]
	s_add_i32 m0, s70, 0x2000
	s_nop 0
	global_load_lds_dwordx4 v[158:159], off
	v_lshl_add_u64 v[158:159], s[38:39], 0, v[134:135]
	s_mov_b32 m0, s27
	s_nop 0
	global_load_lds_dwordx4 v[158:159], off
	s_mov_b32 m0, s45
	s_nop 0
	global_load_lds_dwordx4 v[162:163], off
	s_waitcnt vmcnt(8)
	s_waitcnt lgkmcnt(0)
	s_barrier
	s_setprio 2
	v_mfma_f32_16x16x32_bf16 v[60:63], v[146:149], v[200:203], v[60:63]
	v_mfma_f32_16x16x32_bf16 v[56:59], v[176:179], v[200:203], v[56:59]
	v_mfma_f32_16x16x32_bf16 v[44:47], v[146:149], v[208:211], v[44:47]
	v_mfma_f32_16x16x32_bf16 v[40:43], v[176:179], v[208:211], v[40:43]
	v_mfma_f32_16x16x32_bf16 v[28:31], v[146:149], v[216:219], v[28:31]
	v_mfma_f32_16x16x32_bf16 v[24:27], v[176:179], v[216:219], v[24:27]
	v_mfma_f32_16x16x32_bf16 v[12:15], v[146:149], v[224:227], v[12:15]
	v_mfma_f32_16x16x32_bf16 v[8:11], v[176:179], v[224:227], v[8:11]
	v_mfma_f32_16x16x32_bf16 v[60:63], v[166:169], v[204:207], v[60:63]
	v_mfma_f32_16x16x32_bf16 v[56:59], v[180:183], v[204:207], v[56:59]
	v_mfma_f32_16x16x32_bf16 v[44:47], v[166:169], v[212:215], v[44:47]
	v_mfma_f32_16x16x32_bf16 v[40:43], v[180:183], v[212:215], v[40:43]
	v_mfma_f32_16x16x32_bf16 v[28:31], v[166:169], v[220:223], v[28:31]
	v_mfma_f32_16x16x32_bf16 v[24:27], v[180:183], v[220:223], v[24:27]
	v_mfma_f32_16x16x32_bf16 v[12:15], v[166:169], v[230:233], v[12:15]
	v_mfma_f32_16x16x32_bf16 v[8:11], v[180:183], v[230:233], v[8:11]
	v_mfma_f32_16x16x32_bf16 v[52:55], v[184:187], v[200:203], v[52:55]
	v_mfma_f32_16x16x32_bf16 v[48:51], v[192:195], v[200:203], v[48:51]
	v_mfma_f32_16x16x32_bf16 v[36:39], v[184:187], v[208:211], v[36:39]
	v_mfma_f32_16x16x32_bf16 v[32:35], v[192:195], v[208:211], v[32:35]
	v_mfma_f32_16x16x32_bf16 v[20:23], v[184:187], v[216:219], v[20:23]
	v_mfma_f32_16x16x32_bf16 v[16:19], v[192:195], v[216:219], v[16:19]
	v_mfma_f32_16x16x32_bf16 v[4:7], v[184:187], v[224:227], v[4:7]
	v_mfma_f32_16x16x32_bf16 v[0:3], v[192:195], v[224:227], v[0:3]
	v_mfma_f32_16x16x32_bf16 v[52:55], v[188:191], v[204:207], v[52:55]
	v_mfma_f32_16x16x32_bf16 v[48:51], v[196:199], v[204:207], v[48:51]
	v_mfma_f32_16x16x32_bf16 v[36:39], v[188:191], v[212:215], v[36:39]
	v_mfma_f32_16x16x32_bf16 v[32:35], v[196:199], v[212:215], v[32:35]
	v_mfma_f32_16x16x32_bf16 v[20:23], v[188:191], v[220:223], v[20:23]
	v_mfma_f32_16x16x32_bf16 v[16:19], v[196:199], v[220:223], v[16:19]
	v_mfma_f32_16x16x32_bf16 v[4:7], v[188:191], v[230:233], v[4:7]
	v_mfma_f32_16x16x32_bf16 v[0:3], v[196:199], v[230:233], v[0:3]
	s_setprio 0
	s_add_i32 s68, 0, 0x18000
	v_add_u32_e32 v152, s68, v157
	s_add_i32 s69, 0, 0x1c000
	ds_read_b128 v[146:149], v152
	ds_read_b128 v[166:169], v152 offset:1024
	ds_read_b128 v[176:179], v152 offset:2048
	ds_read_b128 v[180:183], v152 offset:3072
	v_add_u32_e32 v152, s69, v157
	ds_read_b128 v[184:187], v152
	ds_read_b128 v[188:191], v152 offset:1024
	ds_read_b128 v[192:195], v152 offset:2048
	ds_read_b128 v[196:199], v152 offset:3072
	s_add_u32 s38, s38, 0x40000
	s_addc_u32 s39, s39, 0
	s_mov_b32 m0, s46
	v_lshl_add_u64 v[234:235], s[38:39], 0, v[134:135]
	ds_read_b128 v[200:203], v174 offset:32768
	ds_read_b128 v[204:207], v174 offset:33792
	ds_read_b128 v[208:211], v174 offset:34816
	ds_read_b128 v[212:215], v174 offset:35840
	ds_read_b128 v[216:219], v174 offset:36864
	ds_read_b128 v[220:223], v174 offset:37888
	ds_read_b128 v[224:227], v174 offset:38912
	ds_read_b128 v[230:233], v174 offset:39936
	global_load_lds_dwordx4 v[234:235], off
	v_lshl_add_u64 v[234:235], s[38:39], 0, v[130:131]
	s_mov_b32 m0, s47
	s_nop 0
	global_load_lds_dwordx4 v[234:235], off
	s_waitcnt vmcnt(8)
	s_waitcnt lgkmcnt(0)
	s_barrier
	s_setprio 2
	v_mfma_f32_16x16x32_bf16 v[124:127], v[146:149], v[200:203], v[124:127]
	v_mfma_f32_16x16x32_bf16 v[120:123], v[176:179], v[200:203], v[120:123]
	v_mfma_f32_16x16x32_bf16 v[108:111], v[146:149], v[208:211], v[108:111]
	v_mfma_f32_16x16x32_bf16 v[104:107], v[176:179], v[208:211], v[104:107]
	v_mfma_f32_16x16x32_bf16 v[92:95], v[146:149], v[216:219], v[92:95]
	v_mfma_f32_16x16x32_bf16 v[88:91], v[176:179], v[216:219], v[88:91]
	v_mfma_f32_16x16x32_bf16 v[76:79], v[146:149], v[224:227], v[76:79]
	v_mfma_f32_16x16x32_bf16 v[72:75], v[176:179], v[224:227], v[72:75]
	v_mfma_f32_16x16x32_bf16 v[124:127], v[166:169], v[204:207], v[124:127]
	v_mfma_f32_16x16x32_bf16 v[120:123], v[180:183], v[204:207], v[120:123]
	v_mfma_f32_16x16x32_bf16 v[108:111], v[166:169], v[212:215], v[108:111]
	v_mfma_f32_16x16x32_bf16 v[104:107], v[180:183], v[212:215], v[104:107]
	v_mfma_f32_16x16x32_bf16 v[92:95], v[166:169], v[220:223], v[92:95]
	v_mfma_f32_16x16x32_bf16 v[88:91], v[180:183], v[220:223], v[88:91]
	v_mfma_f32_16x16x32_bf16 v[76:79], v[166:169], v[230:233], v[76:79]
	v_mfma_f32_16x16x32_bf16 v[72:75], v[180:183], v[230:233], v[72:75]
	v_mfma_f32_16x16x32_bf16 v[116:119], v[184:187], v[200:203], v[116:119]
	v_mfma_f32_16x16x32_bf16 v[112:115], v[192:195], v[200:203], v[112:115]
	v_mfma_f32_16x16x32_bf16 v[100:103], v[184:187], v[208:211], v[100:103]
	v_mfma_f32_16x16x32_bf16 v[96:99], v[192:195], v[208:211], v[96:99]
	v_mfma_f32_16x16x32_bf16 v[84:87], v[184:187], v[216:219], v[84:87]
	v_mfma_f32_16x16x32_bf16 v[80:83], v[192:195], v[216:219], v[80:83]
	v_mfma_f32_16x16x32_bf16 v[68:71], v[184:187], v[224:227], v[68:71]
	v_mfma_f32_16x16x32_bf16 v[64:67], v[192:195], v[224:227], v[64:67]
	v_mfma_f32_16x16x32_bf16 v[116:119], v[188:191], v[204:207], v[116:119]
	v_mfma_f32_16x16x32_bf16 v[112:115], v[196:199], v[204:207], v[112:115]
	v_mfma_f32_16x16x32_bf16 v[100:103], v[188:191], v[212:215], v[100:103]
	v_mfma_f32_16x16x32_bf16 v[96:99], v[196:199], v[212:215], v[96:99]
	v_mfma_f32_16x16x32_bf16 v[84:87], v[188:191], v[220:223], v[84:87]
	v_mfma_f32_16x16x32_bf16 v[80:83], v[196:199], v[220:223], v[80:83]
	v_mfma_f32_16x16x32_bf16 v[68:71], v[188:191], v[230:233], v[68:71]
	v_mfma_f32_16x16x32_bf16 v[64:67], v[196:199], v[230:233], v[64:67]
	s_setprio 0
	s_add_i32 s38, s68, s42
	v_lshl_add_u64 v[150:151], v[150:151], 0, s[14:15]
	s_mov_b32 m0, s38
	ds_read_b128 v[200:203], v174 offset:49152
	ds_read_b128 v[204:207], v174 offset:50176
	ds_read_b128 v[208:211], v174 offset:51200
	ds_read_b128 v[212:215], v174 offset:52224
	ds_read_b128 v[216:219], v174 offset:53248
	ds_read_b128 v[220:223], v174 offset:54272
	ds_read_b128 v[224:227], v174 offset:55296
	ds_read_b128 v[230:233], v174 offset:56320
	global_load_lds_dwordx4 v[150:151], off
	s_add_i32 m0, s38, 0x2000
	s_add_u32 s36, s36, 0x40080
	v_lshl_add_u64 v[150:151], v[154:155], 0, s[14:15]
	s_addc_u32 s37, s37, 0
	s_add_i32 s38, s69, s42
	global_load_lds_dwordx4 v[150:151], off
	v_lshl_add_u64 v[150:151], s[36:37], 0, v[132:133]
	s_mov_b32 m0, s38
	s_nop 0
	global_load_lds_dwordx4 v[150:151], off
	v_lshl_add_u64 v[150:151], s[36:37], 0, v[128:129]
	s_add_i32 m0, s38, 0x2000
	s_nop 0
	global_load_lds_dwordx4 v[150:151], off
	v_lshl_add_u64 v[150:151], v[158:159], 0, s[14:15]
	s_mov_b32 m0, s49
	s_nop 0
	global_load_lds_dwordx4 v[150:151], off
	v_lshl_add_u64 v[150:151], v[162:163], 0, s[14:15]
	s_mov_b32 m0, s50
	s_nop 0
	global_load_lds_dwordx4 v[150:151], off
	s_waitcnt vmcnt(8)
	s_waitcnt lgkmcnt(0)
	s_barrier
	s_setprio 2
	v_mfma_f32_16x16x32_bf16 v[60:63], v[146:149], v[200:203], v[60:63]
	v_mfma_f32_16x16x32_bf16 v[56:59], v[176:179], v[200:203], v[56:59]
	v_mfma_f32_16x16x32_bf16 v[44:47], v[146:149], v[208:211], v[44:47]
	v_mfma_f32_16x16x32_bf16 v[40:43], v[176:179], v[208:211], v[40:43]
	v_mfma_f32_16x16x32_bf16 v[28:31], v[146:149], v[216:219], v[28:31]
	v_mfma_f32_16x16x32_bf16 v[24:27], v[176:179], v[216:219], v[24:27]
	v_mfma_f32_16x16x32_bf16 v[12:15], v[146:149], v[224:227], v[12:15]
	v_mfma_f32_16x16x32_bf16 v[8:11], v[176:179], v[224:227], v[8:11]
	v_mfma_f32_16x16x32_bf16 v[60:63], v[166:169], v[204:207], v[60:63]
	v_mfma_f32_16x16x32_bf16 v[56:59], v[180:183], v[204:207], v[56:59]
	v_mfma_f32_16x16x32_bf16 v[44:47], v[166:169], v[212:215], v[44:47]
	v_mfma_f32_16x16x32_bf16 v[40:43], v[180:183], v[212:215], v[40:43]
	v_mfma_f32_16x16x32_bf16 v[28:31], v[166:169], v[220:223], v[28:31]
	v_mfma_f32_16x16x32_bf16 v[24:27], v[180:183], v[220:223], v[24:27]
	v_mfma_f32_16x16x32_bf16 v[12:15], v[166:169], v[230:233], v[12:15]
	v_mfma_f32_16x16x32_bf16 v[8:11], v[180:183], v[230:233], v[8:11]
	v_mfma_f32_16x16x32_bf16 v[52:55], v[184:187], v[200:203], v[52:55]
	v_mfma_f32_16x16x32_bf16 v[48:51], v[192:195], v[200:203], v[48:51]
	v_mfma_f32_16x16x32_bf16 v[36:39], v[184:187], v[208:211], v[36:39]
	v_mfma_f32_16x16x32_bf16 v[32:35], v[192:195], v[208:211], v[32:35]
	v_mfma_f32_16x16x32_bf16 v[20:23], v[184:187], v[216:219], v[20:23]
	v_mfma_f32_16x16x32_bf16 v[16:19], v[192:195], v[216:219], v[16:19]
	v_mfma_f32_16x16x32_bf16 v[4:7], v[184:187], v[224:227], v[4:7]
	v_mfma_f32_16x16x32_bf16 v[0:3], v[192:195], v[224:227], v[0:3]
	v_mfma_f32_16x16x32_bf16 v[52:55], v[188:191], v[204:207], v[52:55]
	v_mfma_f32_16x16x32_bf16 v[48:51], v[196:199], v[204:207], v[48:51]
	v_mfma_f32_16x16x32_bf16 v[36:39], v[188:191], v[212:215], v[36:39]
	v_mfma_f32_16x16x32_bf16 v[32:35], v[196:199], v[212:215], v[32:35]
	v_mfma_f32_16x16x32_bf16 v[20:23], v[188:191], v[220:223], v[20:23]
	v_mfma_f32_16x16x32_bf16 v[16:19], v[196:199], v[220:223], v[16:19]
	v_mfma_f32_16x16x32_bf16 v[4:7], v[188:191], v[230:233], v[4:7]
	v_mfma_f32_16x16x32_bf16 v[0:3], v[196:199], v[230:233], v[0:3]
	s_setprio 0
	s_add_i32 s67, s67, 2
	s_add_u32 s4, s4, 0x100
	s_addc_u32 s5, s5, 0
	s_add_u32 s59, s59, 0x100
	s_addc_u32 s66, s66, 0
	s_cmp_gt_u32 s67, 13
	s_cbranch_scc0 .Lh1_5
.Ljoin_5:
	s_and_b64 vcc, exec, s[16:17]
	s_cbranch_vccz .LBB0_762
.LBB0_762:
	v_lshl_add_u32 v168, s26, 8, v153
	v_ashrrev_i32_e32 v169, 31, v168
	v_or_b32_e32 v166, 16, v168
	v_lshlrev_b64 v[146:147], 6, v[168:169]
	v_ashrrev_i32_e32 v167, 31, v166
	v_lshl_add_u64 v[146:147], v[136:137], 0, v[146:147]
	v_lshlrev_b64 v[148:149], 6, v[166:167]
	v_lshl_add_u64 v[148:149], v[136:137], 0, v[148:149]
	global_load_dwordx4 v[176:179], v[146:147], off
	global_load_dwordx4 v[180:183], v[148:149], off
	v_or_b32_e32 v162, 32, v168
	v_ashrrev_i32_e32 v163, 31, v162
	v_or_b32_e32 v158, 48, v168
	v_lshlrev_b64 v[146:147], 6, v[162:163]
	v_ashrrev_i32_e32 v159, 31, v158
	v_add_u32_e32 v154, 0x80, v168
	v_lshl_add_u64 v[146:147], v[136:137], 0, v[146:147]
	v_lshlrev_b64 v[148:149], 6, v[158:159]
	v_ashrrev_i32_e32 v155, 31, v154
	v_lshl_add_u64 v[148:149], v[136:137], 0, v[148:149]
	global_load_dwordx4 v[184:187], v[146:147], off
	global_load_dwordx4 v[188:191], v[148:149], off
	v_lshlrev_b64 v[146:147], 6, v[154:155]
	v_add_u32_e32 v150, 0x90, v168
	v_lshl_add_u64 v[146:147], v[136:137], 0, v[146:147]
	v_ashrrev_i32_e32 v151, 31, v150
	global_load_dwordx4 v[192:195], v[146:147], off
	v_lshlrev_b64 v[146:147], 6, v[150:151]
	v_lshl_add_u64 v[146:147], v[136:137], 0, v[146:147]
	global_load_dwordx4 v[196:199], v[146:147], off
	v_add_u32_e32 v148, 0xa0, v168
	v_ashrrev_i32_e32 v149, 31, v148
	v_lshlrev_b64 v[146:147], 6, v[148:149]
	v_lshl_add_u64 v[146:147], v[136:137], 0, v[146:147]
	global_load_dwordx4 v[200:203], v[146:147], off
	v_add_u32_e32 v146, 0xb0, v168
	v_ashrrev_i32_e32 v147, 31, v146
	v_lshlrev_b64 v[204:205], 6, v[146:147]
	v_lshl_add_u64 v[204:205], v[136:137], 0, v[204:205]
	global_load_dwordx4 v[204:207], v[204:205], off
	s_and_b64 vcc, exec, s[6:7]
	s_waitcnt vmcnt(0)
	v_mov_b32_e32 v208, v177
	v_mov_b32_e32 v209, v178
	v_mov_b32_e32 v177, v179
	v_pk_add_f32 v[176:177], v[208:209], v[176:177]
	v_mov_b32_e32 v178, v181
	v_add_f32_e32 v147, v176, v177
	ds_bpermute_b32 v149, v161, v147
	v_mov_b32_e32 v179, v182
	v_mov_b32_e32 v181, v183
	v_pk_add_f32 v[176:177], v[178:179], v[180:181]
	s_waitcnt lgkmcnt(0)
	v_add_f32_e32 v147, v147, v149
	ds_bpermute_b32 v149, v165, v147
	v_add_f32_e32 v151, v176, v177
	v_mov_b32_e32 v182, v185
	v_mov_b32_e32 v183, v186
	v_mov_b32_e32 v185, v187
	s_waitcnt lgkmcnt(0)
	v_add_f32_e32 v147, v147, v149
	v_fmamk_f32 v147, v147, 0x3a800000, v175
	v_rsq_f32_e32 v176, v147
	v_mov_b32_e32 v186, v189
	v_mov_b32_e32 v187, v190
	v_mov_b32_e32 v189, v191
	v_mov_b32_e32 v190, v193
	v_mov_b32_e32 v191, v194
	v_mov_b32_e32 v193, v195
	v_mov_b32_e32 v194, v197
	v_mov_b32_e32 v195, v198
	v_mov_b32_e32 v197, v199
	v_pk_add_f32 v[178:179], v[182:183], v[184:185]
	v_pk_add_f32 v[184:185], v[194:195], v[196:197]
	v_pk_mul_f32 v[124:125], v[124:125], v[176:177] op_sel_hi:[1,0]
	v_add_f32_e32 v159, v184, v185
	v_exp_f32_e64 v184, -v124
	v_exp_f32_e64 v185, -v125
	v_pk_mul_f32 v[126:127], v[126:127], v[176:177] op_sel_hi:[1,0]
	v_pk_mul_f32 v[122:123], v[122:123], v[176:177] op_sel_hi:[1,0]
	v_pk_mul_f32 v[120:121], v[120:121], v[176:177] op_sel_hi:[1,0]
	v_pk_mul_f32 v[116:117], v[116:117], v[176:177] op_sel_hi:[1,0]
	v_pk_mul_f32 v[118:119], v[118:119], v[176:177] op_sel_hi:[1,0]
	v_pk_mul_f32 v[112:113], v[112:113], v[176:177] op_sel_hi:[1,0]
	v_pk_mul_f32 v[114:115], v[114:115], v[176:177] op_sel_hi:[1,0]
	v_pk_add_f32 v[176:177], v[184:185], 1.0 op_sel_hi:[1,0]
	v_exp_f32_e64 v184, -v126
	v_exp_f32_e64 v185, -v127
	v_add_f32_e32 v152, v178, v179
	v_pk_add_f32 v[180:181], v[186:187], v[188:189]
	v_pk_add_f32 v[182:183], v[190:191], v[192:193]
	ds_bpermute_b32 v160, v161, v151
	ds_bpermute_b32 v163, v161, v152
	v_add_f32_e32 v155, v180, v181
	v_add_f32_e32 v156, v182, v183
	v_pk_mul_f32 v[116:117], v[124:125], v[116:117]
	v_pk_add_f32 v[124:125], v[184:185], 1.0 op_sel_hi:[1,0]
	ds_bpermute_b32 v164, v161, v155
	ds_bpermute_b32 v167, v161, v156
	v_rcp_f32_e32 v124, v124
	v_rcp_f32_e32 v125, v125
	v_rcp_f32_e32 v176, v176
	v_rcp_f32_e32 v177, v177
	s_waitcnt lgkmcnt(3)
	v_add_f32_e32 v151, v151, v160
	s_waitcnt lgkmcnt(2)
	v_add_f32_e32 v152, v152, v163
	v_pk_mul_f32 v[118:119], v[126:127], v[118:119]
	v_exp_f32_e64 v126, -v120
	v_exp_f32_e64 v127, -v121
	ds_bpermute_b32 v160, v165, v151
	ds_bpermute_b32 v163, v165, v152
	v_pk_mul_f32 v[118:119], v[118:119], v[124:125]
	v_exp_f32_e64 v124, -v122
	v_exp_f32_e64 v125, -v123
	s_waitcnt lgkmcnt(3)
	v_add_f32_e32 v155, v155, v164
	s_waitcnt lgkmcnt(2)
	v_add_f32_e32 v156, v156, v167
	ds_bpermute_b32 v164, v165, v155
	ds_bpermute_b32 v167, v165, v156
	v_pk_mul_f32 v[116:117], v[116:117], v[176:177]
	v_pk_mul_f32 v[114:115], v[122:123], v[114:115]
	v_cvt_pk_bf16_f32 v116, v116, v117
	v_cvt_pk_bf16_f32 v117, v118, v119
	v_pk_add_f32 v[118:119], v[126:127], 1.0 op_sel_hi:[1,0]
	v_pk_add_f32 v[122:123], v[124:125], 1.0 op_sel_hi:[1,0]
	v_rcp_f32_e32 v118, v118
	v_rcp_f32_e32 v119, v119
	s_waitcnt lgkmcnt(3)
	v_add_f32_e32 v149, v151, v160
	s_waitcnt lgkmcnt(2)
	v_add_f32_e32 v151, v152, v163
	v_mov_b32_e32 v182, v201
	v_mov_b32_e32 v183, v202
	v_mov_b32_e32 v201, v203
	v_rcp_f32_e32 v122, v122
	v_rcp_f32_e32 v123, v123
	v_fmamk_f32 v147, v149, 0x3a800000, v175
	v_fmamk_f32 v149, v151, 0x3a800000, v175
	v_pk_add_f32 v[182:183], v[182:183], v[200:201]
	s_waitcnt lgkmcnt(1)
	v_add_f32_e32 v152, v155, v164
	s_waitcnt lgkmcnt(0)
	v_add_f32_e32 v155, v156, v167
	v_rsq_f32_e32 v180, v149
	v_add_f32_e32 v149, v182, v183
	v_mov_b32_e32 v182, v205
	v_mov_b32_e32 v183, v206
	v_mov_b32_e32 v205, v207
	v_pk_mul_f32 v[112:113], v[120:121], v[112:113]
	v_fmamk_f32 v151, v152, 0x3a800000, v175
	v_fmamk_f32 v152, v155, 0x3a800000, v175
	v_rsq_f32_e32 v178, v147
	v_pk_add_f32 v[182:183], v[182:183], v[204:205]
	v_pk_mul_f32 v[112:113], v[112:113], v[118:119]
	v_rsq_f32_e32 v164, v152
	v_add_f32_e32 v152, v182, v183
	v_lshl_add_u32 v182, s56, 7, v171
	v_cvt_pk_bf16_f32 v118, v112, v113
	v_pk_mul_f32 v[112:113], v[114:115], v[122:123]
	v_ashrrev_i32_e32 v183, 31, v182
	v_cvt_pk_bf16_f32 v119, v112, v113
	v_mov_b64_e32 v[112:113], s[24:25]
	v_mad_i64_i32 v[120:121], s[4:5], v168, s55, v[112:113]
	v_lshlrev_b64 v[114:115], 1, v[182:183]
	v_lshl_add_u64 v[120:121], v[120:121], 0, v[114:115]
	v_pk_mul_f32 v[108:109], v[108:109], v[178:179] op_sel_hi:[1,0]
	global_store_dwordx4 v[120:121], v[116:119], off
	v_pk_mul_f32 v[110:111], v[110:111], v[178:179] op_sel_hi:[1,0]
	v_pk_mul_f32 v[100:101], v[100:101], v[178:179] op_sel_hi:[1,0]
	v_exp_f32_e64 v116, -v108
	v_exp_f32_e64 v117, -v109
	v_pk_mul_f32 v[118:119], v[96:97], v[178:179] op_sel_hi:[1,0]
	v_pk_mul_f32 v[100:101], v[108:109], v[100:101]
	v_pk_mul_f32 v[102:103], v[102:103], v[178:179] op_sel_hi:[1,0]
	v_pk_add_f32 v[96:97], v[116:117], 1.0 op_sel_hi:[1,0]
	v_exp_f32_e64 v116, -v110
	v_rcp_f32_e32 v96, v96
	v_rcp_f32_e32 v97, v97
	v_exp_f32_e64 v117, -v111
	v_pk_mul_f32 v[106:107], v[106:107], v[178:179] op_sel_hi:[1,0]
	v_pk_mul_f32 v[104:105], v[104:105], v[178:179] op_sel_hi:[1,0]
	v_pk_mul_f32 v[96:97], v[100:101], v[96:97]
	v_pk_add_f32 v[100:101], v[116:117], 1.0 op_sel_hi:[1,0]
	v_pk_mul_f32 v[102:103], v[110:111], v[102:103]
	v_rcp_f32_e32 v100, v100
	v_rcp_f32_e32 v101, v101
	v_exp_f32_e64 v108, -v104
	v_exp_f32_e64 v109, -v105
	v_pk_mul_f32 v[98:99], v[98:99], v[178:179] op_sel_hi:[1,0]
	v_pk_mul_f32 v[100:101], v[102:103], v[100:101]
	v_exp_f32_e64 v102, -v106
	v_exp_f32_e64 v103, -v107
	v_cvt_pk_bf16_f32 v96, v96, v97
	v_cvt_pk_bf16_f32 v97, v100, v101
	v_pk_add_f32 v[100:101], v[108:109], 1.0 op_sel_hi:[1,0]
	v_pk_mul_f32 v[106:107], v[106:107], v[98:99]
	v_pk_add_f32 v[98:99], v[102:103], 1.0 op_sel_hi:[1,0]
	v_rcp_f32_e32 v100, v100
	v_rcp_f32_e32 v101, v101
	v_rcp_f32_e32 v102, v98
	v_rcp_f32_e32 v103, v99
	v_pk_mul_f32 v[98:99], v[104:105], v[118:119]
	v_pk_mul_f32 v[92:93], v[92:93], v[180:181] op_sel_hi:[1,0]
	v_pk_mul_f32 v[98:99], v[98:99], v[100:101]
	v_pk_mul_f32 v[100:101], v[106:107], v[102:103]
	v_cvt_pk_bf16_f32 v98, v98, v99
	v_pk_mul_f32 v[94:95], v[94:95], v[180:181] op_sel_hi:[1,0]
	v_cvt_pk_bf16_f32 v99, v100, v101
	v_mad_i64_i32 v[100:101], s[4:5], v166, s55, v[112:113]
	v_lshl_add_u64 v[100:101], v[100:101], 0, v[114:115]
	global_store_dwordx4 v[100:101], v[96:99], off
	v_pk_mul_f32 v[84:85], v[84:85], v[180:181] op_sel_hi:[1,0]
	v_pk_mul_f32 v[86:87], v[86:87], v[180:181] op_sel_hi:[1,0]
	v_exp_f32_e64 v96, -v92
	v_exp_f32_e64 v97, -v93
	v_pk_mul_f32 v[98:99], v[80:81], v[180:181] op_sel_hi:[1,0]
	v_pk_mul_f32 v[84:85], v[92:93], v[84:85]
	v_pk_mul_f32 v[90:91], v[90:91], v[180:181] op_sel_hi:[1,0]
	v_pk_add_f32 v[80:81], v[96:97], 1.0 op_sel_hi:[1,0]
	v_exp_f32_e64 v96, -v94
	v_rcp_f32_e32 v80, v80
	v_rcp_f32_e32 v81, v81
	v_exp_f32_e64 v97, -v95
	v_pk_mul_f32 v[88:89], v[88:89], v[180:181] op_sel_hi:[1,0]
	v_pk_mul_f32 v[86:87], v[94:95], v[86:87]
	v_pk_mul_f32 v[80:81], v[84:85], v[80:81]
	v_pk_add_f32 v[84:85], v[96:97], 1.0 op_sel_hi:[1,0]
	v_exp_f32_e64 v92, -v88
	v_rcp_f32_e32 v84, v84
	v_rcp_f32_e32 v85, v85
	v_exp_f32_e64 v93, -v89
	v_pk_mul_f32 v[82:83], v[82:83], v[180:181] op_sel_hi:[1,0]
	v_cvt_pk_bf16_f32 v80, v80, v81
	v_pk_mul_f32 v[84:85], v[86:87], v[84:85]
	v_exp_f32_e64 v86, -v90
	v_exp_f32_e64 v87, -v91
	v_cvt_pk_bf16_f32 v81, v84, v85
	v_pk_add_f32 v[84:85], v[92:93], 1.0 op_sel_hi:[1,0]
	v_pk_mul_f32 v[90:91], v[90:91], v[82:83]
	v_pk_add_f32 v[82:83], v[86:87], 1.0 op_sel_hi:[1,0]
	v_rcp_f32_e32 v84, v84
	v_rcp_f32_e32 v85, v85
	v_rcp_f32_e32 v86, v82
	v_rcp_f32_e32 v87, v83
	v_rsq_f32_e32 v170, v151
	v_pk_mul_f32 v[82:83], v[88:89], v[98:99]
	v_pk_mul_f32 v[60:61], v[60:61], v[164:165] op_sel_hi:[1,0]
	v_pk_mul_f32 v[82:83], v[82:83], v[84:85]
	v_pk_mul_f32 v[84:85], v[90:91], v[86:87]
	v_cvt_pk_bf16_f32 v82, v82, v83
	v_pk_mul_f32 v[76:77], v[76:77], v[170:171] op_sel_hi:[1,0]
	v_cvt_pk_bf16_f32 v83, v84, v85
	v_mad_i64_i32 v[84:85], s[4:5], v162, s55, v[112:113]
	v_lshl_add_u64 v[84:85], v[84:85], 0, v[114:115]
	global_store_dwordx4 v[84:85], v[80:83], off
	v_pk_mul_f32 v[78:79], v[78:79], v[170:171] op_sel_hi:[1,0]
	v_pk_mul_f32 v[68:69], v[68:69], v[170:171] op_sel_hi:[1,0]
	v_exp_f32_e64 v80, -v76
	v_exp_f32_e64 v81, -v77
	v_pk_mul_f32 v[82:83], v[64:65], v[170:171] op_sel_hi:[1,0]
	v_pk_mul_f32 v[68:69], v[76:77], v[68:69]
	v_pk_mul_f32 v[70:71], v[70:71], v[170:171] op_sel_hi:[1,0]
	v_pk_add_f32 v[64:65], v[80:81], 1.0 op_sel_hi:[1,0]
	v_exp_f32_e64 v80, -v78
	v_rcp_f32_e32 v64, v64
	v_rcp_f32_e32 v65, v65
	v_exp_f32_e64 v81, -v79
	v_pk_mul_f32 v[74:75], v[74:75], v[170:171] op_sel_hi:[1,0]
	v_pk_mul_f32 v[72:73], v[72:73], v[170:171] op_sel_hi:[1,0]
	v_pk_mul_f32 v[64:65], v[68:69], v[64:65]
	v_pk_add_f32 v[68:69], v[80:81], 1.0 op_sel_hi:[1,0]
	v_pk_mul_f32 v[70:71], v[78:79], v[70:71]
	v_rcp_f32_e32 v68, v68
	v_rcp_f32_e32 v69, v69
	v_exp_f32_e64 v76, -v72
	v_exp_f32_e64 v77, -v73
	v_pk_mul_f32 v[66:67], v[66:67], v[170:171] op_sel_hi:[1,0]
	v_pk_mul_f32 v[68:69], v[70:71], v[68:69]
	v_exp_f32_e64 v70, -v74
	v_exp_f32_e64 v71, -v75
	v_cvt_pk_bf16_f32 v64, v64, v65
	v_cvt_pk_bf16_f32 v65, v68, v69
	v_pk_add_f32 v[68:69], v[76:77], 1.0 op_sel_hi:[1,0]
	v_pk_mul_f32 v[74:75], v[74:75], v[66:67]
	v_pk_add_f32 v[66:67], v[70:71], 1.0 op_sel_hi:[1,0]
	v_rcp_f32_e32 v68, v68
	v_rcp_f32_e32 v69, v69
	v_rcp_f32_e32 v70, v66
	v_rcp_f32_e32 v71, v67
	v_pk_mul_f32 v[66:67], v[72:73], v[82:83]
	v_pk_mul_f32 v[62:63], v[62:63], v[164:165] op_sel_hi:[1,0]
	v_pk_mul_f32 v[66:67], v[66:67], v[68:69]
	v_pk_mul_f32 v[68:69], v[74:75], v[70:71]
	v_cvt_pk_bf16_f32 v66, v66, v67
	v_pk_mul_f32 v[52:53], v[52:53], v[164:165] op_sel_hi:[1,0]
	v_cvt_pk_bf16_f32 v67, v68, v69
	v_mad_i64_i32 v[68:69], s[4:5], v158, s55, v[112:113]
	v_lshl_add_u64 v[68:69], v[68:69], 0, v[114:115]
	global_store_dwordx4 v[68:69], v[64:67], off
	ds_bpermute_b32 v169, v161, v159
	v_pk_mul_f32 v[52:53], v[60:61], v[52:53]
	v_exp_f32_e64 v64, -v60
	v_exp_f32_e64 v65, -v61
	v_pk_mul_f32 v[66:67], v[48:49], v[164:165] op_sel_hi:[1,0]
	v_pk_mul_f32 v[54:55], v[54:55], v[164:165] op_sel_hi:[1,0]
	s_waitcnt lgkmcnt(0)
	v_add_f32_e32 v159, v159, v169
	v_pk_add_f32 v[48:49], v[64:65], 1.0 op_sel_hi:[1,0]
	v_exp_f32_e64 v64, -v62
	v_rcp_f32_e32 v48, v48
	v_rcp_f32_e32 v49, v49
	v_exp_f32_e64 v65, -v63
	v_pk_mul_f32 v[58:59], v[58:59], v[164:165] op_sel_hi:[1,0]
	v_pk_mul_f32 v[56:57], v[56:57], v[164:165] op_sel_hi:[1,0]
	v_pk_mul_f32 v[48:49], v[52:53], v[48:49]
	v_pk_add_f32 v[52:53], v[64:65], 1.0 op_sel_hi:[1,0]
	v_pk_mul_f32 v[54:55], v[62:63], v[54:55]
	v_rcp_f32_e32 v52, v52
	v_rcp_f32_e32 v53, v53
	ds_bpermute_b32 v147, v165, v159
	v_exp_f32_e64 v60, -v56
	v_exp_f32_e64 v61, -v57
	v_pk_mul_f32 v[52:53], v[54:55], v[52:53]
	v_exp_f32_e64 v54, -v58
	v_exp_f32_e64 v55, -v59
	v_pk_mul_f32 v[50:51], v[50:51], v[164:165] op_sel_hi:[1,0]
	v_cvt_pk_bf16_f32 v48, v48, v49
	v_cvt_pk_bf16_f32 v49, v52, v53
	v_pk_add_f32 v[52:53], v[60:61], 1.0 op_sel_hi:[1,0]
	v_pk_mul_f32 v[58:59], v[58:59], v[50:51]
	v_pk_add_f32 v[50:51], v[54:55], 1.0 op_sel_hi:[1,0]
	s_waitcnt lgkmcnt(0)
	v_add_f32_e32 v147, v159, v147
	v_rcp_f32_e32 v52, v52
	v_rcp_f32_e32 v53, v53
	v_rcp_f32_e32 v54, v50
	v_rcp_f32_e32 v55, v51
	v_fmamk_f32 v147, v147, 0x3a800000, v175
	v_rsq_f32_e32 v160, v147
	v_pk_mul_f32 v[50:51], v[56:57], v[66:67]
	ds_bpermute_b32 v151, v161, v149
	v_pk_mul_f32 v[50:51], v[50:51], v[52:53]
	v_pk_mul_f32 v[52:53], v[58:59], v[54:55]
	v_cvt_pk_bf16_f32 v50, v50, v51
	v_pk_mul_f32 v[44:45], v[44:45], v[160:161] op_sel_hi:[1,0]
	v_cvt_pk_bf16_f32 v51, v52, v53
	v_mad_i64_i32 v[52:53], s[4:5], v154, s55, v[112:113]
	v_lshl_add_u64 v[52:53], v[52:53], 0, v[114:115]
	global_store_dwordx4 v[52:53], v[48:51], off
	v_pk_mul_f32 v[46:47], v[46:47], v[160:161] op_sel_hi:[1,0]
	v_pk_mul_f32 v[36:37], v[36:37], v[160:161] op_sel_hi:[1,0]
	v_exp_f32_e64 v48, -v44
	v_exp_f32_e64 v49, -v45
	v_pk_mul_f32 v[50:51], v[32:33], v[160:161] op_sel_hi:[1,0]
	v_pk_mul_f32 v[36:37], v[44:45], v[36:37]
	v_pk_mul_f32 v[38:39], v[38:39], v[160:161] op_sel_hi:[1,0]
	v_pk_add_f32 v[32:33], v[48:49], 1.0 op_sel_hi:[1,0]
	v_exp_f32_e64 v48, -v46
	v_rcp_f32_e32 v32, v32
	v_rcp_f32_e32 v33, v33
	v_exp_f32_e64 v49, -v47
	s_waitcnt lgkmcnt(0)
	v_add_f32_e32 v149, v149, v151
	v_pk_mul_f32 v[42:43], v[42:43], v[160:161] op_sel_hi:[1,0]
	v_pk_mul_f32 v[32:33], v[36:37], v[32:33]
	v_pk_add_f32 v[36:37], v[48:49], 1.0 op_sel_hi:[1,0]
	v_pk_mul_f32 v[40:41], v[40:41], v[160:161] op_sel_hi:[1,0]
	v_rcp_f32_e32 v36, v36
	v_rcp_f32_e32 v37, v37
	v_pk_mul_f32 v[38:39], v[46:47], v[38:39]
	ds_bpermute_b32 v151, v165, v149
	v_exp_f32_e64 v44, -v40
	v_exp_f32_e64 v45, -v41
	v_pk_mul_f32 v[36:37], v[38:39], v[36:37]
	v_exp_f32_e64 v38, -v42
	v_exp_f32_e64 v39, -v43
	v_pk_mul_f32 v[34:35], v[34:35], v[160:161] op_sel_hi:[1,0]
	v_cvt_pk_bf16_f32 v32, v32, v33
	v_cvt_pk_bf16_f32 v33, v36, v37
	v_pk_add_f32 v[36:37], v[44:45], 1.0 op_sel_hi:[1,0]
	v_pk_mul_f32 v[42:43], v[42:43], v[34:35]
	v_pk_add_f32 v[34:35], v[38:39], 1.0 op_sel_hi:[1,0]
	s_waitcnt lgkmcnt(0)
	v_add_f32_e32 v147, v149, v151
	v_rcp_f32_e32 v36, v36
	v_rcp_f32_e32 v37, v37
	v_rcp_f32_e32 v38, v34
	v_rcp_f32_e32 v39, v35
	v_fmamk_f32 v147, v147, 0x3a800000, v175
	v_rsq_f32_e32 v156, v147
	v_pk_mul_f32 v[34:35], v[40:41], v[50:51]
	ds_bpermute_b32 v155, v161, v152
	v_pk_mul_f32 v[34:35], v[34:35], v[36:37]
	v_pk_mul_f32 v[36:37], v[42:43], v[38:39]
	v_cvt_pk_bf16_f32 v34, v34, v35
	v_pk_mul_f32 v[28:29], v[28:29], v[156:157] op_sel_hi:[1,0]
	v_cvt_pk_bf16_f32 v35, v36, v37
	v_mad_i64_i32 v[36:37], s[4:5], v150, s55, v[112:113]
	v_lshl_add_u64 v[36:37], v[36:37], 0, v[114:115]
	global_store_dwordx4 v[36:37], v[32:35], off
	v_pk_mul_f32 v[30:31], v[30:31], v[156:157] op_sel_hi:[1,0]
	v_pk_mul_f32 v[20:21], v[20:21], v[156:157] op_sel_hi:[1,0]
	v_exp_f32_e64 v32, -v28
	v_exp_f32_e64 v33, -v29
	v_pk_mul_f32 v[34:35], v[16:17], v[156:157] op_sel_hi:[1,0]
	v_pk_mul_f32 v[20:21], v[28:29], v[20:21]
	v_pk_mul_f32 v[22:23], v[22:23], v[156:157] op_sel_hi:[1,0]
	v_pk_add_f32 v[16:17], v[32:33], 1.0 op_sel_hi:[1,0]
	v_exp_f32_e64 v32, -v30
	v_rcp_f32_e32 v16, v16
	v_rcp_f32_e32 v17, v17
	v_exp_f32_e64 v33, -v31
	s_waitcnt lgkmcnt(0)
	v_add_f32_e32 v152, v152, v155
	v_pk_mul_f32 v[26:27], v[26:27], v[156:157] op_sel_hi:[1,0]
	v_pk_mul_f32 v[16:17], v[20:21], v[16:17]
	v_pk_add_f32 v[20:21], v[32:33], 1.0 op_sel_hi:[1,0]
	v_pk_mul_f32 v[24:25], v[24:25], v[156:157] op_sel_hi:[1,0]
	v_rcp_f32_e32 v20, v20
	v_rcp_f32_e32 v21, v21
	v_pk_mul_f32 v[22:23], v[30:31], v[22:23]
	ds_bpermute_b32 v155, v165, v152
	v_exp_f32_e64 v28, -v24
	v_exp_f32_e64 v29, -v25
	v_pk_mul_f32 v[20:21], v[22:23], v[20:21]
	v_exp_f32_e64 v22, -v26
	v_exp_f32_e64 v23, -v27
	v_pk_mul_f32 v[18:19], v[18:19], v[156:157] op_sel_hi:[1,0]
	v_cvt_pk_bf16_f32 v16, v16, v17
	v_cvt_pk_bf16_f32 v17, v20, v21
	v_pk_add_f32 v[20:21], v[28:29], 1.0 op_sel_hi:[1,0]
	v_pk_mul_f32 v[26:27], v[26:27], v[18:19]
	v_pk_add_f32 v[18:19], v[22:23], 1.0 op_sel_hi:[1,0]
	s_waitcnt lgkmcnt(0)
	v_add_f32_e32 v147, v152, v155
	v_rcp_f32_e32 v20, v20
	v_rcp_f32_e32 v21, v21
	v_rcp_f32_e32 v22, v18
	v_rcp_f32_e32 v23, v19
	v_fmamk_f32 v147, v147, 0x3a800000, v175
	v_rsq_f32_e32 v152, v147
	v_pk_mul_f32 v[18:19], v[24:25], v[34:35]
	v_pk_mul_f32 v[12:13], v[12:13], v[152:153] op_sel_hi:[1,0]
	v_pk_mul_f32 v[18:19], v[18:19], v[20:21]
	v_pk_mul_f32 v[20:21], v[26:27], v[22:23]
	v_cvt_pk_bf16_f32 v18, v18, v19
	v_pk_mul_f32 v[14:15], v[14:15], v[152:153] op_sel_hi:[1,0]
	v_cvt_pk_bf16_f32 v19, v20, v21
	v_mad_i64_i32 v[20:21], s[4:5], v148, s55, v[112:113]
	v_lshl_add_u64 v[20:21], v[20:21], 0, v[114:115]
	global_store_dwordx4 v[20:21], v[16:19], off
	v_pk_mul_f32 v[4:5], v[4:5], v[152:153] op_sel_hi:[1,0]
	v_pk_mul_f32 v[6:7], v[6:7], v[152:153] op_sel_hi:[1,0]
	v_exp_f32_e64 v16, -v12
	v_exp_f32_e64 v17, -v13
	v_pk_mul_f32 v[18:19], v[0:1], v[152:153] op_sel_hi:[1,0]
	v_pk_mul_f32 v[4:5], v[12:13], v[4:5]
	v_pk_mul_f32 v[10:11], v[10:11], v[152:153] op_sel_hi:[1,0]
	v_pk_add_f32 v[0:1], v[16:17], 1.0 op_sel_hi:[1,0]
	v_exp_f32_e64 v16, -v14
	v_rcp_f32_e32 v0, v0
	v_rcp_f32_e32 v1, v1
	v_exp_f32_e64 v17, -v15
	v_pk_mul_f32 v[8:9], v[8:9], v[152:153] op_sel_hi:[1,0]
	v_pk_mul_f32 v[6:7], v[14:15], v[6:7]
	v_pk_mul_f32 v[0:1], v[4:5], v[0:1]
	v_pk_add_f32 v[4:5], v[16:17], 1.0 op_sel_hi:[1,0]
	v_exp_f32_e64 v12, -v8
	v_rcp_f32_e32 v4, v4
	v_rcp_f32_e32 v5, v5
	v_exp_f32_e64 v13, -v9
	v_pk_mul_f32 v[2:3], v[2:3], v[152:153] op_sel_hi:[1,0]
	v_cvt_pk_bf16_f32 v0, v0, v1
	v_pk_mul_f32 v[4:5], v[6:7], v[4:5]
	v_exp_f32_e64 v6, -v10
	v_exp_f32_e64 v7, -v11
	v_cvt_pk_bf16_f32 v1, v4, v5
	v_pk_add_f32 v[4:5], v[12:13], 1.0 op_sel_hi:[1,0]
	v_pk_mul_f32 v[10:11], v[10:11], v[2:3]
	v_pk_add_f32 v[2:3], v[6:7], 1.0 op_sel_hi:[1,0]
	v_rcp_f32_e32 v4, v4
	v_rcp_f32_e32 v5, v5
	v_rcp_f32_e32 v6, v2
	v_rcp_f32_e32 v7, v3
	v_pk_mul_f32 v[2:3], v[8:9], v[18:19]
	s_nop 0
	v_pk_mul_f32 v[2:3], v[2:3], v[4:5]
	v_pk_mul_f32 v[4:5], v[10:11], v[6:7]
	v_cvt_pk_bf16_f32 v2, v2, v3
	s_nop 0
	v_cvt_pk_bf16_f32 v3, v4, v5
	v_mad_i64_i32 v[4:5], s[4:5], v146, s55, v[112:113]
	v_lshl_add_u64 v[4:5], v[4:5], 0, v[114:115]
	s_mov_b64 s[4:5], -1
	global_store_dwordx4 v[4:5], v[0:3], off
	s_cbranch_vccnz .LBB0_753
	s_andn2_b64 vcc, exec, s[12:13]
	s_cbranch_vccnz .LBB0_752
	s_branch .LBB0_752

.LBB0_826:
	s_mov_b64 s[14:15], 0x80
	s_bfe_u32 s18, s3, 0x20006
	s_add_i32 m0, s43, 0x18000
	v_lshl_add_u64 v[6:7], v[6:7], 0, s[14:15]
	s_lshl_b32 s51, s5, 6
	s_lshl_b32 s5, s5, 13
	s_lshl_b32 s7, s18, 12
	s_nop 0
	global_load_lds_dwordx4 v[6:7], off
	v_lshl_add_u64 v[4:5], v[4:5], 0, s[14:15]
	s_add_i32 m0, s43, 0x1a000
	s_add_i32 s52, s43, 0x8000
	s_add_i32 s53, s43, 0xa000
	global_load_lds_dwordx4 v[4:5], off
	v_lshl_add_u64 v[2:3], v[2:3], 0, s[14:15]
	s_mov_b32 m0, s52
	s_add_u32 s8, s22, 0xb0080
	global_load_lds_dwordx4 v[2:3], off
	v_lshl_add_u64 v[0:1], v[0:1], 0, s[14:15]
	s_mov_b32 m0, s53
	s_addc_u32 s9, s23, 0
	global_load_lds_dwordx4 v[0:1], off
	s_add_i32 m0, s43, 0x1c000
	v_lshl_add_u64 v[0:1], s[8:9], 0, v[180:181]
	global_load_lds_dwordx4 v[0:1], off
	v_lshl_add_u64 v[0:1], s[8:9], 0, v[176:177]
	s_add_i32 m0, s43, 0x1e000
	v_lshlrev_b32_e32 v2, 2, v10
	global_load_lds_dwordx4 v[0:1], off
	v_and_b32_e32 v1, 15, v10
	v_and_b32_e32 v3, 48, v10
	v_lshlrev_b32_e32 v5, 6, v1
	v_and_b32_e32 v2, 32, v2
	v_and_b32_e32 v4, 0x400, v13
	v_bitop3_b32 v3, v5, v2, v3 bitop3:0x36
	v_lshrrev_b32_e32 v0, 1, v10
	v_or3_b32 v5, v4, s5, v3
	v_or3_b32 v202, v4, s7, v3
	s_cmpk_lt_u32 s3, 0x100
	v_lshlrev_b32_e32 v3, 10, v10
	v_cmp_gt_u32_e64 s[8:9], 8, v1
	v_lshrrev_b32_e32 v1, 1, v14
	v_mul_lo_u32 v10, v15, s4
	s_mov_b32 s5, 0xb000
	s_cselect_b64 s[16:17], -1, 0
	s_lshl_b32 s3, s18, 6
	v_mad_u64_u32 v[14:15], s[18:19], v1, s5, v[10:11]
	v_or_b32_e32 v1, v14, v16
	v_add_lshl_u32 v184, v1, v17, 1
	v_lshrrev_b32_e32 v1, 1, v8
	v_mul_lo_u32 v8, v9, s4
	v_mad_u64_u32 v[8:9], s[4:5], v1, s5, v[8:9]
	s_sext_i32_i8 s79, s6
	s_mov_b64 s[6:7], 0xb0080
	s_waitcnt vmcnt(6)
	v_or_b32_e32 v1, v8, v11
	v_and_b32_e32 v0, 56, v0
	v_and_b32_e32 v4, 0x1c00, v3
	v_cndmask_b32_e64 v6, 32, 0, s[8:9]
	v_lshl_add_u64 v[186:187], v[184:185], 0, s[6:7]
	v_add_lshl_u32 v184, v1, v12, 1
	s_add_i32 s59, 0, 0x10000
	s_add_i32 s66, 0, 0x14000
	s_mov_b32 s54, 0x18000
	s_mov_b32 s55, 0x8000
	s_mov_b32 s56, 0x1c000
	s_ashr_i32 s57, s34, 31
	s_mov_b32 s58, s34
	v_lshl_add_u64 v[188:189], v[184:185], 0, s[6:7]
	v_mov_b64_e32 v[190:191], 0x500
	v_mov_b64_e32 v[192:193], 0x4ff
	v_add_u32_e32 v203, s59, v202
	v_add_u32_e32 v204, s66, v202
	v_add_u32_e32 v205, 0, v5
	s_mov_b32 s67, 0xc000
	v_lshlrev_b32_e32 v184, 1, v4
	v_lshlrev_b32_e32 v194, 1, v2
	v_lshlrev_b32_e32 v196, 1, v0
	s_mov_b32 s68, 0x40000
	s_mov_b32 s69, 0x44000
	s_mov_b32 s70, 0x48000
	s_mov_b32 s71, 0x4c000
	s_mov_b32 s72, 0x50000
	s_mov_b32 s73, 0x54000
	s_mov_b32 s74, 0x58000
	s_mov_b32 s75, 0x5c000
	v_lshlrev_b32_e32 v198, 1, v6
	s_barrier
	s_branch .LBB0_829

.LBB0_835:
	s_add_u32 s80, s22, 0x100
	s_addc_u32 s81, s23, 0
	s_mov_b32 s82, -2
	s_and_b64 vcc, exec, s[16:17]
	s_cbranch_vccz .Lh1p_6
	ds_read_b128 v[112:115], v203
	ds_read_b128 v[116:119], v203 offset:1024
	ds_read_b128 v[136:139], v203 offset:2048
	ds_read_b128 v[140:143], v203 offset:3072
	ds_read_b128 v[144:147], v204
	ds_read_b128 v[148:151], v204 offset:1024
	ds_read_b128 v[152:155], v204 offset:2048
	ds_read_b128 v[156:159], v204 offset:3072
	s_add_u32 s22, s20, 0x100
	s_addc_u32 s23, s21, 0
	s_cmp_eq_u32 s82, 40
	s_cselect_b32 s37, s7, s23
	s_cselect_b32 s36, s6, s22
	s_cselect_b32 s27, s19, s81
	s_cselect_b32 s26, s18, s80
	v_lshl_add_u64 v[200:201], s[20:21], 0, v[186:187]
	s_add_i32 m0, s43, 0xc000
	ds_read_b128 v[160:163], v205
	ds_read_b128 v[164:167], v205 offset:1024
	ds_read_b128 v[168:171], v205 offset:2048
	ds_read_b128 v[172:175], v205 offset:3072
	ds_read_b128 v[206:209], v205 offset:4096
	ds_read_b128 v[210:213], v205 offset:5120
	ds_read_b128 v[214:217], v205 offset:6144
	ds_read_b128 v[218:221], v205 offset:7168
	global_load_lds_dwordx4 v[200:201], off
	v_lshl_add_u64 v[200:201], s[20:21], 0, v[188:189]
	s_add_i32 m0, s43, 0xe000
	s_nop 0
	global_load_lds_dwordx4 v[200:201], off
	s_waitcnt vmcnt(8)
	s_waitcnt lgkmcnt(0)
	s_setprio 1
	v_mfma_f32_16x16x32_bf16 v[132:135], v[112:115], v[160:163], 0
	v_mfma_f32_16x16x32_bf16 v[128:131], v[136:139], v[160:163], 0
	v_mfma_f32_16x16x32_bf16 v[108:111], v[112:115], v[168:171], 0
	v_mfma_f32_16x16x32_bf16 v[104:107], v[136:139], v[168:171], 0
	v_mfma_f32_16x16x32_bf16 v[92:95], v[112:115], v[206:209], 0
	v_mfma_f32_16x16x32_bf16 v[88:91], v[136:139], v[206:209], 0
	v_mfma_f32_16x16x32_bf16 v[76:79], v[112:115], v[214:217], 0
	v_mfma_f32_16x16x32_bf16 v[72:75], v[136:139], v[214:217], 0
	v_mfma_f32_16x16x32_bf16 v[132:135], v[116:119], v[164:167], v[132:135]
	v_mfma_f32_16x16x32_bf16 v[128:131], v[140:143], v[164:167], v[128:131]
	v_mfma_f32_16x16x32_bf16 v[108:111], v[116:119], v[172:175], v[108:111]
	v_mfma_f32_16x16x32_bf16 v[104:107], v[140:143], v[172:175], v[104:107]
	v_mfma_f32_16x16x32_bf16 v[92:95], v[116:119], v[210:213], v[92:95]
	v_mfma_f32_16x16x32_bf16 v[88:91], v[140:143], v[210:213], v[88:91]
	v_mfma_f32_16x16x32_bf16 v[76:79], v[116:119], v[218:221], v[76:79]
	v_mfma_f32_16x16x32_bf16 v[72:75], v[140:143], v[218:221], v[72:75]
	v_mfma_f32_16x16x32_bf16 v[124:127], v[144:147], v[160:163], 0
	v_mfma_f32_16x16x32_bf16 v[120:123], v[152:155], v[160:163], 0
	v_mfma_f32_16x16x32_bf16 v[100:103], v[144:147], v[168:171], 0
	v_mfma_f32_16x16x32_bf16 v[96:99], v[152:155], v[168:171], 0
	v_mfma_f32_16x16x32_bf16 v[84:87], v[144:147], v[206:209], 0
	v_mfma_f32_16x16x32_bf16 v[80:83], v[152:155], v[206:209], 0
	v_mfma_f32_16x16x32_bf16 v[68:71], v[144:147], v[214:217], 0
	v_mfma_f32_16x16x32_bf16 v[64:67], v[152:155], v[214:217], 0
	v_mfma_f32_16x16x32_bf16 v[124:127], v[148:151], v[164:167], v[124:127]
	v_mfma_f32_16x16x32_bf16 v[120:123], v[156:159], v[164:167], v[120:123]
	v_mfma_f32_16x16x32_bf16 v[100:103], v[148:151], v[172:175], v[100:103]
	v_mfma_f32_16x16x32_bf16 v[96:99], v[156:159], v[172:175], v[96:99]
	v_mfma_f32_16x16x32_bf16 v[84:87], v[148:151], v[210:213], v[84:87]
	v_mfma_f32_16x16x32_bf16 v[80:83], v[156:159], v[210:213], v[80:83]
	v_mfma_f32_16x16x32_bf16 v[68:71], v[148:151], v[218:221], v[68:71]
	v_mfma_f32_16x16x32_bf16 v[64:67], v[156:159], v[218:221], v[64:67]
	s_setprio 0
	s_barrier
	s_add_i32 s20, s59, s40
	v_lshl_add_u64 v[200:201], s[26:27], 0, v[180:181]
	s_mov_b32 m0, s20
	ds_read_b128 v[160:163], v205 offset:16384
	ds_read_b128 v[164:167], v205 offset:17408
	ds_read_b128 v[168:171], v205 offset:18432
	ds_read_b128 v[172:175], v205 offset:19456
	ds_read_b128 v[206:209], v205 offset:20480
	ds_read_b128 v[210:213], v205 offset:21504
	ds_read_b128 v[214:217], v205 offset:22528
	ds_read_b128 v[218:221], v205 offset:23552
	global_load_lds_dwordx4 v[200:201], off
	s_add_i32 m0, s20, 0x2000
	s_add_u32 s20, s26, 0xb0000
	v_lshl_add_u64 v[222:223], s[26:27], 0, v[176:177]
	s_addc_u32 s21, s27, 0
	s_add_i32 s83, s66, s40
	global_load_lds_dwordx4 v[222:223], off
	v_lshl_add_u64 v[224:225], s[20:21], 0, v[180:181]
	s_mov_b32 m0, s83
	v_lshl_add_u64 v[226:227], s[36:37], 0, v[178:179]
	global_load_lds_dwordx4 v[224:225], off
	v_lshl_add_u64 v[224:225], s[20:21], 0, v[176:177]
	s_add_i32 m0, s83, 0x2000
	s_nop 0
	global_load_lds_dwordx4 v[224:225], off
	v_lshl_add_u64 v[224:225], s[36:37], 0, v[182:183]
	s_mov_b32 m0, s43
	s_nop 0
	global_load_lds_dwordx4 v[224:225], off
	s_mov_b32 m0, s44
	s_nop 0
	global_load_lds_dwordx4 v[226:227], off
	s_waitcnt vmcnt(8)
	s_waitcnt lgkmcnt(0)
	s_setprio 1
	v_mfma_f32_16x16x32_bf16 v[60:63], v[112:115], v[160:163], 0
	v_mfma_f32_16x16x32_bf16 v[56:59], v[136:139], v[160:163], 0
	v_mfma_f32_16x16x32_bf16 v[44:47], v[112:115], v[168:171], 0
	v_mfma_f32_16x16x32_bf16 v[40:43], v[136:139], v[168:171], 0
	v_mfma_f32_16x16x32_bf16 v[28:31], v[112:115], v[206:209], 0
	v_mfma_f32_16x16x32_bf16 v[24:27], v[136:139], v[206:209], 0
	v_mfma_f32_16x16x32_bf16 v[12:15], v[112:115], v[214:217], 0
	v_mfma_f32_16x16x32_bf16 v[8:11], v[136:139], v[214:217], 0
	v_mfma_f32_16x16x32_bf16 v[60:63], v[116:119], v[164:167], v[60:63]
	v_mfma_f32_16x16x32_bf16 v[56:59], v[140:143], v[164:167], v[56:59]
	v_mfma_f32_16x16x32_bf16 v[44:47], v[116:119], v[172:175], v[44:47]
	v_mfma_f32_16x16x32_bf16 v[40:43], v[140:143], v[172:175], v[40:43]
	v_mfma_f32_16x16x32_bf16 v[28:31], v[116:119], v[210:213], v[28:31]
	v_mfma_f32_16x16x32_bf16 v[24:27], v[140:143], v[210:213], v[24:27]
	v_mfma_f32_16x16x32_bf16 v[12:15], v[116:119], v[218:221], v[12:15]
	v_mfma_f32_16x16x32_bf16 v[8:11], v[140:143], v[218:221], v[8:11]
	v_mfma_f32_16x16x32_bf16 v[52:55], v[144:147], v[160:163], 0
	v_mfma_f32_16x16x32_bf16 v[48:51], v[152:155], v[160:163], 0
	v_mfma_f32_16x16x32_bf16 v[36:39], v[144:147], v[168:171], 0
	v_mfma_f32_16x16x32_bf16 v[32:35], v[152:155], v[168:171], 0
	v_mfma_f32_16x16x32_bf16 v[20:23], v[144:147], v[206:209], 0
	v_mfma_f32_16x16x32_bf16 v[16:19], v[152:155], v[206:209], 0
	v_mfma_f32_16x16x32_bf16 v[4:7], v[144:147], v[214:217], 0
	v_mfma_f32_16x16x32_bf16 v[0:3], v[152:155], v[214:217], 0
	v_mfma_f32_16x16x32_bf16 v[52:55], v[148:151], v[164:167], v[52:55]
	v_mfma_f32_16x16x32_bf16 v[48:51], v[156:159], v[164:167], v[48:51]
	v_mfma_f32_16x16x32_bf16 v[36:39], v[148:151], v[172:175], v[36:39]
	v_mfma_f32_16x16x32_bf16 v[32:35], v[156:159], v[172:175], v[32:35]
	v_mfma_f32_16x16x32_bf16 v[20:23], v[148:151], v[210:213], v[20:23]
	v_mfma_f32_16x16x32_bf16 v[16:19], v[156:159], v[210:213], v[16:19]
	v_mfma_f32_16x16x32_bf16 v[4:7], v[148:151], v[218:221], v[4:7]
	v_mfma_f32_16x16x32_bf16 v[0:3], v[156:159], v[218:221], v[0:3]
	s_setprio 0
	s_barrier
	s_add_i32 s83, 0, 0x18000
	s_add_i32 s85, 0, 0x1c000
	v_add_u32_e32 v140, s83, v202
	v_add_u32_e32 v156, s85, v202
	ds_read_b128 v[112:115], v140
	ds_read_b128 v[116:119], v140 offset:1024
	ds_read_b128 v[136:139], v140 offset:2048
	ds_read_b128 v[140:143], v140 offset:3072
	ds_read_b128 v[144:147], v156
	ds_read_b128 v[148:151], v156 offset:1024
	ds_read_b128 v[152:155], v156 offset:2048
	ds_read_b128 v[156:159], v156 offset:3072
	s_add_u32 s20, s36, 0xb0000
	s_addc_u32 s21, s37, 0
	s_mov_b32 m0, s45
	v_lshl_add_u64 v[230:231], s[20:21], 0, v[182:183]
	ds_read_b128 v[160:163], v205 offset:32768
	ds_read_b128 v[164:167], v205 offset:33792
	ds_read_b128 v[168:171], v205 offset:34816
	ds_read_b128 v[172:175], v205 offset:35840
	ds_read_b128 v[206:209], v205 offset:36864
	ds_read_b128 v[210:213], v205 offset:37888
	ds_read_b128 v[214:217], v205 offset:38912
	ds_read_b128 v[218:221], v205 offset:39936
	global_load_lds_dwordx4 v[230:231], off
	v_lshl_add_u64 v[230:231], s[20:21], 0, v[178:179]
	s_mov_b32 m0, s46
	s_nop 0
	global_load_lds_dwordx4 v[230:231], off
	s_waitcnt vmcnt(8)
	s_waitcnt lgkmcnt(0)
	s_setprio 1
	v_mfma_f32_16x16x32_bf16 v[132:135], v[112:115], v[160:163], v[132:135]
	v_mfma_f32_16x16x32_bf16 v[128:131], v[136:139], v[160:163], v[128:131]
	v_mfma_f32_16x16x32_bf16 v[108:111], v[112:115], v[168:171], v[108:111]
	v_mfma_f32_16x16x32_bf16 v[104:107], v[136:139], v[168:171], v[104:107]
	v_mfma_f32_16x16x32_bf16 v[92:95], v[112:115], v[206:209], v[92:95]
	v_mfma_f32_16x16x32_bf16 v[88:91], v[136:139], v[206:209], v[88:91]
	v_mfma_f32_16x16x32_bf16 v[76:79], v[112:115], v[214:217], v[76:79]
	v_mfma_f32_16x16x32_bf16 v[72:75], v[136:139], v[214:217], v[72:75]
	v_mfma_f32_16x16x32_bf16 v[132:135], v[116:119], v[164:167], v[132:135]
	v_mfma_f32_16x16x32_bf16 v[128:131], v[140:143], v[164:167], v[128:131]
	v_mfma_f32_16x16x32_bf16 v[108:111], v[116:119], v[172:175], v[108:111]
	v_mfma_f32_16x16x32_bf16 v[104:107], v[140:143], v[172:175], v[104:107]
	v_mfma_f32_16x16x32_bf16 v[92:95], v[116:119], v[210:213], v[92:95]
	v_mfma_f32_16x16x32_bf16 v[88:91], v[140:143], v[210:213], v[88:91]
	v_mfma_f32_16x16x32_bf16 v[76:79], v[116:119], v[218:221], v[76:79]
	v_mfma_f32_16x16x32_bf16 v[72:75], v[140:143], v[218:221], v[72:75]
	v_mfma_f32_16x16x32_bf16 v[124:127], v[144:147], v[160:163], v[124:127]
	v_mfma_f32_16x16x32_bf16 v[120:123], v[152:155], v[160:163], v[120:123]
	v_mfma_f32_16x16x32_bf16 v[100:103], v[144:147], v[168:171], v[100:103]
	v_mfma_f32_16x16x32_bf16 v[96:99], v[152:155], v[168:171], v[96:99]
	v_mfma_f32_16x16x32_bf16 v[84:87], v[144:147], v[206:209], v[84:87]
	v_mfma_f32_16x16x32_bf16 v[80:83], v[152:155], v[206:209], v[80:83]
	v_mfma_f32_16x16x32_bf16 v[68:71], v[144:147], v[214:217], v[68:71]
	v_mfma_f32_16x16x32_bf16 v[64:67], v[152:155], v[214:217], v[64:67]
	v_mfma_f32_16x16x32_bf16 v[124:127], v[148:151], v[164:167], v[124:127]
	v_mfma_f32_16x16x32_bf16 v[120:123], v[156:159], v[164:167], v[120:123]
	v_mfma_f32_16x16x32_bf16 v[100:103], v[148:151], v[172:175], v[100:103]
	v_mfma_f32_16x16x32_bf16 v[96:99], v[156:159], v[172:175], v[96:99]
	v_mfma_f32_16x16x32_bf16 v[84:87], v[148:151], v[210:213], v[84:87]
	v_mfma_f32_16x16x32_bf16 v[80:83], v[156:159], v[210:213], v[80:83]
	v_mfma_f32_16x16x32_bf16 v[68:71], v[148:151], v[218:221], v[68:71]
	v_mfma_f32_16x16x32_bf16 v[64:67], v[156:159], v[218:221], v[64:67]
	s_setprio 0
	s_barrier
	s_add_i32 s20, s83, s40
	v_lshl_add_u64 v[200:201], v[200:201], 0, s[14:15]
	s_mov_b32 m0, s20
	ds_read_b128 v[160:163], v205 offset:49152
	ds_read_b128 v[164:167], v205 offset:50176
	ds_read_b128 v[168:171], v205 offset:51200
	ds_read_b128 v[172:175], v205 offset:52224
	ds_read_b128 v[206:209], v205 offset:53248
	ds_read_b128 v[210:213], v205 offset:54272
	ds_read_b128 v[214:217], v205 offset:55296
	ds_read_b128 v[218:221], v205 offset:56320
	global_load_lds_dwordx4 v[200:201], off
	s_add_i32 m0, s20, 0x2000
	s_add_u32 s20, s26, 0xb0080
	v_lshl_add_u64 v[200:201], v[222:223], 0, s[14:15]
	s_addc_u32 s21, s27, 0
	s_add_i32 s26, s85, s40
	global_load_lds_dwordx4 v[200:201], off
	v_lshl_add_u64 v[200:201], s[20:21], 0, v[180:181]
	s_mov_b32 m0, s26
	s_nop 0
	global_load_lds_dwordx4 v[200:201], off
	v_lshl_add_u64 v[200:201], s[20:21], 0, v[176:177]
	s_add_i32 m0, s26, 0x2000
	s_nop 0
	global_load_lds_dwordx4 v[200:201], off
	v_lshl_add_u64 v[200:201], v[224:225], 0, s[14:15]
	s_mov_b32 m0, s52
	s_nop 0
	global_load_lds_dwordx4 v[200:201], off
	v_lshl_add_u64 v[200:201], v[226:227], 0, s[14:15]
	s_mov_b32 m0, s53
	s_nop 0
	global_load_lds_dwordx4 v[200:201], off
	s_waitcnt vmcnt(8)
	s_waitcnt lgkmcnt(0)
	s_setprio 1
	v_mfma_f32_16x16x32_bf16 v[60:63], v[112:115], v[160:163], v[60:63]
	v_mfma_f32_16x16x32_bf16 v[56:59], v[136:139], v[160:163], v[56:59]
	v_mfma_f32_16x16x32_bf16 v[44:47], v[112:115], v[168:171], v[44:47]
	v_mfma_f32_16x16x32_bf16 v[40:43], v[136:139], v[168:171], v[40:43]
	v_mfma_f32_16x16x32_bf16 v[28:31], v[112:115], v[206:209], v[28:31]
	v_mfma_f32_16x16x32_bf16 v[24:27], v[136:139], v[206:209], v[24:27]
	v_mfma_f32_16x16x32_bf16 v[12:15], v[112:115], v[214:217], v[12:15]
	v_mfma_f32_16x16x32_bf16 v[8:11], v[136:139], v[214:217], v[8:11]
	v_mfma_f32_16x16x32_bf16 v[60:63], v[116:119], v[164:167], v[60:63]
	v_mfma_f32_16x16x32_bf16 v[56:59], v[140:143], v[164:167], v[56:59]
	v_mfma_f32_16x16x32_bf16 v[44:47], v[116:119], v[172:175], v[44:47]
	v_mfma_f32_16x16x32_bf16 v[40:43], v[140:143], v[172:175], v[40:43]
	v_mfma_f32_16x16x32_bf16 v[28:31], v[116:119], v[210:213], v[28:31]
	v_mfma_f32_16x16x32_bf16 v[24:27], v[140:143], v[210:213], v[24:27]
	v_mfma_f32_16x16x32_bf16 v[12:15], v[116:119], v[218:221], v[12:15]
	v_mfma_f32_16x16x32_bf16 v[8:11], v[140:143], v[218:221], v[8:11]
	v_mfma_f32_16x16x32_bf16 v[52:55], v[144:147], v[160:163], v[52:55]
	v_mfma_f32_16x16x32_bf16 v[48:51], v[152:155], v[160:163], v[48:51]
	v_mfma_f32_16x16x32_bf16 v[36:39], v[144:147], v[168:171], v[36:39]
	v_mfma_f32_16x16x32_bf16 v[32:35], v[152:155], v[168:171], v[32:35]
	v_mfma_f32_16x16x32_bf16 v[20:23], v[144:147], v[206:209], v[20:23]
	v_mfma_f32_16x16x32_bf16 v[16:19], v[152:155], v[206:209], v[16:19]
	v_mfma_f32_16x16x32_bf16 v[4:7], v[144:147], v[214:217], v[4:7]
	v_mfma_f32_16x16x32_bf16 v[0:3], v[152:155], v[214:217], v[0:3]
	v_mfma_f32_16x16x32_bf16 v[52:55], v[148:151], v[164:167], v[52:55]
	v_mfma_f32_16x16x32_bf16 v[48:51], v[156:159], v[164:167], v[48:51]
	v_mfma_f32_16x16x32_bf16 v[36:39], v[148:151], v[172:175], v[36:39]
	v_mfma_f32_16x16x32_bf16 v[32:35], v[156:159], v[172:175], v[32:35]
	v_mfma_f32_16x16x32_bf16 v[20:23], v[148:151], v[210:213], v[20:23]
	v_mfma_f32_16x16x32_bf16 v[16:19], v[156:159], v[210:213], v[16:19]
	v_mfma_f32_16x16x32_bf16 v[4:7], v[148:151], v[218:221], v[4:7]
	v_mfma_f32_16x16x32_bf16 v[0:3], v[156:159], v[218:221], v[0:3]
	s_setprio 0
	s_barrier
	s_add_i32 s82, s82, 2
	s_add_u32 s80, s80, 0x100
	s_addc_u32 s81, s81, 0
	s_cmp_gt_u32 s82, 41
	s_mov_b64 s[20:21], s[22:23]
.Lh0_6:
	ds_read_b128 v[112:115], v203
	ds_read_b128 v[116:119], v203 offset:1024
	ds_read_b128 v[136:139], v203 offset:2048
	ds_read_b128 v[140:143], v203 offset:3072
	ds_read_b128 v[144:147], v204
	ds_read_b128 v[148:151], v204 offset:1024
	ds_read_b128 v[152:155], v204 offset:2048
	ds_read_b128 v[156:159], v204 offset:3072
	s_add_u32 s22, s20, 0x100
	s_addc_u32 s23, s21, 0
	s_cmp_eq_u32 s82, 40
	s_cselect_b32 s37, s7, s23
	s_cselect_b32 s36, s6, s22
	s_cselect_b32 s27, s19, s81
	s_cselect_b32 s26, s18, s80
	v_lshl_add_u64 v[200:201], s[20:21], 0, v[186:187]
	s_add_i32 m0, s43, 0xc000
	ds_read_b128 v[160:163], v205
	ds_read_b128 v[164:167], v205 offset:1024
	ds_read_b128 v[168:171], v205 offset:2048
	ds_read_b128 v[172:175], v205 offset:3072
	ds_read_b128 v[206:209], v205 offset:4096
	ds_read_b128 v[210:213], v205 offset:5120
	ds_read_b128 v[214:217], v205 offset:6144
	ds_read_b128 v[218:221], v205 offset:7168
	global_load_lds_dwordx4 v[200:201], off
	v_lshl_add_u64 v[200:201], s[20:21], 0, v[188:189]
	s_add_i32 m0, s43, 0xe000
	s_nop 0
	global_load_lds_dwordx4 v[200:201], off
	s_waitcnt vmcnt(8)
	s_waitcnt lgkmcnt(0)
	s_setprio 1
	v_mfma_f32_16x16x32_bf16 v[132:135], v[112:115], v[160:163], v[132:135]
	v_mfma_f32_16x16x32_bf16 v[128:131], v[136:139], v[160:163], v[128:131]
	v_mfma_f32_16x16x32_bf16 v[108:111], v[112:115], v[168:171], v[108:111]
	v_mfma_f32_16x16x32_bf16 v[104:107], v[136:139], v[168:171], v[104:107]
	v_mfma_f32_16x16x32_bf16 v[92:95], v[112:115], v[206:209], v[92:95]
	v_mfma_f32_16x16x32_bf16 v[88:91], v[136:139], v[206:209], v[88:91]
	v_mfma_f32_16x16x32_bf16 v[76:79], v[112:115], v[214:217], v[76:79]
	v_mfma_f32_16x16x32_bf16 v[72:75], v[136:139], v[214:217], v[72:75]
	v_mfma_f32_16x16x32_bf16 v[132:135], v[116:119], v[164:167], v[132:135]
	v_mfma_f32_16x16x32_bf16 v[128:131], v[140:143], v[164:167], v[128:131]
	v_mfma_f32_16x16x32_bf16 v[108:111], v[116:119], v[172:175], v[108:111]
	v_mfma_f32_16x16x32_bf16 v[104:107], v[140:143], v[172:175], v[104:107]
	v_mfma_f32_16x16x32_bf16 v[92:95], v[116:119], v[210:213], v[92:95]
	v_mfma_f32_16x16x32_bf16 v[88:91], v[140:143], v[210:213], v[88:91]
	v_mfma_f32_16x16x32_bf16 v[76:79], v[116:119], v[218:221], v[76:79]
	v_mfma_f32_16x16x32_bf16 v[72:75], v[140:143], v[218:221], v[72:75]
	v_mfma_f32_16x16x32_bf16 v[124:127], v[144:147], v[160:163], v[124:127]
	v_mfma_f32_16x16x32_bf16 v[120:123], v[152:155], v[160:163], v[120:123]
	v_mfma_f32_16x16x32_bf16 v[100:103], v[144:147], v[168:171], v[100:103]
	v_mfma_f32_16x16x32_bf16 v[96:99], v[152:155], v[168:171], v[96:99]
	v_mfma_f32_16x16x32_bf16 v[84:87], v[144:147], v[206:209], v[84:87]
	v_mfma_f32_16x16x32_bf16 v[80:83], v[152:155], v[206:209], v[80:83]
	v_mfma_f32_16x16x32_bf16 v[68:71], v[144:147], v[214:217], v[68:71]
	v_mfma_f32_16x16x32_bf16 v[64:67], v[152:155], v[214:217], v[64:67]
	v_mfma_f32_16x16x32_bf16 v[124:127], v[148:151], v[164:167], v[124:127]
	v_mfma_f32_16x16x32_bf16 v[120:123], v[156:159], v[164:167], v[120:123]
	v_mfma_f32_16x16x32_bf16 v[100:103], v[148:151], v[172:175], v[100:103]
	v_mfma_f32_16x16x32_bf16 v[96:99], v[156:159], v[172:175], v[96:99]
	v_mfma_f32_16x16x32_bf16 v[84:87], v[148:151], v[210:213], v[84:87]
	v_mfma_f32_16x16x32_bf16 v[80:83], v[156:159], v[210:213], v[80:83]
	v_mfma_f32_16x16x32_bf16 v[68:71], v[148:151], v[218:221], v[68:71]
	v_mfma_f32_16x16x32_bf16 v[64:67], v[156:159], v[218:221], v[64:67]
	s_setprio 0
	s_barrier
	s_add_i32 s20, s59, s40
	v_lshl_add_u64 v[200:201], s[26:27], 0, v[180:181]
	s_mov_b32 m0, s20
	ds_read_b128 v[160:163], v205 offset:16384
	ds_read_b128 v[164:167], v205 offset:17408
	ds_read_b128 v[168:171], v205 offset:18432
	ds_read_b128 v[172:175], v205 offset:19456
	ds_read_b128 v[206:209], v205 offset:20480
	ds_read_b128 v[210:213], v205 offset:21504
	ds_read_b128 v[214:217], v205 offset:22528
	ds_read_b128 v[218:221], v205 offset:23552
	global_load_lds_dwordx4 v[200:201], off
	s_add_i32 m0, s20, 0x2000
	s_add_u32 s20, s26, 0xb0000
	v_lshl_add_u64 v[222:223], s[26:27], 0, v[176:177]
	s_addc_u32 s21, s27, 0
	s_add_i32 s83, s66, s40
	global_load_lds_dwordx4 v[222:223], off
	v_lshl_add_u64 v[224:225], s[20:21], 0, v[180:181]
	s_mov_b32 m0, s83
	v_lshl_add_u64 v[226:227], s[36:37], 0, v[178:179]
	global_load_lds_dwordx4 v[224:225], off
	v_lshl_add_u64 v[224:225], s[20:21], 0, v[176:177]
	s_add_i32 m0, s83, 0x2000
	s_nop 0
	global_load_lds_dwordx4 v[224:225], off
	v_lshl_add_u64 v[224:225], s[36:37], 0, v[182:183]
	s_mov_b32 m0, s43
	s_nop 0
	global_load_lds_dwordx4 v[224:225], off
	s_mov_b32 m0, s44
	s_nop 0
	global_load_lds_dwordx4 v[226:227], off
	s_waitcnt vmcnt(8)
	s_waitcnt lgkmcnt(0)
	s_setprio 1
	v_mfma_f32_16x16x32_bf16 v[60:63], v[112:115], v[160:163], v[60:63]
	v_mfma_f32_16x16x32_bf16 v[56:59], v[136:139], v[160:163], v[56:59]
	v_mfma_f32_16x16x32_bf16 v[44:47], v[112:115], v[168:171], v[44:47]
	v_mfma_f32_16x16x32_bf16 v[40:43], v[136:139], v[168:171], v[40:43]
	v_mfma_f32_16x16x32_bf16 v[28:31], v[112:115], v[206:209], v[28:31]
	v_mfma_f32_16x16x32_bf16 v[24:27], v[136:139], v[206:209], v[24:27]
	v_mfma_f32_16x16x32_bf16 v[12:15], v[112:115], v[214:217], v[12:15]
	v_mfma_f32_16x16x32_bf16 v[8:11], v[136:139], v[214:217], v[8:11]
	v_mfma_f32_16x16x32_bf16 v[60:63], v[116:119], v[164:167], v[60:63]
	v_mfma_f32_16x16x32_bf16 v[56:59], v[140:143], v[164:167], v[56:59]
	v_mfma_f32_16x16x32_bf16 v[44:47], v[116:119], v[172:175], v[44:47]
	v_mfma_f32_16x16x32_bf16 v[40:43], v[140:143], v[172:175], v[40:43]
	v_mfma_f32_16x16x32_bf16 v[28:31], v[116:119], v[210:213], v[28:31]
	v_mfma_f32_16x16x32_bf16 v[24:27], v[140:143], v[210:213], v[24:27]
	v_mfma_f32_16x16x32_bf16 v[12:15], v[116:119], v[218:221], v[12:15]
	v_mfma_f32_16x16x32_bf16 v[8:11], v[140:143], v[218:221], v[8:11]
	v_mfma_f32_16x16x32_bf16 v[52:55], v[144:147], v[160:163], v[52:55]
	v_mfma_f32_16x16x32_bf16 v[48:51], v[152:155], v[160:163], v[48:51]
	v_mfma_f32_16x16x32_bf16 v[36:39], v[144:147], v[168:171], v[36:39]
	v_mfma_f32_16x16x32_bf16 v[32:35], v[152:155], v[168:171], v[32:35]
	v_mfma_f32_16x16x32_bf16 v[20:23], v[144:147], v[206:209], v[20:23]
	v_mfma_f32_16x16x32_bf16 v[16:19], v[152:155], v[206:209], v[16:19]
	v_mfma_f32_16x16x32_bf16 v[4:7], v[144:147], v[214:217], v[4:7]
	v_mfma_f32_16x16x32_bf16 v[0:3], v[152:155], v[214:217], v[0:3]
	v_mfma_f32_16x16x32_bf16 v[52:55], v[148:151], v[164:167], v[52:55]
	v_mfma_f32_16x16x32_bf16 v[48:51], v[156:159], v[164:167], v[48:51]
	v_mfma_f32_16x16x32_bf16 v[36:39], v[148:151], v[172:175], v[36:39]
	v_mfma_f32_16x16x32_bf16 v[32:35], v[156:159], v[172:175], v[32:35]
	v_mfma_f32_16x16x32_bf16 v[20:23], v[148:151], v[210:213], v[20:23]
	v_mfma_f32_16x16x32_bf16 v[16:19], v[156:159], v[210:213], v[16:19]
	v_mfma_f32_16x16x32_bf16 v[4:7], v[148:151], v[218:221], v[4:7]
	v_mfma_f32_16x16x32_bf16 v[0:3], v[156:159], v[218:221], v[0:3]
	s_setprio 0
	s_barrier
	s_add_i32 s83, 0, 0x18000
	s_add_i32 s85, 0, 0x1c000
	v_add_u32_e32 v140, s83, v202
	v_add_u32_e32 v156, s85, v202
	ds_read_b128 v[112:115], v140
	ds_read_b128 v[116:119], v140 offset:1024
	ds_read_b128 v[136:139], v140 offset:2048
	ds_read_b128 v[140:143], v140 offset:3072
	ds_read_b128 v[144:147], v156
	ds_read_b128 v[148:151], v156 offset:1024
	ds_read_b128 v[152:155], v156 offset:2048
	ds_read_b128 v[156:159], v156 offset:3072
	s_add_u32 s20, s36, 0xb0000
	s_addc_u32 s21, s37, 0
	s_mov_b32 m0, s45
	v_lshl_add_u64 v[230:231], s[20:21], 0, v[182:183]
	ds_read_b128 v[160:163], v205 offset:32768
	ds_read_b128 v[164:167], v205 offset:33792
	ds_read_b128 v[168:171], v205 offset:34816
	ds_read_b128 v[172:175], v205 offset:35840
	ds_read_b128 v[206:209], v205 offset:36864
	ds_read_b128 v[210:213], v205 offset:37888
	ds_read_b128 v[214:217], v205 offset:38912
	ds_read_b128 v[218:221], v205 offset:39936
	global_load_lds_dwordx4 v[230:231], off
	v_lshl_add_u64 v[230:231], s[20:21], 0, v[178:179]
	s_mov_b32 m0, s46
	s_nop 0
	global_load_lds_dwordx4 v[230:231], off
	s_waitcnt vmcnt(8)
	s_waitcnt lgkmcnt(0)
	s_setprio 1
	v_mfma_f32_16x16x32_bf16 v[132:135], v[112:115], v[160:163], v[132:135]
	v_mfma_f32_16x16x32_bf16 v[128:131], v[136:139], v[160:163], v[128:131]
	v_mfma_f32_16x16x32_bf16 v[108:111], v[112:115], v[168:171], v[108:111]
	v_mfma_f32_16x16x32_bf16 v[104:107], v[136:139], v[168:171], v[104:107]
	v_mfma_f32_16x16x32_bf16 v[92:95], v[112:115], v[206:209], v[92:95]
	v_mfma_f32_16x16x32_bf16 v[88:91], v[136:139], v[206:209], v[88:91]
	v_mfma_f32_16x16x32_bf16 v[76:79], v[112:115], v[214:217], v[76:79]
	v_mfma_f32_16x16x32_bf16 v[72:75], v[136:139], v[214:217], v[72:75]
	v_mfma_f32_16x16x32_bf16 v[132:135], v[116:119], v[164:167], v[132:135]
	v_mfma_f32_16x16x32_bf16 v[128:131], v[140:143], v[164:167], v[128:131]
	v_mfma_f32_16x16x32_bf16 v[108:111], v[116:119], v[172:175], v[108:111]
	v_mfma_f32_16x16x32_bf16 v[104:107], v[140:143], v[172:175], v[104:107]
	v_mfma_f32_16x16x32_bf16 v[92:95], v[116:119], v[210:213], v[92:95]
	v_mfma_f32_16x16x32_bf16 v[88:91], v[140:143], v[210:213], v[88:91]
	v_mfma_f32_16x16x32_bf16 v[76:79], v[116:119], v[218:221], v[76:79]
	v_mfma_f32_16x16x32_bf16 v[72:75], v[140:143], v[218:221], v[72:75]
	v_mfma_f32_16x16x32_bf16 v[124:127], v[144:147], v[160:163], v[124:127]
	v_mfma_f32_16x16x32_bf16 v[120:123], v[152:155], v[160:163], v[120:123]
	v_mfma_f32_16x16x32_bf16 v[100:103], v[144:147], v[168:171], v[100:103]
	v_mfma_f32_16x16x32_bf16 v[96:99], v[152:155], v[168:171], v[96:99]
	v_mfma_f32_16x16x32_bf16 v[84:87], v[144:147], v[206:209], v[84:87]
	v_mfma_f32_16x16x32_bf16 v[80:83], v[152:155], v[206:209], v[80:83]
	v_mfma_f32_16x16x32_bf16 v[68:71], v[144:147], v[214:217], v[68:71]
	v_mfma_f32_16x16x32_bf16 v[64:67], v[152:155], v[214:217], v[64:67]
	v_mfma_f32_16x16x32_bf16 v[124:127], v[148:151], v[164:167], v[124:127]
	v_mfma_f32_16x16x32_bf16 v[120:123], v[156:159], v[164:167], v[120:123]
	v_mfma_f32_16x16x32_bf16 v[100:103], v[148:151], v[172:175], v[100:103]
	v_mfma_f32_16x16x32_bf16 v[96:99], v[156:159], v[172:175], v[96:99]
	v_mfma_f32_16x16x32_bf16 v[84:87], v[148:151], v[210:213], v[84:87]
	v_mfma_f32_16x16x32_bf16 v[80:83], v[156:159], v[210:213], v[80:83]
	v_mfma_f32_16x16x32_bf16 v[68:71], v[148:151], v[218:221], v[68:71]
	v_mfma_f32_16x16x32_bf16 v[64:67], v[156:159], v[218:221], v[64:67]
	s_setprio 0
	s_barrier
	s_add_i32 s20, s83, s40
	v_lshl_add_u64 v[200:201], v[200:201], 0, s[14:15]
	s_mov_b32 m0, s20
	ds_read_b128 v[160:163], v205 offset:49152
	ds_read_b128 v[164:167], v205 offset:50176
	ds_read_b128 v[168:171], v205 offset:51200
	ds_read_b128 v[172:175], v205 offset:52224
	ds_read_b128 v[206:209], v205 offset:53248
	ds_read_b128 v[210:213], v205 offset:54272
	ds_read_b128 v[214:217], v205 offset:55296
	ds_read_b128 v[218:221], v205 offset:56320
	global_load_lds_dwordx4 v[200:201], off
	s_add_i32 m0, s20, 0x2000
	s_add_u32 s20, s26, 0xb0080
	v_lshl_add_u64 v[200:201], v[222:223], 0, s[14:15]
	s_addc_u32 s21, s27, 0
	s_add_i32 s26, s85, s40
	global_load_lds_dwordx4 v[200:201], off
	v_lshl_add_u64 v[200:201], s[20:21], 0, v[180:181]
	s_mov_b32 m0, s26
	s_nop 0
	global_load_lds_dwordx4 v[200:201], off
	v_lshl_add_u64 v[200:201], s[20:21], 0, v[176:177]
	s_add_i32 m0, s26, 0x2000
	s_nop 0
	global_load_lds_dwordx4 v[200:201], off
	v_lshl_add_u64 v[200:201], v[224:225], 0, s[14:15]
	s_mov_b32 m0, s52
	s_nop 0
	global_load_lds_dwordx4 v[200:201], off
	v_lshl_add_u64 v[200:201], v[226:227], 0, s[14:15]
	s_mov_b32 m0, s53
	s_nop 0
	global_load_lds_dwordx4 v[200:201], off
	s_waitcnt vmcnt(8)
	s_waitcnt lgkmcnt(0)
	s_setprio 1
	v_mfma_f32_16x16x32_bf16 v[60:63], v[112:115], v[160:163], v[60:63]
	v_mfma_f32_16x16x32_bf16 v[56:59], v[136:139], v[160:163], v[56:59]
	v_mfma_f32_16x16x32_bf16 v[44:47], v[112:115], v[168:171], v[44:47]
	v_mfma_f32_16x16x32_bf16 v[40:43], v[136:139], v[168:171], v[40:43]
	v_mfma_f32_16x16x32_bf16 v[28:31], v[112:115], v[206:209], v[28:31]
	v_mfma_f32_16x16x32_bf16 v[24:27], v[136:139], v[206:209], v[24:27]
	v_mfma_f32_16x16x32_bf16 v[12:15], v[112:115], v[214:217], v[12:15]
	v_mfma_f32_16x16x32_bf16 v[8:11], v[136:139], v[214:217], v[8:11]
	v_mfma_f32_16x16x32_bf16 v[60:63], v[116:119], v[164:167], v[60:63]
	v_mfma_f32_16x16x32_bf16 v[56:59], v[140:143], v[164:167], v[56:59]
	v_mfma_f32_16x16x32_bf16 v[44:47], v[116:119], v[172:175], v[44:47]
	v_mfma_f32_16x16x32_bf16 v[40:43], v[140:143], v[172:175], v[40:43]
	v_mfma_f32_16x16x32_bf16 v[28:31], v[116:119], v[210:213], v[28:31]
	v_mfma_f32_16x16x32_bf16 v[24:27], v[140:143], v[210:213], v[24:27]
	v_mfma_f32_16x16x32_bf16 v[12:15], v[116:119], v[218:221], v[12:15]
	v_mfma_f32_16x16x32_bf16 v[8:11], v[140:143], v[218:221], v[8:11]
	v_mfma_f32_16x16x32_bf16 v[52:55], v[144:147], v[160:163], v[52:55]
	v_mfma_f32_16x16x32_bf16 v[48:51], v[152:155], v[160:163], v[48:51]
	v_mfma_f32_16x16x32_bf16 v[36:39], v[144:147], v[168:171], v[36:39]
	v_mfma_f32_16x16x32_bf16 v[32:35], v[152:155], v[168:171], v[32:35]
	v_mfma_f32_16x16x32_bf16 v[20:23], v[144:147], v[206:209], v[20:23]
	v_mfma_f32_16x16x32_bf16 v[16:19], v[152:155], v[206:209], v[16:19]
	v_mfma_f32_16x16x32_bf16 v[4:7], v[144:147], v[214:217], v[4:7]
	v_mfma_f32_16x16x32_bf16 v[0:3], v[152:155], v[214:217], v[0:3]
	v_mfma_f32_16x16x32_bf16 v[52:55], v[148:151], v[164:167], v[52:55]
	v_mfma_f32_16x16x32_bf16 v[48:51], v[156:159], v[164:167], v[48:51]
	v_mfma_f32_16x16x32_bf16 v[36:39], v[148:151], v[172:175], v[36:39]
	v_mfma_f32_16x16x32_bf16 v[32:35], v[156:159], v[172:175], v[32:35]
	v_mfma_f32_16x16x32_bf16 v[20:23], v[148:151], v[210:213], v[20:23]
	v_mfma_f32_16x16x32_bf16 v[16:19], v[156:159], v[210:213], v[16:19]
	v_mfma_f32_16x16x32_bf16 v[4:7], v[148:151], v[218:221], v[4:7]
	v_mfma_f32_16x16x32_bf16 v[0:3], v[156:159], v[218:221], v[0:3]
	s_setprio 0
	s_barrier
	s_add_i32 s82, s82, 2
	s_add_u32 s80, s80, 0x100
	s_addc_u32 s81, s81, 0
	s_cmp_gt_u32 s82, 41
	s_mov_b64 s[20:21], s[22:23]
	s_cbranch_scc0 .Lh0_6
	s_branch .Ljoin_6
.Lh1p_6:
	ds_read_b128 v[112:115], v203
	ds_read_b128 v[116:119], v203 offset:1024
	ds_read_b128 v[136:139], v203 offset:2048
	ds_read_b128 v[140:143], v203 offset:3072
	ds_read_b128 v[144:147], v204
	ds_read_b128 v[148:151], v204 offset:1024
	ds_read_b128 v[152:155], v204 offset:2048
	ds_read_b128 v[156:159], v204 offset:3072
	s_add_u32 s22, s20, 0x100
	s_addc_u32 s23, s21, 0
	s_cmp_eq_u32 s82, 40
	s_cselect_b32 s37, s7, s23
	s_cselect_b32 s36, s6, s22
	s_cselect_b32 s27, s19, s81
	s_cselect_b32 s26, s18, s80
	v_lshl_add_u64 v[200:201], s[20:21], 0, v[186:187]
	s_add_i32 m0, s43, 0xc000
	ds_read_b128 v[160:163], v205
	ds_read_b128 v[164:167], v205 offset:1024
	ds_read_b128 v[168:171], v205 offset:2048
	ds_read_b128 v[172:175], v205 offset:3072
	ds_read_b128 v[206:209], v205 offset:4096
	ds_read_b128 v[210:213], v205 offset:5120
	ds_read_b128 v[214:217], v205 offset:6144
	ds_read_b128 v[218:221], v205 offset:7168
	global_load_lds_dwordx4 v[200:201], off
	v_lshl_add_u64 v[200:201], s[20:21], 0, v[188:189]
	s_add_i32 m0, s43, 0xe000
	s_nop 0
	global_load_lds_dwordx4 v[200:201], off
	s_waitcnt vmcnt(8)
	s_waitcnt lgkmcnt(0)
	s_barrier
	s_setprio 2
	v_mfma_f32_16x16x32_bf16 v[132:135], v[112:115], v[160:163], 0
	v_mfma_f32_16x16x32_bf16 v[128:131], v[136:139], v[160:163], 0
	v_mfma_f32_16x16x32_bf16 v[108:111], v[112:115], v[168:171], 0
	v_mfma_f32_16x16x32_bf16 v[104:107], v[136:139], v[168:171], 0
	v_mfma_f32_16x16x32_bf16 v[92:95], v[112:115], v[206:209], 0
	v_mfma_f32_16x16x32_bf16 v[88:91], v[136:139], v[206:209], 0
	v_mfma_f32_16x16x32_bf16 v[76:79], v[112:115], v[214:217], 0
	v_mfma_f32_16x16x32_bf16 v[72:75], v[136:139], v[214:217], 0
	v_mfma_f32_16x16x32_bf16 v[132:135], v[116:119], v[164:167], v[132:135]
	v_mfma_f32_16x16x32_bf16 v[128:131], v[140:143], v[164:167], v[128:131]
	v_mfma_f32_16x16x32_bf16 v[108:111], v[116:119], v[172:175], v[108:111]
	v_mfma_f32_16x16x32_bf16 v[104:107], v[140:143], v[172:175], v[104:107]
	v_mfma_f32_16x16x32_bf16 v[92:95], v[116:119], v[210:213], v[92:95]
	v_mfma_f32_16x16x32_bf16 v[88:91], v[140:143], v[210:213], v[88:91]
	v_mfma_f32_16x16x32_bf16 v[76:79], v[116:119], v[218:221], v[76:79]
	v_mfma_f32_16x16x32_bf16 v[72:75], v[140:143], v[218:221], v[72:75]
	v_mfma_f32_16x16x32_bf16 v[124:127], v[144:147], v[160:163], 0
	v_mfma_f32_16x16x32_bf16 v[120:123], v[152:155], v[160:163], 0
	v_mfma_f32_16x16x32_bf16 v[100:103], v[144:147], v[168:171], 0
	v_mfma_f32_16x16x32_bf16 v[96:99], v[152:155], v[168:171], 0
	v_mfma_f32_16x16x32_bf16 v[84:87], v[144:147], v[206:209], 0
	v_mfma_f32_16x16x32_bf16 v[80:83], v[152:155], v[206:209], 0
	v_mfma_f32_16x16x32_bf16 v[68:71], v[144:147], v[214:217], 0
	v_mfma_f32_16x16x32_bf16 v[64:67], v[152:155], v[214:217], 0
	v_mfma_f32_16x16x32_bf16 v[124:127], v[148:151], v[164:167], v[124:127]
	v_mfma_f32_16x16x32_bf16 v[120:123], v[156:159], v[164:167], v[120:123]
	v_mfma_f32_16x16x32_bf16 v[100:103], v[148:151], v[172:175], v[100:103]
	v_mfma_f32_16x16x32_bf16 v[96:99], v[156:159], v[172:175], v[96:99]
	v_mfma_f32_16x16x32_bf16 v[84:87], v[148:151], v[210:213], v[84:87]
	v_mfma_f32_16x16x32_bf16 v[80:83], v[156:159], v[210:213], v[80:83]
	v_mfma_f32_16x16x32_bf16 v[68:71], v[148:151], v[218:221], v[68:71]
	v_mfma_f32_16x16x32_bf16 v[64:67], v[156:159], v[218:221], v[64:67]
	s_setprio 0
	s_add_i32 s20, s59, s40
	v_lshl_add_u64 v[200:201], s[26:27], 0, v[180:181]
	s_mov_b32 m0, s20
	ds_read_b128 v[160:163], v205 offset:16384
	ds_read_b128 v[164:167], v205 offset:17408
	ds_read_b128 v[168:171], v205 offset:18432
	ds_read_b128 v[172:175], v205 offset:19456
	ds_read_b128 v[206:209], v205 offset:20480
	ds_read_b128 v[210:213], v205 offset:21504
	ds_read_b128 v[214:217], v205 offset:22528
	ds_read_b128 v[218:221], v205 offset:23552
	global_load_lds_dwordx4 v[200:201], off
	s_add_i32 m0, s20, 0x2000
	s_add_u32 s20, s26, 0xb0000
	v_lshl_add_u64 v[222:223], s[26:27], 0, v[176:177]
	s_addc_u32 s21, s27, 0
	s_add_i32 s83, s66, s40
	global_load_lds_dwordx4 v[222:223], off
	v_lshl_add_u64 v[224:225], s[20:21], 0, v[180:181]
	s_mov_b32 m0, s83
	v_lshl_add_u64 v[226:227], s[36:37], 0, v[178:179]
	global_load_lds_dwordx4 v[224:225], off
	v_lshl_add_u64 v[224:225], s[20:21], 0, v[176:177]
	s_add_i32 m0, s83, 0x2000
	s_nop 0
	global_load_lds_dwordx4 v[224:225], off
	v_lshl_add_u64 v[224:225], s[36:37], 0, v[182:183]
	s_mov_b32 m0, s43
	s_nop 0
	global_load_lds_dwordx4 v[224:225], off
	s_mov_b32 m0, s44
	s_nop 0
	global_load_lds_dwordx4 v[226:227], off
	s_waitcnt vmcnt(8)
	s_waitcnt lgkmcnt(0)
	s_barrier
	s_setprio 2
	v_mfma_f32_16x16x32_bf16 v[60:63], v[112:115], v[160:163], 0
	v_mfma_f32_16x16x32_bf16 v[56:59], v[136:139], v[160:163], 0
	v_mfma_f32_16x16x32_bf16 v[44:47], v[112:115], v[168:171], 0
	v_mfma_f32_16x16x32_bf16 v[40:43], v[136:139], v[168:171], 0
	v_mfma_f32_16x16x32_bf16 v[28:31], v[112:115], v[206:209], 0
	v_mfma_f32_16x16x32_bf16 v[24:27], v[136:139], v[206:209], 0
	v_mfma_f32_16x16x32_bf16 v[12:15], v[112:115], v[214:217], 0
	v_mfma_f32_16x16x32_bf16 v[8:11], v[136:139], v[214:217], 0
	v_mfma_f32_16x16x32_bf16 v[60:63], v[116:119], v[164:167], v[60:63]
	v_mfma_f32_16x16x32_bf16 v[56:59], v[140:143], v[164:167], v[56:59]
	v_mfma_f32_16x16x32_bf16 v[44:47], v[116:119], v[172:175], v[44:47]
	v_mfma_f32_16x16x32_bf16 v[40:43], v[140:143], v[172:175], v[40:43]
	v_mfma_f32_16x16x32_bf16 v[28:31], v[116:119], v[210:213], v[28:31]
	v_mfma_f32_16x16x32_bf16 v[24:27], v[140:143], v[210:213], v[24:27]
	v_mfma_f32_16x16x32_bf16 v[12:15], v[116:119], v[218:221], v[12:15]
	v_mfma_f32_16x16x32_bf16 v[8:11], v[140:143], v[218:221], v[8:11]
	v_mfma_f32_16x16x32_bf16 v[52:55], v[144:147], v[160:163], 0
	v_mfma_f32_16x16x32_bf16 v[48:51], v[152:155], v[160:163], 0
	v_mfma_f32_16x16x32_bf16 v[36:39], v[144:147], v[168:171], 0
	v_mfma_f32_16x16x32_bf16 v[32:35], v[152:155], v[168:171], 0
	v_mfma_f32_16x16x32_bf16 v[20:23], v[144:147], v[206:209], 0
	v_mfma_f32_16x16x32_bf16 v[16:19], v[152:155], v[206:209], 0
	v_mfma_f32_16x16x32_bf16 v[4:7], v[144:147], v[214:217], 0
	v_mfma_f32_16x16x32_bf16 v[0:3], v[152:155], v[214:217], 0
	v_mfma_f32_16x16x32_bf16 v[52:55], v[148:151], v[164:167], v[52:55]
	v_mfma_f32_16x16x32_bf16 v[48:51], v[156:159], v[164:167], v[48:51]
	v_mfma_f32_16x16x32_bf16 v[36:39], v[148:151], v[172:175], v[36:39]
	v_mfma_f32_16x16x32_bf16 v[32:35], v[156:159], v[172:175], v[32:35]
	v_mfma_f32_16x16x32_bf16 v[20:23], v[148:151], v[210:213], v[20:23]
	v_mfma_f32_16x16x32_bf16 v[16:19], v[156:159], v[210:213], v[16:19]
	v_mfma_f32_16x16x32_bf16 v[4:7], v[148:151], v[218:221], v[4:7]
	v_mfma_f32_16x16x32_bf16 v[0:3], v[156:159], v[218:221], v[0:3]
	s_setprio 0
	s_add_i32 s83, 0, 0x18000
	s_add_i32 s85, 0, 0x1c000
	v_add_u32_e32 v140, s83, v202
	v_add_u32_e32 v156, s85, v202
	ds_read_b128 v[112:115], v140
	ds_read_b128 v[116:119], v140 offset:1024
	ds_read_b128 v[136:139], v140 offset:2048
	ds_read_b128 v[140:143], v140 offset:3072
	ds_read_b128 v[144:147], v156
	ds_read_b128 v[148:151], v156 offset:1024
	ds_read_b128 v[152:155], v156 offset:2048
	ds_read_b128 v[156:159], v156 offset:3072
	s_add_u32 s20, s36, 0xb0000
	s_addc_u32 s21, s37, 0
	s_mov_b32 m0, s45
	v_lshl_add_u64 v[230:231], s[20:21], 0, v[182:183]
	ds_read_b128 v[160:163], v205 offset:32768
	ds_read_b128 v[164:167], v205 offset:33792
	ds_read_b128 v[168:171], v205 offset:34816
	ds_read_b128 v[172:175], v205 offset:35840
	ds_read_b128 v[206:209], v205 offset:36864
	ds_read_b128 v[210:213], v205 offset:37888
	ds_read_b128 v[214:217], v205 offset:38912
	ds_read_b128 v[218:221], v205 offset:39936
	global_load_lds_dwordx4 v[230:231], off
	v_lshl_add_u64 v[230:231], s[20:21], 0, v[178:179]
	s_mov_b32 m0, s46
	s_nop 0
	global_load_lds_dwordx4 v[230:231], off
	s_waitcnt vmcnt(8)
	s_waitcnt lgkmcnt(0)
	s_barrier
	s_setprio 2
	v_mfma_f32_16x16x32_bf16 v[132:135], v[112:115], v[160:163], v[132:135]
	v_mfma_f32_16x16x32_bf16 v[128:131], v[136:139], v[160:163], v[128:131]
	v_mfma_f32_16x16x32_bf16 v[108:111], v[112:115], v[168:171], v[108:111]
	v_mfma_f32_16x16x32_bf16 v[104:107], v[136:139], v[168:171], v[104:107]
	v_mfma_f32_16x16x32_bf16 v[92:95], v[112:115], v[206:209], v[92:95]
	v_mfma_f32_16x16x32_bf16 v[88:91], v[136:139], v[206:209], v[88:91]
	v_mfma_f32_16x16x32_bf16 v[76:79], v[112:115], v[214:217], v[76:79]
	v_mfma_f32_16x16x32_bf16 v[72:75], v[136:139], v[214:217], v[72:75]
	v_mfma_f32_16x16x32_bf16 v[132:135], v[116:119], v[164:167], v[132:135]
	v_mfma_f32_16x16x32_bf16 v[128:131], v[140:143], v[164:167], v[128:131]
	v_mfma_f32_16x16x32_bf16 v[108:111], v[116:119], v[172:175], v[108:111]
	v_mfma_f32_16x16x32_bf16 v[104:107], v[140:143], v[172:175], v[104:107]
	v_mfma_f32_16x16x32_bf16 v[92:95], v[116:119], v[210:213], v[92:95]
	v_mfma_f32_16x16x32_bf16 v[88:91], v[140:143], v[210:213], v[88:91]
	v_mfma_f32_16x16x32_bf16 v[76:79], v[116:119], v[218:221], v[76:79]
	v_mfma_f32_16x16x32_bf16 v[72:75], v[140:143], v[218:221], v[72:75]
	v_mfma_f32_16x16x32_bf16 v[124:127], v[144:147], v[160:163], v[124:127]
	v_mfma_f32_16x16x32_bf16 v[120:123], v[152:155], v[160:163], v[120:123]
	v_mfma_f32_16x16x32_bf16 v[100:103], v[144:147], v[168:171], v[100:103]
	v_mfma_f32_16x16x32_bf16 v[96:99], v[152:155], v[168:171], v[96:99]
	v_mfma_f32_16x16x32_bf16 v[84:87], v[144:147], v[206:209], v[84:87]
	v_mfma_f32_16x16x32_bf16 v[80:83], v[152:155], v[206:209], v[80:83]
	v_mfma_f32_16x16x32_bf16 v[68:71], v[144:147], v[214:217], v[68:71]
	v_mfma_f32_16x16x32_bf16 v[64:67], v[152:155], v[214:217], v[64:67]
	v_mfma_f32_16x16x32_bf16 v[124:127], v[148:151], v[164:167], v[124:127]
	v_mfma_f32_16x16x32_bf16 v[120:123], v[156:159], v[164:167], v[120:123]
	v_mfma_f32_16x16x32_bf16 v[100:103], v[148:151], v[172:175], v[100:103]
	v_mfma_f32_16x16x32_bf16 v[96:99], v[156:159], v[172:175], v[96:99]
	v_mfma_f32_16x16x32_bf16 v[84:87], v[148:151], v[210:213], v[84:87]
	v_mfma_f32_16x16x32_bf16 v[80:83], v[156:159], v[210:213], v[80:83]
	v_mfma_f32_16x16x32_bf16 v[68:71], v[148:151], v[218:221], v[68:71]
	v_mfma_f32_16x16x32_bf16 v[64:67], v[156:159], v[218:221], v[64:67]
	s_setprio 0
	s_add_i32 s20, s83, s40
	v_lshl_add_u64 v[200:201], v[200:201], 0, s[14:15]
	s_mov_b32 m0, s20
	ds_read_b128 v[160:163], v205 offset:49152
	ds_read_b128 v[164:167], v205 offset:50176
	ds_read_b128 v[168:171], v205 offset:51200
	ds_read_b128 v[172:175], v205 offset:52224
	ds_read_b128 v[206:209], v205 offset:53248
	ds_read_b128 v[210:213], v205 offset:54272
	ds_read_b128 v[214:217], v205 offset:55296
	ds_read_b128 v[218:221], v205 offset:56320
	global_load_lds_dwordx4 v[200:201], off
	s_add_i32 m0, s20, 0x2000
	s_add_u32 s20, s26, 0xb0080
	v_lshl_add_u64 v[200:201], v[222:223], 0, s[14:15]
	s_addc_u32 s21, s27, 0
	s_add_i32 s26, s85, s40
	global_load_lds_dwordx4 v[200:201], off
	v_lshl_add_u64 v[200:201], s[20:21], 0, v[180:181]
	s_mov_b32 m0, s26
	s_nop 0
	global_load_lds_dwordx4 v[200:201], off
	v_lshl_add_u64 v[200:201], s[20:21], 0, v[176:177]
	s_add_i32 m0, s26, 0x2000
	s_nop 0
	global_load_lds_dwordx4 v[200:201], off
	v_lshl_add_u64 v[200:201], v[224:225], 0, s[14:15]
	s_mov_b32 m0, s52
	s_nop 0
	global_load_lds_dwordx4 v[200:201], off
	v_lshl_add_u64 v[200:201], v[226:227], 0, s[14:15]
	s_mov_b32 m0, s53
	s_nop 0
	global_load_lds_dwordx4 v[200:201], off
	s_waitcnt vmcnt(8)
	s_waitcnt lgkmcnt(0)
	s_barrier
	s_setprio 2
	v_mfma_f32_16x16x32_bf16 v[60:63], v[112:115], v[160:163], v[60:63]
	v_mfma_f32_16x16x32_bf16 v[56:59], v[136:139], v[160:163], v[56:59]
	v_mfma_f32_16x16x32_bf16 v[44:47], v[112:115], v[168:171], v[44:47]
	v_mfma_f32_16x16x32_bf16 v[40:43], v[136:139], v[168:171], v[40:43]
	v_mfma_f32_16x16x32_bf16 v[28:31], v[112:115], v[206:209], v[28:31]
	v_mfma_f32_16x16x32_bf16 v[24:27], v[136:139], v[206:209], v[24:27]
	v_mfma_f32_16x16x32_bf16 v[12:15], v[112:115], v[214:217], v[12:15]
	v_mfma_f32_16x16x32_bf16 v[8:11], v[136:139], v[214:217], v[8:11]
	v_mfma_f32_16x16x32_bf16 v[60:63], v[116:119], v[164:167], v[60:63]
	v_mfma_f32_16x16x32_bf16 v[56:59], v[140:143], v[164:167], v[56:59]
	v_mfma_f32_16x16x32_bf16 v[44:47], v[116:119], v[172:175], v[44:47]
	v_mfma_f32_16x16x32_bf16 v[40:43], v[140:143], v[172:175], v[40:43]
	v_mfma_f32_16x16x32_bf16 v[28:31], v[116:119], v[210:213], v[28:31]
	v_mfma_f32_16x16x32_bf16 v[24:27], v[140:143], v[210:213], v[24:27]
	v_mfma_f32_16x16x32_bf16 v[12:15], v[116:119], v[218:221], v[12:15]
	v_mfma_f32_16x16x32_bf16 v[8:11], v[140:143], v[218:221], v[8:11]
	v_mfma_f32_16x16x32_bf16 v[52:55], v[144:147], v[160:163], v[52:55]
	v_mfma_f32_16x16x32_bf16 v[48:51], v[152:155], v[160:163], v[48:51]
	v_mfma_f32_16x16x32_bf16 v[36:39], v[144:147], v[168:171], v[36:39]
	v_mfma_f32_16x16x32_bf16 v[32:35], v[152:155], v[168:171], v[32:35]
	v_mfma_f32_16x16x32_bf16 v[20:23], v[144:147], v[206:209], v[20:23]
	v_mfma_f32_16x16x32_bf16 v[16:19], v[152:155], v[206:209], v[16:19]
	v_mfma_f32_16x16x32_bf16 v[4:7], v[144:147], v[214:217], v[4:7]
	v_mfma_f32_16x16x32_bf16 v[0:3], v[152:155], v[214:217], v[0:3]
	v_mfma_f32_16x16x32_bf16 v[52:55], v[148:151], v[164:167], v[52:55]
	v_mfma_f32_16x16x32_bf16 v[48:51], v[156:159], v[164:167], v[48:51]
	v_mfma_f32_16x16x32_bf16 v[36:39], v[148:151], v[172:175], v[36:39]
	v_mfma_f32_16x16x32_bf16 v[32:35], v[156:159], v[172:175], v[32:35]
	v_mfma_f32_16x16x32_bf16 v[20:23], v[148:151], v[210:213], v[20:23]
	v_mfma_f32_16x16x32_bf16 v[16:19], v[156:159], v[210:213], v[16:19]
	v_mfma_f32_16x16x32_bf16 v[4:7], v[148:151], v[218:221], v[4:7]
	v_mfma_f32_16x16x32_bf16 v[0:3], v[156:159], v[218:221], v[0:3]
	s_setprio 0
	s_add_i32 s82, s82, 2
	s_add_u32 s80, s80, 0x100
	s_addc_u32 s81, s81, 0
	s_cmp_gt_u32 s82, 41
	s_mov_b64 s[20:21], s[22:23]
.Lh1_6:
	ds_read_b128 v[112:115], v203
	ds_read_b128 v[116:119], v203 offset:1024
	ds_read_b128 v[136:139], v203 offset:2048
	ds_read_b128 v[140:143], v203 offset:3072
	ds_read_b128 v[144:147], v204
	ds_read_b128 v[148:151], v204 offset:1024
	ds_read_b128 v[152:155], v204 offset:2048
	ds_read_b128 v[156:159], v204 offset:3072
	s_add_u32 s22, s20, 0x100
	s_addc_u32 s23, s21, 0
	s_cmp_eq_u32 s82, 40
	s_cselect_b32 s37, s7, s23
	s_cselect_b32 s36, s6, s22
	s_cselect_b32 s27, s19, s81
	s_cselect_b32 s26, s18, s80
	v_lshl_add_u64 v[200:201], s[20:21], 0, v[186:187]
	s_add_i32 m0, s43, 0xc000
	ds_read_b128 v[160:163], v205
	ds_read_b128 v[164:167], v205 offset:1024
	ds_read_b128 v[168:171], v205 offset:2048
	ds_read_b128 v[172:175], v205 offset:3072
	ds_read_b128 v[206:209], v205 offset:4096
	ds_read_b128 v[210:213], v205 offset:5120
	ds_read_b128 v[214:217], v205 offset:6144
	ds_read_b128 v[218:221], v205 offset:7168
	global_load_lds_dwordx4 v[200:201], off
	v_lshl_add_u64 v[200:201], s[20:21], 0, v[188:189]
	s_add_i32 m0, s43, 0xe000
	s_nop 0
	global_load_lds_dwordx4 v[200:201], off
	s_waitcnt vmcnt(8)
	s_waitcnt lgkmcnt(0)
	s_barrier
	s_setprio 2
	v_mfma_f32_16x16x32_bf16 v[132:135], v[112:115], v[160:163], v[132:135]
	v_mfma_f32_16x16x32_bf16 v[128:131], v[136:139], v[160:163], v[128:131]
	v_mfma_f32_16x16x32_bf16 v[108:111], v[112:115], v[168:171], v[108:111]
	v_mfma_f32_16x16x32_bf16 v[104:107], v[136:139], v[168:171], v[104:107]
	v_mfma_f32_16x16x32_bf16 v[92:95], v[112:115], v[206:209], v[92:95]
	v_mfma_f32_16x16x32_bf16 v[88:91], v[136:139], v[206:209], v[88:91]
	v_mfma_f32_16x16x32_bf16 v[76:79], v[112:115], v[214:217], v[76:79]
	v_mfma_f32_16x16x32_bf16 v[72:75], v[136:139], v[214:217], v[72:75]
	v_mfma_f32_16x16x32_bf16 v[132:135], v[116:119], v[164:167], v[132:135]
	v_mfma_f32_16x16x32_bf16 v[128:131], v[140:143], v[164:167], v[128:131]
	v_mfma_f32_16x16x32_bf16 v[108:111], v[116:119], v[172:175], v[108:111]
	v_mfma_f32_16x16x32_bf16 v[104:107], v[140:143], v[172:175], v[104:107]
	v_mfma_f32_16x16x32_bf16 v[92:95], v[116:119], v[210:213], v[92:95]
	v_mfma_f32_16x16x32_bf16 v[88:91], v[140:143], v[210:213], v[88:91]
	v_mfma_f32_16x16x32_bf16 v[76:79], v[116:119], v[218:221], v[76:79]
	v_mfma_f32_16x16x32_bf16 v[72:75], v[140:143], v[218:221], v[72:75]
	v_mfma_f32_16x16x32_bf16 v[124:127], v[144:147], v[160:163], v[124:127]
	v_mfma_f32_16x16x32_bf16 v[120:123], v[152:155], v[160:163], v[120:123]
	v_mfma_f32_16x16x32_bf16 v[100:103], v[144:147], v[168:171], v[100:103]
	v_mfma_f32_16x16x32_bf16 v[96:99], v[152:155], v[168:171], v[96:99]
	v_mfma_f32_16x16x32_bf16 v[84:87], v[144:147], v[206:209], v[84:87]
	v_mfma_f32_16x16x32_bf16 v[80:83], v[152:155], v[206:209], v[80:83]
	v_mfma_f32_16x16x32_bf16 v[68:71], v[144:147], v[214:217], v[68:71]
	v_mfma_f32_16x16x32_bf16 v[64:67], v[152:155], v[214:217], v[64:67]
	v_mfma_f32_16x16x32_bf16 v[124:127], v[148:151], v[164:167], v[124:127]
	v_mfma_f32_16x16x32_bf16 v[120:123], v[156:159], v[164:167], v[120:123]
	v_mfma_f32_16x16x32_bf16 v[100:103], v[148:151], v[172:175], v[100:103]
	v_mfma_f32_16x16x32_bf16 v[96:99], v[156:159], v[172:175], v[96:99]
	v_mfma_f32_16x16x32_bf16 v[84:87], v[148:151], v[210:213], v[84:87]
	v_mfma_f32_16x16x32_bf16 v[80:83], v[156:159], v[210:213], v[80:83]
	v_mfma_f32_16x16x32_bf16 v[68:71], v[148:151], v[218:221], v[68:71]
	v_mfma_f32_16x16x32_bf16 v[64:67], v[156:159], v[218:221], v[64:67]
	s_setprio 0
	s_add_i32 s20, s59, s40
	v_lshl_add_u64 v[200:201], s[26:27], 0, v[180:181]
	s_mov_b32 m0, s20
	ds_read_b128 v[160:163], v205 offset:16384
	ds_read_b128 v[164:167], v205 offset:17408
	ds_read_b128 v[168:171], v205 offset:18432
	ds_read_b128 v[172:175], v205 offset:19456
	ds_read_b128 v[206:209], v205 offset:20480
	ds_read_b128 v[210:213], v205 offset:21504
	ds_read_b128 v[214:217], v205 offset:22528
	ds_read_b128 v[218:221], v205 offset:23552
	global_load_lds_dwordx4 v[200:201], off
	s_add_i32 m0, s20, 0x2000
	s_add_u32 s20, s26, 0xb0000
	v_lshl_add_u64 v[222:223], s[26:27], 0, v[176:177]
	s_addc_u32 s21, s27, 0
	s_add_i32 s83, s66, s40
	global_load_lds_dwordx4 v[222:223], off
	v_lshl_add_u64 v[224:225], s[20:21], 0, v[180:181]
	s_mov_b32 m0, s83
	v_lshl_add_u64 v[226:227], s[36:37], 0, v[178:179]
	global_load_lds_dwordx4 v[224:225], off
	v_lshl_add_u64 v[224:225], s[20:21], 0, v[176:177]
	s_add_i32 m0, s83, 0x2000
	s_nop 0
	global_load_lds_dwordx4 v[224:225], off
	v_lshl_add_u64 v[224:225], s[36:37], 0, v[182:183]
	s_mov_b32 m0, s43
	s_nop 0
	global_load_lds_dwordx4 v[224:225], off
	s_mov_b32 m0, s44
	s_nop 0
	global_load_lds_dwordx4 v[226:227], off
	s_waitcnt vmcnt(8)
	s_waitcnt lgkmcnt(0)
	s_barrier
	s_setprio 2
	v_mfma_f32_16x16x32_bf16 v[60:63], v[112:115], v[160:163], v[60:63]
	v_mfma_f32_16x16x32_bf16 v[56:59], v[136:139], v[160:163], v[56:59]
	v_mfma_f32_16x16x32_bf16 v[44:47], v[112:115], v[168:171], v[44:47]
	v_mfma_f32_16x16x32_bf16 v[40:43], v[136:139], v[168:171], v[40:43]
	v_mfma_f32_16x16x32_bf16 v[28:31], v[112:115], v[206:209], v[28:31]
	v_mfma_f32_16x16x32_bf16 v[24:27], v[136:139], v[206:209], v[24:27]
	v_mfma_f32_16x16x32_bf16 v[12:15], v[112:115], v[214:217], v[12:15]
	v_mfma_f32_16x16x32_bf16 v[8:11], v[136:139], v[214:217], v[8:11]
	v_mfma_f32_16x16x32_bf16 v[60:63], v[116:119], v[164:167], v[60:63]
	v_mfma_f32_16x16x32_bf16 v[56:59], v[140:143], v[164:167], v[56:59]
	v_mfma_f32_16x16x32_bf16 v[44:47], v[116:119], v[172:175], v[44:47]
	v_mfma_f32_16x16x32_bf16 v[40:43], v[140:143], v[172:175], v[40:43]
	v_mfma_f32_16x16x32_bf16 v[28:31], v[116:119], v[210:213], v[28:31]
	v_mfma_f32_16x16x32_bf16 v[24:27], v[140:143], v[210:213], v[24:27]
	v_mfma_f32_16x16x32_bf16 v[12:15], v[116:119], v[218:221], v[12:15]
	v_mfma_f32_16x16x32_bf16 v[8:11], v[140:143], v[218:221], v[8:11]
	v_mfma_f32_16x16x32_bf16 v[52:55], v[144:147], v[160:163], v[52:55]
	v_mfma_f32_16x16x32_bf16 v[48:51], v[152:155], v[160:163], v[48:51]
	v_mfma_f32_16x16x32_bf16 v[36:39], v[144:147], v[168:171], v[36:39]
	v_mfma_f32_16x16x32_bf16 v[32:35], v[152:155], v[168:171], v[32:35]
	v_mfma_f32_16x16x32_bf16 v[20:23], v[144:147], v[206:209], v[20:23]
	v_mfma_f32_16x16x32_bf16 v[16:19], v[152:155], v[206:209], v[16:19]
	v_mfma_f32_16x16x32_bf16 v[4:7], v[144:147], v[214:217], v[4:7]
	v_mfma_f32_16x16x32_bf16 v[0:3], v[152:155], v[214:217], v[0:3]
	v_mfma_f32_16x16x32_bf16 v[52:55], v[148:151], v[164:167], v[52:55]
	v_mfma_f32_16x16x32_bf16 v[48:51], v[156:159], v[164:167], v[48:51]
	v_mfma_f32_16x16x32_bf16 v[36:39], v[148:151], v[172:175], v[36:39]
	v_mfma_f32_16x16x32_bf16 v[32:35], v[156:159], v[172:175], v[32:35]
	v_mfma_f32_16x16x32_bf16 v[20:23], v[148:151], v[210:213], v[20:23]
	v_mfma_f32_16x16x32_bf16 v[16:19], v[156:159], v[210:213], v[16:19]
	v_mfma_f32_16x16x32_bf16 v[4:7], v[148:151], v[218:221], v[4:7]
	v_mfma_f32_16x16x32_bf16 v[0:3], v[156:159], v[218:221], v[0:3]
	s_setprio 0
	s_add_i32 s83, 0, 0x18000
	s_add_i32 s85, 0, 0x1c000
	v_add_u32_e32 v140, s83, v202
	v_add_u32_e32 v156, s85, v202
	ds_read_b128 v[112:115], v140
	ds_read_b128 v[116:119], v140 offset:1024
	ds_read_b128 v[136:139], v140 offset:2048
	ds_read_b128 v[140:143], v140 offset:3072
	ds_read_b128 v[144:147], v156
	ds_read_b128 v[148:151], v156 offset:1024
	ds_read_b128 v[152:155], v156 offset:2048
	ds_read_b128 v[156:159], v156 offset:3072
	s_add_u32 s20, s36, 0xb0000
	s_addc_u32 s21, s37, 0
	s_mov_b32 m0, s45
	v_lshl_add_u64 v[230:231], s[20:21], 0, v[182:183]
	ds_read_b128 v[160:163], v205 offset:32768
	ds_read_b128 v[164:167], v205 offset:33792
	ds_read_b128 v[168:171], v205 offset:34816
	ds_read_b128 v[172:175], v205 offset:35840
	ds_read_b128 v[206:209], v205 offset:36864
	ds_read_b128 v[210:213], v205 offset:37888
	ds_read_b128 v[214:217], v205 offset:38912
	ds_read_b128 v[218:221], v205 offset:39936
	global_load_lds_dwordx4 v[230:231], off
	v_lshl_add_u64 v[230:231], s[20:21], 0, v[178:179]
	s_mov_b32 m0, s46
	s_nop 0
	global_load_lds_dwordx4 v[230:231], off
	s_waitcnt vmcnt(8)
	s_waitcnt lgkmcnt(0)
	s_barrier
	s_setprio 2
	v_mfma_f32_16x16x32_bf16 v[132:135], v[112:115], v[160:163], v[132:135]
	v_mfma_f32_16x16x32_bf16 v[128:131], v[136:139], v[160:163], v[128:131]
	v_mfma_f32_16x16x32_bf16 v[108:111], v[112:115], v[168:171], v[108:111]
	v_mfma_f32_16x16x32_bf16 v[104:107], v[136:139], v[168:171], v[104:107]
	v_mfma_f32_16x16x32_bf16 v[92:95], v[112:115], v[206:209], v[92:95]
	v_mfma_f32_16x16x32_bf16 v[88:91], v[136:139], v[206:209], v[88:91]
	v_mfma_f32_16x16x32_bf16 v[76:79], v[112:115], v[214:217], v[76:79]
	v_mfma_f32_16x16x32_bf16 v[72:75], v[136:139], v[214:217], v[72:75]
	v_mfma_f32_16x16x32_bf16 v[132:135], v[116:119], v[164:167], v[132:135]
	v_mfma_f32_16x16x32_bf16 v[128:131], v[140:143], v[164:167], v[128:131]
	v_mfma_f32_16x16x32_bf16 v[108:111], v[116:119], v[172:175], v[108:111]
	v_mfma_f32_16x16x32_bf16 v[104:107], v[140:143], v[172:175], v[104:107]
	v_mfma_f32_16x16x32_bf16 v[92:95], v[116:119], v[210:213], v[92:95]
	v_mfma_f32_16x16x32_bf16 v[88:91], v[140:143], v[210:213], v[88:91]
	v_mfma_f32_16x16x32_bf16 v[76:79], v[116:119], v[218:221], v[76:79]
	v_mfma_f32_16x16x32_bf16 v[72:75], v[140:143], v[218:221], v[72:75]
	v_mfma_f32_16x16x32_bf16 v[124:127], v[144:147], v[160:163], v[124:127]
	v_mfma_f32_16x16x32_bf16 v[120:123], v[152:155], v[160:163], v[120:123]
	v_mfma_f32_16x16x32_bf16 v[100:103], v[144:147], v[168:171], v[100:103]
	v_mfma_f32_16x16x32_bf16 v[96:99], v[152:155], v[168:171], v[96:99]
	v_mfma_f32_16x16x32_bf16 v[84:87], v[144:147], v[206:209], v[84:87]
	v_mfma_f32_16x16x32_bf16 v[80:83], v[152:155], v[206:209], v[80:83]
	v_mfma_f32_16x16x32_bf16 v[68:71], v[144:147], v[214:217], v[68:71]
	v_mfma_f32_16x16x32_bf16 v[64:67], v[152:155], v[214:217], v[64:67]
	v_mfma_f32_16x16x32_bf16 v[124:127], v[148:151], v[164:167], v[124:127]
	v_mfma_f32_16x16x32_bf16 v[120:123], v[156:159], v[164:167], v[120:123]
	v_mfma_f32_16x16x32_bf16 v[100:103], v[148:151], v[172:175], v[100:103]
	v_mfma_f32_16x16x32_bf16 v[96:99], v[156:159], v[172:175], v[96:99]
	v_mfma_f32_16x16x32_bf16 v[84:87], v[148:151], v[210:213], v[84:87]
	v_mfma_f32_16x16x32_bf16 v[80:83], v[156:159], v[210:213], v[80:83]
	v_mfma_f32_16x16x32_bf16 v[68:71], v[148:151], v[218:221], v[68:71]
	v_mfma_f32_16x16x32_bf16 v[64:67], v[156:159], v[218:221], v[64:67]
	s_setprio 0
	s_add_i32 s20, s83, s40
	v_lshl_add_u64 v[200:201], v[200:201], 0, s[14:15]
	s_mov_b32 m0, s20
	ds_read_b128 v[160:163], v205 offset:49152
	ds_read_b128 v[164:167], v205 offset:50176
	ds_read_b128 v[168:171], v205 offset:51200
	ds_read_b128 v[172:175], v205 offset:52224
	ds_read_b128 v[206:209], v205 offset:53248
	ds_read_b128 v[210:213], v205 offset:54272
	ds_read_b128 v[214:217], v205 offset:55296
	ds_read_b128 v[218:221], v205 offset:56320
	global_load_lds_dwordx4 v[200:201], off
	s_add_i32 m0, s20, 0x2000
	s_add_u32 s20, s26, 0xb0080
	v_lshl_add_u64 v[200:201], v[222:223], 0, s[14:15]
	s_addc_u32 s21, s27, 0
	s_add_i32 s26, s85, s40
	global_load_lds_dwordx4 v[200:201], off
	v_lshl_add_u64 v[200:201], s[20:21], 0, v[180:181]
	s_mov_b32 m0, s26
	s_nop 0
	global_load_lds_dwordx4 v[200:201], off
	v_lshl_add_u64 v[200:201], s[20:21], 0, v[176:177]
	s_add_i32 m0, s26, 0x2000
	s_nop 0
	global_load_lds_dwordx4 v[200:201], off
	v_lshl_add_u64 v[200:201], v[224:225], 0, s[14:15]
	s_mov_b32 m0, s52
	s_nop 0
	global_load_lds_dwordx4 v[200:201], off
	v_lshl_add_u64 v[200:201], v[226:227], 0, s[14:15]
	s_mov_b32 m0, s53
	s_nop 0
	global_load_lds_dwordx4 v[200:201], off
	s_waitcnt vmcnt(8)
	s_waitcnt lgkmcnt(0)
	s_barrier
	s_setprio 2
	v_mfma_f32_16x16x32_bf16 v[60:63], v[112:115], v[160:163], v[60:63]
	v_mfma_f32_16x16x32_bf16 v[56:59], v[136:139], v[160:163], v[56:59]
	v_mfma_f32_16x16x32_bf16 v[44:47], v[112:115], v[168:171], v[44:47]
	v_mfma_f32_16x16x32_bf16 v[40:43], v[136:139], v[168:171], v[40:43]
	v_mfma_f32_16x16x32_bf16 v[28:31], v[112:115], v[206:209], v[28:31]
	v_mfma_f32_16x16x32_bf16 v[24:27], v[136:139], v[206:209], v[24:27]
	v_mfma_f32_16x16x32_bf16 v[12:15], v[112:115], v[214:217], v[12:15]
	v_mfma_f32_16x16x32_bf16 v[8:11], v[136:139], v[214:217], v[8:11]
	v_mfma_f32_16x16x32_bf16 v[60:63], v[116:119], v[164:167], v[60:63]
	v_mfma_f32_16x16x32_bf16 v[56:59], v[140:143], v[164:167], v[56:59]
	v_mfma_f32_16x16x32_bf16 v[44:47], v[116:119], v[172:175], v[44:47]
	v_mfma_f32_16x16x32_bf16 v[40:43], v[140:143], v[172:175], v[40:43]
	v_mfma_f32_16x16x32_bf16 v[28:31], v[116:119], v[210:213], v[28:31]
	v_mfma_f32_16x16x32_bf16 v[24:27], v[140:143], v[210:213], v[24:27]
	v_mfma_f32_16x16x32_bf16 v[12:15], v[116:119], v[218:221], v[12:15]
	v_mfma_f32_16x16x32_bf16 v[8:11], v[140:143], v[218:221], v[8:11]
	v_mfma_f32_16x16x32_bf16 v[52:55], v[144:147], v[160:163], v[52:55]
	v_mfma_f32_16x16x32_bf16 v[48:51], v[152:155], v[160:163], v[48:51]
	v_mfma_f32_16x16x32_bf16 v[36:39], v[144:147], v[168:171], v[36:39]
	v_mfma_f32_16x16x32_bf16 v[32:35], v[152:155], v[168:171], v[32:35]
	v_mfma_f32_16x16x32_bf16 v[20:23], v[144:147], v[206:209], v[20:23]
	v_mfma_f32_16x16x32_bf16 v[16:19], v[152:155], v[206:209], v[16:19]
	v_mfma_f32_16x16x32_bf16 v[4:7], v[144:147], v[214:217], v[4:7]
	v_mfma_f32_16x16x32_bf16 v[0:3], v[152:155], v[214:217], v[0:3]
	v_mfma_f32_16x16x32_bf16 v[52:55], v[148:151], v[164:167], v[52:55]
	v_mfma_f32_16x16x32_bf16 v[48:51], v[156:159], v[164:167], v[48:51]
	v_mfma_f32_16x16x32_bf16 v[36:39], v[148:151], v[172:175], v[36:39]
	v_mfma_f32_16x16x32_bf16 v[32:35], v[156:159], v[172:175], v[32:35]
	v_mfma_f32_16x16x32_bf16 v[20:23], v[148:151], v[210:213], v[20:23]
	v_mfma_f32_16x16x32_bf16 v[16:19], v[156:159], v[210:213], v[16:19]
	v_mfma_f32_16x16x32_bf16 v[4:7], v[148:151], v[218:221], v[4:7]
	v_mfma_f32_16x16x32_bf16 v[0:3], v[156:159], v[218:221], v[0:3]
	s_setprio 0
	s_add_i32 s82, s82, 2
	s_add_u32 s80, s80, 0x100
	s_addc_u32 s81, s81, 0
	s_cmp_gt_u32 s82, 41
	s_mov_b64 s[20:21], s[22:23]
	s_cbranch_scc0 .Lh1_6

.LBB0_839:
	s_lshl_b32 s20, s78, 8
	s_add_i32 s20, s20, s51
	s_lshl_b32 s21, s79, 8
	s_or_b32 s22, s21, s3
	s_ashr_i32 s21, s20, 31
	s_lshl_b64 s[20:21], s[20:21], 11
	s_add_u32 s26, s62, s20
	s_addc_u32 s27, s63, s21
	s_ashr_i32 s23, s22, 31
	s_lshl_b64 s[20:21], s[22:23], 1
	s_add_u32 s20, s26, s20
	s_addc_u32 s21, s27, s21
	v_lshl_add_u64 v[200:201], s[20:21], 0, v[184:185]
	v_mov_b32_e32 v195, v185
	v_lshl_add_u64 v[112:113], v[200:201], 0, v[194:195]
	v_mov_b32_e32 v197, v185
	v_lshl_add_u64 v[112:113], v[112:113], 0, v[196:197]
	v_add_co_u32_e32 v114, vcc, s50, v112
	v_mov_b32_e32 v199, v185
	s_nop 0
	v_addc_co_u32_e32 v115, vcc, 0, v113, vcc
	global_load_dwordx4 v[206:209], v[112:113], off
	global_load_dwordx4 v[210:213], v[114:115], off
	v_add_co_u32_e32 v114, vcc, s55, v112
	v_mov_b32_e32 v223, v185
	s_nop 0
	v_addc_co_u32_e32 v115, vcc, 0, v113, vcc
	v_add_co_u32_e32 v116, vcc, s67, v112
	v_lshl_add_u64 v[200:201], v[200:201], 0, v[198:199]
	s_nop 0
	v_addc_co_u32_e32 v117, vcc, 0, v113, vcc
	global_load_dwordx4 v[214:217], v[114:115], off
	global_load_dwordx4 v[218:221], v[116:117], off
	v_add_co_u32_e32 v114, vcc, s48, v112
	v_lshl_add_u64 v[200:201], v[200:201], 0, v[196:197]
	s_nop 0
	v_addc_co_u32_e32 v115, vcc, 0, v113, vcc
	v_add_co_u32_e32 v116, vcc, s49, v112
	s_waitcnt vmcnt(0)
	v_cndmask_b32_e64 v222, v206, v210, s[8:9]
	v_addc_co_u32_e32 v117, vcc, 0, v113, vcc
	global_load_dwordx4 v[172:175], v[114:115], off
	global_load_dwordx4 v[168:171], v[116:117], off
	v_add_co_u32_e32 v114, vcc, s54, v112
	v_cndmask_b32_e64 v199, v207, v211, s[8:9]
	s_nop 0
	v_addc_co_u32_e32 v115, vcc, 0, v113, vcc
	v_add_co_u32_e32 v116, vcc, s56, v112
	v_mov_b32_dpp v223, v222 row_ror:8 row_mask:0xf bank_mask:0xf
	s_nop 0
	v_addc_co_u32_e32 v117, vcc, 0, v113, vcc
	global_load_dwordx4 v[164:167], v[114:115], off
	global_load_dwordx4 v[160:163], v[116:117], off
	v_add_co_u32_e32 v114, vcc, s68, v112
	v_mov_b32_e32 v222, v185
	s_nop 0
	v_addc_co_u32_e32 v115, vcc, 0, v113, vcc
	v_add_co_u32_e32 v116, vcc, s69, v112
	v_cndmask_b32_e64 v197, v208, v212, s[8:9]
	s_nop 0
	v_addc_co_u32_e32 v117, vcc, 0, v113, vcc
	global_load_dwordx4 v[156:159], v[114:115], off
	global_load_dwordx4 v[152:155], v[116:117], off
	v_add_co_u32_e32 v114, vcc, s70, v112
	v_mov_b32_dpp v222, v199 row_ror:8 row_mask:0xf bank_mask:0xf
	s_nop 0
	v_addc_co_u32_e32 v115, vcc, 0, v113, vcc
	v_add_co_u32_e32 v116, vcc, s71, v112
	v_mov_b32_e32 v199, v185
	s_nop 0
	v_addc_co_u32_e32 v117, vcc, 0, v113, vcc
	global_load_dwordx4 v[148:151], v[114:115], off
	global_load_dwordx4 v[144:147], v[116:117], off
	v_add_co_u32_e32 v114, vcc, s72, v112
	v_cndmask_b32_e64 v195, v209, v213, s[8:9]
	s_nop 0
	v_addc_co_u32_e32 v115, vcc, 0, v113, vcc
	v_add_co_u32_e32 v116, vcc, s73, v112
	v_mov_b32_dpp v199, v197 row_ror:8 row_mask:0xf bank_mask:0xf
	s_nop 0
	v_addc_co_u32_e32 v117, vcc, 0, v113, vcc
	v_mov_b32_e32 v197, v185
	global_load_dwordx4 v[140:143], v[114:115], off
	global_load_dwordx4 v[136:139], v[116:117], off
	v_add_co_u32_e32 v114, vcc, s74, v112
	v_mov_b32_dpp v197, v195 row_ror:8 row_mask:0xf bank_mask:0xf
	s_nop 0
	v_addc_co_u32_e32 v115, vcc, 0, v113, vcc
	v_cndmask_b32_e64 v195, v197, v209, s[8:9]
	v_cndmask_b32_e64 v224, v199, v208, s[8:9]
	v_cndmask_b32_e64 v209, v222, v207, s[8:9]
	v_cndmask_b32_e64 v207, v223, v206, s[8:9]
	v_add_co_u32_e32 v112, vcc, s75, v112
	v_cndmask_b32_e64 v197, v213, v197, s[8:9]
	v_cndmask_b32_e64 v199, v212, v199, s[8:9]
	v_cndmask_b32_e64 v222, v211, v222, s[8:9]
	v_cndmask_b32_e64 v223, v210, v223, s[8:9]
	v_lshlrev_b32_e32 v206, 16, v207
	v_and_b32_e32 v207, 0xffff0000, v207
	v_lshlrev_b32_e32 v208, 16, v209
	v_and_b32_e32 v209, 0xffff0000, v209
	v_lshlrev_b32_e32 v210, 16, v224
	v_and_b32_e32 v211, 0xffff0000, v224
	v_lshlrev_b32_e32 v212, 16, v195
	v_and_b32_e32 v213, 0xffff0000, v195
	v_addc_co_u32_e32 v113, vcc, 0, v113, vcc
	v_pk_fma_f32 v[134:135], v[134:135], 0.5, v[208:209] op_sel_hi:[1,0,1]
	v_pk_fma_f32 v[132:133], v[132:133], 0.5, v[206:207] op_sel_hi:[1,0,1]
	v_pk_fma_f32 v[130:131], v[130:131], 0.5, v[212:213] op_sel_hi:[1,0,1]
	v_pk_fma_f32 v[128:129], v[128:129], 0.5, v[210:211] op_sel_hi:[1,0,1]
	global_load_dwordx4 v[116:119], v[114:115], off
	s_nop 0
	global_load_dwordx4 v[112:115], v[112:113], off
	v_cvt_pk_bf16_f32 v195, v132, v133
	v_cvt_pk_bf16_f32 v206, v134, v135
	v_cvt_pk_bf16_f32 v207, v128, v129
	v_cvt_pk_bf16_f32 v208, v130, v131
	v_lshlrev_b32_e32 v128, 16, v223
	v_and_b32_e32 v129, 0xffff0000, v223
	v_lshlrev_b32_e32 v130, 16, v222
	v_and_b32_e32 v131, 0xffff0000, v222
	v_lshlrev_b32_e32 v132, 16, v199
	v_and_b32_e32 v133, 0xffff0000, v199
	v_lshlrev_b32_e32 v134, 16, v197
	v_and_b32_e32 v135, 0xffff0000, v197
	v_pk_fma_f32 v[126:127], v[126:127], 0.5, v[130:131] op_sel_hi:[1,0,1]
	v_pk_fma_f32 v[124:125], v[124:125], 0.5, v[128:129] op_sel_hi:[1,0,1]
	v_pk_fma_f32 v[122:123], v[122:123], 0.5, v[134:135] op_sel_hi:[1,0,1]
	v_pk_fma_f32 v[120:121], v[120:121], 0.5, v[132:133] op_sel_hi:[1,0,1]
	v_cvt_pk_bf16_f32 v124, v124, v125
	v_cvt_pk_bf16_f32 v125, v126, v127
	v_mov_b32_e32 v128, v185
	v_cvt_pk_bf16_f32 v126, v120, v121
	v_cvt_pk_bf16_f32 v127, v122, v123
	v_cndmask_b32_e64 v122, v206, v125, s[8:9]
	v_cndmask_b32_e64 v120, v208, v127, s[8:9]
	v_cndmask_b32_e64 v121, v207, v126, s[8:9]
	v_cndmask_b32_e64 v123, v195, v124, s[8:9]
	v_mov_b32_e32 v129, v185
	v_mov_b32_e32 v130, v185
	v_mov_b32_e32 v131, v185
	v_mov_b32_dpp v128, v123 row_ror:8 row_mask:0xf bank_mask:0xf
	v_mov_b32_dpp v129, v122 row_ror:8 row_mask:0xf bank_mask:0xf
	v_mov_b32_dpp v130, v121 row_ror:8 row_mask:0xf bank_mask:0xf
	v_mov_b32_dpp v131, v120 row_ror:8 row_mask:0xf bank_mask:0xf
	v_cndmask_b32_e64 v120, v128, v195, s[8:9]
	v_cndmask_b32_e64 v121, v129, v206, s[8:9]
	v_cndmask_b32_e64 v122, v130, v207, s[8:9]
	v_cndmask_b32_e64 v123, v131, v208, s[8:9]
	global_store_dwordx4 v[200:201], v[120:123], off
	s_nop 1
	v_cndmask_b32_e64 v120, v124, v128, s[8:9]
	v_add_co_u32_e32 v124, vcc, s50, v200
	v_cndmask_b32_e64 v121, v125, v129, s[8:9]
	v_cndmask_b32_e64 v122, v126, v130, s[8:9]
	v_cndmask_b32_e64 v123, v127, v131, s[8:9]
	v_addc_co_u32_e32 v125, vcc, 0, v201, vcc
	global_store_dwordx4 v[124:125], v[120:123], off
	v_mov_b32_e32 v124, v185
	s_nop 0
	v_cndmask_b32_e64 v123, v214, v218, s[8:9]
	v_cndmask_b32_e64 v122, v215, v219, s[8:9]
	v_cndmask_b32_e64 v121, v216, v220, s[8:9]
	v_mov_b32_dpp v124, v123 row_ror:8 row_mask:0xf bank_mask:0xf
	v_mov_b32_e32 v123, v185
	v_cndmask_b32_e64 v120, v217, v221, s[8:9]
	v_cndmask_b32_e64 v128, v124, v214, s[8:9]
	v_mov_b32_dpp v123, v122 row_ror:8 row_mask:0xf bank_mask:0xf
	v_mov_b32_e32 v122, v185
	v_cndmask_b32_e64 v126, v123, v215, s[8:9]
	v_cndmask_b32_e64 v131, v219, v123, s[8:9]
	v_mov_b32_dpp v122, v121 row_ror:8 row_mask:0xf bank_mask:0xf
	v_mov_b32_e32 v121, v185
	v_cndmask_b32_e64 v125, v122, v216, s[8:9]
	v_cndmask_b32_e64 v130, v220, v122, s[8:9]
	v_mov_b32_dpp v121, v120 row_ror:8 row_mask:0xf bank_mask:0xf
	v_cndmask_b32_e64 v127, v121, v217, s[8:9]
	v_cndmask_b32_e64 v129, v221, v121, s[8:9]
	v_lshlrev_b32_e32 v120, 16, v128
	v_and_b32_e32 v121, 0xffff0000, v128
	v_lshlrev_b32_e32 v122, 16, v126
	v_and_b32_e32 v123, 0xffff0000, v126
	v_lshlrev_b32_e32 v126, 16, v127
	v_and_b32_e32 v127, 0xffff0000, v127
	v_cndmask_b32_e64 v132, v218, v124, s[8:9]
	v_lshlrev_b32_e32 v124, 16, v125
	v_and_b32_e32 v125, 0xffff0000, v125
	v_pk_fma_f32 v[110:111], v[110:111], 0.5, v[122:123] op_sel_hi:[1,0,1]
	v_pk_fma_f32 v[108:109], v[108:109], 0.5, v[120:121] op_sel_hi:[1,0,1]
	v_pk_fma_f32 v[106:107], v[106:107], 0.5, v[126:127] op_sel_hi:[1,0,1]
	v_pk_fma_f32 v[104:105], v[104:105], 0.5, v[124:125] op_sel_hi:[1,0,1]
	v_cvt_pk_bf16_f32 v120, v108, v109
	v_cvt_pk_bf16_f32 v121, v110, v111
	v_lshlrev_b32_e32 v108, 16, v130
	v_cvt_pk_bf16_f32 v122, v104, v105
	v_cvt_pk_bf16_f32 v123, v106, v107
	v_lshlrev_b32_e32 v106, 16, v131
	v_and_b32_e32 v107, 0xffff0000, v131
	v_and_b32_e32 v109, 0xffff0000, v130
	v_lshlrev_b32_e32 v110, 16, v129
	v_and_b32_e32 v111, 0xffff0000, v129
	v_lshlrev_b32_e32 v104, 16, v132
	v_and_b32_e32 v105, 0xffff0000, v132
	v_pk_fma_f32 v[102:103], v[102:103], 0.5, v[106:107] op_sel_hi:[1,0,1]
	v_pk_fma_f32 v[98:99], v[98:99], 0.5, v[110:111] op_sel_hi:[1,0,1]
	v_pk_fma_f32 v[96:97], v[96:97], 0.5, v[108:109] op_sel_hi:[1,0,1]
	v_pk_fma_f32 v[100:101], v[100:101], 0.5, v[104:105] op_sel_hi:[1,0,1]
	v_mov_b32_e32 v106, v185
	v_cvt_pk_bf16_f32 v104, v100, v101
	v_cvt_pk_bf16_f32 v102, v102, v103
	v_cvt_pk_bf16_f32 v103, v96, v97
	v_cvt_pk_bf16_f32 v105, v98, v99
	v_mov_b32_e32 v107, v185
	v_cndmask_b32_e64 v96, v123, v105, s[8:9]
	v_cndmask_b32_e64 v97, v122, v103, s[8:9]
	v_cndmask_b32_e64 v98, v121, v102, s[8:9]
	v_cndmask_b32_e64 v99, v120, v104, s[8:9]
	v_mov_b32_e32 v108, v185
	v_mov_b32_e32 v109, v185
	v_mov_b32_dpp v106, v99 row_ror:8 row_mask:0xf bank_mask:0xf
	v_mov_b32_dpp v107, v98 row_ror:8 row_mask:0xf bank_mask:0xf
	v_mov_b32_dpp v108, v97 row_ror:8 row_mask:0xf bank_mask:0xf
	v_mov_b32_dpp v109, v96 row_ror:8 row_mask:0xf bank_mask:0xf
	v_add_co_u32_e32 v100, vcc, s55, v200
	v_cndmask_b32_e64 v96, v106, v120, s[8:9]
	v_cndmask_b32_e64 v97, v107, v121, s[8:9]
	v_cndmask_b32_e64 v98, v108, v122, s[8:9]
	v_cndmask_b32_e64 v99, v109, v123, s[8:9]
	v_addc_co_u32_e32 v101, vcc, 0, v201, vcc
	global_store_dwordx4 v[100:101], v[96:99], off
	v_add_co_u32_e32 v100, vcc, s67, v200
	s_nop 0
	v_cndmask_b32_e64 v96, v104, v106, s[8:9]
	v_cndmask_b32_e64 v97, v102, v107, s[8:9]
	v_cndmask_b32_e64 v98, v103, v108, s[8:9]
	v_cndmask_b32_e64 v99, v105, v109, s[8:9]
	v_addc_co_u32_e32 v101, vcc, 0, v201, vcc
	global_store_dwordx4 v[100:101], v[96:99], off
	v_mov_b32_e32 v100, v185
	s_waitcnt vmcnt(14)
	v_cndmask_b32_e64 v99, v172, v168, s[8:9]
	v_cndmask_b32_e64 v98, v173, v169, s[8:9]
	v_cndmask_b32_e64 v97, v174, v170, s[8:9]
	v_mov_b32_dpp v100, v99 row_ror:8 row_mask:0xf bank_mask:0xf
	v_mov_b32_e32 v99, v185
	v_cndmask_b32_e64 v96, v175, v171, s[8:9]
	v_cndmask_b32_e64 v104, v100, v172, s[8:9]
	v_mov_b32_dpp v99, v98 row_ror:8 row_mask:0xf bank_mask:0xf
	v_mov_b32_e32 v98, v185
	v_cndmask_b32_e64 v102, v99, v173, s[8:9]
	v_cndmask_b32_e64 v107, v169, v99, s[8:9]
	v_mov_b32_dpp v98, v97 row_ror:8 row_mask:0xf bank_mask:0xf
	v_mov_b32_e32 v97, v185
	v_cndmask_b32_e64 v101, v98, v174, s[8:9]
	v_cndmask_b32_e64 v106, v170, v98, s[8:9]
	v_mov_b32_dpp v97, v96 row_ror:8 row_mask:0xf bank_mask:0xf
	v_cndmask_b32_e64 v103, v97, v175, s[8:9]
	v_cndmask_b32_e64 v105, v171, v97, s[8:9]
	v_lshlrev_b32_e32 v96, 16, v104
	v_and_b32_e32 v97, 0xffff0000, v104
	v_lshlrev_b32_e32 v98, 16, v102
	v_and_b32_e32 v99, 0xffff0000, v102
	v_lshlrev_b32_e32 v102, 16, v103
	v_and_b32_e32 v103, 0xffff0000, v103
	v_cndmask_b32_e64 v108, v168, v100, s[8:9]
	v_lshlrev_b32_e32 v100, 16, v101
	v_and_b32_e32 v101, 0xffff0000, v101
	v_pk_fma_f32 v[94:95], v[94:95], 0.5, v[98:99] op_sel_hi:[1,0,1]
	v_pk_fma_f32 v[92:93], v[92:93], 0.5, v[96:97] op_sel_hi:[1,0,1]
	v_pk_fma_f32 v[90:91], v[90:91], 0.5, v[102:103] op_sel_hi:[1,0,1]
	v_pk_fma_f32 v[88:89], v[88:89], 0.5, v[100:101] op_sel_hi:[1,0,1]
	v_cvt_pk_bf16_f32 v96, v92, v93
	v_cvt_pk_bf16_f32 v97, v94, v95
	v_lshlrev_b32_e32 v92, 16, v106
	v_cvt_pk_bf16_f32 v98, v88, v89
	v_cvt_pk_bf16_f32 v99, v90, v91
	v_lshlrev_b32_e32 v90, 16, v107
	v_and_b32_e32 v91, 0xffff0000, v107
	v_and_b32_e32 v93, 0xffff0000, v106
	v_lshlrev_b32_e32 v94, 16, v105
	v_and_b32_e32 v95, 0xffff0000, v105
	v_lshlrev_b32_e32 v88, 16, v108
	v_and_b32_e32 v89, 0xffff0000, v108
	v_pk_fma_f32 v[86:87], v[86:87], 0.5, v[90:91] op_sel_hi:[1,0,1]
	v_pk_fma_f32 v[82:83], v[82:83], 0.5, v[94:95] op_sel_hi:[1,0,1]
	v_pk_fma_f32 v[80:81], v[80:81], 0.5, v[92:93] op_sel_hi:[1,0,1]
	v_pk_fma_f32 v[84:85], v[84:85], 0.5, v[88:89] op_sel_hi:[1,0,1]
	v_mov_b32_e32 v90, v185
	v_cvt_pk_bf16_f32 v88, v84, v85
	v_cvt_pk_bf16_f32 v86, v86, v87
	v_cvt_pk_bf16_f32 v87, v80, v81
	v_cvt_pk_bf16_f32 v89, v82, v83
	v_mov_b32_e32 v91, v185
	v_cndmask_b32_e64 v80, v99, v89, s[8:9]
	v_cndmask_b32_e64 v81, v98, v87, s[8:9]
	v_cndmask_b32_e64 v82, v97, v86, s[8:9]
	v_cndmask_b32_e64 v83, v96, v88, s[8:9]
	v_mov_b32_e32 v92, v185
	v_mov_b32_e32 v93, v185
	v_mov_b32_dpp v90, v83 row_ror:8 row_mask:0xf bank_mask:0xf
	v_mov_b32_dpp v91, v82 row_ror:8 row_mask:0xf bank_mask:0xf
	v_mov_b32_dpp v92, v81 row_ror:8 row_mask:0xf bank_mask:0xf
	v_mov_b32_dpp v93, v80 row_ror:8 row_mask:0xf bank_mask:0xf
	v_add_co_u32_e32 v84, vcc, s48, v200
	v_cndmask_b32_e64 v80, v90, v96, s[8:9]
	v_cndmask_b32_e64 v81, v91, v97, s[8:9]
	v_cndmask_b32_e64 v82, v92, v98, s[8:9]
	v_cndmask_b32_e64 v83, v93, v99, s[8:9]
	v_addc_co_u32_e32 v85, vcc, 0, v201, vcc
	global_store_dwordx4 v[84:85], v[80:83], off
	v_add_co_u32_e32 v84, vcc, s49, v200
	s_nop 0
	v_cndmask_b32_e64 v80, v88, v90, s[8:9]
	v_cndmask_b32_e64 v81, v86, v91, s[8:9]
	v_cndmask_b32_e64 v82, v87, v92, s[8:9]
	v_cndmask_b32_e64 v83, v89, v93, s[8:9]
	v_addc_co_u32_e32 v85, vcc, 0, v201, vcc
	global_store_dwordx4 v[84:85], v[80:83], off
	v_mov_b32_e32 v84, v185
	s_waitcnt vmcnt(14)
	v_cndmask_b32_e64 v83, v164, v160, s[8:9]
	v_cndmask_b32_e64 v82, v165, v161, s[8:9]
	v_cndmask_b32_e64 v81, v166, v162, s[8:9]
	v_mov_b32_dpp v84, v83 row_ror:8 row_mask:0xf bank_mask:0xf
	v_mov_b32_e32 v83, v185
	v_cndmask_b32_e64 v80, v167, v163, s[8:9]
	v_cndmask_b32_e64 v88, v84, v164, s[8:9]
	v_mov_b32_dpp v83, v82 row_ror:8 row_mask:0xf bank_mask:0xf
	v_mov_b32_e32 v82, v185
	v_cndmask_b32_e64 v86, v83, v165, s[8:9]
	v_cndmask_b32_e64 v91, v161, v83, s[8:9]
	v_mov_b32_dpp v82, v81 row_ror:8 row_mask:0xf bank_mask:0xf
	v_mov_b32_e32 v81, v185
	v_cndmask_b32_e64 v85, v82, v166, s[8:9]
	v_cndmask_b32_e64 v90, v162, v82, s[8:9]
	v_mov_b32_dpp v81, v80 row_ror:8 row_mask:0xf bank_mask:0xf
	v_cndmask_b32_e64 v87, v81, v167, s[8:9]
	v_cndmask_b32_e64 v89, v163, v81, s[8:9]
	v_lshlrev_b32_e32 v80, 16, v88
	v_and_b32_e32 v81, 0xffff0000, v88
	v_lshlrev_b32_e32 v82, 16, v86
	v_and_b32_e32 v83, 0xffff0000, v86
	v_lshlrev_b32_e32 v86, 16, v87
	v_and_b32_e32 v87, 0xffff0000, v87
	v_cndmask_b32_e64 v92, v160, v84, s[8:9]
	v_lshlrev_b32_e32 v84, 16, v85
	v_and_b32_e32 v85, 0xffff0000, v85
	v_pk_fma_f32 v[78:79], v[78:79], 0.5, v[82:83] op_sel_hi:[1,0,1]
	v_pk_fma_f32 v[76:77], v[76:77], 0.5, v[80:81] op_sel_hi:[1,0,1]
	v_pk_fma_f32 v[74:75], v[74:75], 0.5, v[86:87] op_sel_hi:[1,0,1]
	v_pk_fma_f32 v[72:73], v[72:73], 0.5, v[84:85] op_sel_hi:[1,0,1]
	v_cvt_pk_bf16_f32 v80, v76, v77
	v_cvt_pk_bf16_f32 v81, v78, v79
	v_lshlrev_b32_e32 v76, 16, v90
	v_cvt_pk_bf16_f32 v82, v72, v73
	v_cvt_pk_bf16_f32 v83, v74, v75
	v_lshlrev_b32_e32 v74, 16, v91
	v_and_b32_e32 v75, 0xffff0000, v91
	v_and_b32_e32 v77, 0xffff0000, v90
	v_lshlrev_b32_e32 v78, 16, v89
	v_and_b32_e32 v79, 0xffff0000, v89
	v_lshlrev_b32_e32 v72, 16, v92
	v_and_b32_e32 v73, 0xffff0000, v92
	v_pk_fma_f32 v[70:71], v[70:71], 0.5, v[74:75] op_sel_hi:[1,0,1]
	v_pk_fma_f32 v[66:67], v[66:67], 0.5, v[78:79] op_sel_hi:[1,0,1]
	v_pk_fma_f32 v[64:65], v[64:65], 0.5, v[76:77] op_sel_hi:[1,0,1]
	v_pk_fma_f32 v[68:69], v[68:69], 0.5, v[72:73] op_sel_hi:[1,0,1]
	v_mov_b32_e32 v74, v185
	v_cvt_pk_bf16_f32 v72, v68, v69
	v_cvt_pk_bf16_f32 v70, v70, v71
	v_cvt_pk_bf16_f32 v71, v64, v65
	v_cvt_pk_bf16_f32 v73, v66, v67
	v_mov_b32_e32 v75, v185
	v_cndmask_b32_e64 v64, v83, v73, s[8:9]
	v_cndmask_b32_e64 v65, v82, v71, s[8:9]
	v_cndmask_b32_e64 v66, v81, v70, s[8:9]
	v_cndmask_b32_e64 v67, v80, v72, s[8:9]
	v_mov_b32_e32 v76, v185
	v_mov_b32_e32 v77, v185
	v_mov_b32_dpp v74, v67 row_ror:8 row_mask:0xf bank_mask:0xf
	v_mov_b32_dpp v75, v66 row_ror:8 row_mask:0xf bank_mask:0xf
	v_mov_b32_dpp v76, v65 row_ror:8 row_mask:0xf bank_mask:0xf
	v_mov_b32_dpp v77, v64 row_ror:8 row_mask:0xf bank_mask:0xf
	v_add_co_u32_e32 v68, vcc, s54, v200
	v_cndmask_b32_e64 v64, v74, v80, s[8:9]
	v_cndmask_b32_e64 v65, v75, v81, s[8:9]
	v_cndmask_b32_e64 v66, v76, v82, s[8:9]
	v_cndmask_b32_e64 v67, v77, v83, s[8:9]
	v_addc_co_u32_e32 v69, vcc, 0, v201, vcc
	global_store_dwordx4 v[68:69], v[64:67], off
	v_add_co_u32_e32 v68, vcc, s56, v200
	s_nop 0
	v_cndmask_b32_e64 v64, v72, v74, s[8:9]
	v_cndmask_b32_e64 v65, v70, v75, s[8:9]
	v_cndmask_b32_e64 v66, v71, v76, s[8:9]
	v_cndmask_b32_e64 v67, v73, v77, s[8:9]
	v_addc_co_u32_e32 v69, vcc, 0, v201, vcc
	global_store_dwordx4 v[68:69], v[64:67], off
	v_mov_b32_e32 v68, v185
	s_waitcnt vmcnt(14)
	v_cndmask_b32_e64 v67, v156, v152, s[8:9]
	v_cndmask_b32_e64 v66, v157, v153, s[8:9]
	v_cndmask_b32_e64 v65, v158, v154, s[8:9]
	v_mov_b32_dpp v68, v67 row_ror:8 row_mask:0xf bank_mask:0xf
	v_mov_b32_e32 v67, v185
	v_cndmask_b32_e64 v64, v159, v155, s[8:9]
	v_cndmask_b32_e64 v72, v68, v156, s[8:9]
	v_mov_b32_dpp v67, v66 row_ror:8 row_mask:0xf bank_mask:0xf
	v_mov_b32_e32 v66, v185
	v_cndmask_b32_e64 v70, v67, v157, s[8:9]
	v_cndmask_b32_e64 v75, v153, v67, s[8:9]
	v_mov_b32_dpp v66, v65 row_ror:8 row_mask:0xf bank_mask:0xf
	v_mov_b32_e32 v65, v185
	v_cndmask_b32_e64 v69, v66, v158, s[8:9]
	v_cndmask_b32_e64 v74, v154, v66, s[8:9]
	v_mov_b32_dpp v65, v64 row_ror:8 row_mask:0xf bank_mask:0xf
	v_cndmask_b32_e64 v71, v65, v159, s[8:9]
	v_cndmask_b32_e64 v73, v155, v65, s[8:9]
	v_lshlrev_b32_e32 v64, 16, v72
	v_and_b32_e32 v65, 0xffff0000, v72
	v_lshlrev_b32_e32 v66, 16, v70
	v_and_b32_e32 v67, 0xffff0000, v70
	v_lshlrev_b32_e32 v70, 16, v71
	v_and_b32_e32 v71, 0xffff0000, v71
	v_cndmask_b32_e64 v76, v152, v68, s[8:9]
	v_lshlrev_b32_e32 v68, 16, v69
	v_and_b32_e32 v69, 0xffff0000, v69
	v_pk_fma_f32 v[62:63], v[62:63], 0.5, v[66:67] op_sel_hi:[1,0,1]
	v_pk_fma_f32 v[60:61], v[60:61], 0.5, v[64:65] op_sel_hi:[1,0,1]
	v_pk_fma_f32 v[58:59], v[58:59], 0.5, v[70:71] op_sel_hi:[1,0,1]
	v_pk_fma_f32 v[56:57], v[56:57], 0.5, v[68:69] op_sel_hi:[1,0,1]
	v_cvt_pk_bf16_f32 v64, v60, v61
	v_cvt_pk_bf16_f32 v65, v62, v63
	v_lshlrev_b32_e32 v60, 16, v74
	v_cvt_pk_bf16_f32 v66, v56, v57
	v_cvt_pk_bf16_f32 v67, v58, v59
	v_lshlrev_b32_e32 v58, 16, v75
	v_and_b32_e32 v59, 0xffff0000, v75
	v_and_b32_e32 v61, 0xffff0000, v74
	v_lshlrev_b32_e32 v62, 16, v73
	v_and_b32_e32 v63, 0xffff0000, v73
	v_lshlrev_b32_e32 v56, 16, v76
	v_and_b32_e32 v57, 0xffff0000, v76
	v_pk_fma_f32 v[54:55], v[54:55], 0.5, v[58:59] op_sel_hi:[1,0,1]
	v_pk_fma_f32 v[50:51], v[50:51], 0.5, v[62:63] op_sel_hi:[1,0,1]
	v_pk_fma_f32 v[48:49], v[48:49], 0.5, v[60:61] op_sel_hi:[1,0,1]
	v_pk_fma_f32 v[52:53], v[52:53], 0.5, v[56:57] op_sel_hi:[1,0,1]
	v_mov_b32_e32 v58, v185
	v_cvt_pk_bf16_f32 v56, v52, v53
	v_cvt_pk_bf16_f32 v54, v54, v55
	v_cvt_pk_bf16_f32 v55, v48, v49
	v_cvt_pk_bf16_f32 v57, v50, v51
	v_mov_b32_e32 v59, v185
	v_cndmask_b32_e64 v48, v67, v57, s[8:9]
	v_cndmask_b32_e64 v49, v66, v55, s[8:9]
	v_cndmask_b32_e64 v50, v65, v54, s[8:9]
	v_cndmask_b32_e64 v51, v64, v56, s[8:9]
	v_mov_b32_e32 v60, v185
	v_mov_b32_e32 v61, v185
	v_mov_b32_dpp v58, v51 row_ror:8 row_mask:0xf bank_mask:0xf
	v_mov_b32_dpp v59, v50 row_ror:8 row_mask:0xf bank_mask:0xf
	v_mov_b32_dpp v60, v49 row_ror:8 row_mask:0xf bank_mask:0xf
	v_mov_b32_dpp v61, v48 row_ror:8 row_mask:0xf bank_mask:0xf
	v_add_co_u32_e32 v52, vcc, s68, v200
	v_cndmask_b32_e64 v48, v58, v64, s[8:9]
	v_cndmask_b32_e64 v49, v59, v65, s[8:9]
	v_cndmask_b32_e64 v50, v60, v66, s[8:9]
	v_cndmask_b32_e64 v51, v61, v67, s[8:9]
	v_addc_co_u32_e32 v53, vcc, 0, v201, vcc
	global_store_dwordx4 v[52:53], v[48:51], off
	v_add_co_u32_e32 v52, vcc, s69, v200
	s_nop 0
	v_cndmask_b32_e64 v48, v56, v58, s[8:9]
	v_cndmask_b32_e64 v49, v54, v59, s[8:9]
	v_cndmask_b32_e64 v50, v55, v60, s[8:9]
	v_cndmask_b32_e64 v51, v57, v61, s[8:9]
	v_addc_co_u32_e32 v53, vcc, 0, v201, vcc
	global_store_dwordx4 v[52:53], v[48:51], off
	v_mov_b32_e32 v52, v185
	s_waitcnt vmcnt(14)
	v_cndmask_b32_e64 v51, v148, v144, s[8:9]
	v_cndmask_b32_e64 v50, v149, v145, s[8:9]
	v_cndmask_b32_e64 v49, v150, v146, s[8:9]
	v_mov_b32_dpp v52, v51 row_ror:8 row_mask:0xf bank_mask:0xf
	v_mov_b32_e32 v51, v185
	v_cndmask_b32_e64 v48, v151, v147, s[8:9]
	v_cndmask_b32_e64 v56, v52, v148, s[8:9]
	v_mov_b32_dpp v51, v50 row_ror:8 row_mask:0xf bank_mask:0xf
	v_mov_b32_e32 v50, v185
	v_cndmask_b32_e64 v54, v51, v149, s[8:9]
	v_cndmask_b32_e64 v59, v145, v51, s[8:9]
	v_mov_b32_dpp v50, v49 row_ror:8 row_mask:0xf bank_mask:0xf
	v_mov_b32_e32 v49, v185
	v_cndmask_b32_e64 v53, v50, v150, s[8:9]
	v_cndmask_b32_e64 v58, v146, v50, s[8:9]
	v_mov_b32_dpp v49, v48 row_ror:8 row_mask:0xf bank_mask:0xf
	v_cndmask_b32_e64 v55, v49, v151, s[8:9]
	v_cndmask_b32_e64 v57, v147, v49, s[8:9]
	v_lshlrev_b32_e32 v48, 16, v56
	v_and_b32_e32 v49, 0xffff0000, v56
	v_lshlrev_b32_e32 v50, 16, v54
	v_and_b32_e32 v51, 0xffff0000, v54
	v_lshlrev_b32_e32 v54, 16, v55
	v_and_b32_e32 v55, 0xffff0000, v55
	v_cndmask_b32_e64 v60, v144, v52, s[8:9]
	v_lshlrev_b32_e32 v52, 16, v53
	v_and_b32_e32 v53, 0xffff0000, v53
	v_pk_fma_f32 v[46:47], v[46:47], 0.5, v[50:51] op_sel_hi:[1,0,1]
	v_pk_fma_f32 v[44:45], v[44:45], 0.5, v[48:49] op_sel_hi:[1,0,1]
	v_pk_fma_f32 v[42:43], v[42:43], 0.5, v[54:55] op_sel_hi:[1,0,1]
	v_pk_fma_f32 v[40:41], v[40:41], 0.5, v[52:53] op_sel_hi:[1,0,1]
	v_cvt_pk_bf16_f32 v48, v44, v45
	v_cvt_pk_bf16_f32 v49, v46, v47
	v_lshlrev_b32_e32 v44, 16, v58
	v_cvt_pk_bf16_f32 v50, v40, v41
	v_cvt_pk_bf16_f32 v51, v42, v43
	v_lshlrev_b32_e32 v42, 16, v59
	v_and_b32_e32 v43, 0xffff0000, v59
	v_and_b32_e32 v45, 0xffff0000, v58
	v_lshlrev_b32_e32 v46, 16, v57
	v_and_b32_e32 v47, 0xffff0000, v57
	v_lshlrev_b32_e32 v40, 16, v60
	v_and_b32_e32 v41, 0xffff0000, v60
	v_pk_fma_f32 v[38:39], v[38:39], 0.5, v[42:43] op_sel_hi:[1,0,1]
	v_pk_fma_f32 v[34:35], v[34:35], 0.5, v[46:47] op_sel_hi:[1,0,1]
	v_pk_fma_f32 v[32:33], v[32:33], 0.5, v[44:45] op_sel_hi:[1,0,1]
	v_pk_fma_f32 v[36:37], v[36:37], 0.5, v[40:41] op_sel_hi:[1,0,1]
	v_mov_b32_e32 v42, v185
	v_cvt_pk_bf16_f32 v40, v36, v37
	v_cvt_pk_bf16_f32 v38, v38, v39
	v_cvt_pk_bf16_f32 v39, v32, v33
	v_cvt_pk_bf16_f32 v41, v34, v35
	v_mov_b32_e32 v43, v185
	v_cndmask_b32_e64 v32, v51, v41, s[8:9]
	v_cndmask_b32_e64 v33, v50, v39, s[8:9]
	v_cndmask_b32_e64 v34, v49, v38, s[8:9]
	v_cndmask_b32_e64 v35, v48, v40, s[8:9]
	v_mov_b32_e32 v44, v185
	v_mov_b32_e32 v45, v185
	v_mov_b32_dpp v42, v35 row_ror:8 row_mask:0xf bank_mask:0xf
	v_mov_b32_dpp v43, v34 row_ror:8 row_mask:0xf bank_mask:0xf
	v_mov_b32_dpp v44, v33 row_ror:8 row_mask:0xf bank_mask:0xf
	v_mov_b32_dpp v45, v32 row_ror:8 row_mask:0xf bank_mask:0xf
	v_add_co_u32_e32 v36, vcc, s70, v200
	v_cndmask_b32_e64 v32, v42, v48, s[8:9]
	v_cndmask_b32_e64 v33, v43, v49, s[8:9]
	v_cndmask_b32_e64 v34, v44, v50, s[8:9]
	v_cndmask_b32_e64 v35, v45, v51, s[8:9]
	v_addc_co_u32_e32 v37, vcc, 0, v201, vcc
	global_store_dwordx4 v[36:37], v[32:35], off
	v_add_co_u32_e32 v36, vcc, s71, v200
	s_nop 0
	v_cndmask_b32_e64 v32, v40, v42, s[8:9]
	v_cndmask_b32_e64 v33, v38, v43, s[8:9]
	v_cndmask_b32_e64 v34, v39, v44, s[8:9]
	v_cndmask_b32_e64 v35, v41, v45, s[8:9]
	v_addc_co_u32_e32 v37, vcc, 0, v201, vcc
	global_store_dwordx4 v[36:37], v[32:35], off
	v_mov_b32_e32 v36, v185
	s_waitcnt vmcnt(14)
	v_cndmask_b32_e64 v35, v140, v136, s[8:9]
	v_cndmask_b32_e64 v34, v141, v137, s[8:9]
	v_cndmask_b32_e64 v33, v142, v138, s[8:9]
	v_mov_b32_dpp v36, v35 row_ror:8 row_mask:0xf bank_mask:0xf
	v_mov_b32_e32 v35, v185
	v_cndmask_b32_e64 v32, v143, v139, s[8:9]
	v_cndmask_b32_e64 v40, v36, v140, s[8:9]
	v_mov_b32_dpp v35, v34 row_ror:8 row_mask:0xf bank_mask:0xf
	v_mov_b32_e32 v34, v185
	v_cndmask_b32_e64 v38, v35, v141, s[8:9]
	v_cndmask_b32_e64 v43, v137, v35, s[8:9]
	v_mov_b32_dpp v34, v33 row_ror:8 row_mask:0xf bank_mask:0xf
	v_mov_b32_e32 v33, v185
	v_cndmask_b32_e64 v37, v34, v142, s[8:9]
	v_cndmask_b32_e64 v42, v138, v34, s[8:9]
	v_mov_b32_dpp v33, v32 row_ror:8 row_mask:0xf bank_mask:0xf
	v_cndmask_b32_e64 v39, v33, v143, s[8:9]
	v_cndmask_b32_e64 v41, v139, v33, s[8:9]
	v_lshlrev_b32_e32 v32, 16, v40
	v_and_b32_e32 v33, 0xffff0000, v40
	v_lshlrev_b32_e32 v34, 16, v38
	v_and_b32_e32 v35, 0xffff0000, v38
	v_lshlrev_b32_e32 v38, 16, v39
	v_and_b32_e32 v39, 0xffff0000, v39
	v_cndmask_b32_e64 v44, v136, v36, s[8:9]
	v_lshlrev_b32_e32 v36, 16, v37
	v_and_b32_e32 v37, 0xffff0000, v37
	v_pk_fma_f32 v[30:31], v[30:31], 0.5, v[34:35] op_sel_hi:[1,0,1]
	v_pk_fma_f32 v[28:29], v[28:29], 0.5, v[32:33] op_sel_hi:[1,0,1]
	v_pk_fma_f32 v[26:27], v[26:27], 0.5, v[38:39] op_sel_hi:[1,0,1]
	v_pk_fma_f32 v[24:25], v[24:25], 0.5, v[36:37] op_sel_hi:[1,0,1]
	v_cvt_pk_bf16_f32 v32, v28, v29
	v_cvt_pk_bf16_f32 v33, v30, v31
	v_lshlrev_b32_e32 v28, 16, v42
	v_cvt_pk_bf16_f32 v34, v24, v25
	v_cvt_pk_bf16_f32 v35, v26, v27
	v_lshlrev_b32_e32 v26, 16, v43
	v_and_b32_e32 v27, 0xffff0000, v43
	v_and_b32_e32 v29, 0xffff0000, v42
	v_lshlrev_b32_e32 v30, 16, v41
	v_and_b32_e32 v31, 0xffff0000, v41
	v_lshlrev_b32_e32 v24, 16, v44
	v_and_b32_e32 v25, 0xffff0000, v44
	v_pk_fma_f32 v[22:23], v[22:23], 0.5, v[26:27] op_sel_hi:[1,0,1]
	v_pk_fma_f32 v[18:19], v[18:19], 0.5, v[30:31] op_sel_hi:[1,0,1]
	v_pk_fma_f32 v[16:17], v[16:17], 0.5, v[28:29] op_sel_hi:[1,0,1]
	v_pk_fma_f32 v[20:21], v[20:21], 0.5, v[24:25] op_sel_hi:[1,0,1]
	v_mov_b32_e32 v26, v185
	v_cvt_pk_bf16_f32 v24, v20, v21
	v_cvt_pk_bf16_f32 v22, v22, v23
	v_cvt_pk_bf16_f32 v23, v16, v17
	v_cvt_pk_bf16_f32 v25, v18, v19
	v_mov_b32_e32 v27, v185
	v_cndmask_b32_e64 v16, v35, v25, s[8:9]
	v_cndmask_b32_e64 v17, v34, v23, s[8:9]
	v_cndmask_b32_e64 v18, v33, v22, s[8:9]
	v_cndmask_b32_e64 v19, v32, v24, s[8:9]
	v_mov_b32_e32 v28, v185
	v_mov_b32_e32 v29, v185
	v_mov_b32_dpp v26, v19 row_ror:8 row_mask:0xf bank_mask:0xf
	v_mov_b32_dpp v27, v18 row_ror:8 row_mask:0xf bank_mask:0xf
	v_mov_b32_dpp v28, v17 row_ror:8 row_mask:0xf bank_mask:0xf
	v_mov_b32_dpp v29, v16 row_ror:8 row_mask:0xf bank_mask:0xf
	v_add_co_u32_e32 v20, vcc, s72, v200
	v_cndmask_b32_e64 v16, v26, v32, s[8:9]
	v_cndmask_b32_e64 v17, v27, v33, s[8:9]
	v_cndmask_b32_e64 v18, v28, v34, s[8:9]
	v_cndmask_b32_e64 v19, v29, v35, s[8:9]
	v_addc_co_u32_e32 v21, vcc, 0, v201, vcc
	global_store_dwordx4 v[20:21], v[16:19], off
	v_add_co_u32_e32 v20, vcc, s73, v200
	s_nop 0
	v_cndmask_b32_e64 v16, v24, v26, s[8:9]
	v_cndmask_b32_e64 v17, v22, v27, s[8:9]
	v_cndmask_b32_e64 v18, v23, v28, s[8:9]
	v_cndmask_b32_e64 v19, v25, v29, s[8:9]
	v_addc_co_u32_e32 v21, vcc, 0, v201, vcc
	global_store_dwordx4 v[20:21], v[16:19], off
	v_mov_b32_e32 v20, v185
	s_waitcnt vmcnt(14)
	v_cndmask_b32_e64 v19, v116, v112, s[8:9]
	v_cndmask_b32_e64 v18, v117, v113, s[8:9]
	v_cndmask_b32_e64 v17, v118, v114, s[8:9]
	v_mov_b32_dpp v20, v19 row_ror:8 row_mask:0xf bank_mask:0xf
	v_mov_b32_e32 v19, v185
	v_cndmask_b32_e64 v16, v119, v115, s[8:9]
	v_cndmask_b32_e64 v24, v20, v116, s[8:9]
	v_mov_b32_dpp v19, v18 row_ror:8 row_mask:0xf bank_mask:0xf
	v_mov_b32_e32 v18, v185
	v_cndmask_b32_e64 v22, v19, v117, s[8:9]
	v_cndmask_b32_e64 v27, v113, v19, s[8:9]
	v_mov_b32_dpp v18, v17 row_ror:8 row_mask:0xf bank_mask:0xf
	v_mov_b32_e32 v17, v185
	v_cndmask_b32_e64 v21, v18, v118, s[8:9]
	v_cndmask_b32_e64 v26, v114, v18, s[8:9]
	v_mov_b32_dpp v17, v16 row_ror:8 row_mask:0xf bank_mask:0xf
	v_cndmask_b32_e64 v23, v17, v119, s[8:9]
	v_cndmask_b32_e64 v25, v115, v17, s[8:9]
	v_lshlrev_b32_e32 v16, 16, v24
	v_and_b32_e32 v17, 0xffff0000, v24
	v_lshlrev_b32_e32 v18, 16, v22
	v_and_b32_e32 v19, 0xffff0000, v22
	v_lshlrev_b32_e32 v22, 16, v23
	v_and_b32_e32 v23, 0xffff0000, v23
	v_cndmask_b32_e64 v28, v112, v20, s[8:9]
	v_lshlrev_b32_e32 v20, 16, v21
	v_and_b32_e32 v21, 0xffff0000, v21
	v_pk_fma_f32 v[14:15], v[14:15], 0.5, v[18:19] op_sel_hi:[1,0,1]
	v_pk_fma_f32 v[12:13], v[12:13], 0.5, v[16:17] op_sel_hi:[1,0,1]
	v_pk_fma_f32 v[10:11], v[10:11], 0.5, v[22:23] op_sel_hi:[1,0,1]
	v_pk_fma_f32 v[8:9], v[8:9], 0.5, v[20:21] op_sel_hi:[1,0,1]
	v_cvt_pk_bf16_f32 v16, v12, v13
	v_cvt_pk_bf16_f32 v17, v14, v15
	v_lshlrev_b32_e32 v12, 16, v26
	v_cvt_pk_bf16_f32 v18, v8, v9
	v_cvt_pk_bf16_f32 v19, v10, v11
	v_lshlrev_b32_e32 v10, 16, v27
	v_and_b32_e32 v11, 0xffff0000, v27
	v_and_b32_e32 v13, 0xffff0000, v26
	v_lshlrev_b32_e32 v14, 16, v25
	v_and_b32_e32 v15, 0xffff0000, v25
	v_lshlrev_b32_e32 v8, 16, v28
	v_and_b32_e32 v9, 0xffff0000, v28
	v_pk_fma_f32 v[6:7], v[6:7], 0.5, v[10:11] op_sel_hi:[1,0,1]
	v_pk_fma_f32 v[2:3], v[2:3], 0.5, v[14:15] op_sel_hi:[1,0,1]
	v_pk_fma_f32 v[0:1], v[0:1], 0.5, v[12:13] op_sel_hi:[1,0,1]
	v_pk_fma_f32 v[4:5], v[4:5], 0.5, v[8:9] op_sel_hi:[1,0,1]
	v_mov_b32_e32 v10, v185
	v_cvt_pk_bf16_f32 v8, v4, v5
	v_cvt_pk_bf16_f32 v6, v6, v7
	v_cvt_pk_bf16_f32 v7, v0, v1
	v_cvt_pk_bf16_f32 v9, v2, v3
	v_mov_b32_e32 v11, v185
	v_cndmask_b32_e64 v0, v19, v9, s[8:9]
	v_cndmask_b32_e64 v1, v18, v7, s[8:9]
	v_cndmask_b32_e64 v2, v17, v6, s[8:9]
	v_cndmask_b32_e64 v3, v16, v8, s[8:9]
	v_mov_b32_e32 v12, v185
	v_mov_b32_e32 v13, v185
	v_mov_b32_dpp v10, v3 row_ror:8 row_mask:0xf bank_mask:0xf
	v_mov_b32_dpp v11, v2 row_ror:8 row_mask:0xf bank_mask:0xf
	v_mov_b32_dpp v12, v1 row_ror:8 row_mask:0xf bank_mask:0xf
	v_mov_b32_dpp v13, v0 row_ror:8 row_mask:0xf bank_mask:0xf
	v_add_co_u32_e32 v4, vcc, s74, v200
	v_cndmask_b32_e64 v0, v10, v16, s[8:9]
	v_cndmask_b32_e64 v1, v11, v17, s[8:9]
	v_cndmask_b32_e64 v2, v12, v18, s[8:9]
	v_cndmask_b32_e64 v3, v13, v19, s[8:9]
	v_addc_co_u32_e32 v5, vcc, 0, v201, vcc
	global_store_dwordx4 v[4:5], v[0:3], off
	v_add_co_u32_e32 v4, vcc, 0x5c000, v200
	s_nop 0
	v_cndmask_b32_e64 v0, v8, v10, s[8:9]
	v_addc_co_u32_e32 v5, vcc, 0, v201, vcc
	v_cndmask_b32_e64 v1, v6, v11, s[8:9]
	v_cndmask_b32_e64 v2, v7, v12, s[8:9]
	v_cndmask_b32_e64 v3, v9, v13, s[8:9]
	s_and_b64 vcc, exec, s[4:5]
	s_mov_b64 s[4:5], -1
	global_store_dwordx4 v[4:5], v[0:3], off
	s_cbranch_vccnz .LBB0_828
	s_andn2_b64 vcc, exec, s[12:13]
	s_cbranch_vccnz .LBB0_827
	s_branch .LBB0_827
